# baseline (speedup 1.0000x reference)
; #define WAIT_V(n) asm volatile("s_waitcnt vmcnt(" #n ")" ::: "memory")
; #define WAIT_L(n) asm volatile("s_waitcnt lgkmcnt(" #n ")" ::: "memory")
; #define BAR __builtin_amdgcn_s_barrier()
; #define SCHED __builtin_amdgcn_sched_barrier(0)
; #define STAGE(P, BASE, br, kt) do { const char* _g = (const char*)((BASE) + (size_t)(br) * GK + (kt) * BK); \
;     __builtin_amdgcn_global_load_lds((const unsigned*)(_g + voff0), (unsigned*)((char*)(P) + tx * 16), 16, 0, 0); \
;     __builtin_amdgcn_global_load_lds((const unsigned*)(_g + voff1), (unsigned*)((char*)(P) + tx * 16 + 8192), 16, 0, 0); } while (0)
; #define LDA(dst, b, h) _Pragma("unroll") for (int m = 0; m < 4; ++m) _Pragma("unroll") for (int k = 0; k < 2; ++k) \
;     dst[m][k] = *reinterpret_cast<const bf16x8*>((char*)shm + abase + (((b) * 2 + (h)) * 16384 + (m * 2 + k) * 1024))
; #define LDB(dst, b, h) _Pragma("unroll") for (int n = 0; n < 2; ++n) _Pragma("unroll") for (int k = 0; k < 2; ++k) \
;     dst[n][k] = *reinterpret_cast<const bf16x8*>((char*)shm + bbase + (((b) * 2 + (h)) * 16384 + (n * 2 + k) * 1024))
; template <bool SWAP>
; __device__ __forceinline__ void gemm_main(const u16* __restrict__ A, const u16* __restrict__ Bt, int brow, int bcol,
;                                           u16* shm, f32x4 (&acc)[2][2][4][2]) {
;     ...
;     LDB(B0, 0, 0); SCHED; LDA(At, 0, 0); STAGE(SA(1, 1), A, brow + HALF, t + 1);
;     WAIT_L(8); BAR; WAIT_L(0); MMA(0, 0, At, B0); BAR; SCHED;
;     LDB(B1, 0, 1); STAGE(SB(0, 0), Bt, bcol, t + 2);
;     BAR; WAIT_L(0); MMA(0, 1, At, B1); BAR;
;     LDA(At, 0, 1); STAGE(SA(0, 0), A, brow, t + 2);
;     BAR; WAIT_L(0); MMA(1, 0, At, B0); BAR; SCHED;
;     STAGE(SB(0, 1), Bt, bcol + HALF, t + 2);
;     WAIT_V(6); BAR; MMA(1, 1, At, B1); BAR;
;     LDB(B0, 1, 0); SCHED; LDA(At, 1, 0); STAGE(SA(0, 1), A, brow + HALF, t + 2);
.LBB0_84:
	ds_read_b128 v[176:179], v128 offset:1024
	ds_read_b128 v[184:187], v128 offset:3072
	ds_read_b128 v[192:195], v128 offset:5120
	ds_read_b128 v[200:203], v128 offset:7168
	v_add_u32_e32 v211, 0, v146
	v_add_u32_e32 v153, 0xc000, v211
	s_add_u32 m0, s29, 0xc000
	s_nop 0
	s_add_u32 vcc_lo, s26, s6
	s_addc_u32 vcc_hi, s27, s7
	global_load_lds_dwordx4 v134, vcc
	v_add_u32_e32 v154, 0xe000, v211
	v_lshl_add_u64 v[224:225], s[26:27], 0, v[136:137]
	s_add_u32 m0, s29, 0xe000
	s_nop 0
	global_load_lds_dwordx4 v136, vcc
	s_waitcnt lgkmcnt(8)
	s_barrier
	s_waitcnt lgkmcnt(0)
	v_mfma_f32_16x16x32_bf16 v[124:127], v[172:175], v[156:159], v[124:127]
	v_mfma_f32_16x16x32_bf16 v[120:123], v[172:175], v[164:167], v[120:123]
	v_mfma_f32_16x16x32_bf16 v[116:119], v[180:183], v[156:159], v[116:119]
	v_mfma_f32_16x16x32_bf16 v[112:115], v[180:183], v[164:167], v[112:115]
	v_mfma_f32_16x16x32_bf16 v[108:111], v[188:191], v[156:159], v[108:111]
	v_mfma_f32_16x16x32_bf16 v[104:107], v[188:191], v[164:167], v[104:107]
	v_mfma_f32_16x16x32_bf16 v[100:103], v[196:199], v[156:159], v[100:103]
	v_mfma_f32_16x16x32_bf16 v[96:99], v[196:199], v[164:167], v[96:99]
	v_mfma_f32_16x16x32_bf16 v[124:127], v[176:179], v[160:163], v[124:127]
	v_mfma_f32_16x16x32_bf16 v[120:123], v[176:179], v[168:171], v[120:123]
	v_mfma_f32_16x16x32_bf16 v[116:119], v[184:187], v[160:163], v[116:119]
	v_mfma_f32_16x16x32_bf16 v[112:115], v[184:187], v[168:171], v[112:115]
	v_mfma_f32_16x16x32_bf16 v[108:111], v[192:195], v[160:163], v[108:111]
	v_mfma_f32_16x16x32_bf16 v[104:107], v[192:195], v[168:171], v[104:107]
	v_mfma_f32_16x16x32_bf16 v[100:103], v[200:203], v[160:163], v[100:103]
	v_mfma_f32_16x16x32_bf16 v[96:99], v[200:203], v[168:171], v[96:99]
	s_barrier
	ds_read_b128 v[204:207], v145 offset:16384
	ds_read_b128 v[212:215], v145 offset:17408
	ds_read_b128 v[216:219], v145 offset:18432
	ds_read_b128 v[220:223], v145 offset:19456
	v_lshl_add_u64 v[226:227], s[26:27], 0, v[130:131]
	s_add_u32 m0, s29, s44
	s_nop 0
	s_add_u32 vcc_lo, s26, s8
	s_addc_u32 vcc_hi, s27, s9
	global_load_lds_dwordx4 v130, vcc
	v_lshl_add_u64 v[228:229], s[26:27], 0, v[132:133]
	s_add_u32 m0, s29, s44
	s_add_u32 m0, m0, 0x2000
	s_nop 0
	global_load_lds_dwordx4 v132, vcc
	s_barrier
	s_waitcnt lgkmcnt(0)
	v_mfma_f32_16x16x32_bf16 v[92:95], v[172:175], v[204:207], v[92:95]
	v_mfma_f32_16x16x32_bf16 v[88:91], v[172:175], v[216:219], v[88:91]
	v_mfma_f32_16x16x32_bf16 v[84:87], v[180:183], v[204:207], v[84:87]
	v_mfma_f32_16x16x32_bf16 v[80:83], v[180:183], v[216:219], v[80:83]
	v_mfma_f32_16x16x32_bf16 v[76:79], v[188:191], v[204:207], v[76:79]
	v_mfma_f32_16x16x32_bf16 v[72:75], v[188:191], v[216:219], v[72:75]
	v_mfma_f32_16x16x32_bf16 v[68:71], v[196:199], v[204:207], v[68:71]
	v_mfma_f32_16x16x32_bf16 v[64:67], v[196:199], v[216:219], v[64:67]
	v_mfma_f32_16x16x32_bf16 v[92:95], v[176:179], v[212:215], v[92:95]
	ds_read_b128 v[172:175], v128 offset:16384
	v_mfma_f32_16x16x32_bf16 v[88:91], v[176:179], v[220:223], v[88:91]
	v_mfma_f32_16x16x32_bf16 v[84:87], v[184:187], v[212:215], v[84:87]
	ds_read_b128 v[180:183], v128 offset:18432
	v_mfma_f32_16x16x32_bf16 v[80:83], v[184:187], v[220:223], v[80:83]
	v_mfma_f32_16x16x32_bf16 v[76:79], v[192:195], v[212:215], v[76:79]
	ds_read_b128 v[188:191], v128 offset:20480
	v_mfma_f32_16x16x32_bf16 v[72:75], v[192:195], v[220:223], v[72:75]
	v_mfma_f32_16x16x32_bf16 v[68:71], v[200:203], v[212:215], v[68:71]
	ds_read_b128 v[196:199], v128 offset:22528
	v_mfma_f32_16x16x32_bf16 v[64:67], v[200:203], v[220:223], v[64:67]
	s_barrier
	ds_read_b128 v[176:179], v128 offset:17408
	ds_read_b128 v[184:187], v128 offset:19456
	ds_read_b128 v[192:195], v128 offset:21504
	ds_read_b128 v[200:203], v128 offset:23552
	s_add_u32 m0, s29, 0x0
	s_nop 0
	s_add_u32 vcc_lo, s26, s10
	s_addc_u32 vcc_hi, s27, s11
	global_load_lds_dwordx4 v134, vcc
	s_add_u32 m0, s29, 0x2000
	s_nop 0
	global_load_lds_dwordx4 v136, vcc
	s_waitcnt vmcnt(8)
	s_barrier
	s_waitcnt lgkmcnt(0)
	v_mfma_f32_16x16x32_bf16 v[60:63], v[172:175], v[156:159], v[60:63]
	v_mfma_f32_16x16x32_bf16 v[56:59], v[172:175], v[164:167], v[56:59]
	v_mfma_f32_16x16x32_bf16 v[52:55], v[180:183], v[156:159], v[52:55]
	v_mfma_f32_16x16x32_bf16 v[48:51], v[180:183], v[164:167], v[48:51]
	v_mfma_f32_16x16x32_bf16 v[44:47], v[188:191], v[156:159], v[44:47]
	v_mfma_f32_16x16x32_bf16 v[40:43], v[188:191], v[164:167], v[40:43]
	v_mfma_f32_16x16x32_bf16 v[36:39], v[196:199], v[156:159], v[36:39]
	v_mfma_f32_16x16x32_bf16 v[32:35], v[196:199], v[164:167], v[32:35]
	v_mfma_f32_16x16x32_bf16 v[60:63], v[176:179], v[160:163], v[60:63]
	v_mfma_f32_16x16x32_bf16 v[56:59], v[176:179], v[168:171], v[56:59]
	v_mfma_f32_16x16x32_bf16 v[52:55], v[184:187], v[160:163], v[52:55]
	v_mfma_f32_16x16x32_bf16 v[48:51], v[184:187], v[168:171], v[48:51]
	v_mfma_f32_16x16x32_bf16 v[44:47], v[192:195], v[160:163], v[44:47]
	v_mfma_f32_16x16x32_bf16 v[40:43], v[192:195], v[168:171], v[40:43]
	v_mfma_f32_16x16x32_bf16 v[36:39], v[200:203], v[160:163], v[36:39]
	v_mfma_f32_16x16x32_bf16 v[32:35], v[200:203], v[168:171], v[32:35]
	s_barrier
	ds_read_b128 v[156:159], v145 offset:32768
	ds_read_b128 v[160:163], v145 offset:33792
	ds_read_b128 v[164:167], v145 offset:34816
	ds_read_b128 v[168:171], v145 offset:35840
	s_add_u32 m0, s29, s45
	s_nop 0
	s_add_u32 vcc_lo, s26, s12
	s_addc_u32 vcc_hi, s27, s13
	global_load_lds_dwordx4 v130, vcc
	s_add_u32 m0, s29, s45
	s_add_u32 m0, m0, 0x2000
	s_nop 0
	global_load_lds_dwordx4 v132, vcc
	s_waitcnt vmcnt(6)
	s_barrier
; #define WAIT_V(n) asm volatile("s_waitcnt vmcnt(" #n ")" ::: "memory")
; #define WAIT_L(n) asm volatile("s_waitcnt lgkmcnt(" #n ")" ::: "memory")
; #define BAR __builtin_amdgcn_s_barrier()
; #define SCHED __builtin_amdgcn_sched_barrier(0)
; #define STAGE(P, BASE, br, kt) do { const char* _g = (const char*)((BASE) + (size_t)(br) * GK + (kt) * BK); \
;     __builtin_amdgcn_global_load_lds((const unsigned*)(_g + voff0), (unsigned*)((char*)(P) + tx * 16), 16, 0, 0); \
;     __builtin_amdgcn_global_load_lds((const unsigned*)(_g + voff1), (unsigned*)((char*)(P) + tx * 16 + 8192), 16, 0, 0); } while (0)
; #define LDA(dst, b, h) _Pragma("unroll") for (int m = 0; m < 4; ++m) _Pragma("unroll") for (int k = 0; k < 2; ++k) \
;     dst[m][k] = *reinterpret_cast<const bf16x8*>((char*)shm + abase + (((b) * 2 + (h)) * 16384 + (m * 2 + k) * 1024))
; #define LDB(dst, b, h) _Pragma("unroll") for (int n = 0; n < 2; ++n) _Pragma("unroll") for (int k = 0; k < 2; ++k) \
;     dst[n][k] = *reinterpret_cast<const bf16x8*>((char*)shm + bbase + (((b) * 2 + (h)) * 16384 + (n * 2 + k) * 1024))
; template <bool SWAP>
; __device__ __forceinline__ void gemm_main(const u16* __restrict__ A, const u16* __restrict__ Bt, int brow, int bcol,
;                                           u16* shm, f32x4 (&acc)[2][2][4][2]) {
;     ...
;     WAIT_V(6); BAR; MMA(1, 1, At, B1); BAR;
;     LDB(B0, 1, 0); SCHED; LDA(At, 1, 0); STAGE(SA(0, 1), A, brow + HALF, t + 2);
;     WAIT_L(8); BAR; WAIT_L(0); MMA(0, 0, At, B0); BAR; SCHED;
;     LDB(B1, 1, 1); STAGE(SB(1, 0), Bt, bcol, t + 3);
;     BAR; WAIT_L(0); MMA(0, 1, At, B1); BAR;
;     LDA(At, 1, 1); STAGE(SA(1, 0), A, brow, t + 3);
;     BAR; WAIT_L(0); MMA(1, 0, At, B0); BAR; SCHED;
;     STAGE(SB(1, 1), Bt, bcol + HALF, t + 3);
	v_mfma_f32_16x16x32_bf16 v[28:31], v[172:175], v[204:207], v[28:31]
	v_mfma_f32_16x16x32_bf16 v[24:27], v[172:175], v[216:219], v[24:27]
	v_mfma_f32_16x16x32_bf16 v[20:23], v[180:183], v[204:207], v[20:23]
	v_mfma_f32_16x16x32_bf16 v[16:19], v[180:183], v[216:219], v[16:19]
	v_mfma_f32_16x16x32_bf16 v[12:15], v[188:191], v[204:207], v[12:15]
	v_mfma_f32_16x16x32_bf16 v[8:11], v[188:191], v[216:219], v[8:11]
	v_mfma_f32_16x16x32_bf16 v[4:7], v[196:199], v[204:207], v[4:7]
	v_mfma_f32_16x16x32_bf16 v[0:3], v[196:199], v[216:219], v[0:3]
	v_mfma_f32_16x16x32_bf16 v[28:31], v[176:179], v[212:215], v[28:31]
	ds_read_b128 v[172:175], v128 offset:32768
	v_mfma_f32_16x16x32_bf16 v[24:27], v[176:179], v[220:223], v[24:27]
	v_mfma_f32_16x16x32_bf16 v[20:23], v[184:187], v[212:215], v[20:23]
	ds_read_b128 v[180:183], v128 offset:34816
	v_mfma_f32_16x16x32_bf16 v[16:19], v[184:187], v[220:223], v[16:19]
	v_mfma_f32_16x16x32_bf16 v[12:15], v[192:195], v[212:215], v[12:15]
	ds_read_b128 v[188:191], v128 offset:36864
	v_mfma_f32_16x16x32_bf16 v[8:11], v[192:195], v[220:223], v[8:11]
	v_mfma_f32_16x16x32_bf16 v[4:7], v[200:203], v[212:215], v[4:7]
	ds_read_b128 v[196:199], v128 offset:38912
	v_mfma_f32_16x16x32_bf16 v[0:3], v[200:203], v[220:223], v[0:3]
	s_barrier
	ds_read_b128 v[176:179], v128 offset:33792
	ds_read_b128 v[184:187], v128 offset:35840
	ds_read_b128 v[192:195], v128 offset:37888
	ds_read_b128 v[200:203], v128 offset:39936
	s_add_u32 m0, s29, 0x4000
	s_nop 0
	s_add_u32 vcc_lo, s26, s14
	s_addc_u32 vcc_hi, s27, s15
	global_load_lds_dwordx4 v134, vcc
	s_add_u32 m0, s29, 0x6000
	s_nop 0
	global_load_lds_dwordx4 v136, vcc
	s_waitcnt lgkmcnt(8)
	s_barrier
	s_waitcnt lgkmcnt(0)
	v_mfma_f32_16x16x32_bf16 v[124:127], v[172:175], v[156:159], v[124:127]
	v_mfma_f32_16x16x32_bf16 v[120:123], v[172:175], v[164:167], v[120:123]
	v_mfma_f32_16x16x32_bf16 v[116:119], v[180:183], v[156:159], v[116:119]
	v_mfma_f32_16x16x32_bf16 v[112:115], v[180:183], v[164:167], v[112:115]
	v_mfma_f32_16x16x32_bf16 v[108:111], v[188:191], v[156:159], v[108:111]
	v_mfma_f32_16x16x32_bf16 v[104:107], v[188:191], v[164:167], v[104:107]
	v_mfma_f32_16x16x32_bf16 v[100:103], v[196:199], v[156:159], v[100:103]
	v_mfma_f32_16x16x32_bf16 v[96:99], v[196:199], v[164:167], v[96:99]
	v_mfma_f32_16x16x32_bf16 v[124:127], v[176:179], v[160:163], v[124:127]
	v_mfma_f32_16x16x32_bf16 v[120:123], v[176:179], v[168:171], v[120:123]
	v_mfma_f32_16x16x32_bf16 v[116:119], v[184:187], v[160:163], v[116:119]
	v_mfma_f32_16x16x32_bf16 v[112:115], v[184:187], v[168:171], v[112:115]
	v_mfma_f32_16x16x32_bf16 v[108:111], v[192:195], v[160:163], v[108:111]
	v_mfma_f32_16x16x32_bf16 v[104:107], v[192:195], v[168:171], v[104:107]
	v_mfma_f32_16x16x32_bf16 v[100:103], v[200:203], v[160:163], v[100:103]
	v_mfma_f32_16x16x32_bf16 v[96:99], v[200:203], v[168:171], v[96:99]
	s_barrier
	ds_read_b128 v[204:207], v145 offset:49152
	ds_read_b128 v[212:215], v145 offset:50176
	ds_read_b128 v[216:219], v145 offset:51200
	ds_read_b128 v[220:223], v145 offset:52224
	s_add_u32 m0, s29, s52
	s_nop 0
	s_add_u32 vcc_lo, s26, s16
	s_addc_u32 vcc_hi, s27, s17
	global_load_lds_dwordx4 v130, vcc
	v_lshl_add_u64 v[230:231], v[228:229], 0, s[16:17]
	s_add_u32 m0, s29, s52
	s_add_u32 m0, m0, 0x2000
	s_nop 0
	global_load_lds_dwordx4 v132, vcc
	s_barrier
	s_waitcnt lgkmcnt(0)
	v_mfma_f32_16x16x32_bf16 v[92:95], v[172:175], v[204:207], v[92:95]
	v_mfma_f32_16x16x32_bf16 v[88:91], v[172:175], v[216:219], v[88:91]
	v_mfma_f32_16x16x32_bf16 v[84:87], v[180:183], v[204:207], v[84:87]
	v_mfma_f32_16x16x32_bf16 v[80:83], v[180:183], v[216:219], v[80:83]
	v_mfma_f32_16x16x32_bf16 v[76:79], v[188:191], v[204:207], v[76:79]
	v_mfma_f32_16x16x32_bf16 v[72:75], v[188:191], v[216:219], v[72:75]
	v_mfma_f32_16x16x32_bf16 v[68:71], v[196:199], v[204:207], v[68:71]
	v_mfma_f32_16x16x32_bf16 v[64:67], v[196:199], v[216:219], v[64:67]
	v_mfma_f32_16x16x32_bf16 v[92:95], v[176:179], v[212:215], v[92:95]
	ds_read_b128 v[172:175], v128 offset:49152
	v_mfma_f32_16x16x32_bf16 v[88:91], v[176:179], v[220:223], v[88:91]
	v_mfma_f32_16x16x32_bf16 v[84:87], v[184:187], v[212:215], v[84:87]
	ds_read_b128 v[180:183], v128 offset:51200
	v_mfma_f32_16x16x32_bf16 v[80:83], v[184:187], v[220:223], v[80:83]
	v_mfma_f32_16x16x32_bf16 v[76:79], v[192:195], v[212:215], v[76:79]
	ds_read_b128 v[188:191], v128 offset:53248
	v_mfma_f32_16x16x32_bf16 v[72:75], v[192:195], v[220:223], v[72:75]
	v_mfma_f32_16x16x32_bf16 v[68:71], v[200:203], v[212:215], v[68:71]
	ds_read_b128 v[196:199], v128 offset:55296
	v_mfma_f32_16x16x32_bf16 v[64:67], v[200:203], v[220:223], v[64:67]
	s_barrier
	ds_read_b128 v[176:179], v128 offset:50176
	ds_read_b128 v[184:187], v128 offset:52224
	ds_read_b128 v[192:195], v128 offset:54272
	ds_read_b128 v[200:203], v128 offset:56320
	s_add_u32 m0, s29, 0x8000
	s_nop 0
	s_add_u32 vcc_lo, s26, s18
	s_addc_u32 vcc_hi, s27, s19
	global_load_lds_dwordx4 v134, vcc
	v_lshl_add_u64 v[208:209], v[224:225], 0, s[18:19]
	s_add_u32 m0, s29, 0xa000
	s_nop 0
	global_load_lds_dwordx4 v136, vcc
	s_waitcnt vmcnt(8)
	s_barrier
; #define WAIT_V(n) asm volatile("s_waitcnt vmcnt(" #n ")" ::: "memory")
; #define WAIT_L(n) asm volatile("s_waitcnt lgkmcnt(" #n ")" ::: "memory")
; #define BAR __builtin_amdgcn_s_barrier()
; #define SCHED __builtin_amdgcn_sched_barrier(0)
; #define STAGE(P, BASE, br, kt) do { const char* _g = (const char*)((BASE) + (size_t)(br) * GK + (kt) * BK); \
;     __builtin_amdgcn_global_load_lds((const unsigned*)(_g + voff0), (unsigned*)((char*)(P) + tx * 16), 16, 0, 0); \
;     __builtin_amdgcn_global_load_lds((const unsigned*)(_g + voff1), (unsigned*)((char*)(P) + tx * 16 + 8192), 16, 0, 0); } while (0)
; #define LDA(dst, b, h) _Pragma("unroll") for (int m = 0; m < 4; ++m) _Pragma("unroll") for (int k = 0; k < 2; ++k) \
;     dst[m][k] = *reinterpret_cast<const bf16x8*>((char*)shm + abase + (((b) * 2 + (h)) * 16384 + (m * 2 + k) * 1024))
; #define LDB(dst, b, h) _Pragma("unroll") for (int n = 0; n < 2; ++n) _Pragma("unroll") for (int k = 0; k < 2; ++k) \
;     dst[n][k] = *reinterpret_cast<const bf16x8*>((char*)shm + bbase + (((b) * 2 + (h)) * 16384 + (n * 2 + k) * 1024))
; template <bool SWAP>
; __device__ __forceinline__ void gemm_main(const u16* __restrict__ A, const u16* __restrict__ Bt, int brow, int bcol,
;                                           u16* shm, f32x4 (&acc)[2][2][4][2]) {
;     ...
;     LDA(At, 1, 1); STAGE(SA(1, 0), A, brow, t + 3);
;     BAR; WAIT_L(0); MMA(1, 0, At, B0); BAR; SCHED;
;     STAGE(SB(1, 1), Bt, bcol + HALF, t + 3);
;     WAIT_V(6); BAR; MMA(1, 1, At, B1); BAR;
;   }
;   { LDB(B0, 0, 0); LDA(At, 0, 0); STAGE(SA(1, 1), A, brow + HALF, nt - 1);
;     BAR; WAIT_L(0); MMA(0, 0, At, B0); BAR;
;     LDB(B1, 0, 1); BAR; WAIT_L(0); MMA(0, 1, At, B1); BAR;
	s_waitcnt lgkmcnt(0)
	v_mfma_f32_16x16x32_bf16 v[60:63], v[172:175], v[156:159], v[60:63]
	v_mfma_f32_16x16x32_bf16 v[56:59], v[172:175], v[164:167], v[56:59]
	v_mfma_f32_16x16x32_bf16 v[52:55], v[180:183], v[156:159], v[52:55]
	v_mfma_f32_16x16x32_bf16 v[48:51], v[180:183], v[164:167], v[48:51]
	v_mfma_f32_16x16x32_bf16 v[44:47], v[188:191], v[156:159], v[44:47]
	v_mfma_f32_16x16x32_bf16 v[40:43], v[188:191], v[164:167], v[40:43]
	v_mfma_f32_16x16x32_bf16 v[36:39], v[196:199], v[156:159], v[36:39]
	v_mfma_f32_16x16x32_bf16 v[32:35], v[196:199], v[164:167], v[32:35]
	v_mfma_f32_16x16x32_bf16 v[60:63], v[176:179], v[160:163], v[60:63]
	v_mfma_f32_16x16x32_bf16 v[56:59], v[176:179], v[168:171], v[56:59]
	v_mfma_f32_16x16x32_bf16 v[52:55], v[184:187], v[160:163], v[52:55]
	v_mfma_f32_16x16x32_bf16 v[48:51], v[184:187], v[168:171], v[48:51]
	v_mfma_f32_16x16x32_bf16 v[44:47], v[192:195], v[160:163], v[44:47]
	v_mfma_f32_16x16x32_bf16 v[40:43], v[192:195], v[168:171], v[40:43]
	v_mfma_f32_16x16x32_bf16 v[36:39], v[200:203], v[160:163], v[36:39]
	v_mfma_f32_16x16x32_bf16 v[32:35], v[200:203], v[168:171], v[32:35]
	s_barrier
	ds_read_b128 v[156:159], v145
	ds_read_b128 v[160:163], v145 offset:1024
	ds_read_b128 v[164:167], v145 offset:2048
	ds_read_b128 v[168:171], v145 offset:3072
	s_add_u32 m0, s29, s53
	s_nop 0
	s_add_u32 vcc_lo, s26, s20
	s_addc_u32 vcc_hi, s27, s21
	global_load_lds_dwordx4 v130, vcc
	v_lshl_add_u64 v[254:255], v[228:229], 0, s[20:21]
	s_add_u32 m0, s29, s53
	s_add_u32 m0, m0, 0x2000
	s_nop 0
	global_load_lds_dwordx4 v132, vcc
	s_waitcnt vmcnt(6)
	s_barrier
	v_mfma_f32_16x16x32_bf16 v[28:31], v[172:175], v[204:207], v[28:31]
	v_mfma_f32_16x16x32_bf16 v[24:27], v[172:175], v[216:219], v[24:27]
	v_mfma_f32_16x16x32_bf16 v[20:23], v[180:183], v[204:207], v[20:23]
	v_mfma_f32_16x16x32_bf16 v[16:19], v[180:183], v[216:219], v[16:19]
	v_mfma_f32_16x16x32_bf16 v[12:15], v[188:191], v[204:207], v[12:15]
	v_mfma_f32_16x16x32_bf16 v[8:11], v[188:191], v[216:219], v[8:11]
	v_mfma_f32_16x16x32_bf16 v[4:7], v[196:199], v[204:207], v[4:7]
	v_mfma_f32_16x16x32_bf16 v[0:3], v[196:199], v[216:219], v[0:3]
	v_mfma_f32_16x16x32_bf16 v[28:31], v[176:179], v[212:215], v[28:31]
	ds_read_b128 v[172:175], v128
	v_mfma_f32_16x16x32_bf16 v[24:27], v[176:179], v[220:223], v[24:27]
	v_mfma_f32_16x16x32_bf16 v[20:23], v[184:187], v[212:215], v[20:23]
	ds_read_b128 v[180:183], v128 offset:2048
	v_mfma_f32_16x16x32_bf16 v[16:19], v[184:187], v[220:223], v[16:19]
	v_mfma_f32_16x16x32_bf16 v[12:15], v[192:195], v[212:215], v[12:15]
	ds_read_b128 v[188:191], v128 offset:4096
	v_mfma_f32_16x16x32_bf16 v[8:11], v[192:195], v[220:223], v[8:11]
	v_mfma_f32_16x16x32_bf16 v[4:7], v[200:203], v[212:215], v[4:7]
	ds_read_b128 v[196:199], v128 offset:6144
	v_mfma_f32_16x16x32_bf16 v[0:3], v[200:203], v[220:223], v[0:3]
	s_add_i32 s28, s28, 2
	s_add_u32 s26, s26, 0x100
	s_addc_u32 s27, s27, 0
	s_cmp_lt_u32 s28, 28
	s_barrier
	s_cbranch_scc1 .LBB0_84
	v_lshlrev_b32_e32 v130, 3, v147
	v_lshlrev_b32_e32 v131, 5, v147
	v_and_b32_e32 v130, 0xffff0, v130
	v_and_b32_e32 v131, 32, v131
	v_add_u32_e32 v131, v131, v149
	v_add_lshl_u32 v130, v148, v130, 12
	s_add_u32 s4, s37, s4
	v_lshl_add_u32 v155, v131, 1, v130
	v_lshlrev_b32_e32 v130, 3, v150
	v_lshlrev_b32_e32 v131, 5, v150
	s_addc_u32 s27, s38, 0
	v_and_b32_e32 v130, 0xffff0, v130
	v_and_b32_e32 v131, 32, v131
	s_add_u32 s26, s4, 0x80f80
	v_readfirstlane_b32 s4, v153
	v_add_u32_e32 v131, v131, v152
	v_add_lshl_u32 v130, v151, v130, 12
	s_addc_u32 s27, s27, 0
	s_mov_b32 m0, s4
	v_readfirstlane_b32 s4, v154
	v_lshl_add_u32 v150, v131, 1, v130
	ds_read_b128 v[130:133], v145
	ds_read_b128 v[134:137], v145 offset:1024
	ds_read_b128 v[146:149], v145 offset:2048
	ds_read_b128 v[156:159], v145 offset:3072
	ds_read_b128 v[160:163], v128
	ds_read_b128 v[164:167], v128 offset:1024
	ds_read_b128 v[168:171], v128 offset:2048
	ds_read_b128 v[172:175], v128 offset:3072
	ds_read_b128 v[176:179], v128 offset:4096
	ds_read_b128 v[180:183], v128 offset:5120
	ds_read_b128 v[184:187], v128 offset:6144
	ds_read_b128 v[188:191], v128 offset:7168
	global_load_lds_dwordx4 v155, s[26:27]
	s_mov_b32 m0, s4
	s_nop 0
	global_load_lds_dwordx4 v150, s[26:27]
	s_barrier
	s_waitcnt lgkmcnt(0)
	v_mfma_f32_16x16x32_bf16 v[124:127], v[160:163], v[130:133], v[124:127]
	v_mfma_f32_16x16x32_bf16 v[116:119], v[168:171], v[130:133], v[116:119]
	v_mfma_f32_16x16x32_bf16 v[108:111], v[176:179], v[130:133], v[108:111]
	v_mfma_f32_16x16x32_bf16 v[100:103], v[184:187], v[130:133], v[100:103]
	v_mfma_f32_16x16x32_bf16 v[96:99], v[184:187], v[146:149], v[96:99]
	v_mfma_f32_16x16x32_bf16 v[124:127], v[164:167], v[134:137], v[124:127]
	v_mfma_f32_16x16x32_bf16 v[120:123], v[160:163], v[146:149], v[120:123]
	v_mfma_f32_16x16x32_bf16 v[116:119], v[172:175], v[134:137], v[116:119]
	v_mfma_f32_16x16x32_bf16 v[112:115], v[168:171], v[146:149], v[112:115]
	v_mfma_f32_16x16x32_bf16 v[108:111], v[180:183], v[134:137], v[108:111]
	v_mfma_f32_16x16x32_bf16 v[104:107], v[176:179], v[146:149], v[104:107]
	v_mfma_f32_16x16x32_bf16 v[100:103], v[188:191], v[134:137], v[100:103]
	v_mfma_f32_16x16x32_bf16 v[96:99], v[188:191], v[156:159], v[96:99]
	v_mfma_f32_16x16x32_bf16 v[150:153], v[164:167], v[156:159], v[120:123]
	v_mfma_f32_16x16x32_bf16 v[192:195], v[172:175], v[156:159], v[112:115]
	v_mfma_f32_16x16x32_bf16 v[196:199], v[180:183], v[156:159], v[104:107]
	s_setprio 0
	s_barrier
	s_nop 0
	ds_read_b128 v[104:107], v145 offset:16384
	ds_read_b128 v[112:115], v145 offset:17408
	ds_read_b128 v[120:123], v145 offset:18432
	ds_read_b128 v[200:203], v145 offset:19456
	s_barrier
; #define WAIT_V(n) asm volatile("s_waitcnt vmcnt(" #n ")" ::: "memory")
; #define WAIT_L(n) asm volatile("s_waitcnt lgkmcnt(" #n ")" ::: "memory")
; #define BAR __builtin_amdgcn_s_barrier()
; #define LDA(dst, b, h) _Pragma("unroll") for (int m = 0; m < 4; ++m) _Pragma("unroll") for (int k = 0; k < 2; ++k) \
;     dst[m][k] = *reinterpret_cast<const bf16x8*>((char*)shm + abase + (((b) * 2 + (h)) * 16384 + (m * 2 + k) * 1024))
; #define LDB(dst, b, h) _Pragma("unroll") for (int n = 0; n < 2; ++n) _Pragma("unroll") for (int k = 0; k < 2; ++k) \
;     dst[n][k] = *reinterpret_cast<const bf16x8*>((char*)shm + bbase + (((b) * 2 + (h)) * 16384 + (n * 2 + k) * 1024))
; template <bool SWAP>
; __device__ __forceinline__ void gemm_main(const u16* __restrict__ A, const u16* __restrict__ Bt, int brow, int bcol,
;                                           u16* shm, f32x4 (&acc)[2][2][4][2]) {
;     ...
;     LDB(B1, 0, 1); BAR; WAIT_L(0); MMA(0, 1, At, B1); BAR;
;     LDA(At, 0, 1); WAIT_V(4); BAR; WAIT_L(0); MMA(1, 0, At, B0); MMA(1, 1, At, B1); BAR; }
;   { LDB(B0, 1, 0); LDA(At, 1, 0); WAIT_V(2); BAR; WAIT_L(0); MMA(0, 0, At, B0); BAR;
	s_waitcnt lgkmcnt(0)
	v_mfma_f32_16x16x32_bf16 v[84:87], v[168:171], v[104:107], v[84:87]
	v_mfma_f32_16x16x32_bf16 v[76:79], v[176:179], v[104:107], v[76:79]
	v_mfma_f32_16x16x32_bf16 v[68:71], v[184:187], v[104:107], v[68:71]
	v_mfma_f32_16x16x32_bf16 v[92:95], v[160:163], v[104:107], v[92:95]
	v_mfma_f32_16x16x32_bf16 v[88:91], v[160:163], v[120:123], v[88:91]
	v_mfma_f32_16x16x32_bf16 v[84:87], v[172:175], v[112:115], v[84:87]
	v_mfma_f32_16x16x32_bf16 v[80:83], v[168:171], v[120:123], v[80:83]
	v_mfma_f32_16x16x32_bf16 v[76:79], v[180:183], v[112:115], v[76:79]
	v_mfma_f32_16x16x32_bf16 v[72:75], v[176:179], v[120:123], v[72:75]
	v_mfma_f32_16x16x32_bf16 v[68:71], v[188:191], v[112:115], v[68:71]
	v_mfma_f32_16x16x32_bf16 v[64:67], v[184:187], v[120:123], v[64:67]
	v_mfma_f32_16x16x32_bf16 v[204:207], v[164:167], v[112:115], v[92:95]
	v_mfma_f32_16x16x32_bf16 v[160:163], v[164:167], v[200:203], v[88:91]
	v_mfma_f32_16x16x32_bf16 v[164:167], v[172:175], v[200:203], v[80:83]
	v_mfma_f32_16x16x32_bf16 v[168:171], v[180:183], v[200:203], v[72:75]
	v_mfma_f32_16x16x32_bf16 v[172:175], v[188:191], v[200:203], v[64:67]
	s_setprio 0
	s_barrier
	s_nop 0
	ds_read_b128 v[64:67], v128 offset:16384
	ds_read_b128 v[72:75], v128 offset:17408
	ds_read_b128 v[80:83], v128 offset:18432
	ds_read_b128 v[88:91], v128 offset:19456
	ds_read_b128 v[92:95], v128 offset:20480
	ds_read_b128 v[176:179], v128 offset:21504
	ds_read_b128 v[180:183], v128 offset:22528
	ds_read_b128 v[184:187], v128 offset:23552
	s_waitcnt vmcnt(4)
	s_barrier
	s_waitcnt lgkmcnt(0)
	v_mfma_f32_16x16x32_bf16 v[60:63], v[64:67], v[130:133], v[60:63]
	v_mfma_f32_16x16x32_bf16 v[52:55], v[80:83], v[130:133], v[52:55]
	v_mfma_f32_16x16x32_bf16 v[44:47], v[92:95], v[130:133], v[44:47]
	v_mfma_f32_16x16x32_bf16 v[36:39], v[180:183], v[130:133], v[36:39]
	v_mfma_f32_16x16x32_bf16 v[60:63], v[72:75], v[134:137], v[60:63]
	v_mfma_f32_16x16x32_bf16 v[56:59], v[64:67], v[146:149], v[56:59]
	v_mfma_f32_16x16x32_bf16 v[52:55], v[88:91], v[134:137], v[52:55]
	v_mfma_f32_16x16x32_bf16 v[48:51], v[80:83], v[146:149], v[48:51]
	v_mfma_f32_16x16x32_bf16 v[44:47], v[176:179], v[134:137], v[44:47]
	v_mfma_f32_16x16x32_bf16 v[40:43], v[92:95], v[146:149], v[40:43]
	v_mfma_f32_16x16x32_bf16 v[36:39], v[184:187], v[134:137], v[36:39]
	v_mfma_f32_16x16x32_bf16 v[32:35], v[180:183], v[146:149], v[32:35]
	v_mfma_f32_16x16x32_bf16 v[188:191], v[72:75], v[156:159], v[56:59]
	v_mfma_f32_16x16x32_bf16 v[212:215], v[88:91], v[156:159], v[48:51]
	v_mfma_f32_16x16x32_bf16 v[216:219], v[176:179], v[156:159], v[40:43]
	v_mfma_f32_16x16x32_bf16 v[130:133], v[184:187], v[156:159], v[32:35]
	s_setprio 0
	v_mfma_f32_16x16x32_bf16 v[28:31], v[64:67], v[104:107], v[28:31]
	v_mfma_f32_16x16x32_bf16 v[20:23], v[80:83], v[104:107], v[20:23]
	v_mfma_f32_16x16x32_bf16 v[12:15], v[92:95], v[104:107], v[12:15]
	v_mfma_f32_16x16x32_bf16 v[4:7], v[180:183], v[104:107], v[4:7]
	v_mfma_f32_16x16x32_bf16 v[28:31], v[72:75], v[112:115], v[28:31]
	v_mfma_f32_16x16x32_bf16 v[24:27], v[64:67], v[120:123], v[24:27]
	v_mfma_f32_16x16x32_bf16 v[20:23], v[88:91], v[112:115], v[20:23]
	v_mfma_f32_16x16x32_bf16 v[16:19], v[80:83], v[120:123], v[16:19]
	v_mfma_f32_16x16x32_bf16 v[12:15], v[176:179], v[112:115], v[12:15]
	v_mfma_f32_16x16x32_bf16 v[8:11], v[92:95], v[120:123], v[8:11]
	v_mfma_f32_16x16x32_bf16 v[4:7], v[184:187], v[112:115], v[4:7]
	v_mfma_f32_16x16x32_bf16 v[0:3], v[180:183], v[120:123], v[0:3]
	v_mfma_f32_16x16x32_bf16 v[134:137], v[72:75], v[200:203], v[24:27]
	v_mfma_f32_16x16x32_bf16 v[146:149], v[88:91], v[200:203], v[16:19]
	v_mfma_f32_16x16x32_bf16 v[154:157], v[176:179], v[200:203], v[8:11]
	v_mfma_f32_16x16x32_bf16 v[176:179], v[184:187], v[200:203], v[0:3]
	s_setprio 0
	s_barrier
	s_nop 1
	ds_read_b128 v[0:3], v145 offset:32768
	ds_read_b128 v[8:11], v145 offset:33792
	ds_read_b128 v[16:19], v145 offset:34816
	ds_read_b128 v[24:27], v145 offset:35840
	ds_read_b128 v[32:35], v128 offset:32768
	ds_read_b128 v[40:43], v128 offset:33792
	ds_read_b128 v[48:51], v128 offset:34816
	ds_read_b128 v[56:59], v128 offset:35840
	ds_read_b128 v[64:67], v128 offset:36864
	ds_read_b128 v[180:183], v128 offset:37888
	ds_read_b128 v[184:187], v128 offset:38912
	ds_read_b128 v[200:203], v128 offset:39936
	s_waitcnt vmcnt(2)
	s_barrier
; #define WAIT_V(n) asm volatile("s_waitcnt vmcnt(" #n ")" ::: "memory")
; #define WAIT_L(n) asm volatile("s_waitcnt lgkmcnt(" #n ")" ::: "memory")
; #define BAR __builtin_amdgcn_s_barrier()
; #define LDA(dst, b, h) _Pragma("unroll") for (int m = 0; m < 4; ++m) _Pragma("unroll") for (int k = 0; k < 2; ++k) \
;     dst[m][k] = *reinterpret_cast<const bf16x8*>((char*)shm + abase + (((b) * 2 + (h)) * 16384 + (m * 2 + k) * 1024))
; #define LDB(dst, b, h) _Pragma("unroll") for (int n = 0; n < 2; ++n) _Pragma("unroll") for (int k = 0; k < 2; ++k) \
;     dst[n][k] = *reinterpret_cast<const bf16x8*>((char*)shm + bbase + (((b) * 2 + (h)) * 16384 + (n * 2 + k) * 1024))
; template <bool SWAP>
; __device__ __forceinline__ void gemm_main(const u16* __restrict__ A, const u16* __restrict__ Bt, int brow, int bcol,
;                                           u16* shm, f32x4 (&acc)[2][2][4][2]) {
;     ...
;   { LDB(B0, 1, 0); LDA(At, 1, 0); WAIT_V(2); BAR; WAIT_L(0); MMA(0, 0, At, B0); BAR;
;     LDB(B1, 1, 1); WAIT_V(0); BAR; WAIT_L(0); MMA(0, 1, At, B1); BAR;
;     LDA(At, 1, 1); BAR; WAIT_L(0); MMA(1, 0, At, B0); MMA(1, 1, At, B1); BAR; }
;   if (wr == 0) BAR;
	s_waitcnt lgkmcnt(0)
	v_mfma_f32_16x16x32_bf16 v[72:75], v[32:35], v[0:3], v[124:127]
	v_mfma_f32_16x16x32_bf16 v[120:123], v[40:43], v[8:11], v[72:75]
	v_mfma_f32_16x16x32_bf16 v[72:75], v[32:35], v[16:19], v[150:153]
	v_mfma_f32_16x16x32_bf16 v[112:115], v[40:43], v[24:27], v[72:75]
	v_mfma_f32_16x16x32_bf16 v[72:75], v[48:51], v[0:3], v[116:119]
	v_mfma_f32_16x16x32_bf16 v[124:127], v[56:59], v[8:11], v[72:75]
	v_mfma_f32_16x16x32_bf16 v[72:75], v[48:51], v[16:19], v[192:195]
	v_mfma_f32_16x16x32_bf16 v[116:119], v[56:59], v[24:27], v[72:75]
	v_mfma_f32_16x16x32_bf16 v[72:75], v[64:67], v[0:3], v[108:111]
	v_mfma_f32_16x16x32_bf16 v[104:107], v[180:183], v[8:11], v[72:75]
	v_mfma_f32_16x16x32_bf16 v[72:75], v[64:67], v[16:19], v[196:199]
	v_mfma_f32_16x16x32_bf16 v[92:95], v[180:183], v[24:27], v[72:75]
	v_mfma_f32_16x16x32_bf16 v[72:75], v[184:187], v[0:3], v[100:103]
	v_mfma_f32_16x16x32_bf16 v[108:111], v[200:203], v[8:11], v[72:75]
	v_mfma_f32_16x16x32_bf16 v[72:75], v[184:187], v[16:19], v[96:99]
	v_mfma_f32_16x16x32_bf16 v[100:103], v[200:203], v[24:27], v[72:75]
	s_setprio 0
	s_barrier
	ds_read_b128 v[150:153], v145 offset:49152
	ds_read_b128 v[192:195], v145 offset:50176
	ds_read_b128 v[196:199], v145 offset:51200
	ds_read_b128 v[220:223], v145 offset:52224
	s_waitcnt vmcnt(0)
	s_barrier
	s_waitcnt lgkmcnt(0)
	v_mfma_f32_16x16x32_bf16 v[72:75], v[32:35], v[150:153], v[204:207]
	v_mfma_f32_16x16x32_bf16 v[32:35], v[32:35], v[196:199], v[160:163]
	v_mfma_f32_16x16x32_bf16 v[80:83], v[40:43], v[220:223], v[32:35]
	v_mfma_f32_16x16x32_bf16 v[32:35], v[48:51], v[150:153], v[84:87]
	v_mfma_f32_16x16x32_bf16 v[96:99], v[56:59], v[192:195], v[32:35]
	v_mfma_f32_16x16x32_bf16 v[32:35], v[48:51], v[196:199], v[164:167]
	v_mfma_f32_16x16x32_bf16 v[84:87], v[56:59], v[220:223], v[32:35]
	v_mfma_f32_16x16x32_bf16 v[32:35], v[64:67], v[150:153], v[76:79]
	v_mfma_f32_16x16x32_bf16 v[88:91], v[40:43], v[192:195], v[72:75]
	v_mfma_f32_16x16x32_bf16 v[72:75], v[180:183], v[192:195], v[32:35]
	v_mfma_f32_16x16x32_bf16 v[32:35], v[64:67], v[196:199], v[168:171]
	v_mfma_f32_16x16x32_bf16 v[64:67], v[180:183], v[220:223], v[32:35]
	v_mfma_f32_16x16x32_bf16 v[32:35], v[184:187], v[150:153], v[68:71]
	v_mfma_f32_16x16x32_bf16 v[76:79], v[200:203], v[192:195], v[32:35]
	v_mfma_f32_16x16x32_bf16 v[32:35], v[184:187], v[196:199], v[172:175]
	v_mfma_f32_16x16x32_bf16 v[68:71], v[200:203], v[220:223], v[32:35]
	s_setprio 0
	s_barrier
	ds_read_b128 v[158:161], v128 offset:49152
	ds_read_b128 v[162:165], v128 offset:50176
	ds_read_b128 v[166:169], v128 offset:51200
	ds_read_b128 v[170:173], v128 offset:52224
	ds_read_b128 v[180:183], v128 offset:53248
	ds_read_b128 v[184:187], v128 offset:54272
	ds_read_b128 v[200:203], v128 offset:55296
	ds_read_b128 v[204:207], v128 offset:56320
	s_barrier
	s_waitcnt lgkmcnt(0)
	v_mfma_f32_16x16x32_bf16 v[32:35], v[158:161], v[0:3], v[60:63]
	v_mfma_f32_16x16x32_bf16 v[56:59], v[162:165], v[8:11], v[32:35]
	v_mfma_f32_16x16x32_bf16 v[32:35], v[158:161], v[16:19], v[188:191]
	v_mfma_f32_16x16x32_bf16 v[48:51], v[162:165], v[24:27], v[32:35]
	v_mfma_f32_16x16x32_bf16 v[32:35], v[166:169], v[0:3], v[52:55]
	v_mfma_f32_16x16x32_bf16 v[60:63], v[170:173], v[8:11], v[32:35]
	v_mfma_f32_16x16x32_bf16 v[32:35], v[166:169], v[16:19], v[212:215]
	v_mfma_f32_16x16x32_bf16 v[52:55], v[170:173], v[24:27], v[32:35]
	v_mfma_f32_16x16x32_bf16 v[32:35], v[180:183], v[0:3], v[44:47]
	v_mfma_f32_16x16x32_bf16 v[0:3], v[200:203], v[0:3], v[36:39]
	v_mfma_f32_16x16x32_bf16 v[40:43], v[184:187], v[8:11], v[32:35]
	v_mfma_f32_16x16x32_bf16 v[32:35], v[180:183], v[16:19], v[216:219]
	v_mfma_f32_16x16x32_bf16 v[44:47], v[204:207], v[8:11], v[0:3]
	v_mfma_f32_16x16x32_bf16 v[0:3], v[200:203], v[16:19], v[130:133]
	v_mfma_f32_16x16x32_bf16 v[32:35], v[184:187], v[24:27], v[32:35]
	v_mfma_f32_16x16x32_bf16 v[36:39], v[204:207], v[24:27], v[0:3]
	s_setprio 0
	v_mfma_f32_16x16x32_bf16 v[0:3], v[158:161], v[150:153], v[28:31]
	v_mfma_f32_16x16x32_bf16 v[24:27], v[162:165], v[192:195], v[0:3]
	v_mfma_f32_16x16x32_bf16 v[0:3], v[158:161], v[196:199], v[134:137]
	v_mfma_f32_16x16x32_bf16 v[16:19], v[162:165], v[220:223], v[0:3]
	v_mfma_f32_16x16x32_bf16 v[0:3], v[166:169], v[150:153], v[20:23]
	v_mfma_f32_16x16x32_bf16 v[28:31], v[170:173], v[192:195], v[0:3]
	v_mfma_f32_16x16x32_bf16 v[0:3], v[166:169], v[196:199], v[146:149]
	v_mfma_f32_16x16x32_bf16 v[20:23], v[170:173], v[220:223], v[0:3]
	v_mfma_f32_16x16x32_bf16 v[0:3], v[180:183], v[150:153], v[12:15]
	v_mfma_f32_16x16x32_bf16 v[4:7], v[200:203], v[150:153], v[4:7]
	v_mfma_f32_16x16x32_bf16 v[8:11], v[184:187], v[192:195], v[0:3]
	v_mfma_f32_16x16x32_bf16 v[0:3], v[180:183], v[196:199], v[154:157]
	v_mfma_f32_16x16x32_bf16 v[12:15], v[204:207], v[192:195], v[4:7]
	v_mfma_f32_16x16x32_bf16 v[4:7], v[200:203], v[196:199], v[176:179]
	v_mfma_f32_16x16x32_bf16 v[0:3], v[184:187], v[220:223], v[0:3]
	v_mfma_f32_16x16x32_bf16 v[4:7], v[204:207], v[220:223], v[4:7]
	s_setprio 0
	v_cmp_gt_u32_e32 vcc, s55, v144
	s_barrier
	s_and_saveexec_b64 s[26:27], vcc
	s_cbranch_execz .LBB0_87
	s_barrier

; #define WAIT_L(n) asm volatile("s_waitcnt lgkmcnt(" #n ")" ::: "memory")
; #define BAR __builtin_amdgcn_s_barrier()
; #define SCHED __builtin_amdgcn_sched_barrier(0)
; #define STAGE(P, BASE, br, kt) do { const char* _g = (const char*)((BASE) + (size_t)(br) * GK + (kt) * BK); \
;     __builtin_amdgcn_global_load_lds((const unsigned*)(_g + voff0), (unsigned*)((char*)(P) + tx * 16), 16, 0, 0); \
;     __builtin_amdgcn_global_load_lds((const unsigned*)(_g + voff1), (unsigned*)((char*)(P) + tx * 16 + 8192), 16, 0, 0); } while (0)
; #define LDA(dst, b, h) _Pragma("unroll") for (int m = 0; m < 4; ++m) _Pragma("unroll") for (int k = 0; k < 2; ++k) \
;     dst[m][k] = *reinterpret_cast<const bf16x8*>((char*)shm + abase + (((b) * 2 + (h)) * 16384 + (m * 2 + k) * 1024))
; #define LDB(dst, b, h) _Pragma("unroll") for (int n = 0; n < 2; ++n) _Pragma("unroll") for (int k = 0; k < 2; ++k) \
;     dst[n][k] = *reinterpret_cast<const bf16x8*>((char*)shm + bbase + (((b) * 2 + (h)) * 16384 + (n * 2 + k) * 1024))
; template <bool SWAP>
; __device__ __forceinline__ void gemm_main(const u16* __restrict__ A, const u16* __restrict__ Bt, int brow, int bcol,
;                                           u16* shm, f32x4 (&acc)[2][2][4][2]) {
;     ...
;     LDB(B0, 0, 0); SCHED; LDA(At, 0, 0); STAGE(SA(1, 1), A, brow + HALF, t + 1);
;     WAIT_L(8); BAR; WAIT_L(0); MMA(0, 0, At, B0); BAR; SCHED;
;     LDB(B1, 0, 1); STAGE(SB(0, 0), Bt, bcol, t + 2);
;     BAR; WAIT_L(0); MMA(0, 1, At, B1); BAR;
;     LDA(At, 0, 1); STAGE(SA(0, 0), A, brow, t + 2);
;     BAR; WAIT_L(0); MMA(1, 0, At, B0); BAR; SCHED;
;     STAGE(SB(0, 1), Bt, bcol + HALF, t + 2);
.LBB0_94:
	ds_read_b128 v[176:179], v145 offset:1024
	ds_read_b128 v[184:187], v145 offset:3072
	ds_read_b128 v[192:195], v145 offset:5120
	ds_read_b128 v[200:203], v145 offset:7168
	v_add_u32_e32 v128, 0, v147
	v_add_u32_e32 v154, 0xc000, v128
	v_add_u32_e32 v155, 0xe000, v128
	s_add_u32 m0, s25, 0xc000
	v_lshl_add_u64 v[224:225], s[28:29], 0, v[132:133]
	s_add_u32 vcc_lo, s28, s6
	s_addc_u32 vcc_hi, s29, s7
	global_load_lds_dwordx4 v136, vcc
	s_add_u32 m0, s25, 0xe000
	s_nop 0
	global_load_lds_dwordx4 v132, vcc
	s_waitcnt lgkmcnt(8)
	s_barrier
	s_waitcnt lgkmcnt(0)
	v_mfma_f32_16x16x32_bf16 v[124:127], v[156:159], v[172:175], v[124:127]
	v_mfma_f32_16x16x32_bf16 v[120:123], v[164:167], v[172:175], v[120:123]
	v_mfma_f32_16x16x32_bf16 v[116:119], v[156:159], v[180:183], v[116:119]
	v_mfma_f32_16x16x32_bf16 v[112:115], v[164:167], v[180:183], v[112:115]
	v_mfma_f32_16x16x32_bf16 v[108:111], v[156:159], v[188:191], v[108:111]
	v_mfma_f32_16x16x32_bf16 v[104:107], v[164:167], v[188:191], v[104:107]
	v_mfma_f32_16x16x32_bf16 v[100:103], v[156:159], v[196:199], v[100:103]
	v_mfma_f32_16x16x32_bf16 v[96:99], v[164:167], v[196:199], v[96:99]
	v_mfma_f32_16x16x32_bf16 v[124:127], v[160:163], v[176:179], v[124:127]
	v_mfma_f32_16x16x32_bf16 v[120:123], v[168:171], v[176:179], v[120:123]
	v_mfma_f32_16x16x32_bf16 v[116:119], v[160:163], v[184:187], v[116:119]
	v_mfma_f32_16x16x32_bf16 v[112:115], v[168:171], v[184:187], v[112:115]
	v_mfma_f32_16x16x32_bf16 v[108:111], v[160:163], v[192:195], v[108:111]
	v_mfma_f32_16x16x32_bf16 v[104:107], v[168:171], v[192:195], v[104:107]
	v_mfma_f32_16x16x32_bf16 v[100:103], v[160:163], v[200:203], v[100:103]
	v_mfma_f32_16x16x32_bf16 v[96:99], v[168:171], v[200:203], v[96:99]
	s_barrier
	ds_read_b128 v[204:207], v146 offset:16384
	ds_read_b128 v[212:215], v146 offset:17408
	ds_read_b128 v[216:219], v146 offset:18432
	ds_read_b128 v[220:223], v146 offset:19456
	v_lshl_add_u64 v[226:227], s[28:29], 0, v[134:135]
	s_add_u32 m0, s25, s44
	s_nop 0
	s_add_u32 vcc_lo, s28, s8
	s_addc_u32 vcc_hi, s29, s9
	global_load_lds_dwordx4 v134, vcc
	v_lshl_add_u64 v[228:229], s[28:29], 0, v[130:131]
	s_add_u32 m0, s25, s44
	s_add_u32 m0, m0, 0x2000
	s_nop 0
	global_load_lds_dwordx4 v130, vcc
	s_barrier
	s_waitcnt lgkmcnt(0)
	v_mfma_f32_16x16x32_bf16 v[92:95], v[204:207], v[172:175], v[92:95]
	v_mfma_f32_16x16x32_bf16 v[88:91], v[216:219], v[172:175], v[88:91]
	v_mfma_f32_16x16x32_bf16 v[84:87], v[204:207], v[180:183], v[84:87]
	v_mfma_f32_16x16x32_bf16 v[80:83], v[216:219], v[180:183], v[80:83]
	v_mfma_f32_16x16x32_bf16 v[76:79], v[204:207], v[188:191], v[76:79]
	v_mfma_f32_16x16x32_bf16 v[72:75], v[216:219], v[188:191], v[72:75]
	v_mfma_f32_16x16x32_bf16 v[68:71], v[204:207], v[196:199], v[68:71]
	v_mfma_f32_16x16x32_bf16 v[64:67], v[216:219], v[196:199], v[64:67]
	v_mfma_f32_16x16x32_bf16 v[92:95], v[212:215], v[176:179], v[92:95]
	ds_read_b128 v[172:175], v145 offset:16384
	v_mfma_f32_16x16x32_bf16 v[88:91], v[220:223], v[176:179], v[88:91]
	v_mfma_f32_16x16x32_bf16 v[84:87], v[212:215], v[184:187], v[84:87]
	ds_read_b128 v[180:183], v145 offset:18432
	v_mfma_f32_16x16x32_bf16 v[80:83], v[220:223], v[184:187], v[80:83]
	v_mfma_f32_16x16x32_bf16 v[76:79], v[212:215], v[192:195], v[76:79]
	ds_read_b128 v[188:191], v145 offset:20480
	v_mfma_f32_16x16x32_bf16 v[72:75], v[220:223], v[192:195], v[72:75]
	v_mfma_f32_16x16x32_bf16 v[68:71], v[212:215], v[200:203], v[68:71]
	ds_read_b128 v[196:199], v145 offset:22528
	v_mfma_f32_16x16x32_bf16 v[64:67], v[220:223], v[200:203], v[64:67]
	s_barrier
	ds_read_b128 v[176:179], v145 offset:17408
	ds_read_b128 v[184:187], v145 offset:19456
	ds_read_b128 v[192:195], v145 offset:21504
	ds_read_b128 v[200:203], v145 offset:23552
	s_add_u32 m0, s25, 0x0
	s_nop 0
	s_add_u32 vcc_lo, s28, s10
	s_addc_u32 vcc_hi, s29, s11
	global_load_lds_dwordx4 v136, vcc
	s_add_u32 m0, s25, 0x2000
	s_nop 0
	global_load_lds_dwordx4 v132, vcc
	s_waitcnt vmcnt(8)
	s_barrier
	s_waitcnt lgkmcnt(0)
	v_mfma_f32_16x16x32_bf16 v[60:63], v[156:159], v[172:175], v[60:63]
	v_mfma_f32_16x16x32_bf16 v[56:59], v[164:167], v[172:175], v[56:59]
	v_mfma_f32_16x16x32_bf16 v[52:55], v[156:159], v[180:183], v[52:55]
	v_mfma_f32_16x16x32_bf16 v[48:51], v[164:167], v[180:183], v[48:51]
	v_mfma_f32_16x16x32_bf16 v[44:47], v[156:159], v[188:191], v[44:47]
	v_mfma_f32_16x16x32_bf16 v[40:43], v[164:167], v[188:191], v[40:43]
	v_mfma_f32_16x16x32_bf16 v[36:39], v[156:159], v[196:199], v[36:39]
	v_mfma_f32_16x16x32_bf16 v[32:35], v[164:167], v[196:199], v[32:35]
	v_mfma_f32_16x16x32_bf16 v[60:63], v[160:163], v[176:179], v[60:63]
	v_mfma_f32_16x16x32_bf16 v[56:59], v[168:171], v[176:179], v[56:59]
	v_mfma_f32_16x16x32_bf16 v[52:55], v[160:163], v[184:187], v[52:55]
	v_mfma_f32_16x16x32_bf16 v[48:51], v[168:171], v[184:187], v[48:51]
	v_mfma_f32_16x16x32_bf16 v[44:47], v[160:163], v[192:195], v[44:47]
	v_mfma_f32_16x16x32_bf16 v[40:43], v[168:171], v[192:195], v[40:43]
	v_mfma_f32_16x16x32_bf16 v[36:39], v[160:163], v[200:203], v[36:39]
	v_mfma_f32_16x16x32_bf16 v[32:35], v[168:171], v[200:203], v[32:35]
	s_barrier
	ds_read_b128 v[156:159], v146 offset:32768
	ds_read_b128 v[160:163], v146 offset:33792
	ds_read_b128 v[164:167], v146 offset:34816
	ds_read_b128 v[168:171], v146 offset:35840
	s_add_u32 m0, s25, s45
	s_nop 0
	s_add_u32 vcc_lo, s28, s12
	s_addc_u32 vcc_hi, s29, s13
	global_load_lds_dwordx4 v134, vcc
	s_add_u32 m0, s25, s45
	s_add_u32 m0, m0, 0x2000
	s_nop 0
	global_load_lds_dwordx4 v130, vcc
	s_waitcnt vmcnt(6)
	s_barrier
; #define WAIT_V(n) asm volatile("s_waitcnt vmcnt(" #n ")" ::: "memory")
; #define WAIT_L(n) asm volatile("s_waitcnt lgkmcnt(" #n ")" ::: "memory")
; #define BAR __builtin_amdgcn_s_barrier()
; #define SCHED __builtin_amdgcn_sched_barrier(0)
; #define STAGE(P, BASE, br, kt) do { const char* _g = (const char*)((BASE) + (size_t)(br) * GK + (kt) * BK); \
;     __builtin_amdgcn_global_load_lds((const unsigned*)(_g + voff0), (unsigned*)((char*)(P) + tx * 16), 16, 0, 0); \
;     __builtin_amdgcn_global_load_lds((const unsigned*)(_g + voff1), (unsigned*)((char*)(P) + tx * 16 + 8192), 16, 0, 0); } while (0)
; #define LDA(dst, b, h) _Pragma("unroll") for (int m = 0; m < 4; ++m) _Pragma("unroll") for (int k = 0; k < 2; ++k) \
;     dst[m][k] = *reinterpret_cast<const bf16x8*>((char*)shm + abase + (((b) * 2 + (h)) * 16384 + (m * 2 + k) * 1024))
; #define LDB(dst, b, h) _Pragma("unroll") for (int n = 0; n < 2; ++n) _Pragma("unroll") for (int k = 0; k < 2; ++k) \
;     dst[n][k] = *reinterpret_cast<const bf16x8*>((char*)shm + bbase + (((b) * 2 + (h)) * 16384 + (n * 2 + k) * 1024))
; template <bool SWAP>
; __device__ __forceinline__ void gemm_main(const u16* __restrict__ A, const u16* __restrict__ Bt, int brow, int bcol,
;                                           u16* shm, f32x4 (&acc)[2][2][4][2]) {
;     ...
;     WAIT_V(6); BAR; MMA(1, 1, At, B1); BAR;
;     LDB(B0, 1, 0); SCHED; LDA(At, 1, 0); STAGE(SA(0, 1), A, brow + HALF, t + 2);
;     WAIT_L(8); BAR; WAIT_L(0); MMA(0, 0, At, B0); BAR; SCHED;
;     LDB(B1, 1, 1); STAGE(SB(1, 0), Bt, bcol, t + 3);
;     BAR; WAIT_L(0); MMA(0, 1, At, B1); BAR;
;     LDA(At, 1, 1); STAGE(SA(1, 0), A, brow, t + 3);
;     BAR; WAIT_L(0); MMA(1, 0, At, B0); BAR; SCHED;
;     STAGE(SB(1, 1), Bt, bcol + HALF, t + 3);
	v_mfma_f32_16x16x32_bf16 v[28:31], v[204:207], v[172:175], v[28:31]
	v_mfma_f32_16x16x32_bf16 v[24:27], v[216:219], v[172:175], v[24:27]
	v_mfma_f32_16x16x32_bf16 v[20:23], v[204:207], v[180:183], v[20:23]
	v_mfma_f32_16x16x32_bf16 v[16:19], v[216:219], v[180:183], v[16:19]
	v_mfma_f32_16x16x32_bf16 v[12:15], v[204:207], v[188:191], v[12:15]
	v_mfma_f32_16x16x32_bf16 v[8:11], v[216:219], v[188:191], v[8:11]
	v_mfma_f32_16x16x32_bf16 v[4:7], v[204:207], v[196:199], v[4:7]
	v_mfma_f32_16x16x32_bf16 v[0:3], v[216:219], v[196:199], v[0:3]
	v_mfma_f32_16x16x32_bf16 v[28:31], v[212:215], v[176:179], v[28:31]
	ds_read_b128 v[172:175], v145 offset:32768
	v_mfma_f32_16x16x32_bf16 v[24:27], v[220:223], v[176:179], v[24:27]
	v_mfma_f32_16x16x32_bf16 v[20:23], v[212:215], v[184:187], v[20:23]
	ds_read_b128 v[180:183], v145 offset:34816
	v_mfma_f32_16x16x32_bf16 v[16:19], v[220:223], v[184:187], v[16:19]
	v_mfma_f32_16x16x32_bf16 v[12:15], v[212:215], v[192:195], v[12:15]
	ds_read_b128 v[188:191], v145 offset:36864
	v_mfma_f32_16x16x32_bf16 v[8:11], v[220:223], v[192:195], v[8:11]
	v_mfma_f32_16x16x32_bf16 v[4:7], v[212:215], v[200:203], v[4:7]
	ds_read_b128 v[196:199], v145 offset:38912
	v_mfma_f32_16x16x32_bf16 v[0:3], v[220:223], v[200:203], v[0:3]
	s_barrier
	ds_read_b128 v[176:179], v145 offset:33792
	ds_read_b128 v[184:187], v145 offset:35840
	ds_read_b128 v[192:195], v145 offset:37888
	ds_read_b128 v[200:203], v145 offset:39936
	s_add_u32 m0, s25, 0x4000
	s_nop 0
	s_add_u32 vcc_lo, s28, s14
	s_addc_u32 vcc_hi, s29, s15
	global_load_lds_dwordx4 v136, vcc
	s_add_u32 m0, s25, 0x6000
	s_nop 0
	global_load_lds_dwordx4 v132, vcc
	s_waitcnt lgkmcnt(8)
	s_barrier
	s_waitcnt lgkmcnt(0)
	v_mfma_f32_16x16x32_bf16 v[124:127], v[156:159], v[172:175], v[124:127]
	v_mfma_f32_16x16x32_bf16 v[120:123], v[164:167], v[172:175], v[120:123]
	v_mfma_f32_16x16x32_bf16 v[116:119], v[156:159], v[180:183], v[116:119]
	v_mfma_f32_16x16x32_bf16 v[112:115], v[164:167], v[180:183], v[112:115]
	v_mfma_f32_16x16x32_bf16 v[108:111], v[156:159], v[188:191], v[108:111]
	v_mfma_f32_16x16x32_bf16 v[104:107], v[164:167], v[188:191], v[104:107]
	v_mfma_f32_16x16x32_bf16 v[100:103], v[156:159], v[196:199], v[100:103]
	v_mfma_f32_16x16x32_bf16 v[96:99], v[164:167], v[196:199], v[96:99]
	v_mfma_f32_16x16x32_bf16 v[124:127], v[160:163], v[176:179], v[124:127]
	v_mfma_f32_16x16x32_bf16 v[120:123], v[168:171], v[176:179], v[120:123]
	v_mfma_f32_16x16x32_bf16 v[116:119], v[160:163], v[184:187], v[116:119]
	v_mfma_f32_16x16x32_bf16 v[112:115], v[168:171], v[184:187], v[112:115]
	v_mfma_f32_16x16x32_bf16 v[108:111], v[160:163], v[192:195], v[108:111]
	v_mfma_f32_16x16x32_bf16 v[104:107], v[168:171], v[192:195], v[104:107]
	v_mfma_f32_16x16x32_bf16 v[100:103], v[160:163], v[200:203], v[100:103]
	v_mfma_f32_16x16x32_bf16 v[96:99], v[168:171], v[200:203], v[96:99]
	s_barrier
	ds_read_b128 v[204:207], v146 offset:49152
	ds_read_b128 v[212:215], v146 offset:50176
	ds_read_b128 v[216:219], v146 offset:51200
	ds_read_b128 v[220:223], v146 offset:52224
	s_add_u32 m0, s25, s52
	s_nop 0
	s_add_u32 vcc_lo, s28, s16
	s_addc_u32 vcc_hi, s29, s17
	global_load_lds_dwordx4 v134, vcc
	v_lshl_add_u64 v[230:231], v[228:229], 0, s[16:17]
	s_add_u32 m0, s25, s52
	s_add_u32 m0, m0, 0x2000
	s_nop 0
	global_load_lds_dwordx4 v130, vcc
	s_barrier
	s_waitcnt lgkmcnt(0)
	v_mfma_f32_16x16x32_bf16 v[92:95], v[204:207], v[172:175], v[92:95]
	v_mfma_f32_16x16x32_bf16 v[88:91], v[216:219], v[172:175], v[88:91]
	v_mfma_f32_16x16x32_bf16 v[84:87], v[204:207], v[180:183], v[84:87]
	v_mfma_f32_16x16x32_bf16 v[80:83], v[216:219], v[180:183], v[80:83]
	v_mfma_f32_16x16x32_bf16 v[76:79], v[204:207], v[188:191], v[76:79]
	v_mfma_f32_16x16x32_bf16 v[72:75], v[216:219], v[188:191], v[72:75]
	v_mfma_f32_16x16x32_bf16 v[68:71], v[204:207], v[196:199], v[68:71]
	v_mfma_f32_16x16x32_bf16 v[64:67], v[216:219], v[196:199], v[64:67]
	v_mfma_f32_16x16x32_bf16 v[92:95], v[212:215], v[176:179], v[92:95]
	ds_read_b128 v[172:175], v145 offset:49152
	v_mfma_f32_16x16x32_bf16 v[88:91], v[220:223], v[176:179], v[88:91]
	v_mfma_f32_16x16x32_bf16 v[84:87], v[212:215], v[184:187], v[84:87]
	ds_read_b128 v[180:183], v145 offset:51200
	v_mfma_f32_16x16x32_bf16 v[80:83], v[220:223], v[184:187], v[80:83]
	v_mfma_f32_16x16x32_bf16 v[76:79], v[212:215], v[192:195], v[76:79]
	ds_read_b128 v[188:191], v145 offset:53248
	v_mfma_f32_16x16x32_bf16 v[72:75], v[220:223], v[192:195], v[72:75]
	v_mfma_f32_16x16x32_bf16 v[68:71], v[212:215], v[200:203], v[68:71]
	ds_read_b128 v[196:199], v145 offset:55296
	v_mfma_f32_16x16x32_bf16 v[64:67], v[220:223], v[200:203], v[64:67]
	s_barrier
	ds_read_b128 v[176:179], v145 offset:50176
	ds_read_b128 v[184:187], v145 offset:52224
	ds_read_b128 v[192:195], v145 offset:54272
	ds_read_b128 v[200:203], v145 offset:56320
	s_add_u32 m0, s25, 0x8000
	s_nop 0
	s_add_u32 vcc_lo, s28, s18
	s_addc_u32 vcc_hi, s29, s19
	global_load_lds_dwordx4 v136, vcc
	v_lshl_add_u64 v[208:209], v[224:225], 0, s[18:19]
	s_add_u32 m0, s25, 0xa000
	s_nop 0
	global_load_lds_dwordx4 v132, vcc
	s_waitcnt vmcnt(8)
	s_barrier
; #define WAIT_V(n) asm volatile("s_waitcnt vmcnt(" #n ")" ::: "memory")
; #define WAIT_L(n) asm volatile("s_waitcnt lgkmcnt(" #n ")" ::: "memory")
; #define BAR __builtin_amdgcn_s_barrier()
; #define SCHED __builtin_amdgcn_sched_barrier(0)
; #define STAGE(P, BASE, br, kt) do { const char* _g = (const char*)((BASE) + (size_t)(br) * GK + (kt) * BK); \
;     __builtin_amdgcn_global_load_lds((const unsigned*)(_g + voff0), (unsigned*)((char*)(P) + tx * 16), 16, 0, 0); \
;     __builtin_amdgcn_global_load_lds((const unsigned*)(_g + voff1), (unsigned*)((char*)(P) + tx * 16 + 8192), 16, 0, 0); } while (0)
; #define LDA(dst, b, h) _Pragma("unroll") for (int m = 0; m < 4; ++m) _Pragma("unroll") for (int k = 0; k < 2; ++k) \
;     dst[m][k] = *reinterpret_cast<const bf16x8*>((char*)shm + abase + (((b) * 2 + (h)) * 16384 + (m * 2 + k) * 1024))
; #define LDB(dst, b, h) _Pragma("unroll") for (int n = 0; n < 2; ++n) _Pragma("unroll") for (int k = 0; k < 2; ++k) \
;     dst[n][k] = *reinterpret_cast<const bf16x8*>((char*)shm + bbase + (((b) * 2 + (h)) * 16384 + (n * 2 + k) * 1024))
; template <bool SWAP>
; __device__ __forceinline__ void gemm_main(const u16* __restrict__ A, const u16* __restrict__ Bt, int brow, int bcol,
;                                           u16* shm, f32x4 (&acc)[2][2][4][2]) {
;     ...
;     LDA(At, 1, 1); STAGE(SA(1, 0), A, brow, t + 3);
;     BAR; WAIT_L(0); MMA(1, 0, At, B0); BAR; SCHED;
;     STAGE(SB(1, 1), Bt, bcol + HALF, t + 3);
;     WAIT_V(6); BAR; MMA(1, 1, At, B1); BAR;
;   }
;   { LDB(B0, 0, 0); LDA(At, 0, 0); STAGE(SA(1, 1), A, brow + HALF, nt - 1);
;     BAR; WAIT_L(0); MMA(0, 0, At, B0); BAR;
;     LDB(B1, 0, 1); BAR; WAIT_L(0); MMA(0, 1, At, B1); BAR;
	s_waitcnt lgkmcnt(0)
	v_mfma_f32_16x16x32_bf16 v[60:63], v[156:159], v[172:175], v[60:63]
	v_mfma_f32_16x16x32_bf16 v[56:59], v[164:167], v[172:175], v[56:59]
	v_mfma_f32_16x16x32_bf16 v[52:55], v[156:159], v[180:183], v[52:55]
	v_mfma_f32_16x16x32_bf16 v[48:51], v[164:167], v[180:183], v[48:51]
	v_mfma_f32_16x16x32_bf16 v[44:47], v[156:159], v[188:191], v[44:47]
	v_mfma_f32_16x16x32_bf16 v[40:43], v[164:167], v[188:191], v[40:43]
	v_mfma_f32_16x16x32_bf16 v[36:39], v[156:159], v[196:199], v[36:39]
	v_mfma_f32_16x16x32_bf16 v[32:35], v[164:167], v[196:199], v[32:35]
	v_mfma_f32_16x16x32_bf16 v[60:63], v[160:163], v[176:179], v[60:63]
	v_mfma_f32_16x16x32_bf16 v[56:59], v[168:171], v[176:179], v[56:59]
	v_mfma_f32_16x16x32_bf16 v[52:55], v[160:163], v[184:187], v[52:55]
	v_mfma_f32_16x16x32_bf16 v[48:51], v[168:171], v[184:187], v[48:51]
	v_mfma_f32_16x16x32_bf16 v[44:47], v[160:163], v[192:195], v[44:47]
	v_mfma_f32_16x16x32_bf16 v[40:43], v[168:171], v[192:195], v[40:43]
	v_mfma_f32_16x16x32_bf16 v[36:39], v[160:163], v[200:203], v[36:39]
	v_mfma_f32_16x16x32_bf16 v[32:35], v[168:171], v[200:203], v[32:35]
	s_barrier
	ds_read_b128 v[156:159], v146
	ds_read_b128 v[160:163], v146 offset:1024
	ds_read_b128 v[164:167], v146 offset:2048
	ds_read_b128 v[168:171], v146 offset:3072
	s_add_u32 m0, s25, s53
	s_nop 0
	s_add_u32 vcc_lo, s28, s20
	s_addc_u32 vcc_hi, s29, s21
	global_load_lds_dwordx4 v134, vcc
	v_lshl_add_u64 v[254:255], v[228:229], 0, s[20:21]
	s_add_u32 m0, s25, s53
	s_add_u32 m0, m0, 0x2000
	s_nop 0
	global_load_lds_dwordx4 v130, vcc
	s_waitcnt vmcnt(6)
	s_barrier
	v_mfma_f32_16x16x32_bf16 v[28:31], v[204:207], v[172:175], v[28:31]
	v_mfma_f32_16x16x32_bf16 v[24:27], v[216:219], v[172:175], v[24:27]
	v_mfma_f32_16x16x32_bf16 v[20:23], v[204:207], v[180:183], v[20:23]
	v_mfma_f32_16x16x32_bf16 v[16:19], v[216:219], v[180:183], v[16:19]
	v_mfma_f32_16x16x32_bf16 v[12:15], v[204:207], v[188:191], v[12:15]
	v_mfma_f32_16x16x32_bf16 v[8:11], v[216:219], v[188:191], v[8:11]
	v_mfma_f32_16x16x32_bf16 v[4:7], v[204:207], v[196:199], v[4:7]
	v_mfma_f32_16x16x32_bf16 v[0:3], v[216:219], v[196:199], v[0:3]
	v_mfma_f32_16x16x32_bf16 v[28:31], v[212:215], v[176:179], v[28:31]
	ds_read_b128 v[172:175], v145
	v_mfma_f32_16x16x32_bf16 v[24:27], v[220:223], v[176:179], v[24:27]
	v_mfma_f32_16x16x32_bf16 v[20:23], v[212:215], v[184:187], v[20:23]
	ds_read_b128 v[180:183], v145 offset:2048
	v_mfma_f32_16x16x32_bf16 v[16:19], v[220:223], v[184:187], v[16:19]
	v_mfma_f32_16x16x32_bf16 v[12:15], v[212:215], v[192:195], v[12:15]
	ds_read_b128 v[188:191], v145 offset:4096
	v_mfma_f32_16x16x32_bf16 v[8:11], v[220:223], v[192:195], v[8:11]
	v_mfma_f32_16x16x32_bf16 v[4:7], v[212:215], v[200:203], v[4:7]
	ds_read_b128 v[196:199], v145 offset:6144
	v_mfma_f32_16x16x32_bf16 v[0:3], v[220:223], v[200:203], v[0:3]
	s_add_i32 s4, s4, 2
	s_add_u32 s28, s28, 0x100
	s_addc_u32 s29, s29, 0
	s_cmp_lt_u32 s4, 28
	s_barrier
	s_cbranch_scc1 .LBB0_94
	v_lshlrev_b32_e32 v128, 3, v148
	v_lshlrev_b32_e32 v130, 5, v148
	v_and_b32_e32 v128, 0xffff0, v128
	v_and_b32_e32 v130, 32, v130
	s_or_b32 s28, s26, 0x80
	v_add_u32_e32 v130, v130, v150
	v_add_lshl_u32 v128, v149, v128, 12
	s_ashr_i32 s29, s28, 31
	v_lshl_add_u32 v128, v130, 1, v128
	v_lshlrev_b32_e32 v130, 3, v151
	v_lshlrev_b32_e32 v131, 5, v151
	s_lshl_b64 s[28:29], s[28:29], 12
	v_and_b32_e32 v130, 0xffff0, v130
	v_and_b32_e32 v131, 32, v131
	s_add_u32 s28, s37, s28
	v_add_u32_e32 v131, v131, v153
	v_add_lshl_u32 v130, v152, v130, 12
	s_addc_u32 s29, s38, s29
	v_lshl_add_u32 v152, v131, 1, v130
	v_mov_b32_e32 v153, v129
	v_lshl_add_u64 v[192:193], s[28:29], 0, v[128:129]
	v_readfirstlane_b32 s4, v154
	v_lshl_add_u64 v[192:193], v[192:193], 0, s[22:23]
	s_mov_b32 m0, s4
	v_lshl_add_u64 v[152:153], s[28:29], 0, v[152:153]
	v_readfirstlane_b32 s4, v155
	ds_read_b128 v[130:133], v146
	ds_read_b128 v[134:137], v146 offset:1024
	ds_read_b128 v[148:151], v146 offset:2048
	ds_read_b128 v[156:159], v146 offset:3072
	ds_read_b128 v[160:163], v145
	ds_read_b128 v[164:167], v145 offset:1024
	ds_read_b128 v[168:171], v145 offset:2048
	ds_read_b128 v[172:175], v145 offset:3072
	ds_read_b128 v[176:179], v145 offset:4096
	ds_read_b128 v[180:183], v145 offset:5120
	ds_read_b128 v[184:187], v145 offset:6144
	ds_read_b128 v[188:191], v145 offset:7168
	global_load_lds_dwordx4 v[192:193], off
	v_lshl_add_u64 v[152:153], v[152:153], 0, s[22:23]
	s_mov_b32 m0, s4
	s_nop 0
	global_load_lds_dwordx4 v[152:153], off
	s_barrier
	s_waitcnt lgkmcnt(0)
	v_mfma_f32_16x16x32_bf16 v[124:127], v[130:133], v[160:163], v[124:127]
	v_mfma_f32_16x16x32_bf16 v[116:119], v[130:133], v[168:171], v[116:119]
	v_mfma_f32_16x16x32_bf16 v[108:111], v[130:133], v[176:179], v[108:111]
	v_mfma_f32_16x16x32_bf16 v[100:103], v[130:133], v[184:187], v[100:103]
	v_mfma_f32_16x16x32_bf16 v[124:127], v[134:137], v[164:167], v[124:127]
	v_mfma_f32_16x16x32_bf16 v[120:123], v[148:151], v[160:163], v[120:123]
	v_mfma_f32_16x16x32_bf16 v[116:119], v[134:137], v[172:175], v[116:119]
	v_mfma_f32_16x16x32_bf16 v[112:115], v[148:151], v[168:171], v[112:115]
	v_mfma_f32_16x16x32_bf16 v[108:111], v[134:137], v[180:183], v[108:111]
	v_mfma_f32_16x16x32_bf16 v[104:107], v[148:151], v[176:179], v[104:107]
	v_mfma_f32_16x16x32_bf16 v[100:103], v[134:137], v[188:191], v[100:103]
	v_mfma_f32_16x16x32_bf16 v[96:99], v[148:151], v[184:187], v[96:99]
	v_mfma_f32_16x16x32_bf16 v[152:155], v[156:159], v[164:167], v[120:123]
	v_mfma_f32_16x16x32_bf16 v[192:195], v[156:159], v[172:175], v[112:115]
	v_mfma_f32_16x16x32_bf16 v[196:199], v[156:159], v[180:183], v[104:107]
	v_mfma_f32_16x16x32_bf16 v[200:203], v[156:159], v[188:191], v[96:99]
	s_setprio 0
	s_barrier
; #define WAIT_V(n) asm volatile("s_waitcnt vmcnt(" #n ")" ::: "memory")
; #define WAIT_L(n) asm volatile("s_waitcnt lgkmcnt(" #n ")" ::: "memory")
; #define BAR __builtin_amdgcn_s_barrier()
; #define LDA(dst, b, h) _Pragma("unroll") for (int m = 0; m < 4; ++m) _Pragma("unroll") for (int k = 0; k < 2; ++k) \
;     dst[m][k] = *reinterpret_cast<const bf16x8*>((char*)shm + abase + (((b) * 2 + (h)) * 16384 + (m * 2 + k) * 1024))
; #define LDB(dst, b, h) _Pragma("unroll") for (int n = 0; n < 2; ++n) _Pragma("unroll") for (int k = 0; k < 2; ++k) \
;     dst[n][k] = *reinterpret_cast<const bf16x8*>((char*)shm + bbase + (((b) * 2 + (h)) * 16384 + (n * 2 + k) * 1024))
; template <bool SWAP>
; __device__ __forceinline__ void gemm_main(const u16* __restrict__ A, const u16* __restrict__ Bt, int brow, int bcol,
;                                           u16* shm, f32x4 (&acc)[2][2][4][2]) {
;     ...
;     LDB(B1, 0, 1); BAR; WAIT_L(0); MMA(0, 1, At, B1); BAR;
;     LDA(At, 0, 1); WAIT_V(4); BAR; WAIT_L(0); MMA(1, 0, At, B0); MMA(1, 1, At, B1); BAR; }
;   { LDB(B0, 1, 0); LDA(At, 1, 0); WAIT_V(2); BAR; WAIT_L(0); MMA(0, 0, At, B0); BAR;
	s_nop 1
	ds_read_b128 v[96:99], v146 offset:16384
	ds_read_b128 v[104:107], v146 offset:17408
	ds_read_b128 v[112:115], v146 offset:18432
	ds_read_b128 v[120:123], v146 offset:19456
	s_barrier
	s_waitcnt lgkmcnt(0)
	v_mfma_f32_16x16x32_bf16 v[92:95], v[96:99], v[160:163], v[92:95]
	v_mfma_f32_16x16x32_bf16 v[84:87], v[96:99], v[168:171], v[84:87]
	v_mfma_f32_16x16x32_bf16 v[76:79], v[96:99], v[176:179], v[76:79]
	v_mfma_f32_16x16x32_bf16 v[68:71], v[96:99], v[184:187], v[68:71]
	v_mfma_f32_16x16x32_bf16 v[92:95], v[104:107], v[164:167], v[92:95]
	v_mfma_f32_16x16x32_bf16 v[88:91], v[112:115], v[160:163], v[88:91]
	v_mfma_f32_16x16x32_bf16 v[84:87], v[104:107], v[172:175], v[84:87]
	v_mfma_f32_16x16x32_bf16 v[80:83], v[112:115], v[168:171], v[80:83]
	v_mfma_f32_16x16x32_bf16 v[76:79], v[104:107], v[180:183], v[76:79]
	v_mfma_f32_16x16x32_bf16 v[72:75], v[112:115], v[176:179], v[72:75]
	v_mfma_f32_16x16x32_bf16 v[68:71], v[104:107], v[188:191], v[68:71]
	v_mfma_f32_16x16x32_bf16 v[64:67], v[112:115], v[184:187], v[64:67]
	v_mfma_f32_16x16x32_bf16 v[160:163], v[120:123], v[164:167], v[88:91]
	v_mfma_f32_16x16x32_bf16 v[164:167], v[120:123], v[172:175], v[80:83]
	v_mfma_f32_16x16x32_bf16 v[168:171], v[120:123], v[180:183], v[72:75]
	v_mfma_f32_16x16x32_bf16 v[172:175], v[120:123], v[188:191], v[64:67]
	s_setprio 0
	s_barrier
	s_nop 1
	ds_read_b128 v[64:67], v145 offset:16384
	ds_read_b128 v[72:75], v145 offset:17408
	ds_read_b128 v[80:83], v145 offset:18432
	ds_read_b128 v[88:91], v145 offset:19456
	ds_read_b128 v[176:179], v145 offset:20480
	ds_read_b128 v[180:183], v145 offset:21504
	ds_read_b128 v[184:187], v145 offset:22528
	ds_read_b128 v[188:191], v145 offset:23552
	s_waitcnt vmcnt(4)
	s_barrier
	s_waitcnt lgkmcnt(0)
	v_mfma_f32_16x16x32_bf16 v[60:63], v[130:133], v[64:67], v[60:63]
	v_mfma_f32_16x16x32_bf16 v[52:55], v[130:133], v[80:83], v[52:55]
	v_mfma_f32_16x16x32_bf16 v[44:47], v[130:133], v[176:179], v[44:47]
	v_mfma_f32_16x16x32_bf16 v[36:39], v[130:133], v[184:187], v[36:39]
	v_mfma_f32_16x16x32_bf16 v[60:63], v[134:137], v[72:75], v[60:63]
	v_mfma_f32_16x16x32_bf16 v[56:59], v[148:151], v[64:67], v[56:59]
	v_mfma_f32_16x16x32_bf16 v[52:55], v[134:137], v[88:91], v[52:55]
	v_mfma_f32_16x16x32_bf16 v[48:51], v[148:151], v[80:83], v[48:51]
	v_mfma_f32_16x16x32_bf16 v[44:47], v[134:137], v[180:183], v[44:47]
	v_mfma_f32_16x16x32_bf16 v[40:43], v[148:151], v[176:179], v[40:43]
	v_mfma_f32_16x16x32_bf16 v[36:39], v[134:137], v[188:191], v[36:39]
	v_mfma_f32_16x16x32_bf16 v[32:35], v[148:151], v[184:187], v[32:35]
	v_mfma_f32_16x16x32_bf16 v[204:207], v[156:159], v[72:75], v[56:59]
	v_mfma_f32_16x16x32_bf16 v[212:215], v[156:159], v[88:91], v[48:51]
	v_mfma_f32_16x16x32_bf16 v[216:219], v[156:159], v[180:183], v[40:43]
	v_mfma_f32_16x16x32_bf16 v[130:133], v[156:159], v[188:191], v[32:35]
	s_setprio 0
	v_mfma_f32_16x16x32_bf16 v[28:31], v[96:99], v[64:67], v[28:31]
	v_mfma_f32_16x16x32_bf16 v[20:23], v[96:99], v[80:83], v[20:23]
	v_mfma_f32_16x16x32_bf16 v[12:15], v[96:99], v[176:179], v[12:15]
	v_mfma_f32_16x16x32_bf16 v[4:7], v[96:99], v[184:187], v[4:7]
	v_mfma_f32_16x16x32_bf16 v[28:31], v[104:107], v[72:75], v[28:31]
	v_mfma_f32_16x16x32_bf16 v[24:27], v[112:115], v[64:67], v[24:27]
	v_mfma_f32_16x16x32_bf16 v[20:23], v[104:107], v[88:91], v[20:23]
	v_mfma_f32_16x16x32_bf16 v[16:19], v[112:115], v[80:83], v[16:19]
	v_mfma_f32_16x16x32_bf16 v[12:15], v[104:107], v[180:183], v[12:15]
	v_mfma_f32_16x16x32_bf16 v[8:11], v[112:115], v[176:179], v[8:11]
	v_mfma_f32_16x16x32_bf16 v[4:7], v[104:107], v[188:191], v[4:7]
	v_mfma_f32_16x16x32_bf16 v[0:3], v[112:115], v[184:187], v[0:3]
	v_mfma_f32_16x16x32_bf16 v[134:137], v[120:123], v[72:75], v[24:27]
	v_mfma_f32_16x16x32_bf16 v[148:151], v[120:123], v[88:91], v[16:19]
	v_mfma_f32_16x16x32_bf16 v[156:159], v[120:123], v[180:183], v[8:11]
	v_mfma_f32_16x16x32_bf16 v[176:179], v[120:123], v[188:191], v[0:3]
	s_setprio 0
	s_barrier
	s_nop 1
	ds_read_b128 v[0:3], v146 offset:32768
	ds_read_b128 v[8:11], v146 offset:33792
	ds_read_b128 v[16:19], v146 offset:34816
	ds_read_b128 v[24:27], v146 offset:35840
	ds_read_b128 v[32:35], v145 offset:32768
	ds_read_b128 v[40:43], v145 offset:33792
	ds_read_b128 v[48:51], v145 offset:34816
	ds_read_b128 v[56:59], v145 offset:35840
	ds_read_b128 v[64:67], v145 offset:36864
	ds_read_b128 v[180:183], v145 offset:37888
	ds_read_b128 v[184:187], v145 offset:38912
	ds_read_b128 v[188:191], v145 offset:39936
	s_waitcnt vmcnt(2)
	s_barrier
; #define WAIT_V(n) asm volatile("s_waitcnt vmcnt(" #n ")" ::: "memory")
; #define WAIT_L(n) asm volatile("s_waitcnt lgkmcnt(" #n ")" ::: "memory")
; #define BAR __builtin_amdgcn_s_barrier()
; #define LDA(dst, b, h) _Pragma("unroll") for (int m = 0; m < 4; ++m) _Pragma("unroll") for (int k = 0; k < 2; ++k) \
;     dst[m][k] = *reinterpret_cast<const bf16x8*>((char*)shm + abase + (((b) * 2 + (h)) * 16384 + (m * 2 + k) * 1024))
; #define LDB(dst, b, h) _Pragma("unroll") for (int n = 0; n < 2; ++n) _Pragma("unroll") for (int k = 0; k < 2; ++k) \
;     dst[n][k] = *reinterpret_cast<const bf16x8*>((char*)shm + bbase + (((b) * 2 + (h)) * 16384 + (n * 2 + k) * 1024))
; template <bool SWAP>
; __device__ __forceinline__ void gemm_main(const u16* __restrict__ A, const u16* __restrict__ Bt, int brow, int bcol,
;                                           u16* shm, f32x4 (&acc)[2][2][4][2]) {
;     ...
;   { LDB(B0, 1, 0); LDA(At, 1, 0); WAIT_V(2); BAR; WAIT_L(0); MMA(0, 0, At, B0); BAR;
;     LDB(B1, 1, 1); WAIT_V(0); BAR; WAIT_L(0); MMA(0, 1, At, B1); BAR;
;     LDA(At, 1, 1); BAR; WAIT_L(0); MMA(1, 0, At, B0); MMA(1, 1, At, B1); BAR; }
;   if (wr == 0) BAR;
	s_waitcnt lgkmcnt(0)
	v_mfma_f32_16x16x32_bf16 v[72:75], v[0:3], v[32:35], v[124:127]
	v_mfma_f32_16x16x32_bf16 v[120:123], v[8:11], v[40:43], v[72:75]
	v_mfma_f32_16x16x32_bf16 v[72:75], v[16:19], v[32:35], v[152:155]
	v_mfma_f32_16x16x32_bf16 v[124:127], v[24:27], v[40:43], v[72:75]
	v_mfma_f32_16x16x32_bf16 v[72:75], v[0:3], v[48:51], v[116:119]
	v_mfma_f32_16x16x32_bf16 v[112:115], v[8:11], v[56:59], v[72:75]
	v_mfma_f32_16x16x32_bf16 v[72:75], v[16:19], v[48:51], v[192:195]
	v_mfma_f32_16x16x32_bf16 v[116:119], v[24:27], v[56:59], v[72:75]
	v_mfma_f32_16x16x32_bf16 v[72:75], v[0:3], v[64:67], v[108:111]
	v_mfma_f32_16x16x32_bf16 v[104:107], v[8:11], v[180:183], v[72:75]
	v_mfma_f32_16x16x32_bf16 v[72:75], v[16:19], v[64:67], v[196:199]
	v_mfma_f32_16x16x32_bf16 v[108:111], v[24:27], v[180:183], v[72:75]
	v_mfma_f32_16x16x32_bf16 v[72:75], v[0:3], v[184:187], v[100:103]
	v_mfma_f32_16x16x32_bf16 v[96:99], v[8:11], v[188:191], v[72:75]
	v_mfma_f32_16x16x32_bf16 v[72:75], v[16:19], v[184:187], v[200:203]
	v_mfma_f32_16x16x32_bf16 v[100:103], v[24:27], v[188:191], v[72:75]
	s_setprio 0
	s_barrier
	ds_read_b128 v[152:155], v146 offset:49152
	ds_read_b128 v[192:195], v146 offset:50176
	ds_read_b128 v[196:199], v146 offset:51200
	ds_read_b128 v[200:203], v146 offset:52224
	s_waitcnt vmcnt(0)
	s_barrier
	s_waitcnt lgkmcnt(0)
	v_mfma_f32_16x16x32_bf16 v[72:75], v[152:155], v[32:35], v[92:95]
	v_mfma_f32_16x16x32_bf16 v[32:35], v[196:199], v[32:35], v[160:163]
	v_mfma_f32_16x16x32_bf16 v[92:95], v[200:203], v[40:43], v[32:35]
	v_mfma_f32_16x16x32_bf16 v[32:35], v[152:155], v[48:51], v[84:87]
	v_mfma_f32_16x16x32_bf16 v[80:83], v[192:195], v[56:59], v[32:35]
	v_mfma_f32_16x16x32_bf16 v[32:35], v[196:199], v[48:51], v[164:167]
	v_mfma_f32_16x16x32_bf16 v[84:87], v[200:203], v[56:59], v[32:35]
	v_mfma_f32_16x16x32_bf16 v[32:35], v[152:155], v[64:67], v[76:79]
	v_mfma_f32_16x16x32_bf16 v[88:91], v[192:195], v[40:43], v[72:75]
	v_mfma_f32_16x16x32_bf16 v[72:75], v[192:195], v[180:183], v[32:35]
	v_mfma_f32_16x16x32_bf16 v[32:35], v[196:199], v[64:67], v[168:171]
	v_mfma_f32_16x16x32_bf16 v[76:79], v[200:203], v[180:183], v[32:35]
	v_mfma_f32_16x16x32_bf16 v[32:35], v[152:155], v[184:187], v[68:71]
	v_mfma_f32_16x16x32_bf16 v[64:67], v[192:195], v[188:191], v[32:35]
	v_mfma_f32_16x16x32_bf16 v[32:35], v[196:199], v[184:187], v[172:175]
	v_mfma_f32_16x16x32_bf16 v[68:71], v[200:203], v[188:191], v[32:35]
	s_setprio 0
	s_barrier
	ds_read_b128 v[160:163], v145 offset:49152
	ds_read_b128 v[164:167], v145 offset:50176
	ds_read_b128 v[168:171], v145 offset:51200
	ds_read_b128 v[172:175], v145 offset:52224
	ds_read_b128 v[180:183], v145 offset:53248
	ds_read_b128 v[184:187], v145 offset:54272
	ds_read_b128 v[188:191], v145 offset:55296
	ds_read_b128 v[220:223], v145 offset:56320
	s_barrier
	s_waitcnt lgkmcnt(0)
	v_mfma_f32_16x16x32_bf16 v[32:35], v[0:3], v[160:163], v[60:63]
	v_mfma_f32_16x16x32_bf16 v[56:59], v[8:11], v[164:167], v[32:35]
	v_mfma_f32_16x16x32_bf16 v[32:35], v[16:19], v[160:163], v[204:207]
	v_mfma_f32_16x16x32_bf16 v[60:63], v[24:27], v[164:167], v[32:35]
	v_mfma_f32_16x16x32_bf16 v[32:35], v[0:3], v[168:171], v[52:55]
	v_mfma_f32_16x16x32_bf16 v[48:51], v[8:11], v[172:175], v[32:35]
	v_mfma_f32_16x16x32_bf16 v[32:35], v[16:19], v[168:171], v[212:215]
	v_mfma_f32_16x16x32_bf16 v[52:55], v[24:27], v[172:175], v[32:35]
	v_mfma_f32_16x16x32_bf16 v[32:35], v[0:3], v[180:183], v[44:47]
	v_mfma_f32_16x16x32_bf16 v[40:43], v[8:11], v[184:187], v[32:35]
	v_mfma_f32_16x16x32_bf16 v[32:35], v[16:19], v[180:183], v[216:219]
	v_mfma_f32_16x16x32_bf16 v[0:3], v[0:3], v[188:191], v[36:39]
	v_mfma_f32_16x16x32_bf16 v[44:47], v[24:27], v[184:187], v[32:35]
	v_mfma_f32_16x16x32_bf16 v[32:35], v[8:11], v[220:223], v[0:3]
	v_mfma_f32_16x16x32_bf16 v[0:3], v[16:19], v[188:191], v[130:133]
	v_mfma_f32_16x16x32_bf16 v[36:39], v[24:27], v[220:223], v[0:3]
	s_setprio 0
	v_mfma_f32_16x16x32_bf16 v[0:3], v[152:155], v[160:163], v[28:31]
	v_mfma_f32_16x16x32_bf16 v[24:27], v[192:195], v[164:167], v[0:3]
	v_mfma_f32_16x16x32_bf16 v[0:3], v[196:199], v[160:163], v[134:137]
	v_mfma_f32_16x16x32_bf16 v[28:31], v[200:203], v[164:167], v[0:3]
	v_mfma_f32_16x16x32_bf16 v[0:3], v[152:155], v[168:171], v[20:23]
	v_mfma_f32_16x16x32_bf16 v[16:19], v[192:195], v[172:175], v[0:3]
	v_mfma_f32_16x16x32_bf16 v[0:3], v[196:199], v[168:171], v[148:151]
	v_mfma_f32_16x16x32_bf16 v[20:23], v[200:203], v[172:175], v[0:3]
	v_mfma_f32_16x16x32_bf16 v[0:3], v[152:155], v[180:183], v[12:15]
	v_mfma_f32_16x16x32_bf16 v[8:11], v[192:195], v[184:187], v[0:3]
	v_mfma_f32_16x16x32_bf16 v[0:3], v[196:199], v[180:183], v[156:159]
	v_mfma_f32_16x16x32_bf16 v[12:15], v[200:203], v[184:187], v[0:3]
	v_mfma_f32_16x16x32_bf16 v[0:3], v[152:155], v[188:191], v[4:7]
	v_mfma_f32_16x16x32_bf16 v[4:7], v[196:199], v[188:191], v[176:179]
	v_mfma_f32_16x16x32_bf16 v[0:3], v[192:195], v[220:223], v[0:3]
	v_mfma_f32_16x16x32_bf16 v[4:7], v[200:203], v[220:223], v[4:7]
	s_setprio 0
	v_cmp_gt_u32_e32 vcc, s55, v144
	s_barrier
	s_and_saveexec_b64 s[28:29], vcc
	s_cbranch_execz .LBB0_97
	s_barrier

; #define WAIT_L(n) asm volatile("s_waitcnt lgkmcnt(" #n ")" ::: "memory")
; #define BAR __builtin_amdgcn_s_barrier()
; #define SCHED __builtin_amdgcn_sched_barrier(0)
; #define STAGE(P, BASE, br, kt) do { const char* _g = (const char*)((BASE) + (size_t)(br) * GK + (kt) * BK); \
;     __builtin_amdgcn_global_load_lds((const unsigned*)(_g + voff0), (unsigned*)((char*)(P) + tx * 16), 16, 0, 0); \
;     __builtin_amdgcn_global_load_lds((const unsigned*)(_g + voff1), (unsigned*)((char*)(P) + tx * 16 + 8192), 16, 0, 0); } while (0)
; #define LDA(dst, b, h) _Pragma("unroll") for (int m = 0; m < 4; ++m) _Pragma("unroll") for (int k = 0; k < 2; ++k) \
;     dst[m][k] = *reinterpret_cast<const bf16x8*>((char*)shm + abase + (((b) * 2 + (h)) * 16384 + (m * 2 + k) * 1024))
; #define LDB(dst, b, h) _Pragma("unroll") for (int n = 0; n < 2; ++n) _Pragma("unroll") for (int k = 0; k < 2; ++k) \
;     dst[n][k] = *reinterpret_cast<const bf16x8*>((char*)shm + bbase + (((b) * 2 + (h)) * 16384 + (n * 2 + k) * 1024))
; template <bool SWAP>
; __device__ __forceinline__ void gemm_main(const u16* __restrict__ A, const u16* __restrict__ Bt, int brow, int bcol,
;                                           u16* shm, f32x4 (&acc)[2][2][4][2]) {
;     ...
;     LDB(B0, 0, 0); SCHED; LDA(At, 0, 0); STAGE(SA(1, 1), A, brow + HALF, t + 1);
;     WAIT_L(8); BAR; WAIT_L(0); MMA(0, 0, At, B0); BAR; SCHED;
;     LDB(B1, 0, 1); STAGE(SB(0, 0), Bt, bcol, t + 2);
;     BAR; WAIT_L(0); MMA(0, 1, At, B1); BAR;
;     LDA(At, 0, 1); STAGE(SA(0, 0), A, brow, t + 2);
;     BAR; WAIT_L(0); MMA(1, 0, At, B0); BAR; SCHED;
;     STAGE(SB(0, 1), Bt, bcol + HALF, t + 2);
.LBB0_114:
	ds_read_b128 v[182:185], v137 offset:1024
	ds_read_b128 v[194:197], v137 offset:3072
	ds_read_b128 v[202:205], v137 offset:5120
	ds_read_b128 v[222:225], v137 offset:7168
	v_add_u32_e32 v192, 0, v153
	v_add_u32_e32 v160, 0xc000, v192
	v_add_u32_e32 v161, 0xe000, v192
	s_add_u32 m0, s4, 0xc000
	v_lshl_add_u64 v[242:243], s[0:1], 0, v[134:135]
	s_add_u32 vcc_lo, s0, s82
	s_addc_u32 vcc_hi, s1, s83
	global_load_lds_dwordx4 v132, vcc
	s_add_u32 m0, s4, 0xe000
	s_nop 0
	global_load_lds_dwordx4 v134, vcc
	s_waitcnt lgkmcnt(8)
	s_barrier
	s_waitcnt lgkmcnt(0)
	v_mfma_f32_16x16x32_bf16 v[124:127], v[178:181], v[162:165], v[124:127]
	v_mfma_f32_16x16x32_bf16 v[120:123], v[178:181], v[170:173], v[120:123]
	v_mfma_f32_16x16x32_bf16 v[116:119], v[186:189], v[162:165], v[116:119]
	v_mfma_f32_16x16x32_bf16 v[112:115], v[186:189], v[170:173], v[112:115]
	v_mfma_f32_16x16x32_bf16 v[108:111], v[198:201], v[162:165], v[108:111]
	v_mfma_f32_16x16x32_bf16 v[104:107], v[198:201], v[170:173], v[104:107]
	v_mfma_f32_16x16x32_bf16 v[100:103], v[206:209], v[162:165], v[100:103]
	v_mfma_f32_16x16x32_bf16 v[96:99], v[206:209], v[170:173], v[96:99]
	v_mfma_f32_16x16x32_bf16 v[124:127], v[182:185], v[166:169], v[124:127]
	v_mfma_f32_16x16x32_bf16 v[120:123], v[182:185], v[174:177], v[120:123]
	v_mfma_f32_16x16x32_bf16 v[116:119], v[194:197], v[166:169], v[116:119]
	v_mfma_f32_16x16x32_bf16 v[112:115], v[194:197], v[174:177], v[112:115]
	v_mfma_f32_16x16x32_bf16 v[108:111], v[202:205], v[166:169], v[108:111]
	v_mfma_f32_16x16x32_bf16 v[104:107], v[202:205], v[174:177], v[104:107]
	v_mfma_f32_16x16x32_bf16 v[100:103], v[222:225], v[166:169], v[100:103]
	v_mfma_f32_16x16x32_bf16 v[96:99], v[222:225], v[174:177], v[96:99]
	s_barrier
	ds_read_b128 v[226:229], v152 offset:16384
	ds_read_b128 v[230:233], v152 offset:17408
	ds_read_b128 v[234:237], v152 offset:18432
	ds_read_b128 v[238:241], v152 offset:19456
	v_lshl_add_u64 v[244:245], s[0:1], 0, v[128:129]
	s_add_u32 m0, s4, s28
	s_nop 0
	s_add_u32 vcc_lo, s0, s74
	s_addc_u32 vcc_hi, s1, s75
	global_load_lds_dwordx4 v128, vcc
	v_lshl_add_u64 v[246:247], s[0:1], 0, v[130:131]
	s_add_u32 m0, s4, s28
	s_add_u32 m0, m0, 0x2000
	s_nop 0
	global_load_lds_dwordx4 v130, vcc
	s_barrier
	s_waitcnt lgkmcnt(0)
	v_mfma_f32_16x16x32_bf16 v[92:95], v[178:181], v[226:229], v[92:95]
	v_mfma_f32_16x16x32_bf16 v[88:91], v[178:181], v[234:237], v[88:91]
	v_mfma_f32_16x16x32_bf16 v[84:87], v[186:189], v[226:229], v[84:87]
	v_mfma_f32_16x16x32_bf16 v[80:83], v[186:189], v[234:237], v[80:83]
	v_mfma_f32_16x16x32_bf16 v[76:79], v[198:201], v[226:229], v[76:79]
	v_mfma_f32_16x16x32_bf16 v[72:75], v[198:201], v[234:237], v[72:75]
	v_mfma_f32_16x16x32_bf16 v[68:71], v[206:209], v[226:229], v[68:71]
	v_mfma_f32_16x16x32_bf16 v[64:67], v[206:209], v[234:237], v[64:67]
	v_mfma_f32_16x16x32_bf16 v[92:95], v[182:185], v[230:233], v[92:95]
	ds_read_b128 v[178:181], v137 offset:16384
	v_mfma_f32_16x16x32_bf16 v[88:91], v[182:185], v[238:241], v[88:91]
	v_mfma_f32_16x16x32_bf16 v[84:87], v[194:197], v[230:233], v[84:87]
	ds_read_b128 v[186:189], v137 offset:18432
	v_mfma_f32_16x16x32_bf16 v[80:83], v[194:197], v[238:241], v[80:83]
	v_mfma_f32_16x16x32_bf16 v[76:79], v[202:205], v[230:233], v[76:79]
	ds_read_b128 v[198:201], v137 offset:20480
	v_mfma_f32_16x16x32_bf16 v[72:75], v[202:205], v[238:241], v[72:75]
	v_mfma_f32_16x16x32_bf16 v[68:71], v[222:225], v[230:233], v[68:71]
	ds_read_b128 v[206:209], v137 offset:22528
	v_mfma_f32_16x16x32_bf16 v[64:67], v[222:225], v[238:241], v[64:67]
	s_barrier
	ds_read_b128 v[182:185], v137 offset:17408
	ds_read_b128 v[194:197], v137 offset:19456
	ds_read_b128 v[202:205], v137 offset:21504
	ds_read_b128 v[222:225], v137 offset:23552
	s_add_u32 m0, s4, 0x0
	s_nop 0
	s_add_u32 vcc_lo, s0, s76
	s_addc_u32 vcc_hi, s1, s77
	global_load_lds_dwordx4 v132, vcc
	s_add_u32 m0, s4, 0x2000
	s_nop 0
	global_load_lds_dwordx4 v134, vcc
	s_waitcnt vmcnt(8)
	s_barrier
	s_waitcnt lgkmcnt(0)
	v_mfma_f32_16x16x32_bf16 v[60:63], v[178:181], v[162:165], v[60:63]
	v_mfma_f32_16x16x32_bf16 v[56:59], v[178:181], v[170:173], v[56:59]
	v_mfma_f32_16x16x32_bf16 v[52:55], v[186:189], v[162:165], v[52:55]
	v_mfma_f32_16x16x32_bf16 v[48:51], v[186:189], v[170:173], v[48:51]
	v_mfma_f32_16x16x32_bf16 v[44:47], v[198:201], v[162:165], v[44:47]
	v_mfma_f32_16x16x32_bf16 v[40:43], v[198:201], v[170:173], v[40:43]
	v_mfma_f32_16x16x32_bf16 v[36:39], v[206:209], v[162:165], v[36:39]
	v_mfma_f32_16x16x32_bf16 v[32:35], v[206:209], v[170:173], v[32:35]
	v_mfma_f32_16x16x32_bf16 v[60:63], v[182:185], v[166:169], v[60:63]
	v_mfma_f32_16x16x32_bf16 v[56:59], v[182:185], v[174:177], v[56:59]
	v_mfma_f32_16x16x32_bf16 v[52:55], v[194:197], v[166:169], v[52:55]
	v_mfma_f32_16x16x32_bf16 v[48:51], v[194:197], v[174:177], v[48:51]
	v_mfma_f32_16x16x32_bf16 v[44:47], v[202:205], v[166:169], v[44:47]
	v_mfma_f32_16x16x32_bf16 v[40:43], v[202:205], v[174:177], v[40:43]
	v_mfma_f32_16x16x32_bf16 v[36:39], v[222:225], v[166:169], v[36:39]
	v_mfma_f32_16x16x32_bf16 v[32:35], v[222:225], v[174:177], v[32:35]
	s_barrier
	ds_read_b128 v[162:165], v152 offset:32768
	ds_read_b128 v[166:169], v152 offset:33792
	ds_read_b128 v[170:173], v152 offset:34816
	ds_read_b128 v[174:177], v152 offset:35840
	s_add_u32 m0, s4, s29
	s_nop 0
	s_add_u32 vcc_lo, s0, s70
	s_addc_u32 vcc_hi, s1, s71
	global_load_lds_dwordx4 v128, vcc
	s_add_u32 m0, s4, s29
	s_add_u32 m0, m0, 0x2000
	s_nop 0
	global_load_lds_dwordx4 v130, vcc
	s_waitcnt vmcnt(6)
	s_barrier
; #define WAIT_V(n) asm volatile("s_waitcnt vmcnt(" #n ")" ::: "memory")
; #define WAIT_L(n) asm volatile("s_waitcnt lgkmcnt(" #n ")" ::: "memory")
; #define BAR __builtin_amdgcn_s_barrier()
; #define SCHED __builtin_amdgcn_sched_barrier(0)
; #define STAGE(P, BASE, br, kt) do { const char* _g = (const char*)((BASE) + (size_t)(br) * GK + (kt) * BK); \
;     __builtin_amdgcn_global_load_lds((const unsigned*)(_g + voff0), (unsigned*)((char*)(P) + tx * 16), 16, 0, 0); \
;     __builtin_amdgcn_global_load_lds((const unsigned*)(_g + voff1), (unsigned*)((char*)(P) + tx * 16 + 8192), 16, 0, 0); } while (0)
; #define LDA(dst, b, h) _Pragma("unroll") for (int m = 0; m < 4; ++m) _Pragma("unroll") for (int k = 0; k < 2; ++k) \
;     dst[m][k] = *reinterpret_cast<const bf16x8*>((char*)shm + abase + (((b) * 2 + (h)) * 16384 + (m * 2 + k) * 1024))
; #define LDB(dst, b, h) _Pragma("unroll") for (int n = 0; n < 2; ++n) _Pragma("unroll") for (int k = 0; k < 2; ++k) \
;     dst[n][k] = *reinterpret_cast<const bf16x8*>((char*)shm + bbase + (((b) * 2 + (h)) * 16384 + (n * 2 + k) * 1024))
; template <bool SWAP>
; __device__ __forceinline__ void gemm_main(const u16* __restrict__ A, const u16* __restrict__ Bt, int brow, int bcol,
;                                           u16* shm, f32x4 (&acc)[2][2][4][2]) {
;     ...
;     WAIT_V(6); BAR; MMA(1, 1, At, B1); BAR;
;     LDB(B0, 1, 0); SCHED; LDA(At, 1, 0); STAGE(SA(0, 1), A, brow + HALF, t + 2);
;     WAIT_L(8); BAR; WAIT_L(0); MMA(0, 0, At, B0); BAR; SCHED;
;     LDB(B1, 1, 1); STAGE(SB(1, 0), Bt, bcol, t + 3);
;     BAR; WAIT_L(0); MMA(0, 1, At, B1); BAR;
;     LDA(At, 1, 1); STAGE(SA(1, 0), A, brow, t + 3);
;     BAR; WAIT_L(0); MMA(1, 0, At, B0); BAR; SCHED;
;     STAGE(SB(1, 1), Bt, bcol + HALF, t + 3);
	v_mfma_f32_16x16x32_bf16 v[28:31], v[178:181], v[226:229], v[28:31]
	v_mfma_f32_16x16x32_bf16 v[24:27], v[178:181], v[234:237], v[24:27]
	v_mfma_f32_16x16x32_bf16 v[20:23], v[186:189], v[226:229], v[20:23]
	v_mfma_f32_16x16x32_bf16 v[16:19], v[186:189], v[234:237], v[16:19]
	v_mfma_f32_16x16x32_bf16 v[12:15], v[198:201], v[226:229], v[12:15]
	v_mfma_f32_16x16x32_bf16 v[8:11], v[198:201], v[234:237], v[8:11]
	v_mfma_f32_16x16x32_bf16 v[4:7], v[206:209], v[226:229], v[4:7]
	v_mfma_f32_16x16x32_bf16 v[0:3], v[206:209], v[234:237], v[0:3]
	v_mfma_f32_16x16x32_bf16 v[28:31], v[182:185], v[230:233], v[28:31]
	ds_read_b128 v[178:181], v137 offset:32768
	v_mfma_f32_16x16x32_bf16 v[24:27], v[182:185], v[238:241], v[24:27]
	v_mfma_f32_16x16x32_bf16 v[20:23], v[194:197], v[230:233], v[20:23]
	ds_read_b128 v[186:189], v137 offset:34816
	v_mfma_f32_16x16x32_bf16 v[16:19], v[194:197], v[238:241], v[16:19]
	v_mfma_f32_16x16x32_bf16 v[12:15], v[202:205], v[230:233], v[12:15]
	ds_read_b128 v[198:201], v137 offset:36864
	v_mfma_f32_16x16x32_bf16 v[8:11], v[202:205], v[238:241], v[8:11]
	v_mfma_f32_16x16x32_bf16 v[4:7], v[222:225], v[230:233], v[4:7]
	ds_read_b128 v[206:209], v137 offset:38912
	v_mfma_f32_16x16x32_bf16 v[0:3], v[222:225], v[238:241], v[0:3]
	s_barrier
	ds_read_b128 v[182:185], v137 offset:33792
	ds_read_b128 v[194:197], v137 offset:35840
	ds_read_b128 v[202:205], v137 offset:37888
	ds_read_b128 v[222:225], v137 offset:39936
	s_add_u32 m0, s4, 0x4000
	s_nop 0
	s_add_u32 vcc_lo, s0, s96
	s_addc_u32 vcc_hi, s1, s97
	global_load_lds_dwordx4 v132, vcc
	s_add_u32 m0, s4, 0x6000
	s_nop 0
	global_load_lds_dwordx4 v134, vcc
	s_waitcnt lgkmcnt(8)
	s_barrier
	s_waitcnt lgkmcnt(0)
	v_mfma_f32_16x16x32_bf16 v[124:127], v[178:181], v[162:165], v[124:127]
	v_mfma_f32_16x16x32_bf16 v[120:123], v[178:181], v[170:173], v[120:123]
	v_mfma_f32_16x16x32_bf16 v[116:119], v[186:189], v[162:165], v[116:119]
	v_mfma_f32_16x16x32_bf16 v[112:115], v[186:189], v[170:173], v[112:115]
	v_mfma_f32_16x16x32_bf16 v[108:111], v[198:201], v[162:165], v[108:111]
	v_mfma_f32_16x16x32_bf16 v[104:107], v[198:201], v[170:173], v[104:107]
	v_mfma_f32_16x16x32_bf16 v[100:103], v[206:209], v[162:165], v[100:103]
	v_mfma_f32_16x16x32_bf16 v[96:99], v[206:209], v[170:173], v[96:99]
	v_mfma_f32_16x16x32_bf16 v[124:127], v[182:185], v[166:169], v[124:127]
	v_mfma_f32_16x16x32_bf16 v[120:123], v[182:185], v[174:177], v[120:123]
	v_mfma_f32_16x16x32_bf16 v[116:119], v[194:197], v[166:169], v[116:119]
	v_mfma_f32_16x16x32_bf16 v[112:115], v[194:197], v[174:177], v[112:115]
	v_mfma_f32_16x16x32_bf16 v[108:111], v[202:205], v[166:169], v[108:111]
	v_mfma_f32_16x16x32_bf16 v[104:107], v[202:205], v[174:177], v[104:107]
	v_mfma_f32_16x16x32_bf16 v[100:103], v[222:225], v[166:169], v[100:103]
	v_mfma_f32_16x16x32_bf16 v[96:99], v[222:225], v[174:177], v[96:99]
	s_barrier
	ds_read_b128 v[226:229], v152 offset:49152
	ds_read_b128 v[230:233], v152 offset:50176
	ds_read_b128 v[234:237], v152 offset:51200
	ds_read_b128 v[238:241], v152 offset:52224
	v_add_u32_e32 v250, s30, v153
	v_add_u32_e32 v250, 0x2000, v250
	s_add_u32 m0, s4, s30
	s_nop 0
	s_add_u32 vcc_lo, s0, s34
	s_addc_u32 vcc_hi, s1, s35
	global_load_lds_dwordx4 v128, vcc
	v_lshl_add_u64 v[248:249], v[246:247], 0, s[34:35]
	s_add_u32 m0, s4, s30
	s_add_u32 m0, m0, 0x2000
	s_nop 0
	global_load_lds_dwordx4 v130, vcc
	s_barrier
	s_waitcnt lgkmcnt(0)
	v_mfma_f32_16x16x32_bf16 v[92:95], v[178:181], v[226:229], v[92:95]
	v_mfma_f32_16x16x32_bf16 v[88:91], v[178:181], v[234:237], v[88:91]
	v_mfma_f32_16x16x32_bf16 v[84:87], v[186:189], v[226:229], v[84:87]
	v_mfma_f32_16x16x32_bf16 v[80:83], v[186:189], v[234:237], v[80:83]
	v_mfma_f32_16x16x32_bf16 v[76:79], v[198:201], v[226:229], v[76:79]
	v_mfma_f32_16x16x32_bf16 v[72:75], v[198:201], v[234:237], v[72:75]
	v_mfma_f32_16x16x32_bf16 v[68:71], v[206:209], v[226:229], v[68:71]
	v_mfma_f32_16x16x32_bf16 v[64:67], v[206:209], v[234:237], v[64:67]
	v_mfma_f32_16x16x32_bf16 v[92:95], v[182:185], v[230:233], v[92:95]
	ds_read_b128 v[178:181], v137 offset:49152
	v_mfma_f32_16x16x32_bf16 v[88:91], v[182:185], v[238:241], v[88:91]
	v_mfma_f32_16x16x32_bf16 v[84:87], v[194:197], v[230:233], v[84:87]
	ds_read_b128 v[186:189], v137 offset:51200
	v_mfma_f32_16x16x32_bf16 v[80:83], v[194:197], v[238:241], v[80:83]
	v_mfma_f32_16x16x32_bf16 v[76:79], v[202:205], v[230:233], v[76:79]
	ds_read_b128 v[198:201], v137 offset:53248
	v_mfma_f32_16x16x32_bf16 v[72:75], v[202:205], v[238:241], v[72:75]
	v_mfma_f32_16x16x32_bf16 v[68:71], v[222:225], v[230:233], v[68:71]
	ds_read_b128 v[206:209], v137 offset:55296
	v_mfma_f32_16x16x32_bf16 v[64:67], v[222:225], v[238:241], v[64:67]
	s_barrier
	ds_read_b128 v[182:185], v137 offset:50176
	ds_read_b128 v[194:197], v137 offset:52224
	ds_read_b128 v[202:205], v137 offset:54272
	ds_read_b128 v[222:225], v137 offset:56320
	v_add_u32_e32 v248, 0x8000, v192
	s_add_u32 m0, s4, 0x8000
	s_nop 0
	s_add_u32 vcc_lo, s0, s36
	s_addc_u32 vcc_hi, s1, s37
	global_load_lds_dwordx4 v132, vcc
	s_add_u32 m0, s4, 0xa000
	s_nop 0
	global_load_lds_dwordx4 v134, vcc
	s_waitcnt vmcnt(8)
	s_barrier
; #define WAIT_V(n) asm volatile("s_waitcnt vmcnt(" #n ")" ::: "memory")
; #define WAIT_L(n) asm volatile("s_waitcnt lgkmcnt(" #n ")" ::: "memory")
; #define BAR __builtin_amdgcn_s_barrier()
; #define SCHED __builtin_amdgcn_sched_barrier(0)
; #define STAGE(P, BASE, br, kt) do { const char* _g = (const char*)((BASE) + (size_t)(br) * GK + (kt) * BK); \
;     __builtin_amdgcn_global_load_lds((const unsigned*)(_g + voff0), (unsigned*)((char*)(P) + tx * 16), 16, 0, 0); \
;     __builtin_amdgcn_global_load_lds((const unsigned*)(_g + voff1), (unsigned*)((char*)(P) + tx * 16 + 8192), 16, 0, 0); } while (0)
; #define LDA(dst, b, h) _Pragma("unroll") for (int m = 0; m < 4; ++m) _Pragma("unroll") for (int k = 0; k < 2; ++k) \
;     dst[m][k] = *reinterpret_cast<const bf16x8*>((char*)shm + abase + (((b) * 2 + (h)) * 16384 + (m * 2 + k) * 1024))
; #define LDB(dst, b, h) _Pragma("unroll") for (int n = 0; n < 2; ++n) _Pragma("unroll") for (int k = 0; k < 2; ++k) \
;     dst[n][k] = *reinterpret_cast<const bf16x8*>((char*)shm + bbase + (((b) * 2 + (h)) * 16384 + (n * 2 + k) * 1024))
; template <bool SWAP>
; __device__ __forceinline__ void gemm_main(const u16* __restrict__ A, const u16* __restrict__ Bt, int brow, int bcol,
;                                           u16* shm, f32x4 (&acc)[2][2][4][2]) {
;     ...
;     LDA(At, 1, 1); STAGE(SA(1, 0), A, brow, t + 3);
;     BAR; WAIT_L(0); MMA(1, 0, At, B0); BAR; SCHED;
;     STAGE(SB(1, 1), Bt, bcol + HALF, t + 3);
;     WAIT_V(6); BAR; MMA(1, 1, At, B1); BAR;
;   }
;   { LDB(B0, 0, 0); LDA(At, 0, 0); STAGE(SA(1, 1), A, brow + HALF, nt - 1);
;     BAR; WAIT_L(0); MMA(0, 0, At, B0); BAR;
;     LDB(B1, 0, 1); BAR; WAIT_L(0); MMA(0, 1, At, B1); BAR;
	s_waitcnt lgkmcnt(0)
	v_mfma_f32_16x16x32_bf16 v[60:63], v[178:181], v[162:165], v[60:63]
	v_mfma_f32_16x16x32_bf16 v[56:59], v[178:181], v[170:173], v[56:59]
	v_mfma_f32_16x16x32_bf16 v[52:55], v[186:189], v[162:165], v[52:55]
	v_mfma_f32_16x16x32_bf16 v[48:51], v[186:189], v[170:173], v[48:51]
	v_mfma_f32_16x16x32_bf16 v[44:47], v[198:201], v[162:165], v[44:47]
	v_mfma_f32_16x16x32_bf16 v[40:43], v[198:201], v[170:173], v[40:43]
	v_mfma_f32_16x16x32_bf16 v[36:39], v[206:209], v[162:165], v[36:39]
	v_mfma_f32_16x16x32_bf16 v[32:35], v[206:209], v[170:173], v[32:35]
	v_mfma_f32_16x16x32_bf16 v[60:63], v[182:185], v[166:169], v[60:63]
	v_mfma_f32_16x16x32_bf16 v[56:59], v[182:185], v[174:177], v[56:59]
	v_mfma_f32_16x16x32_bf16 v[52:55], v[194:197], v[166:169], v[52:55]
	v_mfma_f32_16x16x32_bf16 v[48:51], v[194:197], v[174:177], v[48:51]
	v_mfma_f32_16x16x32_bf16 v[44:47], v[202:205], v[166:169], v[44:47]
	v_mfma_f32_16x16x32_bf16 v[40:43], v[202:205], v[174:177], v[40:43]
	v_mfma_f32_16x16x32_bf16 v[36:39], v[222:225], v[166:169], v[36:39]
	v_mfma_f32_16x16x32_bf16 v[32:35], v[222:225], v[174:177], v[32:35]
	s_barrier
	ds_read_b128 v[162:165], v152
	ds_read_b128 v[166:169], v152 offset:1024
	ds_read_b128 v[170:173], v152 offset:2048
	ds_read_b128 v[174:177], v152 offset:3072
	s_add_u32 m0, s4, s31
	s_nop 0
	s_add_u32 vcc_lo, s0, s64
	s_addc_u32 vcc_hi, s1, s65
	global_load_lds_dwordx4 v128, vcc
	v_lshl_add_u64 v[254:255], v[246:247], 0, s[64:65]
	s_add_u32 m0, s4, s31
	s_add_u32 m0, m0, 0x2000
	s_nop 0
	global_load_lds_dwordx4 v130, vcc
	s_waitcnt vmcnt(6)
	s_barrier
	v_mfma_f32_16x16x32_bf16 v[28:31], v[178:181], v[226:229], v[28:31]
	v_mfma_f32_16x16x32_bf16 v[24:27], v[178:181], v[234:237], v[24:27]
	v_mfma_f32_16x16x32_bf16 v[20:23], v[186:189], v[226:229], v[20:23]
	v_mfma_f32_16x16x32_bf16 v[16:19], v[186:189], v[234:237], v[16:19]
	v_mfma_f32_16x16x32_bf16 v[12:15], v[198:201], v[226:229], v[12:15]
	v_mfma_f32_16x16x32_bf16 v[8:11], v[198:201], v[234:237], v[8:11]
	v_mfma_f32_16x16x32_bf16 v[4:7], v[206:209], v[226:229], v[4:7]
	v_mfma_f32_16x16x32_bf16 v[0:3], v[206:209], v[234:237], v[0:3]
	v_mfma_f32_16x16x32_bf16 v[28:31], v[182:185], v[230:233], v[28:31]
	ds_read_b128 v[178:181], v137
	v_mfma_f32_16x16x32_bf16 v[24:27], v[182:185], v[238:241], v[24:27]
	v_mfma_f32_16x16x32_bf16 v[20:23], v[194:197], v[230:233], v[20:23]
	ds_read_b128 v[186:189], v137 offset:2048
	v_mfma_f32_16x16x32_bf16 v[16:19], v[194:197], v[238:241], v[16:19]
	v_mfma_f32_16x16x32_bf16 v[12:15], v[202:205], v[230:233], v[12:15]
	ds_read_b128 v[198:201], v137 offset:4096
	v_mfma_f32_16x16x32_bf16 v[8:11], v[202:205], v[238:241], v[8:11]
	v_mfma_f32_16x16x32_bf16 v[4:7], v[222:225], v[230:233], v[4:7]
	ds_read_b128 v[206:209], v137 offset:6144
	v_mfma_f32_16x16x32_bf16 v[0:3], v[222:225], v[238:241], v[0:3]
	s_add_i32 s3, s3, 2
	s_add_u32 s0, s0, 0x100
	s_addc_u32 s1, s1, 0
	s_cmp_lt_u32 s3, 28
	s_barrier
	s_cbranch_scc1 .LBB0_114
	v_lshlrev_b32_e32 v128, 3, v154
	v_lshlrev_b32_e32 v129, 5, v154
	v_and_b32_e32 v128, 0xffff0, v128
	v_and_b32_e32 v129, 32, v129
	s_or_b32 s0, s24, 0x80
	v_add_u32_e32 v129, v129, v156
	v_add_lshl_u32 v128, v155, v128, 12
	s_ashr_i32 s1, s0, 31
	v_lshl_add_u32 v192, v129, 1, v128
	v_lshlrev_b32_e32 v128, 3, v157
	v_lshlrev_b32_e32 v129, 5, v157
	s_mov_b32 s22, s0
	s_lshl_b64 s[0:1], s[0:1], 12
	v_readlane_b32 s4, v253, 35
	v_and_b32_e32 v128, 0xffff0, v128
	v_and_b32_e32 v129, 32, v129
	v_readlane_b32 s5, v253, 36
	s_add_u32 s0, s4, s0
	v_add_u32_e32 v129, v129, v159
	v_add_lshl_u32 v128, v158, v128, 12
	s_addc_u32 s1, s5, s1
	v_lshl_add_u32 v158, v129, 1, v128
	v_mov_b32_e32 v159, v193
	v_lshl_add_u64 v[190:191], s[0:1], 0, v[192:193]
	s_mov_b64 s[4:5], 0xf80
	v_readfirstlane_b32 s3, v160
	v_lshl_add_u64 v[190:191], v[190:191], 0, s[4:5]
	s_mov_b32 m0, s3
	v_lshl_add_u64 v[158:159], s[0:1], 0, v[158:159]
	v_readfirstlane_b32 s0, v161
	ds_read_b128 v[128:131], v152
	ds_read_b128 v[132:135], v152 offset:1024
	ds_read_b128 v[154:157], v152 offset:2048
	ds_read_b128 v[162:165], v152 offset:3072
	ds_read_b128 v[166:169], v137
	ds_read_b128 v[170:173], v137 offset:1024
	ds_read_b128 v[174:177], v137 offset:2048
	ds_read_b128 v[178:181], v137 offset:3072
	ds_read_b128 v[182:185], v137 offset:4096
	ds_read_b128 v[186:189], v137 offset:5120
	ds_read_b128 v[194:197], v137 offset:6144
	ds_read_b128 v[198:201], v137 offset:7168
	global_load_lds_dwordx4 v[190:191], off
	v_lshl_add_u64 v[158:159], v[158:159], 0, s[4:5]
	s_mov_b32 m0, s0
	s_nop 0
	global_load_lds_dwordx4 v[158:159], off
	s_barrier
	s_waitcnt lgkmcnt(0)
	v_mfma_f32_16x16x32_bf16 v[124:127], v[166:169], v[128:131], v[124:127]
	v_mfma_f32_16x16x32_bf16 v[120:123], v[166:169], v[154:157], v[120:123]
	v_mfma_f32_16x16x32_bf16 v[116:119], v[174:177], v[128:131], v[116:119]
	v_mfma_f32_16x16x32_bf16 v[112:115], v[174:177], v[154:157], v[112:115]
	v_mfma_f32_16x16x32_bf16 v[108:111], v[182:185], v[128:131], v[108:111]
	v_mfma_f32_16x16x32_bf16 v[104:107], v[182:185], v[154:157], v[104:107]
	v_mfma_f32_16x16x32_bf16 v[100:103], v[194:197], v[128:131], v[100:103]
	v_mfma_f32_16x16x32_bf16 v[96:99], v[194:197], v[154:157], v[96:99]
	v_mfma_f32_16x16x32_bf16 v[124:127], v[170:173], v[132:135], v[124:127]
	v_mfma_f32_16x16x32_bf16 v[120:123], v[170:173], v[162:165], v[120:123]
	v_mfma_f32_16x16x32_bf16 v[116:119], v[178:181], v[132:135], v[116:119]
	v_mfma_f32_16x16x32_bf16 v[112:115], v[178:181], v[162:165], v[112:115]
	v_mfma_f32_16x16x32_bf16 v[108:111], v[186:189], v[132:135], v[108:111]
	v_mfma_f32_16x16x32_bf16 v[104:107], v[186:189], v[162:165], v[104:107]
	v_mfma_f32_16x16x32_bf16 v[100:103], v[198:201], v[132:135], v[100:103]
	v_mfma_f32_16x16x32_bf16 v[96:99], v[198:201], v[162:165], v[96:99]
	s_setprio 0
	s_barrier
; #define WAIT_V(n) asm volatile("s_waitcnt vmcnt(" #n ")" ::: "memory")
; #define WAIT_L(n) asm volatile("s_waitcnt lgkmcnt(" #n ")" ::: "memory")
; #define BAR __builtin_amdgcn_s_barrier()
; #define LDA(dst, b, h) _Pragma("unroll") for (int m = 0; m < 4; ++m) _Pragma("unroll") for (int k = 0; k < 2; ++k) \
;     dst[m][k] = *reinterpret_cast<const bf16x8*>((char*)shm + abase + (((b) * 2 + (h)) * 16384 + (m * 2 + k) * 1024))
; #define LDB(dst, b, h) _Pragma("unroll") for (int n = 0; n < 2; ++n) _Pragma("unroll") for (int k = 0; k < 2; ++k) \
;     dst[n][k] = *reinterpret_cast<const bf16x8*>((char*)shm + bbase + (((b) * 2 + (h)) * 16384 + (n * 2 + k) * 1024))
; template <bool SWAP>
; __device__ __forceinline__ void gemm_main(const u16* __restrict__ A, const u16* __restrict__ Bt, int brow, int bcol,
;                                           u16* shm, f32x4 (&acc)[2][2][4][2]) {
;     ...
;     LDB(B1, 0, 1); BAR; WAIT_L(0); MMA(0, 1, At, B1); BAR;
;     LDA(At, 0, 1); WAIT_V(4); BAR; WAIT_L(0); MMA(1, 0, At, B0); MMA(1, 1, At, B1); BAR; }
;   { LDB(B0, 1, 0); LDA(At, 1, 0); WAIT_V(2); BAR; WAIT_L(0); MMA(0, 0, At, B0); BAR;
	ds_read_b128 v[158:161], v152 offset:16384
	ds_read_b128 v[202:205], v152 offset:17408
	ds_read_b128 v[206:209], v152 offset:18432
	ds_read_b128 v[222:225], v152 offset:19456
	s_barrier
	s_waitcnt lgkmcnt(0)
	v_mfma_f32_16x16x32_bf16 v[92:95], v[166:169], v[158:161], v[92:95]
	v_mfma_f32_16x16x32_bf16 v[88:91], v[166:169], v[206:209], v[88:91]
	v_mfma_f32_16x16x32_bf16 v[84:87], v[174:177], v[158:161], v[84:87]
	v_mfma_f32_16x16x32_bf16 v[80:83], v[174:177], v[206:209], v[80:83]
	v_mfma_f32_16x16x32_bf16 v[76:79], v[182:185], v[158:161], v[76:79]
	v_mfma_f32_16x16x32_bf16 v[72:75], v[182:185], v[206:209], v[72:75]
	v_mfma_f32_16x16x32_bf16 v[68:71], v[194:197], v[158:161], v[68:71]
	v_mfma_f32_16x16x32_bf16 v[64:67], v[194:197], v[206:209], v[64:67]
	v_mfma_f32_16x16x32_bf16 v[92:95], v[170:173], v[202:205], v[92:95]
	v_mfma_f32_16x16x32_bf16 v[88:91], v[170:173], v[222:225], v[88:91]
	v_mfma_f32_16x16x32_bf16 v[84:87], v[178:181], v[202:205], v[84:87]
	v_mfma_f32_16x16x32_bf16 v[80:83], v[178:181], v[222:225], v[80:83]
	v_mfma_f32_16x16x32_bf16 v[76:79], v[186:189], v[202:205], v[76:79]
	v_mfma_f32_16x16x32_bf16 v[72:75], v[186:189], v[222:225], v[72:75]
	v_mfma_f32_16x16x32_bf16 v[68:71], v[198:201], v[202:205], v[68:71]
	v_mfma_f32_16x16x32_bf16 v[64:67], v[198:201], v[222:225], v[64:67]
	s_setprio 0
	s_barrier
	ds_read_b128 v[166:169], v137 offset:16384
	ds_read_b128 v[170:173], v137 offset:17408
	ds_read_b128 v[174:177], v137 offset:18432
	ds_read_b128 v[178:181], v137 offset:19456
	ds_read_b128 v[182:185], v137 offset:20480
	ds_read_b128 v[186:189], v137 offset:21504
	ds_read_b128 v[194:197], v137 offset:22528
	ds_read_b128 v[198:201], v137 offset:23552
	s_waitcnt vmcnt(4)
	s_barrier
	s_waitcnt lgkmcnt(0)
	v_mfma_f32_16x16x32_bf16 v[60:63], v[166:169], v[128:131], v[60:63]
	v_mfma_f32_16x16x32_bf16 v[56:59], v[166:169], v[154:157], v[56:59]
	v_mfma_f32_16x16x32_bf16 v[52:55], v[174:177], v[128:131], v[52:55]
	v_mfma_f32_16x16x32_bf16 v[48:51], v[174:177], v[154:157], v[48:51]
	v_mfma_f32_16x16x32_bf16 v[44:47], v[182:185], v[128:131], v[44:47]
	v_mfma_f32_16x16x32_bf16 v[40:43], v[182:185], v[154:157], v[40:43]
	v_mfma_f32_16x16x32_bf16 v[36:39], v[194:197], v[128:131], v[36:39]
	v_mfma_f32_16x16x32_bf16 v[32:35], v[194:197], v[154:157], v[32:35]
	v_mfma_f32_16x16x32_bf16 v[60:63], v[170:173], v[132:135], v[60:63]
	v_mfma_f32_16x16x32_bf16 v[56:59], v[170:173], v[162:165], v[56:59]
	v_mfma_f32_16x16x32_bf16 v[52:55], v[178:181], v[132:135], v[52:55]
	v_mfma_f32_16x16x32_bf16 v[48:51], v[178:181], v[162:165], v[48:51]
	v_mfma_f32_16x16x32_bf16 v[44:47], v[186:189], v[132:135], v[44:47]
	v_mfma_f32_16x16x32_bf16 v[40:43], v[186:189], v[162:165], v[40:43]
	v_mfma_f32_16x16x32_bf16 v[36:39], v[198:201], v[132:135], v[36:39]
	v_mfma_f32_16x16x32_bf16 v[32:35], v[198:201], v[162:165], v[32:35]
	s_setprio 0
	v_mfma_f32_16x16x32_bf16 v[28:31], v[166:169], v[158:161], v[28:31]
	v_mfma_f32_16x16x32_bf16 v[24:27], v[166:169], v[206:209], v[24:27]
	v_mfma_f32_16x16x32_bf16 v[20:23], v[174:177], v[158:161], v[20:23]
	v_mfma_f32_16x16x32_bf16 v[16:19], v[174:177], v[206:209], v[16:19]
	v_mfma_f32_16x16x32_bf16 v[12:15], v[182:185], v[158:161], v[12:15]
	v_mfma_f32_16x16x32_bf16 v[8:11], v[182:185], v[206:209], v[8:11]
	v_mfma_f32_16x16x32_bf16 v[4:7], v[194:197], v[158:161], v[4:7]
	v_mfma_f32_16x16x32_bf16 v[0:3], v[194:197], v[206:209], v[0:3]
	v_mfma_f32_16x16x32_bf16 v[28:31], v[170:173], v[202:205], v[28:31]
	v_mfma_f32_16x16x32_bf16 v[24:27], v[170:173], v[222:225], v[24:27]
	v_mfma_f32_16x16x32_bf16 v[20:23], v[178:181], v[202:205], v[20:23]
	v_mfma_f32_16x16x32_bf16 v[16:19], v[178:181], v[222:225], v[16:19]
	v_mfma_f32_16x16x32_bf16 v[12:15], v[186:189], v[202:205], v[12:15]
	v_mfma_f32_16x16x32_bf16 v[8:11], v[186:189], v[222:225], v[8:11]
	v_mfma_f32_16x16x32_bf16 v[4:7], v[198:201], v[202:205], v[4:7]
	v_mfma_f32_16x16x32_bf16 v[0:3], v[198:201], v[222:225], v[0:3]
	s_setprio 0
	s_barrier
	ds_read_b128 v[128:131], v152 offset:32768
	ds_read_b128 v[132:135], v152 offset:33792
	ds_read_b128 v[154:157], v152 offset:34816
	ds_read_b128 v[158:161], v152 offset:35840
	ds_read_b128 v[162:165], v137 offset:32768
	ds_read_b128 v[166:169], v137 offset:33792
	ds_read_b128 v[170:173], v137 offset:34816
	ds_read_b128 v[174:177], v137 offset:35840
	ds_read_b128 v[178:181], v137 offset:36864
	ds_read_b128 v[182:185], v137 offset:37888
	ds_read_b128 v[186:189], v137 offset:38912
	ds_read_b128 v[194:197], v137 offset:39936
	s_waitcnt vmcnt(2)
	s_barrier
; #define WAIT_V(n) asm volatile("s_waitcnt vmcnt(" #n ")" ::: "memory")
; #define WAIT_L(n) asm volatile("s_waitcnt lgkmcnt(" #n ")" ::: "memory")
; #define BAR __builtin_amdgcn_s_barrier()
; #define LDA(dst, b, h) _Pragma("unroll") for (int m = 0; m < 4; ++m) _Pragma("unroll") for (int k = 0; k < 2; ++k) \
;     dst[m][k] = *reinterpret_cast<const bf16x8*>((char*)shm + abase + (((b) * 2 + (h)) * 16384 + (m * 2 + k) * 1024))
; #define LDB(dst, b, h) _Pragma("unroll") for (int n = 0; n < 2; ++n) _Pragma("unroll") for (int k = 0; k < 2; ++k) \
;     dst[n][k] = *reinterpret_cast<const bf16x8*>((char*)shm + bbase + (((b) * 2 + (h)) * 16384 + (n * 2 + k) * 1024))
; template <bool SWAP>
; __device__ __forceinline__ void gemm_main(const u16* __restrict__ A, const u16* __restrict__ Bt, int brow, int bcol,
;                                           u16* shm, f32x4 (&acc)[2][2][4][2]) {
;     ...
;   { LDB(B0, 1, 0); LDA(At, 1, 0); WAIT_V(2); BAR; WAIT_L(0); MMA(0, 0, At, B0); BAR;
;     LDB(B1, 1, 1); WAIT_V(0); BAR; WAIT_L(0); MMA(0, 1, At, B1); BAR;
;     LDA(At, 1, 1); BAR; WAIT_L(0); MMA(1, 0, At, B0); MMA(1, 1, At, B1); BAR; }
;   if (wr == 0) BAR;
; __device__ __forceinline__ void phase_inproj1(const Params& p, char* smem) {
;     ...
;       if (nt < 16) {
	s_waitcnt lgkmcnt(0)
	v_mfma_f32_16x16x32_bf16 v[124:127], v[162:165], v[128:131], v[124:127]
	v_mfma_f32_16x16x32_bf16 v[120:123], v[162:165], v[154:157], v[120:123]
	v_mfma_f32_16x16x32_bf16 v[116:119], v[170:173], v[128:131], v[116:119]
	v_mfma_f32_16x16x32_bf16 v[112:115], v[170:173], v[154:157], v[112:115]
	v_mfma_f32_16x16x32_bf16 v[108:111], v[178:181], v[128:131], v[108:111]
	v_mfma_f32_16x16x32_bf16 v[104:107], v[178:181], v[154:157], v[104:107]
	v_mfma_f32_16x16x32_bf16 v[100:103], v[186:189], v[128:131], v[100:103]
	v_mfma_f32_16x16x32_bf16 v[96:99], v[186:189], v[154:157], v[96:99]
	v_mfma_f32_16x16x32_bf16 v[124:127], v[166:169], v[132:135], v[124:127]
	v_mfma_f32_16x16x32_bf16 v[120:123], v[166:169], v[158:161], v[120:123]
	v_mfma_f32_16x16x32_bf16 v[116:119], v[174:177], v[132:135], v[116:119]
	v_mfma_f32_16x16x32_bf16 v[112:115], v[174:177], v[158:161], v[112:115]
	v_mfma_f32_16x16x32_bf16 v[108:111], v[182:185], v[132:135], v[108:111]
	v_mfma_f32_16x16x32_bf16 v[104:107], v[182:185], v[158:161], v[104:107]
	v_mfma_f32_16x16x32_bf16 v[100:103], v[194:197], v[132:135], v[100:103]
	v_mfma_f32_16x16x32_bf16 v[96:99], v[194:197], v[158:161], v[96:99]
	s_setprio 0
	s_barrier
	ds_read_b128 v[198:201], v152 offset:49152
	ds_read_b128 v[202:205], v152 offset:50176
	ds_read_b128 v[206:209], v152 offset:51200
	ds_read_b128 v[222:225], v152 offset:52224
	s_waitcnt vmcnt(0)
	s_barrier
	s_waitcnt lgkmcnt(0)
	v_mfma_f32_16x16x32_bf16 v[92:95], v[162:165], v[198:201], v[92:95]
	v_mfma_f32_16x16x32_bf16 v[88:91], v[162:165], v[206:209], v[88:91]
	v_mfma_f32_16x16x32_bf16 v[84:87], v[170:173], v[198:201], v[84:87]
	v_mfma_f32_16x16x32_bf16 v[80:83], v[170:173], v[206:209], v[80:83]
	v_mfma_f32_16x16x32_bf16 v[76:79], v[178:181], v[198:201], v[76:79]
	v_mfma_f32_16x16x32_bf16 v[72:75], v[178:181], v[206:209], v[72:75]
	v_mfma_f32_16x16x32_bf16 v[68:71], v[186:189], v[198:201], v[68:71]
	v_mfma_f32_16x16x32_bf16 v[64:67], v[186:189], v[206:209], v[64:67]
	v_mfma_f32_16x16x32_bf16 v[92:95], v[166:169], v[202:205], v[92:95]
	v_mfma_f32_16x16x32_bf16 v[88:91], v[166:169], v[222:225], v[88:91]
	v_mfma_f32_16x16x32_bf16 v[84:87], v[174:177], v[202:205], v[84:87]
	v_mfma_f32_16x16x32_bf16 v[80:83], v[174:177], v[222:225], v[80:83]
	v_mfma_f32_16x16x32_bf16 v[76:79], v[182:185], v[202:205], v[76:79]
	v_mfma_f32_16x16x32_bf16 v[72:75], v[182:185], v[222:225], v[72:75]
	v_mfma_f32_16x16x32_bf16 v[68:71], v[194:197], v[202:205], v[68:71]
	v_mfma_f32_16x16x32_bf16 v[64:67], v[194:197], v[222:225], v[64:67]
	s_setprio 0
	s_barrier
	ds_read_b128 v[162:165], v137 offset:49152
	ds_read_b128 v[166:169], v137 offset:50176
	ds_read_b128 v[170:173], v137 offset:51200
	ds_read_b128 v[174:177], v137 offset:52224
	ds_read_b128 v[178:181], v137 offset:53248
	ds_read_b128 v[182:185], v137 offset:54272
	ds_read_b128 v[186:189], v137 offset:55296
	ds_read_b128 v[194:197], v137 offset:56320
	s_barrier
	s_waitcnt lgkmcnt(0)
	v_mfma_f32_16x16x32_bf16 v[60:63], v[162:165], v[128:131], v[60:63]
	v_mfma_f32_16x16x32_bf16 v[56:59], v[162:165], v[154:157], v[56:59]
	v_mfma_f32_16x16x32_bf16 v[52:55], v[170:173], v[128:131], v[52:55]
	v_mfma_f32_16x16x32_bf16 v[48:51], v[170:173], v[154:157], v[48:51]
	v_mfma_f32_16x16x32_bf16 v[44:47], v[178:181], v[128:131], v[44:47]
	v_mfma_f32_16x16x32_bf16 v[40:43], v[178:181], v[154:157], v[40:43]
	v_mfma_f32_16x16x32_bf16 v[36:39], v[186:189], v[128:131], v[36:39]
	v_mfma_f32_16x16x32_bf16 v[32:35], v[186:189], v[154:157], v[32:35]
	v_mfma_f32_16x16x32_bf16 v[60:63], v[166:169], v[132:135], v[60:63]
	v_mfma_f32_16x16x32_bf16 v[56:59], v[166:169], v[158:161], v[56:59]
	v_mfma_f32_16x16x32_bf16 v[52:55], v[174:177], v[132:135], v[52:55]
	v_mfma_f32_16x16x32_bf16 v[48:51], v[174:177], v[158:161], v[48:51]
	v_mfma_f32_16x16x32_bf16 v[44:47], v[182:185], v[132:135], v[44:47]
	v_mfma_f32_16x16x32_bf16 v[40:43], v[182:185], v[158:161], v[40:43]
	v_mfma_f32_16x16x32_bf16 v[36:39], v[194:197], v[132:135], v[36:39]
	v_mfma_f32_16x16x32_bf16 v[32:35], v[194:197], v[158:161], v[32:35]
	s_setprio 0
	v_mfma_f32_16x16x32_bf16 v[28:31], v[162:165], v[198:201], v[28:31]
	v_mfma_f32_16x16x32_bf16 v[24:27], v[162:165], v[206:209], v[24:27]
	v_mfma_f32_16x16x32_bf16 v[20:23], v[170:173], v[198:201], v[20:23]
	v_mfma_f32_16x16x32_bf16 v[16:19], v[170:173], v[206:209], v[16:19]
	v_mfma_f32_16x16x32_bf16 v[12:15], v[178:181], v[198:201], v[12:15]
	v_mfma_f32_16x16x32_bf16 v[8:11], v[178:181], v[206:209], v[8:11]
	v_mfma_f32_16x16x32_bf16 v[4:7], v[186:189], v[198:201], v[4:7]
	v_mfma_f32_16x16x32_bf16 v[0:3], v[186:189], v[206:209], v[0:3]
	v_mfma_f32_16x16x32_bf16 v[28:31], v[166:169], v[202:205], v[28:31]
	v_mfma_f32_16x16x32_bf16 v[24:27], v[166:169], v[222:225], v[24:27]
	v_mfma_f32_16x16x32_bf16 v[20:23], v[174:177], v[202:205], v[20:23]
	v_mfma_f32_16x16x32_bf16 v[16:19], v[174:177], v[222:225], v[16:19]
	v_mfma_f32_16x16x32_bf16 v[12:15], v[182:185], v[202:205], v[12:15]
	v_mfma_f32_16x16x32_bf16 v[8:11], v[182:185], v[222:225], v[8:11]
	v_mfma_f32_16x16x32_bf16 v[4:7], v[194:197], v[202:205], v[4:7]
	v_mfma_f32_16x16x32_bf16 v[0:3], v[194:197], v[222:225], v[0:3]
	s_setprio 0
	s_movk_i32 s0, 0x100
	v_cmp_gt_u32_e32 vcc, s0, v136
	s_barrier
	s_and_saveexec_b64 s[0:1], vcc
	s_cbranch_execz .LBB0_118
	s_barrier
	s_or_b64 exec, exec, s[0:1]
	s_cmp_gt_u32 s2, 15
	s_mov_b64 s[0:1], -1
	s_cbranch_scc1 .LBB0_119

; #define WAIT_L(n) asm volatile("s_waitcnt lgkmcnt(" #n ")" ::: "memory")
; #define BAR __builtin_amdgcn_s_barrier()
; #define SCHED __builtin_amdgcn_sched_barrier(0)
; #define STAGE(P, BASE, br, kt) do { const char* _g = (const char*)((BASE) + (size_t)(br) * GK + (kt) * BK); \
;     __builtin_amdgcn_global_load_lds((const unsigned*)(_g + voff0), (unsigned*)((char*)(P) + tx * 16), 16, 0, 0); \
;     __builtin_amdgcn_global_load_lds((const unsigned*)(_g + voff1), (unsigned*)((char*)(P) + tx * 16 + 8192), 16, 0, 0); } while (0)
; #define LDA(dst, b, h) _Pragma("unroll") for (int m = 0; m < 4; ++m) _Pragma("unroll") for (int k = 0; k < 2; ++k) \
;     dst[m][k] = *reinterpret_cast<const bf16x8*>((char*)shm + abase + (((b) * 2 + (h)) * 16384 + (m * 2 + k) * 1024))
; #define LDB(dst, b, h) _Pragma("unroll") for (int n = 0; n < 2; ++n) _Pragma("unroll") for (int k = 0; k < 2; ++k) \
;     dst[n][k] = *reinterpret_cast<const bf16x8*>((char*)shm + bbase + (((b) * 2 + (h)) * 16384 + (n * 2 + k) * 1024))
; template <bool SWAP>
; __device__ __forceinline__ void gemm_main(const u16* __restrict__ A, const u16* __restrict__ Bt, int brow, int bcol,
;                                           u16* shm, f32x4 (&acc)[2][2][4][2]) {
;     ...
;     LDB(B0, 0, 0); SCHED; LDA(At, 0, 0); STAGE(SA(1, 1), A, brow + HALF, t + 1);
;     WAIT_L(8); BAR; WAIT_L(0); MMA(0, 0, At, B0); BAR; SCHED;
;     LDB(B1, 0, 1); STAGE(SB(0, 0), Bt, bcol, t + 2);
;     BAR; WAIT_L(0); MMA(0, 1, At, B1); BAR;
;     LDA(At, 0, 1); STAGE(SA(0, 0), A, brow, t + 2);
;     BAR; WAIT_L(0); MMA(1, 0, At, B0); BAR; SCHED;
;     STAGE(SB(0, 1), Bt, bcol + HALF, t + 2);
.LBB0_200:
	ds_read_b128 v[182:185], v137 offset:1024
	ds_read_b128 v[194:197], v137 offset:3072
	ds_read_b128 v[202:205], v137 offset:5120
	ds_read_b128 v[222:225], v137 offset:7168
	v_add_u32_e32 v192, 0, v153
	v_add_u32_e32 v160, 0xc000, v192
	v_add_u32_e32 v161, 0xe000, v192
	s_add_u32 m0, s3, 0xc000
	v_lshl_add_u64 v[242:243], s[0:1], 0, v[134:135]
	s_add_u32 vcc_lo, s0, s82
	s_addc_u32 vcc_hi, s1, s83
	global_load_lds_dwordx4 v132, vcc
	s_add_u32 m0, s3, 0xe000
	s_nop 0
	global_load_lds_dwordx4 v134, vcc
	s_waitcnt lgkmcnt(8)
	s_barrier
	s_waitcnt lgkmcnt(0)
	v_mfma_f32_16x16x32_bf16 v[124:127], v[162:165], v[178:181], v[124:127]
	v_mfma_f32_16x16x32_bf16 v[120:123], v[170:173], v[178:181], v[120:123]
	v_mfma_f32_16x16x32_bf16 v[116:119], v[162:165], v[186:189], v[116:119]
	v_mfma_f32_16x16x32_bf16 v[112:115], v[170:173], v[186:189], v[112:115]
	v_mfma_f32_16x16x32_bf16 v[108:111], v[162:165], v[198:201], v[108:111]
	v_mfma_f32_16x16x32_bf16 v[104:107], v[170:173], v[198:201], v[104:107]
	v_mfma_f32_16x16x32_bf16 v[100:103], v[162:165], v[206:209], v[100:103]
	v_mfma_f32_16x16x32_bf16 v[96:99], v[170:173], v[206:209], v[96:99]
	v_mfma_f32_16x16x32_bf16 v[124:127], v[166:169], v[182:185], v[124:127]
	v_mfma_f32_16x16x32_bf16 v[120:123], v[174:177], v[182:185], v[120:123]
	v_mfma_f32_16x16x32_bf16 v[116:119], v[166:169], v[194:197], v[116:119]
	v_mfma_f32_16x16x32_bf16 v[112:115], v[174:177], v[194:197], v[112:115]
	v_mfma_f32_16x16x32_bf16 v[108:111], v[166:169], v[202:205], v[108:111]
	v_mfma_f32_16x16x32_bf16 v[104:107], v[174:177], v[202:205], v[104:107]
	v_mfma_f32_16x16x32_bf16 v[100:103], v[166:169], v[222:225], v[100:103]
	v_mfma_f32_16x16x32_bf16 v[96:99], v[174:177], v[222:225], v[96:99]
	s_barrier
	ds_read_b128 v[226:229], v152 offset:16384
	ds_read_b128 v[230:233], v152 offset:17408
	ds_read_b128 v[234:237], v152 offset:18432
	ds_read_b128 v[238:241], v152 offset:19456
	v_lshl_add_u64 v[244:245], s[0:1], 0, v[128:129]
	s_add_u32 m0, s3, s28
	s_nop 0
	s_add_u32 vcc_lo, s0, s74
	s_addc_u32 vcc_hi, s1, s75
	global_load_lds_dwordx4 v128, vcc
	v_lshl_add_u64 v[246:247], s[0:1], 0, v[130:131]
	s_add_u32 m0, s3, s28
	s_add_u32 m0, m0, 0x2000
	s_nop 0
	global_load_lds_dwordx4 v130, vcc
	s_barrier
	s_waitcnt lgkmcnt(0)
	v_mfma_f32_16x16x32_bf16 v[92:95], v[226:229], v[178:181], v[92:95]
	v_mfma_f32_16x16x32_bf16 v[88:91], v[234:237], v[178:181], v[88:91]
	v_mfma_f32_16x16x32_bf16 v[84:87], v[226:229], v[186:189], v[84:87]
	v_mfma_f32_16x16x32_bf16 v[80:83], v[234:237], v[186:189], v[80:83]
	v_mfma_f32_16x16x32_bf16 v[76:79], v[226:229], v[198:201], v[76:79]
	v_mfma_f32_16x16x32_bf16 v[72:75], v[234:237], v[198:201], v[72:75]
	v_mfma_f32_16x16x32_bf16 v[68:71], v[226:229], v[206:209], v[68:71]
	v_mfma_f32_16x16x32_bf16 v[64:67], v[234:237], v[206:209], v[64:67]
	v_mfma_f32_16x16x32_bf16 v[92:95], v[230:233], v[182:185], v[92:95]
	ds_read_b128 v[178:181], v137 offset:16384
	v_mfma_f32_16x16x32_bf16 v[88:91], v[238:241], v[182:185], v[88:91]
	v_mfma_f32_16x16x32_bf16 v[84:87], v[230:233], v[194:197], v[84:87]
	ds_read_b128 v[186:189], v137 offset:18432
	v_mfma_f32_16x16x32_bf16 v[80:83], v[238:241], v[194:197], v[80:83]
	v_mfma_f32_16x16x32_bf16 v[76:79], v[230:233], v[202:205], v[76:79]
	ds_read_b128 v[198:201], v137 offset:20480
	v_mfma_f32_16x16x32_bf16 v[72:75], v[238:241], v[202:205], v[72:75]
	v_mfma_f32_16x16x32_bf16 v[68:71], v[230:233], v[222:225], v[68:71]
	ds_read_b128 v[206:209], v137 offset:22528
	v_mfma_f32_16x16x32_bf16 v[64:67], v[238:241], v[222:225], v[64:67]
	s_barrier
	ds_read_b128 v[182:185], v137 offset:17408
	ds_read_b128 v[194:197], v137 offset:19456
	ds_read_b128 v[202:205], v137 offset:21504
	ds_read_b128 v[222:225], v137 offset:23552
	s_add_u32 m0, s3, 0x0
	s_nop 0
	s_add_u32 vcc_lo, s0, s76
	s_addc_u32 vcc_hi, s1, s77
	global_load_lds_dwordx4 v132, vcc
	s_add_u32 m0, s3, 0x2000
	s_nop 0
	global_load_lds_dwordx4 v134, vcc
	s_waitcnt vmcnt(8)
	s_barrier
	s_waitcnt lgkmcnt(0)
	v_mfma_f32_16x16x32_bf16 v[60:63], v[162:165], v[178:181], v[60:63]
	v_mfma_f32_16x16x32_bf16 v[56:59], v[170:173], v[178:181], v[56:59]
	v_mfma_f32_16x16x32_bf16 v[52:55], v[162:165], v[186:189], v[52:55]
	v_mfma_f32_16x16x32_bf16 v[48:51], v[170:173], v[186:189], v[48:51]
	v_mfma_f32_16x16x32_bf16 v[44:47], v[162:165], v[198:201], v[44:47]
	v_mfma_f32_16x16x32_bf16 v[40:43], v[170:173], v[198:201], v[40:43]
	v_mfma_f32_16x16x32_bf16 v[36:39], v[162:165], v[206:209], v[36:39]
	v_mfma_f32_16x16x32_bf16 v[32:35], v[170:173], v[206:209], v[32:35]
	v_mfma_f32_16x16x32_bf16 v[60:63], v[166:169], v[182:185], v[60:63]
	v_mfma_f32_16x16x32_bf16 v[56:59], v[174:177], v[182:185], v[56:59]
	v_mfma_f32_16x16x32_bf16 v[52:55], v[166:169], v[194:197], v[52:55]
	v_mfma_f32_16x16x32_bf16 v[48:51], v[174:177], v[194:197], v[48:51]
	v_mfma_f32_16x16x32_bf16 v[44:47], v[166:169], v[202:205], v[44:47]
	v_mfma_f32_16x16x32_bf16 v[40:43], v[174:177], v[202:205], v[40:43]
	v_mfma_f32_16x16x32_bf16 v[36:39], v[166:169], v[222:225], v[36:39]
	v_mfma_f32_16x16x32_bf16 v[32:35], v[174:177], v[222:225], v[32:35]
	s_barrier
	ds_read_b128 v[162:165], v152 offset:32768
	ds_read_b128 v[166:169], v152 offset:33792
	ds_read_b128 v[170:173], v152 offset:34816
	ds_read_b128 v[174:177], v152 offset:35840
	s_add_u32 m0, s3, s29
	s_nop 0
	s_add_u32 vcc_lo, s0, s70
	s_addc_u32 vcc_hi, s1, s71
	global_load_lds_dwordx4 v128, vcc
	s_add_u32 m0, s3, s29
	s_add_u32 m0, m0, 0x2000
	s_nop 0
	global_load_lds_dwordx4 v130, vcc
	s_waitcnt vmcnt(6)
	s_barrier
; #define WAIT_V(n) asm volatile("s_waitcnt vmcnt(" #n ")" ::: "memory")
; #define WAIT_L(n) asm volatile("s_waitcnt lgkmcnt(" #n ")" ::: "memory")
; #define BAR __builtin_amdgcn_s_barrier()
; #define SCHED __builtin_amdgcn_sched_barrier(0)
; #define STAGE(P, BASE, br, kt) do { const char* _g = (const char*)((BASE) + (size_t)(br) * GK + (kt) * BK); \
;     __builtin_amdgcn_global_load_lds((const unsigned*)(_g + voff0), (unsigned*)((char*)(P) + tx * 16), 16, 0, 0); \
;     __builtin_amdgcn_global_load_lds((const unsigned*)(_g + voff1), (unsigned*)((char*)(P) + tx * 16 + 8192), 16, 0, 0); } while (0)
; #define LDA(dst, b, h) _Pragma("unroll") for (int m = 0; m < 4; ++m) _Pragma("unroll") for (int k = 0; k < 2; ++k) \
;     dst[m][k] = *reinterpret_cast<const bf16x8*>((char*)shm + abase + (((b) * 2 + (h)) * 16384 + (m * 2 + k) * 1024))
; #define LDB(dst, b, h) _Pragma("unroll") for (int n = 0; n < 2; ++n) _Pragma("unroll") for (int k = 0; k < 2; ++k) \
;     dst[n][k] = *reinterpret_cast<const bf16x8*>((char*)shm + bbase + (((b) * 2 + (h)) * 16384 + (n * 2 + k) * 1024))
; template <bool SWAP>
; __device__ __forceinline__ void gemm_main(const u16* __restrict__ A, const u16* __restrict__ Bt, int brow, int bcol,
;                                           u16* shm, f32x4 (&acc)[2][2][4][2]) {
;     ...
;     WAIT_V(6); BAR; MMA(1, 1, At, B1); BAR;
;     LDB(B0, 1, 0); SCHED; LDA(At, 1, 0); STAGE(SA(0, 1), A, brow + HALF, t + 2);
;     WAIT_L(8); BAR; WAIT_L(0); MMA(0, 0, At, B0); BAR; SCHED;
;     LDB(B1, 1, 1); STAGE(SB(1, 0), Bt, bcol, t + 3);
;     BAR; WAIT_L(0); MMA(0, 1, At, B1); BAR;
;     LDA(At, 1, 1); STAGE(SA(1, 0), A, brow, t + 3);
;     BAR; WAIT_L(0); MMA(1, 0, At, B0); BAR; SCHED;
;     STAGE(SB(1, 1), Bt, bcol + HALF, t + 3);
	v_mfma_f32_16x16x32_bf16 v[28:31], v[226:229], v[178:181], v[28:31]
	v_mfma_f32_16x16x32_bf16 v[24:27], v[234:237], v[178:181], v[24:27]
	v_mfma_f32_16x16x32_bf16 v[20:23], v[226:229], v[186:189], v[20:23]
	v_mfma_f32_16x16x32_bf16 v[16:19], v[234:237], v[186:189], v[16:19]
	v_mfma_f32_16x16x32_bf16 v[12:15], v[226:229], v[198:201], v[12:15]
	v_mfma_f32_16x16x32_bf16 v[8:11], v[234:237], v[198:201], v[8:11]
	v_mfma_f32_16x16x32_bf16 v[4:7], v[226:229], v[206:209], v[4:7]
	v_mfma_f32_16x16x32_bf16 v[0:3], v[234:237], v[206:209], v[0:3]
	v_mfma_f32_16x16x32_bf16 v[28:31], v[230:233], v[182:185], v[28:31]
	ds_read_b128 v[178:181], v137 offset:32768
	v_mfma_f32_16x16x32_bf16 v[24:27], v[238:241], v[182:185], v[24:27]
	v_mfma_f32_16x16x32_bf16 v[20:23], v[230:233], v[194:197], v[20:23]
	ds_read_b128 v[186:189], v137 offset:34816
	v_mfma_f32_16x16x32_bf16 v[16:19], v[238:241], v[194:197], v[16:19]
	v_mfma_f32_16x16x32_bf16 v[12:15], v[230:233], v[202:205], v[12:15]
	ds_read_b128 v[198:201], v137 offset:36864
	v_mfma_f32_16x16x32_bf16 v[8:11], v[238:241], v[202:205], v[8:11]
	v_mfma_f32_16x16x32_bf16 v[4:7], v[230:233], v[222:225], v[4:7]
	ds_read_b128 v[206:209], v137 offset:38912
	v_mfma_f32_16x16x32_bf16 v[0:3], v[238:241], v[222:225], v[0:3]
	s_barrier
	ds_read_b128 v[182:185], v137 offset:33792
	ds_read_b128 v[194:197], v137 offset:35840
	ds_read_b128 v[202:205], v137 offset:37888
	ds_read_b128 v[222:225], v137 offset:39936
	s_add_u32 m0, s3, 0x4000
	s_nop 0
	s_add_u32 vcc_lo, s0, s96
	s_addc_u32 vcc_hi, s1, s97
	global_load_lds_dwordx4 v132, vcc
	s_add_u32 m0, s3, 0x6000
	s_nop 0
	global_load_lds_dwordx4 v134, vcc
	s_waitcnt lgkmcnt(8)
	s_barrier
	s_waitcnt lgkmcnt(0)
	v_mfma_f32_16x16x32_bf16 v[124:127], v[162:165], v[178:181], v[124:127]
	v_mfma_f32_16x16x32_bf16 v[120:123], v[170:173], v[178:181], v[120:123]
	v_mfma_f32_16x16x32_bf16 v[116:119], v[162:165], v[186:189], v[116:119]
	v_mfma_f32_16x16x32_bf16 v[112:115], v[170:173], v[186:189], v[112:115]
	v_mfma_f32_16x16x32_bf16 v[108:111], v[162:165], v[198:201], v[108:111]
	v_mfma_f32_16x16x32_bf16 v[104:107], v[170:173], v[198:201], v[104:107]
	v_mfma_f32_16x16x32_bf16 v[100:103], v[162:165], v[206:209], v[100:103]
	v_mfma_f32_16x16x32_bf16 v[96:99], v[170:173], v[206:209], v[96:99]
	v_mfma_f32_16x16x32_bf16 v[124:127], v[166:169], v[182:185], v[124:127]
	v_mfma_f32_16x16x32_bf16 v[120:123], v[174:177], v[182:185], v[120:123]
	v_mfma_f32_16x16x32_bf16 v[116:119], v[166:169], v[194:197], v[116:119]
	v_mfma_f32_16x16x32_bf16 v[112:115], v[174:177], v[194:197], v[112:115]
	v_mfma_f32_16x16x32_bf16 v[108:111], v[166:169], v[202:205], v[108:111]
	v_mfma_f32_16x16x32_bf16 v[104:107], v[174:177], v[202:205], v[104:107]
	v_mfma_f32_16x16x32_bf16 v[100:103], v[166:169], v[222:225], v[100:103]
	v_mfma_f32_16x16x32_bf16 v[96:99], v[174:177], v[222:225], v[96:99]
	s_barrier
	ds_read_b128 v[226:229], v152 offset:49152
	ds_read_b128 v[230:233], v152 offset:50176
	ds_read_b128 v[234:237], v152 offset:51200
	ds_read_b128 v[238:241], v152 offset:52224
	v_add_u32_e32 v250, s30, v153
	v_add_u32_e32 v250, 0x2000, v250
	s_add_u32 m0, s3, s30
	s_nop 0
	s_add_u32 vcc_lo, s0, s34
	s_addc_u32 vcc_hi, s1, s35
	global_load_lds_dwordx4 v128, vcc
	v_lshl_add_u64 v[248:249], v[246:247], 0, s[34:35]
	s_add_u32 m0, s3, s30
	s_add_u32 m0, m0, 0x2000
	s_nop 0
	global_load_lds_dwordx4 v130, vcc
	s_barrier
	s_waitcnt lgkmcnt(0)
	v_mfma_f32_16x16x32_bf16 v[92:95], v[226:229], v[178:181], v[92:95]
	v_mfma_f32_16x16x32_bf16 v[88:91], v[234:237], v[178:181], v[88:91]
	v_mfma_f32_16x16x32_bf16 v[84:87], v[226:229], v[186:189], v[84:87]
	v_mfma_f32_16x16x32_bf16 v[80:83], v[234:237], v[186:189], v[80:83]
	v_mfma_f32_16x16x32_bf16 v[76:79], v[226:229], v[198:201], v[76:79]
	v_mfma_f32_16x16x32_bf16 v[72:75], v[234:237], v[198:201], v[72:75]
	v_mfma_f32_16x16x32_bf16 v[68:71], v[226:229], v[206:209], v[68:71]
	v_mfma_f32_16x16x32_bf16 v[64:67], v[234:237], v[206:209], v[64:67]
	v_mfma_f32_16x16x32_bf16 v[92:95], v[230:233], v[182:185], v[92:95]
	ds_read_b128 v[178:181], v137 offset:49152
	v_mfma_f32_16x16x32_bf16 v[88:91], v[238:241], v[182:185], v[88:91]
	v_mfma_f32_16x16x32_bf16 v[84:87], v[230:233], v[194:197], v[84:87]
	ds_read_b128 v[186:189], v137 offset:51200
	v_mfma_f32_16x16x32_bf16 v[80:83], v[238:241], v[194:197], v[80:83]
	v_mfma_f32_16x16x32_bf16 v[76:79], v[230:233], v[202:205], v[76:79]
	ds_read_b128 v[198:201], v137 offset:53248
	v_mfma_f32_16x16x32_bf16 v[72:75], v[238:241], v[202:205], v[72:75]
	v_mfma_f32_16x16x32_bf16 v[68:71], v[230:233], v[222:225], v[68:71]
	ds_read_b128 v[206:209], v137 offset:55296
	v_mfma_f32_16x16x32_bf16 v[64:67], v[238:241], v[222:225], v[64:67]
	s_barrier
	ds_read_b128 v[182:185], v137 offset:50176
	ds_read_b128 v[194:197], v137 offset:52224
	ds_read_b128 v[202:205], v137 offset:54272
	ds_read_b128 v[222:225], v137 offset:56320
	v_add_u32_e32 v248, 0x8000, v192
	s_add_u32 m0, s3, 0x8000
	s_nop 0
	s_add_u32 vcc_lo, s0, s36
	s_addc_u32 vcc_hi, s1, s37
	global_load_lds_dwordx4 v132, vcc
	s_add_u32 m0, s3, 0xa000
	s_nop 0
	global_load_lds_dwordx4 v134, vcc
	s_waitcnt vmcnt(8)
	s_barrier
; #define WAIT_V(n) asm volatile("s_waitcnt vmcnt(" #n ")" ::: "memory")
; #define WAIT_L(n) asm volatile("s_waitcnt lgkmcnt(" #n ")" ::: "memory")
; #define BAR __builtin_amdgcn_s_barrier()
; #define SCHED __builtin_amdgcn_sched_barrier(0)
; #define STAGE(P, BASE, br, kt) do { const char* _g = (const char*)((BASE) + (size_t)(br) * GK + (kt) * BK); \
;     __builtin_amdgcn_global_load_lds((const unsigned*)(_g + voff0), (unsigned*)((char*)(P) + tx * 16), 16, 0, 0); \
;     __builtin_amdgcn_global_load_lds((const unsigned*)(_g + voff1), (unsigned*)((char*)(P) + tx * 16 + 8192), 16, 0, 0); } while (0)
; #define LDA(dst, b, h) _Pragma("unroll") for (int m = 0; m < 4; ++m) _Pragma("unroll") for (int k = 0; k < 2; ++k) \
;     dst[m][k] = *reinterpret_cast<const bf16x8*>((char*)shm + abase + (((b) * 2 + (h)) * 16384 + (m * 2 + k) * 1024))
; #define LDB(dst, b, h) _Pragma("unroll") for (int n = 0; n < 2; ++n) _Pragma("unroll") for (int k = 0; k < 2; ++k) \
;     dst[n][k] = *reinterpret_cast<const bf16x8*>((char*)shm + bbase + (((b) * 2 + (h)) * 16384 + (n * 2 + k) * 1024))
; template <bool SWAP>
; __device__ __forceinline__ void gemm_main(const u16* __restrict__ A, const u16* __restrict__ Bt, int brow, int bcol,
;                                           u16* shm, f32x4 (&acc)[2][2][4][2]) {
;     ...
;     LDA(At, 1, 1); STAGE(SA(1, 0), A, brow, t + 3);
;     BAR; WAIT_L(0); MMA(1, 0, At, B0); BAR; SCHED;
;     STAGE(SB(1, 1), Bt, bcol + HALF, t + 3);
;     WAIT_V(6); BAR; MMA(1, 1, At, B1); BAR;
;   }
;   { LDB(B0, 0, 0); LDA(At, 0, 0); STAGE(SA(1, 1), A, brow + HALF, nt - 1);
;     BAR; WAIT_L(0); MMA(0, 0, At, B0); BAR;
;     LDB(B1, 0, 1); BAR; WAIT_L(0); MMA(0, 1, At, B1); BAR;
	s_waitcnt lgkmcnt(0)
	v_mfma_f32_16x16x32_bf16 v[60:63], v[162:165], v[178:181], v[60:63]
	v_mfma_f32_16x16x32_bf16 v[56:59], v[170:173], v[178:181], v[56:59]
	v_mfma_f32_16x16x32_bf16 v[52:55], v[162:165], v[186:189], v[52:55]
	v_mfma_f32_16x16x32_bf16 v[48:51], v[170:173], v[186:189], v[48:51]
	v_mfma_f32_16x16x32_bf16 v[44:47], v[162:165], v[198:201], v[44:47]
	v_mfma_f32_16x16x32_bf16 v[40:43], v[170:173], v[198:201], v[40:43]
	v_mfma_f32_16x16x32_bf16 v[36:39], v[162:165], v[206:209], v[36:39]
	v_mfma_f32_16x16x32_bf16 v[32:35], v[170:173], v[206:209], v[32:35]
	v_mfma_f32_16x16x32_bf16 v[60:63], v[166:169], v[182:185], v[60:63]
	v_mfma_f32_16x16x32_bf16 v[56:59], v[174:177], v[182:185], v[56:59]
	v_mfma_f32_16x16x32_bf16 v[52:55], v[166:169], v[194:197], v[52:55]
	v_mfma_f32_16x16x32_bf16 v[48:51], v[174:177], v[194:197], v[48:51]
	v_mfma_f32_16x16x32_bf16 v[44:47], v[166:169], v[202:205], v[44:47]
	v_mfma_f32_16x16x32_bf16 v[40:43], v[174:177], v[202:205], v[40:43]
	v_mfma_f32_16x16x32_bf16 v[36:39], v[166:169], v[222:225], v[36:39]
	v_mfma_f32_16x16x32_bf16 v[32:35], v[174:177], v[222:225], v[32:35]
	s_barrier
	ds_read_b128 v[162:165], v152
	ds_read_b128 v[166:169], v152 offset:1024
	ds_read_b128 v[170:173], v152 offset:2048
	ds_read_b128 v[174:177], v152 offset:3072
	s_add_u32 m0, s3, s31
	s_nop 0
	s_add_u32 vcc_lo, s0, s64
	s_addc_u32 vcc_hi, s1, s65
	global_load_lds_dwordx4 v128, vcc
	v_lshl_add_u64 v[254:255], v[246:247], 0, s[64:65]
	s_add_u32 m0, s3, s31
	s_add_u32 m0, m0, 0x2000
	s_nop 0
	global_load_lds_dwordx4 v130, vcc
	s_waitcnt vmcnt(6)
	s_barrier
	v_mfma_f32_16x16x32_bf16 v[28:31], v[226:229], v[178:181], v[28:31]
	v_mfma_f32_16x16x32_bf16 v[24:27], v[234:237], v[178:181], v[24:27]
	v_mfma_f32_16x16x32_bf16 v[20:23], v[226:229], v[186:189], v[20:23]
	v_mfma_f32_16x16x32_bf16 v[16:19], v[234:237], v[186:189], v[16:19]
	v_mfma_f32_16x16x32_bf16 v[12:15], v[226:229], v[198:201], v[12:15]
	v_mfma_f32_16x16x32_bf16 v[8:11], v[234:237], v[198:201], v[8:11]
	v_mfma_f32_16x16x32_bf16 v[4:7], v[226:229], v[206:209], v[4:7]
	v_mfma_f32_16x16x32_bf16 v[0:3], v[234:237], v[206:209], v[0:3]
	v_mfma_f32_16x16x32_bf16 v[28:31], v[230:233], v[182:185], v[28:31]
	ds_read_b128 v[178:181], v137
	v_mfma_f32_16x16x32_bf16 v[24:27], v[238:241], v[182:185], v[24:27]
	v_mfma_f32_16x16x32_bf16 v[20:23], v[230:233], v[194:197], v[20:23]
	ds_read_b128 v[186:189], v137 offset:2048
	v_mfma_f32_16x16x32_bf16 v[16:19], v[238:241], v[194:197], v[16:19]
	v_mfma_f32_16x16x32_bf16 v[12:15], v[230:233], v[202:205], v[12:15]
	ds_read_b128 v[198:201], v137 offset:4096
	v_mfma_f32_16x16x32_bf16 v[8:11], v[238:241], v[202:205], v[8:11]
	v_mfma_f32_16x16x32_bf16 v[4:7], v[230:233], v[222:225], v[4:7]
	ds_read_b128 v[206:209], v137 offset:6144
	v_mfma_f32_16x16x32_bf16 v[0:3], v[238:241], v[222:225], v[0:3]
	s_add_i32 s2, s2, 2
	s_add_u32 s0, s0, 0x100
	s_addc_u32 s1, s1, 0
	s_cmp_lt_u32 s2, 28
	s_barrier
	s_cbranch_scc1 .LBB0_200
	v_lshlrev_b32_e32 v128, 3, v154
	v_lshlrev_b32_e32 v129, 5, v154
	v_and_b32_e32 v128, 0xffff0, v128
	v_and_b32_e32 v129, 32, v129
	s_or_b32 s0, s24, 0x80
	v_add_u32_e32 v129, v129, v156
	v_add_lshl_u32 v128, v155, v128, 12
	s_ashr_i32 s1, s0, 31
	v_lshl_add_u32 v192, v129, 1, v128
	v_lshlrev_b32_e32 v128, 3, v157
	v_lshlrev_b32_e32 v129, 5, v157
	s_lshl_b64 s[0:1], s[0:1], 12
	v_readlane_b32 s2, v253, 35
	v_and_b32_e32 v128, 0xffff0, v128
	v_and_b32_e32 v129, 32, v129
	v_readlane_b32 s3, v253, 36
	s_add_u32 s0, s2, s0
	v_add_u32_e32 v129, v129, v159
	v_add_lshl_u32 v128, v158, v128, 12
	s_addc_u32 s1, s3, s1
	v_lshl_add_u32 v158, v129, 1, v128
	v_mov_b32_e32 v159, v193
	v_lshl_add_u64 v[190:191], s[0:1], 0, v[192:193]
	s_mov_b64 s[4:5], 0xf80
	v_readfirstlane_b32 s2, v160
	v_lshl_add_u64 v[190:191], v[190:191], 0, s[4:5]
	s_mov_b32 m0, s2
	v_lshl_add_u64 v[158:159], s[0:1], 0, v[158:159]
	v_readfirstlane_b32 s0, v161
	ds_read_b128 v[128:131], v152
	ds_read_b128 v[132:135], v152 offset:1024
	ds_read_b128 v[154:157], v152 offset:2048
	ds_read_b128 v[162:165], v152 offset:3072
	ds_read_b128 v[166:169], v137
	ds_read_b128 v[170:173], v137 offset:1024
	ds_read_b128 v[174:177], v137 offset:2048
	ds_read_b128 v[178:181], v137 offset:3072
	ds_read_b128 v[182:185], v137 offset:4096
	ds_read_b128 v[186:189], v137 offset:5120
	ds_read_b128 v[194:197], v137 offset:6144
	ds_read_b128 v[198:201], v137 offset:7168
	global_load_lds_dwordx4 v[190:191], off
	v_lshl_add_u64 v[158:159], v[158:159], 0, s[4:5]
	s_mov_b32 m0, s0
	s_nop 0
	global_load_lds_dwordx4 v[158:159], off
	s_barrier
	s_waitcnt lgkmcnt(0)
	v_mfma_f32_16x16x32_bf16 v[124:127], v[128:131], v[166:169], v[124:127]
	v_mfma_f32_16x16x32_bf16 v[116:119], v[128:131], v[174:177], v[116:119]
	v_mfma_f32_16x16x32_bf16 v[108:111], v[128:131], v[182:185], v[108:111]
	v_mfma_f32_16x16x32_bf16 v[100:103], v[128:131], v[194:197], v[100:103]
	v_mfma_f32_16x16x32_bf16 v[124:127], v[132:135], v[170:173], v[124:127]
	v_mfma_f32_16x16x32_bf16 v[120:123], v[154:157], v[166:169], v[120:123]
	v_mfma_f32_16x16x32_bf16 v[116:119], v[132:135], v[178:181], v[116:119]
	v_mfma_f32_16x16x32_bf16 v[112:115], v[154:157], v[174:177], v[112:115]
	v_mfma_f32_16x16x32_bf16 v[108:111], v[132:135], v[186:189], v[108:111]
	v_mfma_f32_16x16x32_bf16 v[104:107], v[154:157], v[182:185], v[104:107]
	v_mfma_f32_16x16x32_bf16 v[100:103], v[132:135], v[198:201], v[100:103]
	v_mfma_f32_16x16x32_bf16 v[96:99], v[154:157], v[194:197], v[96:99]
	v_mfma_f32_16x16x32_bf16 v[158:161], v[162:165], v[170:173], v[120:123]
	v_mfma_f32_16x16x32_bf16 v[202:205], v[162:165], v[178:181], v[112:115]
	v_mfma_f32_16x16x32_bf16 v[206:209], v[162:165], v[186:189], v[104:107]
	v_mfma_f32_16x16x32_bf16 v[222:225], v[162:165], v[198:201], v[96:99]
	s_setprio 0
	s_barrier
; #define WAIT_V(n) asm volatile("s_waitcnt vmcnt(" #n ")" ::: "memory")
; #define WAIT_L(n) asm volatile("s_waitcnt lgkmcnt(" #n ")" ::: "memory")
; #define BAR __builtin_amdgcn_s_barrier()
; #define LDA(dst, b, h) _Pragma("unroll") for (int m = 0; m < 4; ++m) _Pragma("unroll") for (int k = 0; k < 2; ++k) \
;     dst[m][k] = *reinterpret_cast<const bf16x8*>((char*)shm + abase + (((b) * 2 + (h)) * 16384 + (m * 2 + k) * 1024))
; #define LDB(dst, b, h) _Pragma("unroll") for (int n = 0; n < 2; ++n) _Pragma("unroll") for (int k = 0; k < 2; ++k) \
;     dst[n][k] = *reinterpret_cast<const bf16x8*>((char*)shm + bbase + (((b) * 2 + (h)) * 16384 + (n * 2 + k) * 1024))
; template <bool SWAP>
; __device__ __forceinline__ void gemm_main(const u16* __restrict__ A, const u16* __restrict__ Bt, int brow, int bcol,
;                                           u16* shm, f32x4 (&acc)[2][2][4][2]) {
;     ...
;     LDB(B1, 0, 1); BAR; WAIT_L(0); MMA(0, 1, At, B1); BAR;
;     LDA(At, 0, 1); WAIT_V(4); BAR; WAIT_L(0); MMA(1, 0, At, B0); MMA(1, 1, At, B1); BAR; }
;   { LDB(B0, 1, 0); LDA(At, 1, 0); WAIT_V(2); BAR; WAIT_L(0); MMA(0, 0, At, B0); BAR;
	s_nop 1
	ds_read_b128 v[96:99], v152 offset:16384
	ds_read_b128 v[104:107], v152 offset:17408
	ds_read_b128 v[112:115], v152 offset:18432
	ds_read_b128 v[120:123], v152 offset:19456
	s_barrier
	s_waitcnt lgkmcnt(0)
	v_mfma_f32_16x16x32_bf16 v[92:95], v[96:99], v[166:169], v[92:95]
	v_mfma_f32_16x16x32_bf16 v[84:87], v[96:99], v[174:177], v[84:87]
	v_mfma_f32_16x16x32_bf16 v[76:79], v[96:99], v[182:185], v[76:79]
	v_mfma_f32_16x16x32_bf16 v[68:71], v[96:99], v[194:197], v[68:71]
	v_mfma_f32_16x16x32_bf16 v[92:95], v[104:107], v[170:173], v[92:95]
	v_mfma_f32_16x16x32_bf16 v[88:91], v[112:115], v[166:169], v[88:91]
	v_mfma_f32_16x16x32_bf16 v[84:87], v[104:107], v[178:181], v[84:87]
	v_mfma_f32_16x16x32_bf16 v[80:83], v[112:115], v[174:177], v[80:83]
	v_mfma_f32_16x16x32_bf16 v[76:79], v[104:107], v[186:189], v[76:79]
	v_mfma_f32_16x16x32_bf16 v[72:75], v[112:115], v[182:185], v[72:75]
	v_mfma_f32_16x16x32_bf16 v[68:71], v[104:107], v[198:201], v[68:71]
	v_mfma_f32_16x16x32_bf16 v[64:67], v[112:115], v[194:197], v[64:67]
	v_mfma_f32_16x16x32_bf16 v[166:169], v[120:123], v[170:173], v[88:91]
	v_mfma_f32_16x16x32_bf16 v[170:173], v[120:123], v[178:181], v[80:83]
	v_mfma_f32_16x16x32_bf16 v[174:177], v[120:123], v[186:189], v[72:75]
	v_mfma_f32_16x16x32_bf16 v[178:181], v[120:123], v[198:201], v[64:67]
	s_setprio 0
	s_barrier
	s_nop 1
	ds_read_b128 v[64:67], v137 offset:16384
	ds_read_b128 v[72:75], v137 offset:17408
	ds_read_b128 v[80:83], v137 offset:18432
	ds_read_b128 v[88:91], v137 offset:19456
	ds_read_b128 v[182:185], v137 offset:20480
	ds_read_b128 v[186:189], v137 offset:21504
	ds_read_b128 v[194:197], v137 offset:22528
	ds_read_b128 v[198:201], v137 offset:23552
	s_waitcnt vmcnt(4)
	s_barrier
	s_waitcnt lgkmcnt(0)
	v_mfma_f32_16x16x32_bf16 v[60:63], v[128:131], v[64:67], v[60:63]
	v_mfma_f32_16x16x32_bf16 v[52:55], v[128:131], v[80:83], v[52:55]
	v_mfma_f32_16x16x32_bf16 v[44:47], v[128:131], v[182:185], v[44:47]
	v_mfma_f32_16x16x32_bf16 v[36:39], v[128:131], v[194:197], v[36:39]
	v_mfma_f32_16x16x32_bf16 v[60:63], v[132:135], v[72:75], v[60:63]
	v_mfma_f32_16x16x32_bf16 v[56:59], v[154:157], v[64:67], v[56:59]
	v_mfma_f32_16x16x32_bf16 v[52:55], v[132:135], v[88:91], v[52:55]
	v_mfma_f32_16x16x32_bf16 v[48:51], v[154:157], v[80:83], v[48:51]
	v_mfma_f32_16x16x32_bf16 v[44:47], v[132:135], v[186:189], v[44:47]
	v_mfma_f32_16x16x32_bf16 v[40:43], v[154:157], v[182:185], v[40:43]
	v_mfma_f32_16x16x32_bf16 v[36:39], v[132:135], v[198:201], v[36:39]
	v_mfma_f32_16x16x32_bf16 v[32:35], v[154:157], v[194:197], v[32:35]
	v_mfma_f32_16x16x32_bf16 v[226:229], v[162:165], v[72:75], v[56:59]
	v_mfma_f32_16x16x32_bf16 v[230:233], v[162:165], v[88:91], v[48:51]
	v_mfma_f32_16x16x32_bf16 v[234:237], v[162:165], v[186:189], v[40:43]
	v_mfma_f32_16x16x32_bf16 v[128:131], v[162:165], v[198:201], v[32:35]
	s_setprio 0
	v_mfma_f32_16x16x32_bf16 v[28:31], v[96:99], v[64:67], v[28:31]
	v_mfma_f32_16x16x32_bf16 v[20:23], v[96:99], v[80:83], v[20:23]
	v_mfma_f32_16x16x32_bf16 v[12:15], v[96:99], v[182:185], v[12:15]
	v_mfma_f32_16x16x32_bf16 v[4:7], v[96:99], v[194:197], v[4:7]
	v_mfma_f32_16x16x32_bf16 v[28:31], v[104:107], v[72:75], v[28:31]
	v_mfma_f32_16x16x32_bf16 v[24:27], v[112:115], v[64:67], v[24:27]
	v_mfma_f32_16x16x32_bf16 v[20:23], v[104:107], v[88:91], v[20:23]
	v_mfma_f32_16x16x32_bf16 v[16:19], v[112:115], v[80:83], v[16:19]
	v_mfma_f32_16x16x32_bf16 v[12:15], v[104:107], v[186:189], v[12:15]
	v_mfma_f32_16x16x32_bf16 v[8:11], v[112:115], v[182:185], v[8:11]
	v_mfma_f32_16x16x32_bf16 v[4:7], v[104:107], v[198:201], v[4:7]
	v_mfma_f32_16x16x32_bf16 v[0:3], v[112:115], v[194:197], v[0:3]
	v_mfma_f32_16x16x32_bf16 v[132:135], v[120:123], v[72:75], v[24:27]
	v_mfma_f32_16x16x32_bf16 v[154:157], v[120:123], v[88:91], v[16:19]
	v_mfma_f32_16x16x32_bf16 v[162:165], v[120:123], v[186:189], v[8:11]
	v_mfma_f32_16x16x32_bf16 v[182:185], v[120:123], v[198:201], v[0:3]
	s_setprio 0
	s_barrier
	s_nop 1
	ds_read_b128 v[0:3], v152 offset:32768
	ds_read_b128 v[8:11], v152 offset:33792
	ds_read_b128 v[16:19], v152 offset:34816
	ds_read_b128 v[24:27], v152 offset:35840
	ds_read_b128 v[32:35], v137 offset:32768
	ds_read_b128 v[40:43], v137 offset:33792
	ds_read_b128 v[48:51], v137 offset:34816
	ds_read_b128 v[56:59], v137 offset:35840
	ds_read_b128 v[64:67], v137 offset:36864
	ds_read_b128 v[186:189], v137 offset:37888
	ds_read_b128 v[194:197], v137 offset:38912
	ds_read_b128 v[198:201], v137 offset:39936
	s_waitcnt vmcnt(2)
	s_barrier
; #define WAIT_V(n) asm volatile("s_waitcnt vmcnt(" #n ")" ::: "memory")
; #define WAIT_L(n) asm volatile("s_waitcnt lgkmcnt(" #n ")" ::: "memory")
; #define BAR __builtin_amdgcn_s_barrier()
; #define LDA(dst, b, h) _Pragma("unroll") for (int m = 0; m < 4; ++m) _Pragma("unroll") for (int k = 0; k < 2; ++k) \
;     dst[m][k] = *reinterpret_cast<const bf16x8*>((char*)shm + abase + (((b) * 2 + (h)) * 16384 + (m * 2 + k) * 1024))
; #define LDB(dst, b, h) _Pragma("unroll") for (int n = 0; n < 2; ++n) _Pragma("unroll") for (int k = 0; k < 2; ++k) \
;     dst[n][k] = *reinterpret_cast<const bf16x8*>((char*)shm + bbase + (((b) * 2 + (h)) * 16384 + (n * 2 + k) * 1024))
; template <bool SWAP>
; __device__ __forceinline__ void gemm_main(const u16* __restrict__ A, const u16* __restrict__ Bt, int brow, int bcol,
;                                           u16* shm, f32x4 (&acc)[2][2][4][2]) {
;     ...
;   { LDB(B0, 1, 0); LDA(At, 1, 0); WAIT_V(2); BAR; WAIT_L(0); MMA(0, 0, At, B0); BAR;
;     LDB(B1, 1, 1); WAIT_V(0); BAR; WAIT_L(0); MMA(0, 1, At, B1); BAR;
;     LDA(At, 1, 1); BAR; WAIT_L(0); MMA(1, 0, At, B0); MMA(1, 1, At, B1); BAR; }
;   if (wr == 0) BAR;
	s_waitcnt lgkmcnt(0)
	v_mfma_f32_16x16x32_bf16 v[72:75], v[0:3], v[32:35], v[124:127]
	v_mfma_f32_16x16x32_bf16 v[120:123], v[8:11], v[40:43], v[72:75]
	v_mfma_f32_16x16x32_bf16 v[72:75], v[16:19], v[32:35], v[158:161]
	v_mfma_f32_16x16x32_bf16 v[124:127], v[24:27], v[40:43], v[72:75]
	v_mfma_f32_16x16x32_bf16 v[72:75], v[0:3], v[48:51], v[116:119]
	v_mfma_f32_16x16x32_bf16 v[112:115], v[8:11], v[56:59], v[72:75]
	v_mfma_f32_16x16x32_bf16 v[72:75], v[16:19], v[48:51], v[202:205]
	v_mfma_f32_16x16x32_bf16 v[116:119], v[24:27], v[56:59], v[72:75]
	v_mfma_f32_16x16x32_bf16 v[72:75], v[0:3], v[64:67], v[108:111]
	v_mfma_f32_16x16x32_bf16 v[104:107], v[8:11], v[186:189], v[72:75]
	v_mfma_f32_16x16x32_bf16 v[72:75], v[16:19], v[64:67], v[206:209]
	v_mfma_f32_16x16x32_bf16 v[108:111], v[24:27], v[186:189], v[72:75]
	v_mfma_f32_16x16x32_bf16 v[72:75], v[0:3], v[194:197], v[100:103]
	v_mfma_f32_16x16x32_bf16 v[96:99], v[8:11], v[198:201], v[72:75]
	v_mfma_f32_16x16x32_bf16 v[72:75], v[16:19], v[194:197], v[222:225]
	v_mfma_f32_16x16x32_bf16 v[100:103], v[24:27], v[198:201], v[72:75]
	s_setprio 0
	s_barrier
	ds_read_b128 v[158:161], v152 offset:49152
	ds_read_b128 v[202:205], v152 offset:50176
	ds_read_b128 v[206:209], v152 offset:51200
	ds_read_b128 v[222:225], v152 offset:52224
	s_waitcnt vmcnt(0)
	s_barrier
	s_waitcnt lgkmcnt(0)
	v_mfma_f32_16x16x32_bf16 v[72:75], v[158:161], v[32:35], v[92:95]
	v_mfma_f32_16x16x32_bf16 v[32:35], v[206:209], v[32:35], v[166:169]
	v_mfma_f32_16x16x32_bf16 v[92:95], v[222:225], v[40:43], v[32:35]
	v_mfma_f32_16x16x32_bf16 v[32:35], v[158:161], v[48:51], v[84:87]
	v_mfma_f32_16x16x32_bf16 v[80:83], v[202:205], v[56:59], v[32:35]
	v_mfma_f32_16x16x32_bf16 v[32:35], v[206:209], v[48:51], v[170:173]
	v_mfma_f32_16x16x32_bf16 v[84:87], v[222:225], v[56:59], v[32:35]
	v_mfma_f32_16x16x32_bf16 v[32:35], v[158:161], v[64:67], v[76:79]
	v_mfma_f32_16x16x32_bf16 v[88:91], v[202:205], v[40:43], v[72:75]
	v_mfma_f32_16x16x32_bf16 v[72:75], v[202:205], v[186:189], v[32:35]
	v_mfma_f32_16x16x32_bf16 v[32:35], v[206:209], v[64:67], v[174:177]
	v_mfma_f32_16x16x32_bf16 v[76:79], v[222:225], v[186:189], v[32:35]
	v_mfma_f32_16x16x32_bf16 v[32:35], v[158:161], v[194:197], v[68:71]
	v_mfma_f32_16x16x32_bf16 v[64:67], v[202:205], v[198:201], v[32:35]
	v_mfma_f32_16x16x32_bf16 v[32:35], v[206:209], v[194:197], v[178:181]
	v_mfma_f32_16x16x32_bf16 v[68:71], v[222:225], v[198:201], v[32:35]
	s_setprio 0
	s_barrier
	ds_read_b128 v[166:169], v137 offset:49152
	ds_read_b128 v[170:173], v137 offset:50176
	ds_read_b128 v[174:177], v137 offset:51200
	ds_read_b128 v[178:181], v137 offset:52224
	ds_read_b128 v[186:189], v137 offset:53248
	ds_read_b128 v[194:197], v137 offset:54272
	ds_read_b128 v[198:201], v137 offset:55296
	ds_read_b128 v[238:241], v137 offset:56320
	s_barrier
	s_waitcnt lgkmcnt(0)
	v_mfma_f32_16x16x32_bf16 v[32:35], v[0:3], v[166:169], v[60:63]
	v_mfma_f32_16x16x32_bf16 v[56:59], v[8:11], v[170:173], v[32:35]
	v_mfma_f32_16x16x32_bf16 v[32:35], v[16:19], v[166:169], v[226:229]
	v_mfma_f32_16x16x32_bf16 v[60:63], v[24:27], v[170:173], v[32:35]
	v_mfma_f32_16x16x32_bf16 v[32:35], v[0:3], v[174:177], v[52:55]
	v_mfma_f32_16x16x32_bf16 v[48:51], v[8:11], v[178:181], v[32:35]
	v_mfma_f32_16x16x32_bf16 v[32:35], v[16:19], v[174:177], v[230:233]
	v_mfma_f32_16x16x32_bf16 v[52:55], v[24:27], v[178:181], v[32:35]
	v_mfma_f32_16x16x32_bf16 v[32:35], v[0:3], v[186:189], v[44:47]
	v_mfma_f32_16x16x32_bf16 v[40:43], v[8:11], v[194:197], v[32:35]
	v_mfma_f32_16x16x32_bf16 v[32:35], v[16:19], v[186:189], v[234:237]
	v_mfma_f32_16x16x32_bf16 v[0:3], v[0:3], v[198:201], v[36:39]
	v_mfma_f32_16x16x32_bf16 v[44:47], v[24:27], v[194:197], v[32:35]
	v_mfma_f32_16x16x32_bf16 v[32:35], v[8:11], v[238:241], v[0:3]
	v_mfma_f32_16x16x32_bf16 v[0:3], v[16:19], v[198:201], v[128:131]
	v_mfma_f32_16x16x32_bf16 v[36:39], v[24:27], v[238:241], v[0:3]
	s_setprio 0
	v_mfma_f32_16x16x32_bf16 v[0:3], v[158:161], v[166:169], v[28:31]
	v_mfma_f32_16x16x32_bf16 v[24:27], v[202:205], v[170:173], v[0:3]
	v_mfma_f32_16x16x32_bf16 v[0:3], v[206:209], v[166:169], v[132:135]
	v_mfma_f32_16x16x32_bf16 v[28:31], v[222:225], v[170:173], v[0:3]
	v_mfma_f32_16x16x32_bf16 v[0:3], v[158:161], v[174:177], v[20:23]
	v_mfma_f32_16x16x32_bf16 v[16:19], v[202:205], v[178:181], v[0:3]
	v_mfma_f32_16x16x32_bf16 v[0:3], v[206:209], v[174:177], v[154:157]
	v_mfma_f32_16x16x32_bf16 v[20:23], v[222:225], v[178:181], v[0:3]
	v_mfma_f32_16x16x32_bf16 v[0:3], v[158:161], v[186:189], v[12:15]
	v_mfma_f32_16x16x32_bf16 v[8:11], v[202:205], v[194:197], v[0:3]
	v_mfma_f32_16x16x32_bf16 v[0:3], v[206:209], v[186:189], v[162:165]
	v_mfma_f32_16x16x32_bf16 v[12:15], v[222:225], v[194:197], v[0:3]
	v_mfma_f32_16x16x32_bf16 v[0:3], v[158:161], v[198:201], v[4:7]
	v_mfma_f32_16x16x32_bf16 v[4:7], v[206:209], v[198:201], v[182:185]
	v_mfma_f32_16x16x32_bf16 v[0:3], v[202:205], v[238:241], v[0:3]
	v_mfma_f32_16x16x32_bf16 v[4:7], v[222:225], v[238:241], v[4:7]
	s_setprio 0
	s_movk_i32 s0, 0x100
	v_cmp_gt_u32_e32 vcc, s0, v136
	s_barrier
	s_and_saveexec_b64 s[0:1], vcc
	s_cbranch_execz .LBB0_203
	s_barrier

; #define WAIT_L(n) asm volatile("s_waitcnt lgkmcnt(" #n ")" ::: "memory")
; #define BAR __builtin_amdgcn_s_barrier()
; #define SCHED __builtin_amdgcn_sched_barrier(0)
; #define STAGE(P, BASE, br, kt) do { const char* _g = (const char*)((BASE) + (size_t)(br) * GK + (kt) * BK); \
;     __builtin_amdgcn_global_load_lds((const unsigned*)(_g + voff0), (unsigned*)((char*)(P) + tx * 16), 16, 0, 0); \
;     __builtin_amdgcn_global_load_lds((const unsigned*)(_g + voff1), (unsigned*)((char*)(P) + tx * 16 + 8192), 16, 0, 0); } while (0)
; #define LDA(dst, b, h) _Pragma("unroll") for (int m = 0; m < 4; ++m) _Pragma("unroll") for (int k = 0; k < 2; ++k) \
;     dst[m][k] = *reinterpret_cast<const bf16x8*>((char*)shm + abase + (((b) * 2 + (h)) * 16384 + (m * 2 + k) * 1024))
; #define LDB(dst, b, h) _Pragma("unroll") for (int n = 0; n < 2; ++n) _Pragma("unroll") for (int k = 0; k < 2; ++k) \
;     dst[n][k] = *reinterpret_cast<const bf16x8*>((char*)shm + bbase + (((b) * 2 + (h)) * 16384 + (n * 2 + k) * 1024))
; template <bool SWAP>
; __device__ __forceinline__ void gemm_main(const u16* __restrict__ A, const u16* __restrict__ Bt, int brow, int bcol,
;                                           u16* shm, f32x4 (&acc)[2][2][4][2]) {
;     ...
;     LDB(B0, 0, 0); SCHED; LDA(At, 0, 0); STAGE(SA(1, 1), A, brow + HALF, t + 1);
;     WAIT_L(8); BAR; WAIT_L(0); MMA(0, 0, At, B0); BAR; SCHED;
;     LDB(B1, 0, 1); STAGE(SB(0, 0), Bt, bcol, t + 2);
;     BAR; WAIT_L(0); MMA(0, 1, At, B1); BAR;
;     LDA(At, 0, 1); STAGE(SA(0, 0), A, brow, t + 2);
;     BAR; WAIT_L(0); MMA(1, 0, At, B0); BAR; SCHED;
;     STAGE(SB(0, 1), Bt, bcol + HALF, t + 2);
.LBB0_436:
	ds_read_b128 v[170:173], v137 offset:1024
	ds_read_b128 v[178:181], v137 offset:3072
	ds_read_b128 v[186:189], v137 offset:5120
	ds_read_b128 v[198:201], v137 offset:7168
	v_add_u32_e32 v192, 0, v139
	v_add_u32_e32 v148, 0xc000, v192
	v_add_u32_e32 v149, 0xe000, v192
	s_add_u32 m0, s2, 0xc000
	v_lshl_add_u64 v[232:233], s[50:51], 0, v[134:135]
	s_add_u32 vcc_lo, s50, s82
	s_addc_u32 vcc_hi, s51, s83
	global_load_lds_dwordx4 v132, vcc
	s_add_u32 m0, s2, 0xe000
	s_nop 0
	global_load_lds_dwordx4 v134, vcc
	s_waitcnt lgkmcnt(8)
	s_barrier
	s_waitcnt lgkmcnt(0)
	v_mfma_f32_16x16x32_bf16 v[124:127], v[150:153], v[166:169], v[124:127]
	v_mfma_f32_16x16x32_bf16 v[120:123], v[158:161], v[166:169], v[120:123]
	v_mfma_f32_16x16x32_bf16 v[116:119], v[150:153], v[174:177], v[116:119]
	v_mfma_f32_16x16x32_bf16 v[112:115], v[158:161], v[174:177], v[112:115]
	v_mfma_f32_16x16x32_bf16 v[108:111], v[150:153], v[182:185], v[108:111]
	v_mfma_f32_16x16x32_bf16 v[104:107], v[158:161], v[182:185], v[104:107]
	v_mfma_f32_16x16x32_bf16 v[100:103], v[150:153], v[194:197], v[100:103]
	v_mfma_f32_16x16x32_bf16 v[96:99], v[158:161], v[194:197], v[96:99]
	v_mfma_f32_16x16x32_bf16 v[124:127], v[154:157], v[170:173], v[124:127]
	v_mfma_f32_16x16x32_bf16 v[120:123], v[162:165], v[170:173], v[120:123]
	v_mfma_f32_16x16x32_bf16 v[116:119], v[154:157], v[178:181], v[116:119]
	v_mfma_f32_16x16x32_bf16 v[112:115], v[162:165], v[178:181], v[112:115]
	v_mfma_f32_16x16x32_bf16 v[108:111], v[154:157], v[186:189], v[108:111]
	v_mfma_f32_16x16x32_bf16 v[104:107], v[162:165], v[186:189], v[104:107]
	v_mfma_f32_16x16x32_bf16 v[100:103], v[154:157], v[198:201], v[100:103]
	v_mfma_f32_16x16x32_bf16 v[96:99], v[162:165], v[198:201], v[96:99]
	s_barrier
	ds_read_b128 v[202:205], v138 offset:16384
	ds_read_b128 v[206:209], v138 offset:17408
	ds_read_b128 v[224:227], v138 offset:18432
	ds_read_b128 v[228:231], v138 offset:19456
	s_add_u32 m0, s2, s28
	s_nop 0
	s_add_u32 vcc_lo, s50, s74
	s_addc_u32 vcc_hi, s51, s75
	global_load_lds_dwordx4 v128, vcc
	v_lshl_add_u64 v[236:237], s[50:51], 0, v[130:131]
	s_add_u32 m0, s2, s28
	s_add_u32 m0, m0, 0x2000
	s_nop 0
	global_load_lds_dwordx4 v130, vcc
	s_barrier
	s_waitcnt lgkmcnt(0)
	v_mfma_f32_16x16x32_bf16 v[92:95], v[202:205], v[166:169], v[92:95]
	v_mfma_f32_16x16x32_bf16 v[88:91], v[224:227], v[166:169], v[88:91]
	v_mfma_f32_16x16x32_bf16 v[84:87], v[202:205], v[174:177], v[84:87]
	v_mfma_f32_16x16x32_bf16 v[80:83], v[224:227], v[174:177], v[80:83]
	v_mfma_f32_16x16x32_bf16 v[76:79], v[202:205], v[182:185], v[76:79]
	v_mfma_f32_16x16x32_bf16 v[72:75], v[224:227], v[182:185], v[72:75]
	v_mfma_f32_16x16x32_bf16 v[68:71], v[202:205], v[194:197], v[68:71]
	v_mfma_f32_16x16x32_bf16 v[64:67], v[224:227], v[194:197], v[64:67]
	v_mfma_f32_16x16x32_bf16 v[92:95], v[206:209], v[170:173], v[92:95]
	ds_read_b128 v[166:169], v137 offset:16384
	v_mfma_f32_16x16x32_bf16 v[88:91], v[228:231], v[170:173], v[88:91]
	v_mfma_f32_16x16x32_bf16 v[84:87], v[206:209], v[178:181], v[84:87]
	ds_read_b128 v[174:177], v137 offset:18432
	v_mfma_f32_16x16x32_bf16 v[80:83], v[228:231], v[178:181], v[80:83]
	v_mfma_f32_16x16x32_bf16 v[76:79], v[206:209], v[186:189], v[76:79]
	ds_read_b128 v[182:185], v137 offset:20480
	v_mfma_f32_16x16x32_bf16 v[72:75], v[228:231], v[186:189], v[72:75]
	v_mfma_f32_16x16x32_bf16 v[68:71], v[206:209], v[198:201], v[68:71]
	ds_read_b128 v[194:197], v137 offset:22528
	v_mfma_f32_16x16x32_bf16 v[64:67], v[228:231], v[198:201], v[64:67]
	s_barrier
	ds_read_b128 v[170:173], v137 offset:17408
	ds_read_b128 v[178:181], v137 offset:19456
	ds_read_b128 v[186:189], v137 offset:21504
	ds_read_b128 v[198:201], v137 offset:23552
	s_add_u32 m0, s2, 0x0
	s_nop 0
	s_add_u32 vcc_lo, s50, s76
	s_addc_u32 vcc_hi, s51, s77
	global_load_lds_dwordx4 v132, vcc
	s_add_u32 m0, s2, 0x2000
	s_nop 0
	global_load_lds_dwordx4 v134, vcc
	s_waitcnt vmcnt(8)
	s_barrier
	s_waitcnt lgkmcnt(0)
	v_mfma_f32_16x16x32_bf16 v[60:63], v[150:153], v[166:169], v[60:63]
	v_mfma_f32_16x16x32_bf16 v[56:59], v[158:161], v[166:169], v[56:59]
	v_mfma_f32_16x16x32_bf16 v[52:55], v[150:153], v[174:177], v[52:55]
	v_mfma_f32_16x16x32_bf16 v[48:51], v[158:161], v[174:177], v[48:51]
	v_mfma_f32_16x16x32_bf16 v[44:47], v[150:153], v[182:185], v[44:47]
	v_mfma_f32_16x16x32_bf16 v[40:43], v[158:161], v[182:185], v[40:43]
	v_mfma_f32_16x16x32_bf16 v[36:39], v[150:153], v[194:197], v[36:39]
	v_mfma_f32_16x16x32_bf16 v[32:35], v[158:161], v[194:197], v[32:35]
	v_mfma_f32_16x16x32_bf16 v[60:63], v[154:157], v[170:173], v[60:63]
	v_mfma_f32_16x16x32_bf16 v[56:59], v[162:165], v[170:173], v[56:59]
	v_mfma_f32_16x16x32_bf16 v[52:55], v[154:157], v[178:181], v[52:55]
	v_mfma_f32_16x16x32_bf16 v[48:51], v[162:165], v[178:181], v[48:51]
	v_mfma_f32_16x16x32_bf16 v[44:47], v[154:157], v[186:189], v[44:47]
	v_mfma_f32_16x16x32_bf16 v[40:43], v[162:165], v[186:189], v[40:43]
	v_mfma_f32_16x16x32_bf16 v[36:39], v[154:157], v[198:201], v[36:39]
	v_mfma_f32_16x16x32_bf16 v[32:35], v[162:165], v[198:201], v[32:35]
	s_barrier
	ds_read_b128 v[150:153], v138 offset:32768
	ds_read_b128 v[154:157], v138 offset:33792
	ds_read_b128 v[158:161], v138 offset:34816
	ds_read_b128 v[162:165], v138 offset:35840
	s_add_u32 m0, s2, s29
	s_nop 0
	s_add_u32 vcc_lo, s50, s70
	s_addc_u32 vcc_hi, s51, s71
	global_load_lds_dwordx4 v128, vcc
	s_add_u32 m0, s2, s29
	s_add_u32 m0, m0, 0x2000
	s_nop 0
	global_load_lds_dwordx4 v130, vcc
	s_waitcnt vmcnt(6)
	s_barrier
; #define WAIT_V(n) asm volatile("s_waitcnt vmcnt(" #n ")" ::: "memory")
; #define WAIT_L(n) asm volatile("s_waitcnt lgkmcnt(" #n ")" ::: "memory")
; #define BAR __builtin_amdgcn_s_barrier()
; #define SCHED __builtin_amdgcn_sched_barrier(0)
; #define STAGE(P, BASE, br, kt) do { const char* _g = (const char*)((BASE) + (size_t)(br) * GK + (kt) * BK); \
;     __builtin_amdgcn_global_load_lds((const unsigned*)(_g + voff0), (unsigned*)((char*)(P) + tx * 16), 16, 0, 0); \
;     __builtin_amdgcn_global_load_lds((const unsigned*)(_g + voff1), (unsigned*)((char*)(P) + tx * 16 + 8192), 16, 0, 0); } while (0)
; #define LDA(dst, b, h) _Pragma("unroll") for (int m = 0; m < 4; ++m) _Pragma("unroll") for (int k = 0; k < 2; ++k) \
;     dst[m][k] = *reinterpret_cast<const bf16x8*>((char*)shm + abase + (((b) * 2 + (h)) * 16384 + (m * 2 + k) * 1024))
; #define LDB(dst, b, h) _Pragma("unroll") for (int n = 0; n < 2; ++n) _Pragma("unroll") for (int k = 0; k < 2; ++k) \
;     dst[n][k] = *reinterpret_cast<const bf16x8*>((char*)shm + bbase + (((b) * 2 + (h)) * 16384 + (n * 2 + k) * 1024))
; template <bool SWAP>
; __device__ __forceinline__ void gemm_main(const u16* __restrict__ A, const u16* __restrict__ Bt, int brow, int bcol,
;                                           u16* shm, f32x4 (&acc)[2][2][4][2]) {
;     ...
;     WAIT_V(6); BAR; MMA(1, 1, At, B1); BAR;
;     LDB(B0, 1, 0); SCHED; LDA(At, 1, 0); STAGE(SA(0, 1), A, brow + HALF, t + 2);
;     WAIT_L(8); BAR; WAIT_L(0); MMA(0, 0, At, B0); BAR; SCHED;
;     LDB(B1, 1, 1); STAGE(SB(1, 0), Bt, bcol, t + 3);
;     BAR; WAIT_L(0); MMA(0, 1, At, B1); BAR;
;     LDA(At, 1, 1); STAGE(SA(1, 0), A, brow, t + 3);
;     BAR; WAIT_L(0); MMA(1, 0, At, B0); BAR; SCHED;
;     STAGE(SB(1, 1), Bt, bcol + HALF, t + 3);
	v_mfma_f32_16x16x32_bf16 v[28:31], v[202:205], v[166:169], v[28:31]
	v_mfma_f32_16x16x32_bf16 v[24:27], v[224:227], v[166:169], v[24:27]
	v_mfma_f32_16x16x32_bf16 v[20:23], v[202:205], v[174:177], v[20:23]
	v_mfma_f32_16x16x32_bf16 v[16:19], v[224:227], v[174:177], v[16:19]
	v_mfma_f32_16x16x32_bf16 v[12:15], v[202:205], v[182:185], v[12:15]
	v_mfma_f32_16x16x32_bf16 v[8:11], v[224:227], v[182:185], v[8:11]
	v_mfma_f32_16x16x32_bf16 v[4:7], v[202:205], v[194:197], v[4:7]
	v_mfma_f32_16x16x32_bf16 v[0:3], v[224:227], v[194:197], v[0:3]
	v_mfma_f32_16x16x32_bf16 v[28:31], v[206:209], v[170:173], v[28:31]
	ds_read_b128 v[166:169], v137 offset:32768
	v_mfma_f32_16x16x32_bf16 v[24:27], v[228:231], v[170:173], v[24:27]
	v_mfma_f32_16x16x32_bf16 v[20:23], v[206:209], v[178:181], v[20:23]
	ds_read_b128 v[174:177], v137 offset:34816
	v_mfma_f32_16x16x32_bf16 v[16:19], v[228:231], v[178:181], v[16:19]
	v_mfma_f32_16x16x32_bf16 v[12:15], v[206:209], v[186:189], v[12:15]
	ds_read_b128 v[182:185], v137 offset:36864
	v_mfma_f32_16x16x32_bf16 v[8:11], v[228:231], v[186:189], v[8:11]
	v_mfma_f32_16x16x32_bf16 v[4:7], v[206:209], v[198:201], v[4:7]
	ds_read_b128 v[194:197], v137 offset:38912
	v_mfma_f32_16x16x32_bf16 v[0:3], v[228:231], v[198:201], v[0:3]
	s_barrier
	ds_read_b128 v[170:173], v137 offset:33792
	ds_read_b128 v[178:181], v137 offset:35840
	ds_read_b128 v[186:189], v137 offset:37888
	ds_read_b128 v[198:201], v137 offset:39936
	s_add_u32 m0, s2, 0x4000
	s_nop 0
	s_add_u32 vcc_lo, s50, s96
	s_addc_u32 vcc_hi, s51, s97
	global_load_lds_dwordx4 v132, vcc
	s_add_u32 m0, s2, 0x6000
	s_nop 0
	global_load_lds_dwordx4 v134, vcc
	s_waitcnt lgkmcnt(8)
	s_barrier
	s_waitcnt lgkmcnt(0)
	v_mfma_f32_16x16x32_bf16 v[124:127], v[150:153], v[166:169], v[124:127]
	v_mfma_f32_16x16x32_bf16 v[120:123], v[158:161], v[166:169], v[120:123]
	v_mfma_f32_16x16x32_bf16 v[116:119], v[150:153], v[174:177], v[116:119]
	v_mfma_f32_16x16x32_bf16 v[112:115], v[158:161], v[174:177], v[112:115]
	v_mfma_f32_16x16x32_bf16 v[108:111], v[150:153], v[182:185], v[108:111]
	v_mfma_f32_16x16x32_bf16 v[104:107], v[158:161], v[182:185], v[104:107]
	v_mfma_f32_16x16x32_bf16 v[100:103], v[150:153], v[194:197], v[100:103]
	v_mfma_f32_16x16x32_bf16 v[96:99], v[158:161], v[194:197], v[96:99]
	v_mfma_f32_16x16x32_bf16 v[124:127], v[154:157], v[170:173], v[124:127]
	v_mfma_f32_16x16x32_bf16 v[120:123], v[162:165], v[170:173], v[120:123]
	v_mfma_f32_16x16x32_bf16 v[116:119], v[154:157], v[178:181], v[116:119]
	v_mfma_f32_16x16x32_bf16 v[112:115], v[162:165], v[178:181], v[112:115]
	v_mfma_f32_16x16x32_bf16 v[108:111], v[154:157], v[186:189], v[108:111]
	v_mfma_f32_16x16x32_bf16 v[104:107], v[162:165], v[186:189], v[104:107]
	v_mfma_f32_16x16x32_bf16 v[100:103], v[154:157], v[198:201], v[100:103]
	v_mfma_f32_16x16x32_bf16 v[96:99], v[162:165], v[198:201], v[96:99]
	s_barrier
	ds_read_b128 v[202:205], v138 offset:49152
	ds_read_b128 v[206:209], v138 offset:50176
	ds_read_b128 v[224:227], v138 offset:51200
	ds_read_b128 v[228:231], v138 offset:52224
	s_add_u32 m0, s2, s30
	s_nop 0
	s_add_u32 vcc_lo, s50, s34
	s_addc_u32 vcc_hi, s51, s35
	global_load_lds_dwordx4 v128, vcc
	v_lshl_add_u64 v[238:239], v[236:237], 0, s[34:35]
	s_add_u32 m0, s2, s30
	s_add_u32 m0, m0, 0x2000
	s_nop 0
	global_load_lds_dwordx4 v130, vcc
	s_barrier
	s_waitcnt lgkmcnt(0)
	v_mfma_f32_16x16x32_bf16 v[92:95], v[202:205], v[166:169], v[92:95]
	v_mfma_f32_16x16x32_bf16 v[88:91], v[224:227], v[166:169], v[88:91]
	v_mfma_f32_16x16x32_bf16 v[84:87], v[202:205], v[174:177], v[84:87]
	v_mfma_f32_16x16x32_bf16 v[80:83], v[224:227], v[174:177], v[80:83]
	v_mfma_f32_16x16x32_bf16 v[76:79], v[202:205], v[182:185], v[76:79]
	v_mfma_f32_16x16x32_bf16 v[72:75], v[224:227], v[182:185], v[72:75]
	v_mfma_f32_16x16x32_bf16 v[68:71], v[202:205], v[194:197], v[68:71]
	v_mfma_f32_16x16x32_bf16 v[64:67], v[224:227], v[194:197], v[64:67]
	v_mfma_f32_16x16x32_bf16 v[92:95], v[206:209], v[170:173], v[92:95]
	ds_read_b128 v[166:169], v137 offset:49152
	v_mfma_f32_16x16x32_bf16 v[88:91], v[228:231], v[170:173], v[88:91]
	v_mfma_f32_16x16x32_bf16 v[84:87], v[206:209], v[178:181], v[84:87]
	ds_read_b128 v[174:177], v137 offset:51200
	v_mfma_f32_16x16x32_bf16 v[80:83], v[228:231], v[178:181], v[80:83]
	v_mfma_f32_16x16x32_bf16 v[76:79], v[206:209], v[186:189], v[76:79]
	ds_read_b128 v[182:185], v137 offset:53248
	v_mfma_f32_16x16x32_bf16 v[72:75], v[228:231], v[186:189], v[72:75]
	v_mfma_f32_16x16x32_bf16 v[68:71], v[206:209], v[198:201], v[68:71]
	ds_read_b128 v[194:197], v137 offset:55296
	v_mfma_f32_16x16x32_bf16 v[64:67], v[228:231], v[198:201], v[64:67]
	s_barrier
	ds_read_b128 v[170:173], v137 offset:50176
	ds_read_b128 v[178:181], v137 offset:52224
	ds_read_b128 v[186:189], v137 offset:54272
	ds_read_b128 v[198:201], v137 offset:56320
	v_add_u32_e32 v223, 0x8000, v192
	s_add_u32 m0, s2, 0x8000
	s_nop 0
	s_add_u32 vcc_lo, s50, s36
	s_addc_u32 vcc_hi, s51, s37
	global_load_lds_dwordx4 v132, vcc
	v_lshl_add_u64 v[190:191], v[232:233], 0, s[36:37]
	s_add_u32 m0, s2, 0xa000
	s_nop 0
	global_load_lds_dwordx4 v134, vcc
	s_waitcnt vmcnt(8)
	s_barrier
; #define WAIT_V(n) asm volatile("s_waitcnt vmcnt(" #n ")" ::: "memory")
; #define WAIT_L(n) asm volatile("s_waitcnt lgkmcnt(" #n ")" ::: "memory")
; #define BAR __builtin_amdgcn_s_barrier()
; #define SCHED __builtin_amdgcn_sched_barrier(0)
; #define STAGE(P, BASE, br, kt) do { const char* _g = (const char*)((BASE) + (size_t)(br) * GK + (kt) * BK); \
;     __builtin_amdgcn_global_load_lds((const unsigned*)(_g + voff0), (unsigned*)((char*)(P) + tx * 16), 16, 0, 0); \
;     __builtin_amdgcn_global_load_lds((const unsigned*)(_g + voff1), (unsigned*)((char*)(P) + tx * 16 + 8192), 16, 0, 0); } while (0)
; #define LDA(dst, b, h) _Pragma("unroll") for (int m = 0; m < 4; ++m) _Pragma("unroll") for (int k = 0; k < 2; ++k) \
;     dst[m][k] = *reinterpret_cast<const bf16x8*>((char*)shm + abase + (((b) * 2 + (h)) * 16384 + (m * 2 + k) * 1024))
; #define LDB(dst, b, h) _Pragma("unroll") for (int n = 0; n < 2; ++n) _Pragma("unroll") for (int k = 0; k < 2; ++k) \
;     dst[n][k] = *reinterpret_cast<const bf16x8*>((char*)shm + bbase + (((b) * 2 + (h)) * 16384 + (n * 2 + k) * 1024))
; template <bool SWAP>
; __device__ __forceinline__ void gemm_main(const u16* __restrict__ A, const u16* __restrict__ Bt, int brow, int bcol,
;                                           u16* shm, f32x4 (&acc)[2][2][4][2]) {
;     ...
;     LDA(At, 1, 1); STAGE(SA(1, 0), A, brow, t + 3);
;     BAR; WAIT_L(0); MMA(1, 0, At, B0); BAR; SCHED;
;     STAGE(SB(1, 1), Bt, bcol + HALF, t + 3);
;     WAIT_V(6); BAR; MMA(1, 1, At, B1); BAR;
;   }
;   { LDB(B0, 0, 0); LDA(At, 0, 0); STAGE(SA(1, 1), A, brow + HALF, nt - 1);
;     BAR; WAIT_L(0); MMA(0, 0, At, B0); BAR;
;     LDB(B1, 0, 1); BAR; WAIT_L(0); MMA(0, 1, At, B1); BAR;
	s_waitcnt lgkmcnt(0)
	v_mfma_f32_16x16x32_bf16 v[60:63], v[150:153], v[166:169], v[60:63]
	v_mfma_f32_16x16x32_bf16 v[56:59], v[158:161], v[166:169], v[56:59]
	v_mfma_f32_16x16x32_bf16 v[52:55], v[150:153], v[174:177], v[52:55]
	v_mfma_f32_16x16x32_bf16 v[48:51], v[158:161], v[174:177], v[48:51]
	v_mfma_f32_16x16x32_bf16 v[44:47], v[150:153], v[182:185], v[44:47]
	v_mfma_f32_16x16x32_bf16 v[40:43], v[158:161], v[182:185], v[40:43]
	v_mfma_f32_16x16x32_bf16 v[36:39], v[150:153], v[194:197], v[36:39]
	v_mfma_f32_16x16x32_bf16 v[32:35], v[158:161], v[194:197], v[32:35]
	v_mfma_f32_16x16x32_bf16 v[60:63], v[154:157], v[170:173], v[60:63]
	v_mfma_f32_16x16x32_bf16 v[56:59], v[162:165], v[170:173], v[56:59]
	v_mfma_f32_16x16x32_bf16 v[52:55], v[154:157], v[178:181], v[52:55]
	v_mfma_f32_16x16x32_bf16 v[48:51], v[162:165], v[178:181], v[48:51]
	v_mfma_f32_16x16x32_bf16 v[44:47], v[154:157], v[186:189], v[44:47]
	v_mfma_f32_16x16x32_bf16 v[40:43], v[162:165], v[186:189], v[40:43]
	v_mfma_f32_16x16x32_bf16 v[36:39], v[154:157], v[198:201], v[36:39]
	v_mfma_f32_16x16x32_bf16 v[32:35], v[162:165], v[198:201], v[32:35]
	s_barrier
	ds_read_b128 v[150:153], v138
	ds_read_b128 v[154:157], v138 offset:1024
	ds_read_b128 v[158:161], v138 offset:2048
	ds_read_b128 v[162:165], v138 offset:3072
	s_add_u32 m0, s2, s31
	s_nop 0
	s_add_u32 vcc_lo, s50, s64
	s_addc_u32 vcc_hi, s51, s65
	global_load_lds_dwordx4 v128, vcc
	v_lshl_add_u64 v[254:255], v[236:237], 0, s[64:65]
	s_add_u32 m0, s2, s31
	s_add_u32 m0, m0, 0x2000
	s_nop 0
	global_load_lds_dwordx4 v130, vcc
	s_waitcnt vmcnt(6)
	s_barrier
	v_mfma_f32_16x16x32_bf16 v[28:31], v[202:205], v[166:169], v[28:31]
	v_mfma_f32_16x16x32_bf16 v[24:27], v[224:227], v[166:169], v[24:27]
	v_mfma_f32_16x16x32_bf16 v[20:23], v[202:205], v[174:177], v[20:23]
	v_mfma_f32_16x16x32_bf16 v[16:19], v[224:227], v[174:177], v[16:19]
	v_mfma_f32_16x16x32_bf16 v[12:15], v[202:205], v[182:185], v[12:15]
	v_mfma_f32_16x16x32_bf16 v[8:11], v[224:227], v[182:185], v[8:11]
	v_mfma_f32_16x16x32_bf16 v[4:7], v[202:205], v[194:197], v[4:7]
	v_mfma_f32_16x16x32_bf16 v[0:3], v[224:227], v[194:197], v[0:3]
	v_mfma_f32_16x16x32_bf16 v[28:31], v[206:209], v[170:173], v[28:31]
	ds_read_b128 v[166:169], v137
	v_mfma_f32_16x16x32_bf16 v[24:27], v[228:231], v[170:173], v[24:27]
	v_mfma_f32_16x16x32_bf16 v[20:23], v[206:209], v[178:181], v[20:23]
	ds_read_b128 v[174:177], v137 offset:2048
	v_mfma_f32_16x16x32_bf16 v[16:19], v[228:231], v[178:181], v[16:19]
	v_mfma_f32_16x16x32_bf16 v[12:15], v[206:209], v[186:189], v[12:15]
	ds_read_b128 v[182:185], v137 offset:4096
	v_mfma_f32_16x16x32_bf16 v[8:11], v[228:231], v[186:189], v[8:11]
	v_mfma_f32_16x16x32_bf16 v[4:7], v[206:209], v[198:201], v[4:7]
	ds_read_b128 v[194:197], v137 offset:6144
	v_mfma_f32_16x16x32_bf16 v[0:3], v[228:231], v[198:201], v[0:3]
	s_add_i32 s1, s1, 2
	v_lshl_add_u64 v[128:129], v[128:129], 0, s[74:75]
	v_lshl_add_u64 v[130:131], v[130:131], 0, s[74:75]
	v_lshl_add_u64 v[132:133], v[132:133], 0, s[74:75]
	s_cmp_lt_u32 s1, 28
	v_lshl_add_u64 v[134:135], v[134:135], 0, s[74:75]
	s_barrier
	s_cbranch_scc1 .LBB0_436
	v_lshlrev_b32_e32 v128, 3, v142
	v_lshlrev_b32_e32 v129, 5, v142
	v_and_b32_e32 v128, 0xffff0, v128
	v_and_b32_e32 v129, 32, v129
	s_or_b32 s2, s0, 0x80
	v_add_u32_e32 v129, v129, v144
	v_add_lshl_u32 v128, v143, v128, 12
	s_ashr_i32 s3, s2, 31
	v_lshl_add_u32 v192, v129, 1, v128
	v_lshlrev_b32_e32 v128, 3, v145
	v_lshlrev_b32_e32 v129, 5, v145
	s_lshl_b64 s[2:3], s[2:3], 12
	v_and_b32_e32 v128, 0xffff0, v128
	v_and_b32_e32 v129, 32, v129
	s_add_u32 s2, s16, s2
	v_add_u32_e32 v129, v129, v147
	v_add_lshl_u32 v128, v146, v128, 12
	s_addc_u32 s3, s17, s3
	v_lshl_add_u32 v146, v129, 1, v128
	v_mov_b32_e32 v147, v193
	v_lshl_add_u64 v[186:187], s[2:3], 0, v[192:193]
	s_mov_b64 s[8:9], 0xf80
	v_readfirstlane_b32 s1, v148
	v_lshl_add_u64 v[186:187], v[186:187], 0, s[8:9]
	s_mov_b32 m0, s1
	v_lshl_add_u64 v[146:147], s[2:3], 0, v[146:147]
	v_readfirstlane_b32 s1, v149
	ds_read_b128 v[128:131], v138
	ds_read_b128 v[132:135], v138 offset:1024
	ds_read_b128 v[142:145], v138 offset:2048
	ds_read_b128 v[150:153], v138 offset:3072
	ds_read_b128 v[154:157], v137
	ds_read_b128 v[158:161], v137 offset:1024
	ds_read_b128 v[162:165], v137 offset:2048
	ds_read_b128 v[166:169], v137 offset:3072
	ds_read_b128 v[170:173], v137 offset:4096
	ds_read_b128 v[174:177], v137 offset:5120
	ds_read_b128 v[178:181], v137 offset:6144
	ds_read_b128 v[182:185], v137 offset:7168
	global_load_lds_dwordx4 v[186:187], off
	v_lshl_add_u64 v[146:147], v[146:147], 0, s[8:9]
	s_mov_b32 m0, s1
	s_nop 0
	global_load_lds_dwordx4 v[146:147], off
	s_barrier
	s_waitcnt lgkmcnt(0)
	v_mfma_f32_16x16x32_bf16 v[124:127], v[128:131], v[154:157], v[124:127]
	v_mfma_f32_16x16x32_bf16 v[112:115], v[142:145], v[162:165], v[112:115]
	v_mfma_f32_16x16x32_bf16 v[104:107], v[142:145], v[170:173], v[104:107]
	v_mfma_f32_16x16x32_bf16 v[96:99], v[142:145], v[178:181], v[96:99]
	v_mfma_f32_16x16x32_bf16 v[124:127], v[132:135], v[158:161], v[124:127]
	v_mfma_f32_16x16x32_bf16 v[120:123], v[142:145], v[154:157], v[120:123]
	v_mfma_f32_16x16x32_bf16 v[116:119], v[128:131], v[162:165], v[116:119]
	v_mfma_f32_16x16x32_bf16 v[112:115], v[150:153], v[166:169], v[112:115]
	v_mfma_f32_16x16x32_bf16 v[108:111], v[128:131], v[170:173], v[108:111]
	v_mfma_f32_16x16x32_bf16 v[104:107], v[150:153], v[174:177], v[104:107]
	v_mfma_f32_16x16x32_bf16 v[100:103], v[128:131], v[178:181], v[100:103]
	v_mfma_f32_16x16x32_bf16 v[96:99], v[150:153], v[182:185], v[96:99]
	v_mfma_f32_16x16x32_bf16 v[146:149], v[150:153], v[158:161], v[120:123]
	v_mfma_f32_16x16x32_bf16 v[186:189], v[132:135], v[166:169], v[116:119]
	v_mfma_f32_16x16x32_bf16 v[194:197], v[132:135], v[174:177], v[108:111]
	v_mfma_f32_16x16x32_bf16 v[198:201], v[132:135], v[182:185], v[100:103]
	s_setprio 0
	s_barrier
; #define WAIT_V(n) asm volatile("s_waitcnt vmcnt(" #n ")" ::: "memory")
; #define WAIT_L(n) asm volatile("s_waitcnt lgkmcnt(" #n ")" ::: "memory")
; #define BAR __builtin_amdgcn_s_barrier()
; #define LDA(dst, b, h) _Pragma("unroll") for (int m = 0; m < 4; ++m) _Pragma("unroll") for (int k = 0; k < 2; ++k) \
;     dst[m][k] = *reinterpret_cast<const bf16x8*>((char*)shm + abase + (((b) * 2 + (h)) * 16384 + (m * 2 + k) * 1024))
; #define LDB(dst, b, h) _Pragma("unroll") for (int n = 0; n < 2; ++n) _Pragma("unroll") for (int k = 0; k < 2; ++k) \
;     dst[n][k] = *reinterpret_cast<const bf16x8*>((char*)shm + bbase + (((b) * 2 + (h)) * 16384 + (n * 2 + k) * 1024))
; template <bool SWAP>
; __device__ __forceinline__ void gemm_main(const u16* __restrict__ A, const u16* __restrict__ Bt, int brow, int bcol,
;                                           u16* shm, f32x4 (&acc)[2][2][4][2]) {
;     ...
;     LDB(B1, 0, 1); BAR; WAIT_L(0); MMA(0, 1, At, B1); BAR;
;     LDA(At, 0, 1); WAIT_V(4); BAR; WAIT_L(0); MMA(1, 0, At, B0); MMA(1, 1, At, B1); BAR; }
;   { LDB(B0, 1, 0); LDA(At, 1, 0); WAIT_V(2); BAR; WAIT_L(0); MMA(0, 0, At, B0); BAR;
	s_nop 0
	ds_read_b128 v[100:103], v138 offset:16384
	ds_read_b128 v[108:111], v138 offset:17408
	ds_read_b128 v[116:119], v138 offset:18432
	ds_read_b128 v[120:123], v138 offset:19456
	s_barrier
	s_waitcnt lgkmcnt(0)
	v_mfma_f32_16x16x32_bf16 v[88:91], v[116:119], v[154:157], v[88:91]
	v_mfma_f32_16x16x32_bf16 v[80:83], v[116:119], v[162:165], v[80:83]
	v_mfma_f32_16x16x32_bf16 v[72:75], v[116:119], v[170:173], v[72:75]
	v_mfma_f32_16x16x32_bf16 v[64:67], v[116:119], v[178:181], v[64:67]
	v_mfma_f32_16x16x32_bf16 v[92:95], v[100:103], v[154:157], v[92:95]
	v_mfma_f32_16x16x32_bf16 v[88:91], v[120:123], v[158:161], v[88:91]
	v_mfma_f32_16x16x32_bf16 v[84:87], v[100:103], v[162:165], v[84:87]
	v_mfma_f32_16x16x32_bf16 v[80:83], v[120:123], v[166:169], v[80:83]
	v_mfma_f32_16x16x32_bf16 v[76:79], v[100:103], v[170:173], v[76:79]
	v_mfma_f32_16x16x32_bf16 v[72:75], v[120:123], v[174:177], v[72:75]
	v_mfma_f32_16x16x32_bf16 v[68:71], v[100:103], v[178:181], v[68:71]
	v_mfma_f32_16x16x32_bf16 v[64:67], v[120:123], v[182:185], v[64:67]
	v_mfma_f32_16x16x32_bf16 v[202:205], v[108:111], v[158:161], v[92:95]
	v_mfma_f32_16x16x32_bf16 v[154:157], v[108:111], v[166:169], v[84:87]
	v_mfma_f32_16x16x32_bf16 v[158:161], v[108:111], v[174:177], v[76:79]
	v_mfma_f32_16x16x32_bf16 v[162:165], v[108:111], v[182:185], v[68:71]
	s_setprio 0
	s_barrier
	s_nop 0
	ds_read_b128 v[68:71], v137 offset:16384
	ds_read_b128 v[76:79], v137 offset:17408
	ds_read_b128 v[84:87], v137 offset:18432
	ds_read_b128 v[92:95], v137 offset:19456
	ds_read_b128 v[166:169], v137 offset:20480
	ds_read_b128 v[170:173], v137 offset:21504
	ds_read_b128 v[174:177], v137 offset:22528
	ds_read_b128 v[178:181], v137 offset:23552
	s_waitcnt vmcnt(4)
	s_barrier
	s_waitcnt lgkmcnt(0)
	v_mfma_f32_16x16x32_bf16 v[60:63], v[128:131], v[68:71], v[60:63]
	v_mfma_f32_16x16x32_bf16 v[56:59], v[142:145], v[68:71], v[56:59]
	v_mfma_f32_16x16x32_bf16 v[48:51], v[142:145], v[84:87], v[48:51]
	v_mfma_f32_16x16x32_bf16 v[40:43], v[142:145], v[166:169], v[40:43]
	v_mfma_f32_16x16x32_bf16 v[32:35], v[142:145], v[174:177], v[32:35]
	v_mfma_f32_16x16x32_bf16 v[60:63], v[132:135], v[76:79], v[60:63]
	v_mfma_f32_16x16x32_bf16 v[56:59], v[150:153], v[76:79], v[56:59]
	v_mfma_f32_16x16x32_bf16 v[52:55], v[128:131], v[84:87], v[52:55]
	v_mfma_f32_16x16x32_bf16 v[48:51], v[150:153], v[92:95], v[48:51]
	v_mfma_f32_16x16x32_bf16 v[44:47], v[128:131], v[166:169], v[44:47]
	v_mfma_f32_16x16x32_bf16 v[40:43], v[150:153], v[170:173], v[40:43]
	v_mfma_f32_16x16x32_bf16 v[36:39], v[128:131], v[174:177], v[36:39]
	v_mfma_f32_16x16x32_bf16 v[32:35], v[150:153], v[178:181], v[32:35]
	v_mfma_f32_16x16x32_bf16 v[182:185], v[132:135], v[92:95], v[52:55]
	v_mfma_f32_16x16x32_bf16 v[206:209], v[132:135], v[170:173], v[44:47]
	v_mfma_f32_16x16x32_bf16 v[128:131], v[132:135], v[178:181], v[36:39]
	s_setprio 0
	v_mfma_f32_16x16x32_bf16 v[24:27], v[116:119], v[68:71], v[24:27]
	v_mfma_f32_16x16x32_bf16 v[16:19], v[116:119], v[84:87], v[16:19]
	v_mfma_f32_16x16x32_bf16 v[8:11], v[116:119], v[166:169], v[8:11]
	v_mfma_f32_16x16x32_bf16 v[0:3], v[116:119], v[174:177], v[0:3]
	v_mfma_f32_16x16x32_bf16 v[28:31], v[100:103], v[68:71], v[28:31]
	v_mfma_f32_16x16x32_bf16 v[24:27], v[120:123], v[76:79], v[24:27]
	v_mfma_f32_16x16x32_bf16 v[20:23], v[100:103], v[84:87], v[20:23]
	v_mfma_f32_16x16x32_bf16 v[16:19], v[120:123], v[92:95], v[16:19]
	v_mfma_f32_16x16x32_bf16 v[12:15], v[100:103], v[166:169], v[12:15]
	v_mfma_f32_16x16x32_bf16 v[8:11], v[120:123], v[170:173], v[8:11]
	v_mfma_f32_16x16x32_bf16 v[4:7], v[100:103], v[174:177], v[4:7]
	v_mfma_f32_16x16x32_bf16 v[0:3], v[120:123], v[178:181], v[0:3]
	v_mfma_f32_16x16x32_bf16 v[132:135], v[108:111], v[76:79], v[28:31]
	v_mfma_f32_16x16x32_bf16 v[142:145], v[108:111], v[92:95], v[20:23]
	v_mfma_f32_16x16x32_bf16 v[150:153], v[108:111], v[170:173], v[12:15]
	v_mfma_f32_16x16x32_bf16 v[166:169], v[108:111], v[178:181], v[4:7]
	s_setprio 0
	s_barrier
	s_nop 0
	ds_read_b128 v[4:7], v138 offset:32768
	ds_read_b128 v[12:15], v138 offset:33792
	ds_read_b128 v[170:173], v138 offset:34816
	ds_read_b128 v[174:177], v138 offset:35840
	ds_read_b128 v[20:23], v137 offset:32768
	ds_read_b128 v[28:31], v137 offset:33792
	ds_read_b128 v[36:39], v137 offset:34816
	ds_read_b128 v[44:47], v137 offset:35840
	ds_read_b128 v[52:55], v137 offset:36864
	ds_read_b128 v[178:181], v137 offset:37888
	ds_read_b128 v[224:227], v137 offset:38912
	ds_read_b128 v[228:231], v137 offset:39936
	s_waitcnt vmcnt(2)
	s_barrier
; #define WAIT_V(n) asm volatile("s_waitcnt vmcnt(" #n ")" ::: "memory")
; #define WAIT_L(n) asm volatile("s_waitcnt lgkmcnt(" #n ")" ::: "memory")
; #define BAR __builtin_amdgcn_s_barrier()
; #define LDA(dst, b, h) _Pragma("unroll") for (int m = 0; m < 4; ++m) _Pragma("unroll") for (int k = 0; k < 2; ++k) \
;     dst[m][k] = *reinterpret_cast<const bf16x8*>((char*)shm + abase + (((b) * 2 + (h)) * 16384 + (m * 2 + k) * 1024))
; #define LDB(dst, b, h) _Pragma("unroll") for (int n = 0; n < 2; ++n) _Pragma("unroll") for (int k = 0; k < 2; ++k) \
;     dst[n][k] = *reinterpret_cast<const bf16x8*>((char*)shm + bbase + (((b) * 2 + (h)) * 16384 + (n * 2 + k) * 1024))
; template <bool SWAP>
; __device__ __forceinline__ void gemm_main(const u16* __restrict__ A, const u16* __restrict__ Bt, int brow, int bcol,
;                                           u16* shm, f32x4 (&acc)[2][2][4][2]) {
;     ...
;   { LDB(B0, 1, 0); LDA(At, 1, 0); WAIT_V(2); BAR; WAIT_L(0); MMA(0, 0, At, B0); BAR;
;     LDB(B1, 1, 1); WAIT_V(0); BAR; WAIT_L(0); MMA(0, 1, At, B1); BAR;
;     LDA(At, 1, 1); BAR; WAIT_L(0); MMA(1, 0, At, B0); MMA(1, 1, At, B1); BAR; }
;   if (wr == 0) BAR;
	s_waitcnt lgkmcnt(0)
	v_mfma_f32_16x16x32_bf16 v[68:71], v[4:7], v[20:23], v[124:127]
	v_mfma_f32_16x16x32_bf16 v[120:123], v[12:15], v[28:31], v[68:71]
	v_mfma_f32_16x16x32_bf16 v[68:71], v[170:173], v[20:23], v[146:149]
	v_mfma_f32_16x16x32_bf16 v[116:119], v[174:177], v[28:31], v[68:71]
	v_mfma_f32_16x16x32_bf16 v[68:71], v[4:7], v[36:39], v[186:189]
	v_mfma_f32_16x16x32_bf16 v[108:111], v[12:15], v[44:47], v[68:71]
	v_mfma_f32_16x16x32_bf16 v[68:71], v[170:173], v[36:39], v[112:115]
	v_mfma_f32_16x16x32_bf16 v[100:103], v[174:177], v[44:47], v[68:71]
	v_mfma_f32_16x16x32_bf16 v[68:71], v[4:7], v[52:55], v[194:197]
	v_mfma_f32_16x16x32_bf16 v[92:95], v[12:15], v[178:181], v[68:71]
	v_mfma_f32_16x16x32_bf16 v[68:71], v[170:173], v[52:55], v[104:107]
	v_mfma_f32_16x16x32_bf16 v[84:87], v[174:177], v[178:181], v[68:71]
	v_mfma_f32_16x16x32_bf16 v[68:71], v[4:7], v[224:227], v[198:201]
	v_mfma_f32_16x16x32_bf16 v[76:79], v[12:15], v[228:231], v[68:71]
	v_mfma_f32_16x16x32_bf16 v[68:71], v[170:173], v[224:227], v[96:99]
	v_mfma_f32_16x16x32_bf16 v[68:71], v[174:177], v[228:231], v[68:71]
	s_setprio 0
	s_barrier
	ds_read_b128 v[146:149], v138 offset:49152
	ds_read_b128 v[186:189], v138 offset:50176
	ds_read_b128 v[194:197], v138 offset:51200
	ds_read_b128 v[198:201], v138 offset:52224
	s_waitcnt vmcnt(0)
	s_barrier
	s_waitcnt lgkmcnt(0)
	v_mfma_f32_16x16x32_bf16 v[96:99], v[146:149], v[20:23], v[202:205]
	v_mfma_f32_16x16x32_bf16 v[20:23], v[194:197], v[20:23], v[88:91]
	v_mfma_f32_16x16x32_bf16 v[112:115], v[198:201], v[28:31], v[20:23]
	v_mfma_f32_16x16x32_bf16 v[20:23], v[146:149], v[36:39], v[154:157]
	v_mfma_f32_16x16x32_bf16 v[104:107], v[186:189], v[44:47], v[20:23]
	v_mfma_f32_16x16x32_bf16 v[20:23], v[194:197], v[36:39], v[80:83]
	v_mfma_f32_16x16x32_bf16 v[124:127], v[186:189], v[28:31], v[96:99]
	v_mfma_f32_16x16x32_bf16 v[96:99], v[198:201], v[44:47], v[20:23]
	v_mfma_f32_16x16x32_bf16 v[20:23], v[146:149], v[52:55], v[158:161]
	v_mfma_f32_16x16x32_bf16 v[88:91], v[186:189], v[178:181], v[20:23]
	v_mfma_f32_16x16x32_bf16 v[20:23], v[194:197], v[52:55], v[72:75]
	v_mfma_f32_16x16x32_bf16 v[80:83], v[198:201], v[178:181], v[20:23]
	v_mfma_f32_16x16x32_bf16 v[20:23], v[146:149], v[224:227], v[162:165]
	v_mfma_f32_16x16x32_bf16 v[72:75], v[186:189], v[228:231], v[20:23]
	v_mfma_f32_16x16x32_bf16 v[20:23], v[194:197], v[224:227], v[64:67]
	v_mfma_f32_16x16x32_bf16 v[64:67], v[198:201], v[228:231], v[20:23]
	s_setprio 0
	s_barrier
	ds_read_b128 v[154:157], v137 offset:49152
	ds_read_b128 v[158:161], v137 offset:50176
	ds_read_b128 v[162:165], v137 offset:51200
	ds_read_b128 v[178:181], v137 offset:52224
	ds_read_b128 v[202:205], v137 offset:53248
	ds_read_b128 v[224:227], v137 offset:54272
	ds_read_b128 v[228:231], v137 offset:55296
	ds_read_b128 v[232:235], v137 offset:56320
	s_barrier
	s_waitcnt lgkmcnt(0)
	v_mfma_f32_16x16x32_bf16 v[20:23], v[4:7], v[154:157], v[60:63]
	v_mfma_f32_16x16x32_bf16 v[60:63], v[12:15], v[158:161], v[20:23]
	v_mfma_f32_16x16x32_bf16 v[20:23], v[170:173], v[154:157], v[56:59]
	v_mfma_f32_16x16x32_bf16 v[52:55], v[174:177], v[158:161], v[20:23]
	v_mfma_f32_16x16x32_bf16 v[20:23], v[4:7], v[162:165], v[182:185]
	v_mfma_f32_16x16x32_bf16 v[44:47], v[12:15], v[178:181], v[20:23]
	v_mfma_f32_16x16x32_bf16 v[20:23], v[170:173], v[162:165], v[48:51]
	v_mfma_f32_16x16x32_bf16 v[36:39], v[174:177], v[178:181], v[20:23]
	v_mfma_f32_16x16x32_bf16 v[20:23], v[4:7], v[202:205], v[206:209]
	v_mfma_f32_16x16x32_bf16 v[4:7], v[4:7], v[228:231], v[128:131]
	v_mfma_f32_16x16x32_bf16 v[28:31], v[12:15], v[224:227], v[20:23]
	v_mfma_f32_16x16x32_bf16 v[20:23], v[170:173], v[202:205], v[40:43]
	v_mfma_f32_16x16x32_bf16 v[12:15], v[12:15], v[232:235], v[4:7]
	v_mfma_f32_16x16x32_bf16 v[4:7], v[170:173], v[228:231], v[32:35]
	v_mfma_f32_16x16x32_bf16 v[20:23], v[174:177], v[224:227], v[20:23]
	v_mfma_f32_16x16x32_bf16 v[4:7], v[174:177], v[232:235], v[4:7]
	s_setprio 0
	v_mfma_f32_16x16x32_bf16 v[32:35], v[146:149], v[154:157], v[132:135]
	v_mfma_f32_16x16x32_bf16 v[24:27], v[194:197], v[154:157], v[24:27]
	v_mfma_f32_16x16x32_bf16 v[16:19], v[194:197], v[162:165], v[16:19]
	v_mfma_f32_16x16x32_bf16 v[56:59], v[186:189], v[158:161], v[32:35]
	v_mfma_f32_16x16x32_bf16 v[48:51], v[198:201], v[158:161], v[24:27]
	v_mfma_f32_16x16x32_bf16 v[24:27], v[146:149], v[162:165], v[142:145]
	v_mfma_f32_16x16x32_bf16 v[32:35], v[198:201], v[178:181], v[16:19]
	v_mfma_f32_16x16x32_bf16 v[16:19], v[146:149], v[202:205], v[150:153]
	v_mfma_f32_16x16x32_bf16 v[8:11], v[194:197], v[202:205], v[8:11]
	v_mfma_f32_16x16x32_bf16 v[40:43], v[186:189], v[178:181], v[24:27]
	v_mfma_f32_16x16x32_bf16 v[24:27], v[186:189], v[224:227], v[16:19]
	v_mfma_f32_16x16x32_bf16 v[16:19], v[198:201], v[224:227], v[8:11]
	v_mfma_f32_16x16x32_bf16 v[8:11], v[146:149], v[228:231], v[166:169]
	v_mfma_f32_16x16x32_bf16 v[0:3], v[194:197], v[228:231], v[0:3]
	v_mfma_f32_16x16x32_bf16 v[8:11], v[186:189], v[232:235], v[8:11]
	v_mfma_f32_16x16x32_bf16 v[0:3], v[198:201], v[232:235], v[0:3]
	s_setprio 0
	s_movk_i32 s1, 0x100
	v_cmp_gt_u32_e32 vcc, s1, v136
	s_barrier
	s_and_saveexec_b64 s[8:9], vcc
	s_cbranch_execz .LBB0_439
	s_barrier

; #define WAIT_V(n) asm volatile("s_waitcnt vmcnt(" #n ")" ::: "memory")
; #define WAIT_L(n) asm volatile("s_waitcnt lgkmcnt(" #n ")" ::: "memory")
; #define BAR __builtin_amdgcn_s_barrier()
; #define SCHED __builtin_amdgcn_sched_barrier(0)
; #define STAGE(P, BASE, br, kt) do { const char* _g = (const char*)((BASE) + (size_t)(br) * GK + (kt) * BK); \
;     __builtin_amdgcn_global_load_lds((const unsigned*)(_g + voff0), (unsigned*)((char*)(P) + tx * 16), 16, 0, 0); \
;     __builtin_amdgcn_global_load_lds((const unsigned*)(_g + voff1), (unsigned*)((char*)(P) + tx * 16 + 8192), 16, 0, 0); } while (0)
; #define LDA(dst, b, h) _Pragma("unroll") for (int m = 0; m < 4; ++m) _Pragma("unroll") for (int k = 0; k < 2; ++k) \
;     dst[m][k] = *reinterpret_cast<const bf16x8*>((char*)shm + abase + (((b) * 2 + (h)) * 16384 + (m * 2 + k) * 1024))
; #define LDB(dst, b, h) _Pragma("unroll") for (int n = 0; n < 2; ++n) _Pragma("unroll") for (int k = 0; k < 2; ++k) \
;     dst[n][k] = *reinterpret_cast<const bf16x8*>((char*)shm + bbase + (((b) * 2 + (h)) * 16384 + (n * 2 + k) * 1024))
; template <bool SWAP>
; __device__ __forceinline__ void gemm_main(const u16* __restrict__ A, const u16* __restrict__ Bt, int brow, int bcol,
;                                           u16* shm, f32x4 (&acc)[2][2][4][2]) {
;     ...
;     LDB(B0, 0, 0); SCHED; LDA(At, 0, 0); STAGE(SA(1, 1), A, brow + HALF, t + 1);
;     WAIT_L(8); BAR; WAIT_L(0); MMA(0, 0, At, B0); BAR; SCHED;
;     LDB(B1, 0, 1); STAGE(SB(0, 0), Bt, bcol, t + 2);
;     BAR; WAIT_L(0); MMA(0, 1, At, B1); BAR;
;     LDA(At, 0, 1); STAGE(SA(0, 0), A, brow, t + 2);
;     BAR; WAIT_L(0); MMA(1, 0, At, B0); BAR; SCHED;
;     STAGE(SB(0, 1), Bt, bcol + HALF, t + 2);
;     WAIT_V(6); BAR; MMA(1, 1, At, B1); BAR;
.LBB0_564:
	ds_read_b128 v[168:171], v137 offset:1024
	ds_read_b128 v[176:179], v137 offset:3072
	ds_read_b128 v[184:187], v137 offset:5120
	ds_read_b128 v[194:197], v137 offset:7168
	v_add_u32_e32 v192, 0, v141
	v_add_u32_e32 v146, 0xc000, v192
	v_lshl_add_u64 v[230:231], s[0:1], 0, v[132:133]
	v_add_u32_e32 v147, 0xe000, v192
	v_lshl_add_u64 v[198:199], v[230:231], 0, s[8:9]
	s_add_u32 m0, s4, 0xc000
	v_lshl_add_u64 v[232:233], s[0:1], 0, v[134:135]
	global_load_lds_dwordx4 v[198:199], off
	v_lshl_add_u64 v[198:199], v[232:233], 0, s[8:9]
	s_add_u32 m0, s4, 0xe000
	s_nop 0
	global_load_lds_dwordx4 v[198:199], off
	s_waitcnt lgkmcnt(8)
	s_barrier
	s_waitcnt lgkmcnt(0)
	v_mfma_f32_16x16x32_bf16 v[124:127], v[148:151], v[164:167], v[124:127]
	v_mfma_f32_16x16x32_bf16 v[120:123], v[156:159], v[164:167], v[120:123]
	v_mfma_f32_16x16x32_bf16 v[116:119], v[148:151], v[172:175], v[116:119]
	v_mfma_f32_16x16x32_bf16 v[112:115], v[156:159], v[172:175], v[112:115]
	v_mfma_f32_16x16x32_bf16 v[108:111], v[148:151], v[180:183], v[108:111]
	v_mfma_f32_16x16x32_bf16 v[104:107], v[156:159], v[180:183], v[104:107]
	v_mfma_f32_16x16x32_bf16 v[100:103], v[148:151], v[188:191], v[100:103]
	v_mfma_f32_16x16x32_bf16 v[96:99], v[156:159], v[188:191], v[96:99]
	v_mfma_f32_16x16x32_bf16 v[124:127], v[152:155], v[168:171], v[124:127]
	v_mfma_f32_16x16x32_bf16 v[120:123], v[160:163], v[168:171], v[120:123]
	v_mfma_f32_16x16x32_bf16 v[116:119], v[152:155], v[176:179], v[116:119]
	v_mfma_f32_16x16x32_bf16 v[112:115], v[160:163], v[176:179], v[112:115]
	v_mfma_f32_16x16x32_bf16 v[108:111], v[152:155], v[184:187], v[108:111]
	v_mfma_f32_16x16x32_bf16 v[104:107], v[160:163], v[184:187], v[104:107]
	v_mfma_f32_16x16x32_bf16 v[100:103], v[152:155], v[194:197], v[100:103]
	v_mfma_f32_16x16x32_bf16 v[96:99], v[160:163], v[194:197], v[96:99]
	s_barrier
	ds_read_b128 v[198:201], v138 offset:16384
	ds_read_b128 v[202:205], v138 offset:17408
	ds_read_b128 v[206:209], v138 offset:18432
	ds_read_b128 v[226:229], v138 offset:19456
	v_lshl_add_u64 v[234:235], s[0:1], 0, v[128:129]
	v_lshl_add_u64 v[236:237], v[234:235], 0, s[12:13]
	s_add_u32 m0, s4, s28
	s_nop 0
	global_load_lds_dwordx4 v[236:237], off
	v_lshl_add_u64 v[236:237], s[0:1], 0, v[130:131]
	v_lshl_add_u64 v[238:239], v[236:237], 0, s[12:13]
	s_add_u32 m0, s4, s28
	s_add_u32 m0, m0, 0x2000
	s_nop 0
	global_load_lds_dwordx4 v[238:239], off
	s_barrier
	s_waitcnt lgkmcnt(0)
	v_mfma_f32_16x16x32_bf16 v[92:95], v[198:201], v[164:167], v[92:95]
	v_mfma_f32_16x16x32_bf16 v[88:91], v[206:209], v[164:167], v[88:91]
	v_mfma_f32_16x16x32_bf16 v[84:87], v[198:201], v[172:175], v[84:87]
	v_mfma_f32_16x16x32_bf16 v[80:83], v[206:209], v[172:175], v[80:83]
	v_mfma_f32_16x16x32_bf16 v[76:79], v[198:201], v[180:183], v[76:79]
	v_mfma_f32_16x16x32_bf16 v[72:75], v[206:209], v[180:183], v[72:75]
	v_mfma_f32_16x16x32_bf16 v[68:71], v[198:201], v[188:191], v[68:71]
	v_mfma_f32_16x16x32_bf16 v[64:67], v[206:209], v[188:191], v[64:67]
	v_mfma_f32_16x16x32_bf16 v[92:95], v[202:205], v[168:171], v[92:95]
	ds_read_b128 v[164:167], v137 offset:16384
	v_mfma_f32_16x16x32_bf16 v[88:91], v[226:229], v[168:171], v[88:91]
	v_mfma_f32_16x16x32_bf16 v[84:87], v[202:205], v[176:179], v[84:87]
	ds_read_b128 v[172:175], v137 offset:18432
	v_mfma_f32_16x16x32_bf16 v[80:83], v[226:229], v[176:179], v[80:83]
	v_mfma_f32_16x16x32_bf16 v[76:79], v[202:205], v[184:187], v[76:79]
	ds_read_b128 v[180:183], v137 offset:20480
	v_mfma_f32_16x16x32_bf16 v[72:75], v[226:229], v[184:187], v[72:75]
	v_mfma_f32_16x16x32_bf16 v[68:71], v[202:205], v[194:197], v[68:71]
	ds_read_b128 v[188:191], v137 offset:22528
	v_mfma_f32_16x16x32_bf16 v[64:67], v[226:229], v[194:197], v[64:67]
	s_barrier
	ds_read_b128 v[168:171], v137 offset:17408
	ds_read_b128 v[176:179], v137 offset:19456
	ds_read_b128 v[184:187], v137 offset:21504
	ds_read_b128 v[194:197], v137 offset:23552
	v_lshl_add_u64 v[238:239], v[230:231], 0, s[14:15]
	s_add_u32 m0, s4, 0x0
	s_nop 0
	global_load_lds_dwordx4 v[238:239], off
	v_lshl_add_u64 v[238:239], v[232:233], 0, s[14:15]
	s_add_u32 m0, s4, 0x2000
	s_nop 0
	global_load_lds_dwordx4 v[238:239], off
	s_waitcnt vmcnt(8)
	s_barrier
	s_waitcnt lgkmcnt(0)
	v_mfma_f32_16x16x32_bf16 v[60:63], v[148:151], v[164:167], v[60:63]
	v_mfma_f32_16x16x32_bf16 v[56:59], v[156:159], v[164:167], v[56:59]
	v_mfma_f32_16x16x32_bf16 v[52:55], v[148:151], v[172:175], v[52:55]
	v_mfma_f32_16x16x32_bf16 v[48:51], v[156:159], v[172:175], v[48:51]
	v_mfma_f32_16x16x32_bf16 v[44:47], v[148:151], v[180:183], v[44:47]
	v_mfma_f32_16x16x32_bf16 v[40:43], v[156:159], v[180:183], v[40:43]
	v_mfma_f32_16x16x32_bf16 v[36:39], v[148:151], v[188:191], v[36:39]
	v_mfma_f32_16x16x32_bf16 v[32:35], v[156:159], v[188:191], v[32:35]
	v_mfma_f32_16x16x32_bf16 v[60:63], v[152:155], v[168:171], v[60:63]
	v_mfma_f32_16x16x32_bf16 v[56:59], v[160:163], v[168:171], v[56:59]
	v_mfma_f32_16x16x32_bf16 v[52:55], v[152:155], v[176:179], v[52:55]
	v_mfma_f32_16x16x32_bf16 v[48:51], v[160:163], v[176:179], v[48:51]
	v_mfma_f32_16x16x32_bf16 v[44:47], v[152:155], v[184:187], v[44:47]
	v_mfma_f32_16x16x32_bf16 v[40:43], v[160:163], v[184:187], v[40:43]
	v_mfma_f32_16x16x32_bf16 v[36:39], v[152:155], v[194:197], v[36:39]
	v_mfma_f32_16x16x32_bf16 v[32:35], v[160:163], v[194:197], v[32:35]
	s_barrier
	ds_read_b128 v[148:151], v138 offset:32768
	ds_read_b128 v[152:155], v138 offset:33792
	ds_read_b128 v[156:159], v138 offset:34816
	ds_read_b128 v[160:163], v138 offset:35840
	v_lshl_add_u64 v[254:255], v[234:235], 0, s[16:17]
	s_add_u32 m0, s4, s29
	s_nop 0
	global_load_lds_dwordx4 v[254:255], off
	v_lshl_add_u64 v[254:255], v[236:237], 0, s[16:17]
	s_add_u32 m0, s4, s29
	s_add_u32 m0, m0, 0x2000
	s_nop 0
	global_load_lds_dwordx4 v[254:255], off
	s_waitcnt vmcnt(6)
	s_barrier
; #define WAIT_V(n) asm volatile("s_waitcnt vmcnt(" #n ")" ::: "memory")
; #define WAIT_L(n) asm volatile("s_waitcnt lgkmcnt(" #n ")" ::: "memory")
; #define BAR __builtin_amdgcn_s_barrier()
; #define SCHED __builtin_amdgcn_sched_barrier(0)
; #define STAGE(P, BASE, br, kt) do { const char* _g = (const char*)((BASE) + (size_t)(br) * GK + (kt) * BK); \
;     __builtin_amdgcn_global_load_lds((const unsigned*)(_g + voff0), (unsigned*)((char*)(P) + tx * 16), 16, 0, 0); \
;     __builtin_amdgcn_global_load_lds((const unsigned*)(_g + voff1), (unsigned*)((char*)(P) + tx * 16 + 8192), 16, 0, 0); } while (0)
; #define LDA(dst, b, h) _Pragma("unroll") for (int m = 0; m < 4; ++m) _Pragma("unroll") for (int k = 0; k < 2; ++k) \
;     dst[m][k] = *reinterpret_cast<const bf16x8*>((char*)shm + abase + (((b) * 2 + (h)) * 16384 + (m * 2 + k) * 1024))
; #define LDB(dst, b, h) _Pragma("unroll") for (int n = 0; n < 2; ++n) _Pragma("unroll") for (int k = 0; k < 2; ++k) \
;     dst[n][k] = *reinterpret_cast<const bf16x8*>((char*)shm + bbase + (((b) * 2 + (h)) * 16384 + (n * 2 + k) * 1024))
; template <bool SWAP>
; __device__ __forceinline__ void gemm_main(const u16* __restrict__ A, const u16* __restrict__ Bt, int brow, int bcol,
;                                           u16* shm, f32x4 (&acc)[2][2][4][2]) {
;     ...
;     WAIT_V(6); BAR; MMA(1, 1, At, B1); BAR;
;     LDB(B0, 1, 0); SCHED; LDA(At, 1, 0); STAGE(SA(0, 1), A, brow + HALF, t + 2);
;     WAIT_L(8); BAR; WAIT_L(0); MMA(0, 0, At, B0); BAR; SCHED;
;     LDB(B1, 1, 1); STAGE(SB(1, 0), Bt, bcol, t + 3);
;     BAR; WAIT_L(0); MMA(0, 1, At, B1); BAR;
;     LDA(At, 1, 1); STAGE(SA(1, 0), A, brow, t + 3);
	v_mfma_f32_16x16x32_bf16 v[28:31], v[198:201], v[164:167], v[28:31]
	v_mfma_f32_16x16x32_bf16 v[24:27], v[206:209], v[164:167], v[24:27]
	v_mfma_f32_16x16x32_bf16 v[20:23], v[198:201], v[172:175], v[20:23]
	v_mfma_f32_16x16x32_bf16 v[16:19], v[206:209], v[172:175], v[16:19]
	v_mfma_f32_16x16x32_bf16 v[12:15], v[198:201], v[180:183], v[12:15]
	v_mfma_f32_16x16x32_bf16 v[8:11], v[206:209], v[180:183], v[8:11]
	v_mfma_f32_16x16x32_bf16 v[4:7], v[198:201], v[188:191], v[4:7]
	v_mfma_f32_16x16x32_bf16 v[0:3], v[206:209], v[188:191], v[0:3]
	v_mfma_f32_16x16x32_bf16 v[28:31], v[202:205], v[168:171], v[28:31]
	ds_read_b128 v[164:167], v137 offset:32768
	v_mfma_f32_16x16x32_bf16 v[24:27], v[226:229], v[168:171], v[24:27]
	v_mfma_f32_16x16x32_bf16 v[20:23], v[202:205], v[176:179], v[20:23]
	ds_read_b128 v[172:175], v137 offset:34816
	v_mfma_f32_16x16x32_bf16 v[16:19], v[226:229], v[176:179], v[16:19]
	v_mfma_f32_16x16x32_bf16 v[12:15], v[202:205], v[184:187], v[12:15]
	ds_read_b128 v[180:183], v137 offset:36864
	v_mfma_f32_16x16x32_bf16 v[8:11], v[226:229], v[184:187], v[8:11]
	v_mfma_f32_16x16x32_bf16 v[4:7], v[202:205], v[194:197], v[4:7]
	ds_read_b128 v[188:191], v137 offset:38912
	v_mfma_f32_16x16x32_bf16 v[0:3], v[226:229], v[194:197], v[0:3]
	s_barrier
	ds_read_b128 v[168:171], v137 offset:33792
	ds_read_b128 v[176:179], v137 offset:35840
	ds_read_b128 v[184:187], v137 offset:37888
	ds_read_b128 v[194:197], v137 offset:39936
	v_lshl_add_u64 v[198:199], v[230:231], 0, s[18:19]
	s_add_u32 m0, s4, 0x4000
	s_nop 0
	global_load_lds_dwordx4 v[198:199], off
	v_lshl_add_u64 v[198:199], v[232:233], 0, s[18:19]
	s_add_u32 m0, s4, 0x6000
	s_nop 0
	global_load_lds_dwordx4 v[198:199], off
	s_waitcnt lgkmcnt(8)
	s_barrier
	s_waitcnt lgkmcnt(0)
	v_mfma_f32_16x16x32_bf16 v[124:127], v[148:151], v[164:167], v[124:127]
	v_mfma_f32_16x16x32_bf16 v[120:123], v[156:159], v[164:167], v[120:123]
	v_mfma_f32_16x16x32_bf16 v[116:119], v[148:151], v[172:175], v[116:119]
	v_mfma_f32_16x16x32_bf16 v[112:115], v[156:159], v[172:175], v[112:115]
	v_mfma_f32_16x16x32_bf16 v[108:111], v[148:151], v[180:183], v[108:111]
	v_mfma_f32_16x16x32_bf16 v[104:107], v[156:159], v[180:183], v[104:107]
	v_mfma_f32_16x16x32_bf16 v[100:103], v[148:151], v[188:191], v[100:103]
	v_mfma_f32_16x16x32_bf16 v[96:99], v[156:159], v[188:191], v[96:99]
	v_mfma_f32_16x16x32_bf16 v[124:127], v[152:155], v[168:171], v[124:127]
	v_mfma_f32_16x16x32_bf16 v[120:123], v[160:163], v[168:171], v[120:123]
	v_mfma_f32_16x16x32_bf16 v[116:119], v[152:155], v[176:179], v[116:119]
	v_mfma_f32_16x16x32_bf16 v[112:115], v[160:163], v[176:179], v[112:115]
	v_mfma_f32_16x16x32_bf16 v[108:111], v[152:155], v[184:187], v[108:111]
	v_mfma_f32_16x16x32_bf16 v[104:107], v[160:163], v[184:187], v[104:107]
	v_mfma_f32_16x16x32_bf16 v[100:103], v[152:155], v[194:197], v[100:103]
	v_mfma_f32_16x16x32_bf16 v[96:99], v[160:163], v[194:197], v[96:99]
	s_barrier
	ds_read_b128 v[198:201], v138 offset:49152
	ds_read_b128 v[202:205], v138 offset:50176
	ds_read_b128 v[206:209], v138 offset:51200
	ds_read_b128 v[226:229], v138 offset:52224
	v_lshl_add_u64 v[238:239], v[234:235], 0, s[24:25]
	s_add_u32 m0, s4, s30
	s_nop 0
	global_load_lds_dwordx4 v[238:239], off
	v_lshl_add_u64 v[238:239], v[236:237], 0, s[24:25]
	s_add_u32 m0, s4, s30
	s_add_u32 m0, m0, 0x2000
	s_nop 0
	global_load_lds_dwordx4 v[238:239], off
	s_barrier
	s_waitcnt lgkmcnt(0)
	v_mfma_f32_16x16x32_bf16 v[92:95], v[198:201], v[164:167], v[92:95]
	v_mfma_f32_16x16x32_bf16 v[88:91], v[206:209], v[164:167], v[88:91]
	v_mfma_f32_16x16x32_bf16 v[84:87], v[198:201], v[172:175], v[84:87]
	v_mfma_f32_16x16x32_bf16 v[80:83], v[206:209], v[172:175], v[80:83]
	v_mfma_f32_16x16x32_bf16 v[76:79], v[198:201], v[180:183], v[76:79]
	v_mfma_f32_16x16x32_bf16 v[72:75], v[206:209], v[180:183], v[72:75]
	v_mfma_f32_16x16x32_bf16 v[68:71], v[198:201], v[188:191], v[68:71]
	v_mfma_f32_16x16x32_bf16 v[64:67], v[206:209], v[188:191], v[64:67]
	v_mfma_f32_16x16x32_bf16 v[92:95], v[202:205], v[168:171], v[92:95]
	ds_read_b128 v[164:167], v137 offset:49152
	v_mfma_f32_16x16x32_bf16 v[88:91], v[226:229], v[168:171], v[88:91]
	v_mfma_f32_16x16x32_bf16 v[84:87], v[202:205], v[176:179], v[84:87]
	ds_read_b128 v[172:175], v137 offset:51200
	v_mfma_f32_16x16x32_bf16 v[80:83], v[226:229], v[176:179], v[80:83]
	v_mfma_f32_16x16x32_bf16 v[76:79], v[202:205], v[184:187], v[76:79]
	ds_read_b128 v[180:183], v137 offset:53248
	v_mfma_f32_16x16x32_bf16 v[72:75], v[226:229], v[184:187], v[72:75]
	v_mfma_f32_16x16x32_bf16 v[68:71], v[202:205], v[194:197], v[68:71]
	ds_read_b128 v[188:191], v137 offset:55296
	v_mfma_f32_16x16x32_bf16 v[64:67], v[226:229], v[194:197], v[64:67]
	s_barrier
	ds_read_b128 v[168:171], v137 offset:50176
	ds_read_b128 v[176:179], v137 offset:52224
	ds_read_b128 v[184:187], v137 offset:54272
	ds_read_b128 v[194:197], v137 offset:56320
	v_add_u32_e32 v225, 0x8000, v192
	v_lshl_add_u64 v[230:231], v[230:231], 0, vcc
	s_add_u32 m0, s4, 0x8000
	s_nop 0
	global_load_lds_dwordx4 v[230:231], off
	v_lshl_add_u64 v[230:231], v[232:233], 0, vcc
	s_add_u32 m0, s4, 0xa000
	s_nop 0
	global_load_lds_dwordx4 v[230:231], off
	s_waitcnt vmcnt(8)
	s_barrier
; #define WAIT_V(n) asm volatile("s_waitcnt vmcnt(" #n ")" ::: "memory")
; #define WAIT_L(n) asm volatile("s_waitcnt lgkmcnt(" #n ")" ::: "memory")
; #define BAR __builtin_amdgcn_s_barrier()
; #define SCHED __builtin_amdgcn_sched_barrier(0)
; #define STAGE(P, BASE, br, kt) do { const char* _g = (const char*)((BASE) + (size_t)(br) * GK + (kt) * BK); \
;     __builtin_amdgcn_global_load_lds((const unsigned*)(_g + voff0), (unsigned*)((char*)(P) + tx * 16), 16, 0, 0); \
;     __builtin_amdgcn_global_load_lds((const unsigned*)(_g + voff1), (unsigned*)((char*)(P) + tx * 16 + 8192), 16, 0, 0); } while (0)
; #define LDA(dst, b, h) _Pragma("unroll") for (int m = 0; m < 4; ++m) _Pragma("unroll") for (int k = 0; k < 2; ++k) \
;     dst[m][k] = *reinterpret_cast<const bf16x8*>((char*)shm + abase + (((b) * 2 + (h)) * 16384 + (m * 2 + k) * 1024))
; #define LDB(dst, b, h) _Pragma("unroll") for (int n = 0; n < 2; ++n) _Pragma("unroll") for (int k = 0; k < 2; ++k) \
;     dst[n][k] = *reinterpret_cast<const bf16x8*>((char*)shm + bbase + (((b) * 2 + (h)) * 16384 + (n * 2 + k) * 1024))
; template <bool SWAP>
; __device__ __forceinline__ void gemm_main(const u16* __restrict__ A, const u16* __restrict__ Bt, int brow, int bcol,
;                                           u16* shm, f32x4 (&acc)[2][2][4][2]) {
;     ...
;     BAR; WAIT_L(0); MMA(1, 0, At, B0); BAR; SCHED;
;     STAGE(SB(1, 1), Bt, bcol + HALF, t + 3);
;     WAIT_V(6); BAR; MMA(1, 1, At, B1); BAR;
;   }
;   { LDB(B0, 0, 0); LDA(At, 0, 0); STAGE(SA(1, 1), A, brow + HALF, nt - 1);
;     BAR; WAIT_L(0); MMA(0, 0, At, B0); BAR;
	s_waitcnt lgkmcnt(0)
	v_mfma_f32_16x16x32_bf16 v[60:63], v[148:151], v[164:167], v[60:63]
	v_mfma_f32_16x16x32_bf16 v[56:59], v[156:159], v[164:167], v[56:59]
	v_mfma_f32_16x16x32_bf16 v[52:55], v[148:151], v[172:175], v[52:55]
	v_mfma_f32_16x16x32_bf16 v[48:51], v[156:159], v[172:175], v[48:51]
	v_mfma_f32_16x16x32_bf16 v[44:47], v[148:151], v[180:183], v[44:47]
	v_mfma_f32_16x16x32_bf16 v[40:43], v[156:159], v[180:183], v[40:43]
	v_mfma_f32_16x16x32_bf16 v[36:39], v[148:151], v[188:191], v[36:39]
	v_mfma_f32_16x16x32_bf16 v[32:35], v[156:159], v[188:191], v[32:35]
	v_mfma_f32_16x16x32_bf16 v[60:63], v[152:155], v[168:171], v[60:63]
	v_mfma_f32_16x16x32_bf16 v[56:59], v[160:163], v[168:171], v[56:59]
	v_mfma_f32_16x16x32_bf16 v[52:55], v[152:155], v[176:179], v[52:55]
	v_mfma_f32_16x16x32_bf16 v[48:51], v[160:163], v[176:179], v[48:51]
	v_mfma_f32_16x16x32_bf16 v[44:47], v[152:155], v[184:187], v[44:47]
	v_mfma_f32_16x16x32_bf16 v[40:43], v[160:163], v[184:187], v[40:43]
	v_mfma_f32_16x16x32_bf16 v[36:39], v[152:155], v[194:197], v[36:39]
	v_mfma_f32_16x16x32_bf16 v[32:35], v[160:163], v[194:197], v[32:35]
	s_barrier
	ds_read_b128 v[148:151], v138
	ds_read_b128 v[152:155], v138 offset:1024
	ds_read_b128 v[156:159], v138 offset:2048
	ds_read_b128 v[160:163], v138 offset:3072
	v_lshl_add_u64 v[254:255], v[234:235], 0, s[42:43]
	s_add_u32 m0, s4, s31
	s_nop 0
	global_load_lds_dwordx4 v[254:255], off
	v_lshl_add_u64 v[254:255], v[236:237], 0, s[42:43]
	s_add_u32 m0, s4, s31
	s_add_u32 m0, m0, 0x2000
	s_nop 0
	global_load_lds_dwordx4 v[254:255], off
	s_waitcnt vmcnt(6)
	s_barrier
	v_mfma_f32_16x16x32_bf16 v[28:31], v[198:201], v[164:167], v[28:31]
	v_mfma_f32_16x16x32_bf16 v[24:27], v[206:209], v[164:167], v[24:27]
	v_mfma_f32_16x16x32_bf16 v[20:23], v[198:201], v[172:175], v[20:23]
	v_mfma_f32_16x16x32_bf16 v[16:19], v[206:209], v[172:175], v[16:19]
	v_mfma_f32_16x16x32_bf16 v[12:15], v[198:201], v[180:183], v[12:15]
	v_mfma_f32_16x16x32_bf16 v[8:11], v[206:209], v[180:183], v[8:11]
	v_mfma_f32_16x16x32_bf16 v[4:7], v[198:201], v[188:191], v[4:7]
	v_mfma_f32_16x16x32_bf16 v[0:3], v[206:209], v[188:191], v[0:3]
	v_mfma_f32_16x16x32_bf16 v[28:31], v[202:205], v[168:171], v[28:31]
	ds_read_b128 v[164:167], v137
	v_mfma_f32_16x16x32_bf16 v[24:27], v[226:229], v[168:171], v[24:27]
	v_mfma_f32_16x16x32_bf16 v[20:23], v[202:205], v[176:179], v[20:23]
	ds_read_b128 v[172:175], v137 offset:2048
	v_mfma_f32_16x16x32_bf16 v[16:19], v[226:229], v[176:179], v[16:19]
	v_mfma_f32_16x16x32_bf16 v[12:15], v[202:205], v[184:187], v[12:15]
	ds_read_b128 v[180:183], v137 offset:4096
	v_mfma_f32_16x16x32_bf16 v[8:11], v[226:229], v[184:187], v[8:11]
	v_mfma_f32_16x16x32_bf16 v[4:7], v[202:205], v[194:197], v[4:7]
	ds_read_b128 v[188:191], v137 offset:6144
	v_mfma_f32_16x16x32_bf16 v[0:3], v[226:229], v[194:197], v[0:3]
	s_add_i32 s3, s3, 2
	s_add_u32 s0, s0, 0x100
	s_addc_u32 s1, s1, 0
	s_cmp_lt_u32 s3, 28
	s_barrier
	s_cbranch_scc1 .LBB0_564
	s_and_b32 s0, s2, 0xffffe0
	s_and_b32 s1, s54, 31
	s_or_b32 s0, s0, s1
	s_lshl_b32 s8, s0, 8
	v_lshlrev_b32_e32 v128, 3, v139
	v_lshlrev_b32_e32 v129, 5, v139
	v_and_b32_e32 v128, 0xffff0, v128
	v_and_b32_e32 v129, 32, v129
	s_or_b32 s0, s8, 0x80
	v_add_u32_e32 v129, v129, v142
	v_add_lshl_u32 v128, v140, v128, 12
	s_ashr_i32 s1, s0, 31
	v_lshl_add_u32 v192, v129, 1, v128
	v_lshlrev_b32_e32 v128, 3, v143
	v_lshlrev_b32_e32 v129, 5, v143
	s_lshl_b64 s[12:13], s[0:1], 12
	v_readlane_b32 s0, v251, 36
	v_and_b32_e32 v128, 0xffff0, v128
	v_and_b32_e32 v129, 32, v129
	v_readlane_b32 s1, v251, 37
	s_add_u32 s0, s0, s12
	v_add_u32_e32 v129, v129, v145
	v_add_lshl_u32 v128, v144, v128, 12
	s_addc_u32 s1, s1, s13
	v_lshl_add_u32 v144, v129, 1, v128
	v_mov_b32_e32 v145, v193
	v_lshl_add_u64 v[184:185], s[0:1], 0, v[192:193]
	s_mov_b64 s[4:5], 0xf80
	v_readfirstlane_b32 s2, v146
	v_lshl_add_u64 v[184:185], v[184:185], 0, s[4:5]
	s_mov_b32 m0, s2
	v_lshl_add_u64 v[144:145], s[0:1], 0, v[144:145]
	v_readfirstlane_b32 s0, v147
	ds_read_b128 v[128:131], v138
	ds_read_b128 v[132:135], v138 offset:1024
	ds_read_b128 v[140:143], v138 offset:2048
	ds_read_b128 v[148:151], v138 offset:3072
	ds_read_b128 v[152:155], v137
	ds_read_b128 v[156:159], v137 offset:1024
	ds_read_b128 v[160:163], v137 offset:2048
	ds_read_b128 v[164:167], v137 offset:3072
	ds_read_b128 v[168:171], v137 offset:4096
	ds_read_b128 v[172:175], v137 offset:5120
	ds_read_b128 v[176:179], v137 offset:6144
	ds_read_b128 v[180:183], v137 offset:7168
	global_load_lds_dwordx4 v[184:185], off
	v_lshl_add_u64 v[144:145], v[144:145], 0, s[4:5]
	s_mov_b32 m0, s0
	s_nop 0
	global_load_lds_dwordx4 v[144:145], off
	s_barrier
	s_waitcnt lgkmcnt(0)
	v_mfma_f32_16x16x32_bf16 v[124:127], v[128:131], v[152:155], v[124:127]
	v_mfma_f32_16x16x32_bf16 v[116:119], v[128:131], v[160:163], v[116:119]
	v_mfma_f32_16x16x32_bf16 v[112:115], v[140:143], v[160:163], v[112:115]
	v_mfma_f32_16x16x32_bf16 v[108:111], v[128:131], v[168:171], v[108:111]
	v_mfma_f32_16x16x32_bf16 v[104:107], v[140:143], v[168:171], v[104:107]
	v_mfma_f32_16x16x32_bf16 v[100:103], v[128:131], v[176:179], v[100:103]
	v_mfma_f32_16x16x32_bf16 v[96:99], v[140:143], v[176:179], v[96:99]
	v_mfma_f32_16x16x32_bf16 v[124:127], v[132:135], v[156:159], v[124:127]
	v_mfma_f32_16x16x32_bf16 v[120:123], v[140:143], v[152:155], v[120:123]
	v_mfma_f32_16x16x32_bf16 v[116:119], v[132:135], v[164:167], v[116:119]
	v_mfma_f32_16x16x32_bf16 v[112:115], v[148:151], v[164:167], v[112:115]
	v_mfma_f32_16x16x32_bf16 v[108:111], v[132:135], v[172:175], v[108:111]
	v_mfma_f32_16x16x32_bf16 v[104:107], v[148:151], v[172:175], v[104:107]
	v_mfma_f32_16x16x32_bf16 v[100:103], v[132:135], v[180:183], v[100:103]
	v_mfma_f32_16x16x32_bf16 v[96:99], v[148:151], v[180:183], v[96:99]
	v_mfma_f32_16x16x32_bf16 v[120:123], v[148:151], v[156:159], v[120:123]
	s_setprio 0
	s_barrier
; #define WAIT_V(n) asm volatile("s_waitcnt vmcnt(" #n ")" ::: "memory")
; #define WAIT_L(n) asm volatile("s_waitcnt lgkmcnt(" #n ")" ::: "memory")
; #define BAR __builtin_amdgcn_s_barrier()
; #define LDA(dst, b, h) _Pragma("unroll") for (int m = 0; m < 4; ++m) _Pragma("unroll") for (int k = 0; k < 2; ++k) \
;     dst[m][k] = *reinterpret_cast<const bf16x8*>((char*)shm + abase + (((b) * 2 + (h)) * 16384 + (m * 2 + k) * 1024))
; #define LDB(dst, b, h) _Pragma("unroll") for (int n = 0; n < 2; ++n) _Pragma("unroll") for (int k = 0; k < 2; ++k) \
;     dst[n][k] = *reinterpret_cast<const bf16x8*>((char*)shm + bbase + (((b) * 2 + (h)) * 16384 + (n * 2 + k) * 1024))
; template <bool SWAP>
; __device__ __forceinline__ void gemm_main(const u16* __restrict__ A, const u16* __restrict__ Bt, int brow, int bcol,
;                                           u16* shm, f32x4 (&acc)[2][2][4][2]) {
;     ...
;     BAR; WAIT_L(0); MMA(0, 0, At, B0); BAR;
;     LDB(B1, 0, 1); BAR; WAIT_L(0); MMA(0, 1, At, B1); BAR;
;     LDA(At, 0, 1); WAIT_V(4); BAR; WAIT_L(0); MMA(1, 0, At, B0); MMA(1, 1, At, B1); BAR; }
;   { LDB(B0, 1, 0); LDA(At, 1, 0); WAIT_V(2); BAR; WAIT_L(0); MMA(0, 0, At, B0); BAR;
	ds_read_b128 v[144:147], v138 offset:16384
	ds_read_b128 v[184:187], v138 offset:17408
	ds_read_b128 v[188:191], v138 offset:18432
	ds_read_b128 v[194:197], v138 offset:19456
	s_barrier
	s_waitcnt lgkmcnt(0)
	v_mfma_f32_16x16x32_bf16 v[92:95], v[144:147], v[152:155], v[92:95]
	v_mfma_f32_16x16x32_bf16 v[88:91], v[188:191], v[152:155], v[88:91]
	v_mfma_f32_16x16x32_bf16 v[84:87], v[144:147], v[160:163], v[84:87]
	v_mfma_f32_16x16x32_bf16 v[80:83], v[188:191], v[160:163], v[80:83]
	v_mfma_f32_16x16x32_bf16 v[76:79], v[144:147], v[168:171], v[76:79]
	v_mfma_f32_16x16x32_bf16 v[72:75], v[188:191], v[168:171], v[72:75]
	v_mfma_f32_16x16x32_bf16 v[68:71], v[144:147], v[176:179], v[68:71]
	v_mfma_f32_16x16x32_bf16 v[64:67], v[188:191], v[176:179], v[64:67]
	v_mfma_f32_16x16x32_bf16 v[92:95], v[184:187], v[156:159], v[92:95]
	v_mfma_f32_16x16x32_bf16 v[88:91], v[194:197], v[156:159], v[88:91]
	v_mfma_f32_16x16x32_bf16 v[84:87], v[184:187], v[164:167], v[84:87]
	v_mfma_f32_16x16x32_bf16 v[80:83], v[194:197], v[164:167], v[80:83]
	v_mfma_f32_16x16x32_bf16 v[76:79], v[184:187], v[172:175], v[76:79]
	v_mfma_f32_16x16x32_bf16 v[72:75], v[194:197], v[172:175], v[72:75]
	v_mfma_f32_16x16x32_bf16 v[68:71], v[184:187], v[180:183], v[68:71]
	v_mfma_f32_16x16x32_bf16 v[64:67], v[194:197], v[180:183], v[64:67]
	s_setprio 0
	s_barrier
	ds_read_b128 v[152:155], v137 offset:16384
	ds_read_b128 v[156:159], v137 offset:17408
	ds_read_b128 v[160:163], v137 offset:18432
	ds_read_b128 v[164:167], v137 offset:19456
	ds_read_b128 v[168:171], v137 offset:20480
	ds_read_b128 v[172:175], v137 offset:21504
	ds_read_b128 v[176:179], v137 offset:22528
	ds_read_b128 v[180:183], v137 offset:23552
	s_waitcnt vmcnt(4)
	s_barrier
	s_waitcnt lgkmcnt(0)
	v_mfma_f32_16x16x32_bf16 v[60:63], v[128:131], v[152:155], v[60:63]
	v_mfma_f32_16x16x32_bf16 v[56:59], v[140:143], v[152:155], v[56:59]
	v_mfma_f32_16x16x32_bf16 v[52:55], v[128:131], v[160:163], v[52:55]
	v_mfma_f32_16x16x32_bf16 v[48:51], v[140:143], v[160:163], v[48:51]
	v_mfma_f32_16x16x32_bf16 v[44:47], v[128:131], v[168:171], v[44:47]
	v_mfma_f32_16x16x32_bf16 v[40:43], v[140:143], v[168:171], v[40:43]
	v_mfma_f32_16x16x32_bf16 v[36:39], v[128:131], v[176:179], v[36:39]
	v_mfma_f32_16x16x32_bf16 v[32:35], v[140:143], v[176:179], v[32:35]
	v_mfma_f32_16x16x32_bf16 v[60:63], v[132:135], v[156:159], v[60:63]
	v_mfma_f32_16x16x32_bf16 v[56:59], v[148:151], v[156:159], v[56:59]
	v_mfma_f32_16x16x32_bf16 v[52:55], v[132:135], v[164:167], v[52:55]
	v_mfma_f32_16x16x32_bf16 v[48:51], v[148:151], v[164:167], v[48:51]
	v_mfma_f32_16x16x32_bf16 v[44:47], v[132:135], v[172:175], v[44:47]
	v_mfma_f32_16x16x32_bf16 v[40:43], v[148:151], v[172:175], v[40:43]
	v_mfma_f32_16x16x32_bf16 v[36:39], v[132:135], v[180:183], v[36:39]
	v_mfma_f32_16x16x32_bf16 v[32:35], v[148:151], v[180:183], v[32:35]
	s_setprio 0
	v_mfma_f32_16x16x32_bf16 v[28:31], v[144:147], v[152:155], v[28:31]
	v_mfma_f32_16x16x32_bf16 v[24:27], v[188:191], v[152:155], v[24:27]
	v_mfma_f32_16x16x32_bf16 v[20:23], v[144:147], v[160:163], v[20:23]
	v_mfma_f32_16x16x32_bf16 v[16:19], v[188:191], v[160:163], v[16:19]
	v_mfma_f32_16x16x32_bf16 v[12:15], v[144:147], v[168:171], v[12:15]
	v_mfma_f32_16x16x32_bf16 v[8:11], v[188:191], v[168:171], v[8:11]
	v_mfma_f32_16x16x32_bf16 v[4:7], v[144:147], v[176:179], v[4:7]
	v_mfma_f32_16x16x32_bf16 v[0:3], v[188:191], v[176:179], v[0:3]
	v_mfma_f32_16x16x32_bf16 v[28:31], v[184:187], v[156:159], v[28:31]
	v_mfma_f32_16x16x32_bf16 v[24:27], v[194:197], v[156:159], v[24:27]
	v_mfma_f32_16x16x32_bf16 v[20:23], v[184:187], v[164:167], v[20:23]
	v_mfma_f32_16x16x32_bf16 v[16:19], v[194:197], v[164:167], v[16:19]
	v_mfma_f32_16x16x32_bf16 v[12:15], v[184:187], v[172:175], v[12:15]
	v_mfma_f32_16x16x32_bf16 v[8:11], v[194:197], v[172:175], v[8:11]
	v_mfma_f32_16x16x32_bf16 v[4:7], v[184:187], v[180:183], v[4:7]
	v_mfma_f32_16x16x32_bf16 v[0:3], v[194:197], v[180:183], v[0:3]
	s_setprio 0
	s_barrier
	ds_read_b128 v[132:135], v138 offset:32768
	ds_read_b128 v[140:143], v138 offset:33792
	ds_read_b128 v[144:147], v138 offset:34816
	ds_read_b128 v[148:151], v138 offset:35840
	ds_read_b128 v[152:155], v137 offset:32768
	ds_read_b128 v[156:159], v137 offset:33792
	ds_read_b128 v[160:163], v137 offset:34816
	ds_read_b128 v[164:167], v137 offset:35840
	ds_read_b128 v[168:171], v137 offset:36864
	ds_read_b128 v[172:175], v137 offset:37888
	ds_read_b128 v[176:179], v137 offset:38912
	ds_read_b128 v[180:183], v137 offset:39936
	s_waitcnt vmcnt(2)
	s_barrier
; #define WAIT_V(n) asm volatile("s_waitcnt vmcnt(" #n ")" ::: "memory")
; #define WAIT_L(n) asm volatile("s_waitcnt lgkmcnt(" #n ")" ::: "memory")
; #define BAR __builtin_amdgcn_s_barrier()
; #define LDA(dst, b, h) _Pragma("unroll") for (int m = 0; m < 4; ++m) _Pragma("unroll") for (int k = 0; k < 2; ++k) \
;     dst[m][k] = *reinterpret_cast<const bf16x8*>((char*)shm + abase + (((b) * 2 + (h)) * 16384 + (m * 2 + k) * 1024))
; #define LDB(dst, b, h) _Pragma("unroll") for (int n = 0; n < 2; ++n) _Pragma("unroll") for (int k = 0; k < 2; ++k) \
;     dst[n][k] = *reinterpret_cast<const bf16x8*>((char*)shm + bbase + (((b) * 2 + (h)) * 16384 + (n * 2 + k) * 1024))
; template <bool SWAP>
; __device__ __forceinline__ void gemm_main(const u16* __restrict__ A, const u16* __restrict__ Bt, int brow, int bcol,
;                                           u16* shm, f32x4 (&acc)[2][2][4][2]) {
;     ...
;   { LDB(B0, 1, 0); LDA(At, 1, 0); WAIT_V(2); BAR; WAIT_L(0); MMA(0, 0, At, B0); BAR;
;     LDB(B1, 1, 1); WAIT_V(0); BAR; WAIT_L(0); MMA(0, 1, At, B1); BAR;
;     LDA(At, 1, 1); BAR; WAIT_L(0); MMA(1, 0, At, B0); MMA(1, 1, At, B1); BAR; }
;   if (wr == 0) BAR;
	s_waitcnt lgkmcnt(0)
	v_mfma_f32_16x16x32_bf16 v[124:127], v[132:135], v[152:155], v[124:127]
	v_mfma_f32_16x16x32_bf16 v[120:123], v[144:147], v[152:155], v[120:123]
	v_mfma_f32_16x16x32_bf16 v[116:119], v[132:135], v[160:163], v[116:119]
	v_mfma_f32_16x16x32_bf16 v[112:115], v[144:147], v[160:163], v[112:115]
	v_mfma_f32_16x16x32_bf16 v[108:111], v[132:135], v[168:171], v[108:111]
	v_mfma_f32_16x16x32_bf16 v[104:107], v[144:147], v[168:171], v[104:107]
	v_mfma_f32_16x16x32_bf16 v[100:103], v[132:135], v[176:179], v[100:103]
	v_mfma_f32_16x16x32_bf16 v[96:99], v[144:147], v[176:179], v[96:99]
	v_mfma_f32_16x16x32_bf16 v[128:131], v[140:143], v[156:159], v[124:127]
	v_mfma_f32_16x16x32_bf16 v[124:127], v[148:151], v[156:159], v[120:123]
	v_mfma_f32_16x16x32_bf16 v[116:119], v[140:143], v[164:167], v[116:119]
	v_mfma_f32_16x16x32_bf16 v[112:115], v[148:151], v[164:167], v[112:115]
	v_mfma_f32_16x16x32_bf16 v[108:111], v[140:143], v[172:175], v[108:111]
	v_mfma_f32_16x16x32_bf16 v[104:107], v[148:151], v[172:175], v[104:107]
	v_mfma_f32_16x16x32_bf16 v[100:103], v[140:143], v[180:183], v[100:103]
	v_mfma_f32_16x16x32_bf16 v[96:99], v[148:151], v[180:183], v[96:99]
	s_setprio 0
	s_barrier
	ds_read_b128 v[120:123], v138 offset:49152
	ds_read_b128 v[184:187], v138 offset:50176
	ds_read_b128 v[188:191], v138 offset:51200
	ds_read_b128 v[194:197], v138 offset:52224
	s_waitcnt vmcnt(0)
	s_barrier
	s_waitcnt lgkmcnt(0)
	v_mfma_f32_16x16x32_bf16 v[92:95], v[120:123], v[152:155], v[92:95]
	v_mfma_f32_16x16x32_bf16 v[88:91], v[188:191], v[152:155], v[88:91]
	v_mfma_f32_16x16x32_bf16 v[84:87], v[120:123], v[160:163], v[84:87]
	v_mfma_f32_16x16x32_bf16 v[80:83], v[188:191], v[160:163], v[80:83]
	v_mfma_f32_16x16x32_bf16 v[76:79], v[120:123], v[168:171], v[76:79]
	v_mfma_f32_16x16x32_bf16 v[72:75], v[188:191], v[168:171], v[72:75]
	v_mfma_f32_16x16x32_bf16 v[68:71], v[120:123], v[176:179], v[68:71]
	v_mfma_f32_16x16x32_bf16 v[64:67], v[188:191], v[176:179], v[64:67]
	v_mfma_f32_16x16x32_bf16 v[92:95], v[184:187], v[156:159], v[92:95]
	v_mfma_f32_16x16x32_bf16 v[88:91], v[194:197], v[156:159], v[88:91]
	v_mfma_f32_16x16x32_bf16 v[84:87], v[184:187], v[164:167], v[84:87]
	v_mfma_f32_16x16x32_bf16 v[80:83], v[194:197], v[164:167], v[80:83]
	v_mfma_f32_16x16x32_bf16 v[76:79], v[184:187], v[172:175], v[76:79]
	v_mfma_f32_16x16x32_bf16 v[72:75], v[194:197], v[172:175], v[72:75]
	v_mfma_f32_16x16x32_bf16 v[68:71], v[184:187], v[180:183], v[68:71]
	v_mfma_f32_16x16x32_bf16 v[64:67], v[194:197], v[180:183], v[64:67]
	s_setprio 0
	s_barrier
	ds_read_b128 v[152:155], v137 offset:49152
	ds_read_b128 v[156:159], v137 offset:50176
	ds_read_b128 v[160:163], v137 offset:51200
	ds_read_b128 v[164:167], v137 offset:52224
	ds_read_b128 v[168:171], v137 offset:53248
	ds_read_b128 v[172:175], v137 offset:54272
	ds_read_b128 v[176:179], v137 offset:55296
	ds_read_b128 v[180:183], v137 offset:56320
	s_barrier
	s_waitcnt lgkmcnt(0)
	v_mfma_f32_16x16x32_bf16 v[60:63], v[132:135], v[152:155], v[60:63]
	v_mfma_f32_16x16x32_bf16 v[56:59], v[144:147], v[152:155], v[56:59]
	v_mfma_f32_16x16x32_bf16 v[52:55], v[132:135], v[160:163], v[52:55]
	v_mfma_f32_16x16x32_bf16 v[48:51], v[144:147], v[160:163], v[48:51]
	v_mfma_f32_16x16x32_bf16 v[44:47], v[132:135], v[168:171], v[44:47]
	v_mfma_f32_16x16x32_bf16 v[40:43], v[144:147], v[168:171], v[40:43]
	v_mfma_f32_16x16x32_bf16 v[36:39], v[132:135], v[176:179], v[36:39]
	v_mfma_f32_16x16x32_bf16 v[32:35], v[144:147], v[176:179], v[32:35]
	v_mfma_f32_16x16x32_bf16 v[60:63], v[140:143], v[156:159], v[60:63]
	v_mfma_f32_16x16x32_bf16 v[56:59], v[148:151], v[156:159], v[56:59]
	v_mfma_f32_16x16x32_bf16 v[52:55], v[140:143], v[164:167], v[52:55]
	v_mfma_f32_16x16x32_bf16 v[48:51], v[148:151], v[164:167], v[48:51]
	v_mfma_f32_16x16x32_bf16 v[44:47], v[140:143], v[172:175], v[44:47]
	v_mfma_f32_16x16x32_bf16 v[40:43], v[148:151], v[172:175], v[40:43]
	v_mfma_f32_16x16x32_bf16 v[36:39], v[140:143], v[180:183], v[36:39]
	v_mfma_f32_16x16x32_bf16 v[32:35], v[148:151], v[180:183], v[32:35]
	s_setprio 0
	v_mfma_f32_16x16x32_bf16 v[28:31], v[120:123], v[152:155], v[28:31]
	v_mfma_f32_16x16x32_bf16 v[24:27], v[188:191], v[152:155], v[24:27]
	v_mfma_f32_16x16x32_bf16 v[20:23], v[120:123], v[160:163], v[20:23]
	v_mfma_f32_16x16x32_bf16 v[16:19], v[188:191], v[160:163], v[16:19]
	v_mfma_f32_16x16x32_bf16 v[12:15], v[120:123], v[168:171], v[12:15]
	v_mfma_f32_16x16x32_bf16 v[8:11], v[188:191], v[168:171], v[8:11]
	v_mfma_f32_16x16x32_bf16 v[4:7], v[120:123], v[176:179], v[4:7]
	v_mfma_f32_16x16x32_bf16 v[0:3], v[188:191], v[176:179], v[0:3]
	v_mfma_f32_16x16x32_bf16 v[28:31], v[184:187], v[156:159], v[28:31]
	v_mfma_f32_16x16x32_bf16 v[24:27], v[194:197], v[156:159], v[24:27]
	v_mfma_f32_16x16x32_bf16 v[20:23], v[184:187], v[164:167], v[20:23]
	v_mfma_f32_16x16x32_bf16 v[16:19], v[194:197], v[164:167], v[16:19]
	v_mfma_f32_16x16x32_bf16 v[12:15], v[184:187], v[172:175], v[12:15]
	v_mfma_f32_16x16x32_bf16 v[8:11], v[194:197], v[172:175], v[8:11]
	v_mfma_f32_16x16x32_bf16 v[4:7], v[184:187], v[180:183], v[4:7]
	v_mfma_f32_16x16x32_bf16 v[0:3], v[194:197], v[180:183], v[0:3]
	s_setprio 0
	s_movk_i32 s0, 0x100
	v_cmp_gt_u32_e32 vcc, s0, v136
	s_barrier
	s_and_saveexec_b64 s[0:1], vcc
	s_cbranch_execz .LBB0_567
	s_barrier

; #define WAIT_V(n) asm volatile("s_waitcnt vmcnt(" #n ")" ::: "memory")
; #define WAIT_L(n) asm volatile("s_waitcnt lgkmcnt(" #n ")" ::: "memory")
; #define BAR __builtin_amdgcn_s_barrier()
; #define SCHED __builtin_amdgcn_sched_barrier(0)
; #define STAGE(P, BASE, br, kt) do { const char* _g = (const char*)((BASE) + (size_t)(br) * GK + (kt) * BK); \
;     __builtin_amdgcn_global_load_lds((const unsigned*)(_g + voff0), (unsigned*)((char*)(P) + tx * 16), 16, 0, 0); \
;     __builtin_amdgcn_global_load_lds((const unsigned*)(_g + voff1), (unsigned*)((char*)(P) + tx * 16 + 8192), 16, 0, 0); } while (0)
; #define LDA(dst, b, h) _Pragma("unroll") for (int m = 0; m < 4; ++m) _Pragma("unroll") for (int k = 0; k < 2; ++k) \
;     dst[m][k] = *reinterpret_cast<const bf16x8*>((char*)shm + abase + (((b) * 2 + (h)) * 16384 + (m * 2 + k) * 1024))
; #define LDB(dst, b, h) _Pragma("unroll") for (int n = 0; n < 2; ++n) _Pragma("unroll") for (int k = 0; k < 2; ++k) \
;     dst[n][k] = *reinterpret_cast<const bf16x8*>((char*)shm + bbase + (((b) * 2 + (h)) * 16384 + (n * 2 + k) * 1024))
; template <bool SWAP>
; __device__ __forceinline__ void gemm_main(const u16* __restrict__ A, const u16* __restrict__ Bt, int brow, int bcol,
;                                           u16* shm, f32x4 (&acc)[2][2][4][2]) {
;     ...
;     LDB(B0, 0, 0); SCHED; LDA(At, 0, 0); STAGE(SA(1, 1), A, brow + HALF, t + 1);
;     WAIT_L(8); BAR; WAIT_L(0); MMA(0, 0, At, B0); BAR; SCHED;
;     LDB(B1, 0, 1); STAGE(SB(0, 0), Bt, bcol, t + 2);
;     BAR; WAIT_L(0); MMA(0, 1, At, B1); BAR;
;     LDA(At, 0, 1); STAGE(SA(0, 0), A, brow, t + 2);
;     BAR; WAIT_L(0); MMA(1, 0, At, B0); BAR; SCHED;
;     STAGE(SB(0, 1), Bt, bcol + HALF, t + 2);
;     WAIT_V(6); BAR; MMA(1, 1, At, B1); BAR;
.LBB0_570:
	ds_read_b128 v[168:171], v137 offset:1024
	ds_read_b128 v[176:179], v137 offset:3072
	ds_read_b128 v[184:187], v137 offset:5120
	ds_read_b128 v[194:197], v137 offset:7168
	v_add_u32_e32 v192, 0, v140
	v_add_u32_e32 v146, 0xc000, v192
	v_lshl_add_u64 v[230:231], vcc, 0, v[132:133]
	v_add_u32_e32 v147, 0xe000, v192
	v_lshl_add_u64 v[198:199], v[230:231], 0, s[14:15]
	s_add_u32 m0, s24, 0xc000
	v_lshl_add_u64 v[232:233], vcc, 0, v[134:135]
	global_load_lds_dwordx4 v[198:199], off
	v_lshl_add_u64 v[198:199], v[232:233], 0, s[14:15]
	s_add_u32 m0, s24, 0xe000
	s_nop 0
	global_load_lds_dwordx4 v[198:199], off
	s_waitcnt lgkmcnt(8)
	s_barrier
	s_waitcnt lgkmcnt(0)
	v_mfma_f32_16x16x32_bf16 v[124:127], v[148:151], v[164:167], v[124:127]
	v_mfma_f32_16x16x32_bf16 v[120:123], v[156:159], v[164:167], v[120:123]
	v_mfma_f32_16x16x32_bf16 v[116:119], v[148:151], v[172:175], v[116:119]
	v_mfma_f32_16x16x32_bf16 v[112:115], v[156:159], v[172:175], v[112:115]
	v_mfma_f32_16x16x32_bf16 v[108:111], v[148:151], v[180:183], v[108:111]
	v_mfma_f32_16x16x32_bf16 v[104:107], v[156:159], v[180:183], v[104:107]
	v_mfma_f32_16x16x32_bf16 v[100:103], v[148:151], v[188:191], v[100:103]
	v_mfma_f32_16x16x32_bf16 v[96:99], v[156:159], v[188:191], v[96:99]
	v_mfma_f32_16x16x32_bf16 v[124:127], v[152:155], v[168:171], v[124:127]
	v_mfma_f32_16x16x32_bf16 v[120:123], v[160:163], v[168:171], v[120:123]
	v_mfma_f32_16x16x32_bf16 v[116:119], v[152:155], v[176:179], v[116:119]
	v_mfma_f32_16x16x32_bf16 v[112:115], v[160:163], v[176:179], v[112:115]
	v_mfma_f32_16x16x32_bf16 v[108:111], v[152:155], v[184:187], v[108:111]
	v_mfma_f32_16x16x32_bf16 v[104:107], v[160:163], v[184:187], v[104:107]
	v_mfma_f32_16x16x32_bf16 v[100:103], v[152:155], v[194:197], v[100:103]
	v_mfma_f32_16x16x32_bf16 v[96:99], v[160:163], v[194:197], v[96:99]
	s_barrier
	ds_read_b128 v[198:201], v138 offset:16384
	ds_read_b128 v[202:205], v138 offset:17408
	ds_read_b128 v[206:209], v138 offset:18432
	ds_read_b128 v[226:229], v138 offset:19456
	v_lshl_add_u64 v[234:235], vcc, 0, v[128:129]
	v_lshl_add_u64 v[236:237], v[234:235], 0, s[16:17]
	s_add_u32 m0, s24, s28
	s_nop 0
	global_load_lds_dwordx4 v[236:237], off
	v_lshl_add_u64 v[236:237], vcc, 0, v[130:131]
	v_lshl_add_u64 v[238:239], v[236:237], 0, s[16:17]
	s_add_u32 m0, s24, s28
	s_add_u32 m0, m0, 0x2000
	s_nop 0
	global_load_lds_dwordx4 v[238:239], off
	s_barrier
	s_waitcnt lgkmcnt(0)
	v_mfma_f32_16x16x32_bf16 v[92:95], v[198:201], v[164:167], v[92:95]
	v_mfma_f32_16x16x32_bf16 v[88:91], v[206:209], v[164:167], v[88:91]
	v_mfma_f32_16x16x32_bf16 v[84:87], v[198:201], v[172:175], v[84:87]
	v_mfma_f32_16x16x32_bf16 v[80:83], v[206:209], v[172:175], v[80:83]
	v_mfma_f32_16x16x32_bf16 v[76:79], v[198:201], v[180:183], v[76:79]
	v_mfma_f32_16x16x32_bf16 v[72:75], v[206:209], v[180:183], v[72:75]
	v_mfma_f32_16x16x32_bf16 v[68:71], v[198:201], v[188:191], v[68:71]
	v_mfma_f32_16x16x32_bf16 v[64:67], v[206:209], v[188:191], v[64:67]
	v_mfma_f32_16x16x32_bf16 v[92:95], v[202:205], v[168:171], v[92:95]
	ds_read_b128 v[164:167], v137 offset:16384
	v_mfma_f32_16x16x32_bf16 v[88:91], v[226:229], v[168:171], v[88:91]
	v_mfma_f32_16x16x32_bf16 v[84:87], v[202:205], v[176:179], v[84:87]
	ds_read_b128 v[172:175], v137 offset:18432
	v_mfma_f32_16x16x32_bf16 v[80:83], v[226:229], v[176:179], v[80:83]
	v_mfma_f32_16x16x32_bf16 v[76:79], v[202:205], v[184:187], v[76:79]
	ds_read_b128 v[180:183], v137 offset:20480
	v_mfma_f32_16x16x32_bf16 v[72:75], v[226:229], v[184:187], v[72:75]
	v_mfma_f32_16x16x32_bf16 v[68:71], v[202:205], v[194:197], v[68:71]
	ds_read_b128 v[188:191], v137 offset:22528
	v_mfma_f32_16x16x32_bf16 v[64:67], v[226:229], v[194:197], v[64:67]
	s_barrier
	ds_read_b128 v[168:171], v137 offset:17408
	ds_read_b128 v[176:179], v137 offset:19456
	ds_read_b128 v[184:187], v137 offset:21504
	ds_read_b128 v[194:197], v137 offset:23552
	v_lshl_add_u64 v[238:239], v[230:231], 0, s[18:19]
	s_add_u32 m0, s24, 0x0
	s_nop 0
	global_load_lds_dwordx4 v[238:239], off
	v_lshl_add_u64 v[238:239], v[232:233], 0, s[18:19]
	s_add_u32 m0, s24, 0x2000
	s_nop 0
	global_load_lds_dwordx4 v[238:239], off
	s_waitcnt vmcnt(8)
	s_barrier
	s_waitcnt lgkmcnt(0)
	v_mfma_f32_16x16x32_bf16 v[60:63], v[148:151], v[164:167], v[60:63]
	v_mfma_f32_16x16x32_bf16 v[56:59], v[156:159], v[164:167], v[56:59]
	v_mfma_f32_16x16x32_bf16 v[52:55], v[148:151], v[172:175], v[52:55]
	v_mfma_f32_16x16x32_bf16 v[48:51], v[156:159], v[172:175], v[48:51]
	v_mfma_f32_16x16x32_bf16 v[44:47], v[148:151], v[180:183], v[44:47]
	v_mfma_f32_16x16x32_bf16 v[40:43], v[156:159], v[180:183], v[40:43]
	v_mfma_f32_16x16x32_bf16 v[36:39], v[148:151], v[188:191], v[36:39]
	v_mfma_f32_16x16x32_bf16 v[32:35], v[156:159], v[188:191], v[32:35]
	v_mfma_f32_16x16x32_bf16 v[60:63], v[152:155], v[168:171], v[60:63]
	v_mfma_f32_16x16x32_bf16 v[56:59], v[160:163], v[168:171], v[56:59]
	v_mfma_f32_16x16x32_bf16 v[52:55], v[152:155], v[176:179], v[52:55]
	v_mfma_f32_16x16x32_bf16 v[48:51], v[160:163], v[176:179], v[48:51]
	v_mfma_f32_16x16x32_bf16 v[44:47], v[152:155], v[184:187], v[44:47]
	v_mfma_f32_16x16x32_bf16 v[40:43], v[160:163], v[184:187], v[40:43]
	v_mfma_f32_16x16x32_bf16 v[36:39], v[152:155], v[194:197], v[36:39]
	v_mfma_f32_16x16x32_bf16 v[32:35], v[160:163], v[194:197], v[32:35]
	s_barrier
	ds_read_b128 v[148:151], v138 offset:32768
	ds_read_b128 v[152:155], v138 offset:33792
	ds_read_b128 v[156:159], v138 offset:34816
	ds_read_b128 v[160:163], v138 offset:35840
	v_lshl_add_u64 v[254:255], v[234:235], 0, s[42:43]
	s_add_u32 m0, s24, s29
	s_nop 0
	global_load_lds_dwordx4 v[254:255], off
	v_lshl_add_u64 v[254:255], v[236:237], 0, s[42:43]
	s_add_u32 m0, s24, s29
	s_add_u32 m0, m0, 0x2000
	s_nop 0
	global_load_lds_dwordx4 v[254:255], off
	s_waitcnt vmcnt(6)
	s_barrier
; #define WAIT_V(n) asm volatile("s_waitcnt vmcnt(" #n ")" ::: "memory")
; #define WAIT_L(n) asm volatile("s_waitcnt lgkmcnt(" #n ")" ::: "memory")
; #define BAR __builtin_amdgcn_s_barrier()
; #define SCHED __builtin_amdgcn_sched_barrier(0)
; #define STAGE(P, BASE, br, kt) do { const char* _g = (const char*)((BASE) + (size_t)(br) * GK + (kt) * BK); \
;     __builtin_amdgcn_global_load_lds((const unsigned*)(_g + voff0), (unsigned*)((char*)(P) + tx * 16), 16, 0, 0); \
;     __builtin_amdgcn_global_load_lds((const unsigned*)(_g + voff1), (unsigned*)((char*)(P) + tx * 16 + 8192), 16, 0, 0); } while (0)
; #define LDA(dst, b, h) _Pragma("unroll") for (int m = 0; m < 4; ++m) _Pragma("unroll") for (int k = 0; k < 2; ++k) \
;     dst[m][k] = *reinterpret_cast<const bf16x8*>((char*)shm + abase + (((b) * 2 + (h)) * 16384 + (m * 2 + k) * 1024))
; #define LDB(dst, b, h) _Pragma("unroll") for (int n = 0; n < 2; ++n) _Pragma("unroll") for (int k = 0; k < 2; ++k) \
;     dst[n][k] = *reinterpret_cast<const bf16x8*>((char*)shm + bbase + (((b) * 2 + (h)) * 16384 + (n * 2 + k) * 1024))
; template <bool SWAP>
; __device__ __forceinline__ void gemm_main(const u16* __restrict__ A, const u16* __restrict__ Bt, int brow, int bcol,
;                                           u16* shm, f32x4 (&acc)[2][2][4][2]) {
;     ...
;     WAIT_V(6); BAR; MMA(1, 1, At, B1); BAR;
;     LDB(B0, 1, 0); SCHED; LDA(At, 1, 0); STAGE(SA(0, 1), A, brow + HALF, t + 2);
;     WAIT_L(8); BAR; WAIT_L(0); MMA(0, 0, At, B0); BAR; SCHED;
;     LDB(B1, 1, 1); STAGE(SB(1, 0), Bt, bcol, t + 3);
;     BAR; WAIT_L(0); MMA(0, 1, At, B1); BAR;
;     LDA(At, 1, 1); STAGE(SA(1, 0), A, brow, t + 3);
	v_mfma_f32_16x16x32_bf16 v[28:31], v[198:201], v[164:167], v[28:31]
	v_mfma_f32_16x16x32_bf16 v[24:27], v[206:209], v[164:167], v[24:27]
	v_mfma_f32_16x16x32_bf16 v[20:23], v[198:201], v[172:175], v[20:23]
	v_mfma_f32_16x16x32_bf16 v[16:19], v[206:209], v[172:175], v[16:19]
	v_mfma_f32_16x16x32_bf16 v[12:15], v[198:201], v[180:183], v[12:15]
	v_mfma_f32_16x16x32_bf16 v[8:11], v[206:209], v[180:183], v[8:11]
	v_mfma_f32_16x16x32_bf16 v[4:7], v[198:201], v[188:191], v[4:7]
	v_mfma_f32_16x16x32_bf16 v[0:3], v[206:209], v[188:191], v[0:3]
	v_mfma_f32_16x16x32_bf16 v[28:31], v[202:205], v[168:171], v[28:31]
	ds_read_b128 v[164:167], v137 offset:32768
	v_mfma_f32_16x16x32_bf16 v[24:27], v[226:229], v[168:171], v[24:27]
	v_mfma_f32_16x16x32_bf16 v[20:23], v[202:205], v[176:179], v[20:23]
	ds_read_b128 v[172:175], v137 offset:34816
	v_mfma_f32_16x16x32_bf16 v[16:19], v[226:229], v[176:179], v[16:19]
	v_mfma_f32_16x16x32_bf16 v[12:15], v[202:205], v[184:187], v[12:15]
	ds_read_b128 v[180:183], v137 offset:36864
	v_mfma_f32_16x16x32_bf16 v[8:11], v[226:229], v[184:187], v[8:11]
	v_mfma_f32_16x16x32_bf16 v[4:7], v[202:205], v[194:197], v[4:7]
	ds_read_b128 v[188:191], v137 offset:38912
	v_mfma_f32_16x16x32_bf16 v[0:3], v[226:229], v[194:197], v[0:3]
	s_barrier
	ds_read_b128 v[168:171], v137 offset:33792
	ds_read_b128 v[176:179], v137 offset:35840
	ds_read_b128 v[184:187], v137 offset:37888
	ds_read_b128 v[194:197], v137 offset:39936
	v_lshl_add_u64 v[198:199], v[230:231], 0, s[22:23]
	s_add_u32 m0, s24, 0x4000
	s_nop 0
	global_load_lds_dwordx4 v[198:199], off
	v_lshl_add_u64 v[198:199], v[232:233], 0, s[22:23]
	s_add_u32 m0, s24, 0x6000
	s_nop 0
	global_load_lds_dwordx4 v[198:199], off
	s_waitcnt lgkmcnt(8)
	s_barrier
	s_waitcnt lgkmcnt(0)
	v_mfma_f32_16x16x32_bf16 v[124:127], v[148:151], v[164:167], v[124:127]
	v_mfma_f32_16x16x32_bf16 v[120:123], v[156:159], v[164:167], v[120:123]
	v_mfma_f32_16x16x32_bf16 v[116:119], v[148:151], v[172:175], v[116:119]
	v_mfma_f32_16x16x32_bf16 v[112:115], v[156:159], v[172:175], v[112:115]
	v_mfma_f32_16x16x32_bf16 v[108:111], v[148:151], v[180:183], v[108:111]
	v_mfma_f32_16x16x32_bf16 v[104:107], v[156:159], v[180:183], v[104:107]
	v_mfma_f32_16x16x32_bf16 v[100:103], v[148:151], v[188:191], v[100:103]
	v_mfma_f32_16x16x32_bf16 v[96:99], v[156:159], v[188:191], v[96:99]
	v_mfma_f32_16x16x32_bf16 v[124:127], v[152:155], v[168:171], v[124:127]
	v_mfma_f32_16x16x32_bf16 v[120:123], v[160:163], v[168:171], v[120:123]
	v_mfma_f32_16x16x32_bf16 v[116:119], v[152:155], v[176:179], v[116:119]
	v_mfma_f32_16x16x32_bf16 v[112:115], v[160:163], v[176:179], v[112:115]
	v_mfma_f32_16x16x32_bf16 v[108:111], v[152:155], v[184:187], v[108:111]
	v_mfma_f32_16x16x32_bf16 v[104:107], v[160:163], v[184:187], v[104:107]
	v_mfma_f32_16x16x32_bf16 v[100:103], v[152:155], v[194:197], v[100:103]
	v_mfma_f32_16x16x32_bf16 v[96:99], v[160:163], v[194:197], v[96:99]
	s_barrier
	ds_read_b128 v[198:201], v138 offset:49152
	ds_read_b128 v[202:205], v138 offset:50176
	ds_read_b128 v[206:209], v138 offset:51200
	ds_read_b128 v[226:229], v138 offset:52224
	v_lshl_add_u64 v[238:239], v[234:235], 0, s[20:21]
	s_add_u32 m0, s24, s30
	s_nop 0
	global_load_lds_dwordx4 v[238:239], off
	v_lshl_add_u64 v[238:239], v[236:237], 0, s[20:21]
	s_add_u32 m0, s24, s30
	s_add_u32 m0, m0, 0x2000
	s_nop 0
	global_load_lds_dwordx4 v[238:239], off
	s_barrier
	s_waitcnt lgkmcnt(0)
	v_mfma_f32_16x16x32_bf16 v[92:95], v[198:201], v[164:167], v[92:95]
	v_mfma_f32_16x16x32_bf16 v[88:91], v[206:209], v[164:167], v[88:91]
	v_mfma_f32_16x16x32_bf16 v[84:87], v[198:201], v[172:175], v[84:87]
	v_mfma_f32_16x16x32_bf16 v[80:83], v[206:209], v[172:175], v[80:83]
	v_mfma_f32_16x16x32_bf16 v[76:79], v[198:201], v[180:183], v[76:79]
	v_mfma_f32_16x16x32_bf16 v[72:75], v[206:209], v[180:183], v[72:75]
	v_mfma_f32_16x16x32_bf16 v[68:71], v[198:201], v[188:191], v[68:71]
	v_mfma_f32_16x16x32_bf16 v[64:67], v[206:209], v[188:191], v[64:67]
	v_mfma_f32_16x16x32_bf16 v[92:95], v[202:205], v[168:171], v[92:95]
	ds_read_b128 v[164:167], v137 offset:49152
	v_mfma_f32_16x16x32_bf16 v[88:91], v[226:229], v[168:171], v[88:91]
	v_mfma_f32_16x16x32_bf16 v[84:87], v[202:205], v[176:179], v[84:87]
	ds_read_b128 v[172:175], v137 offset:51200
	v_mfma_f32_16x16x32_bf16 v[80:83], v[226:229], v[176:179], v[80:83]
	v_mfma_f32_16x16x32_bf16 v[76:79], v[202:205], v[184:187], v[76:79]
	ds_read_b128 v[180:183], v137 offset:53248
	v_mfma_f32_16x16x32_bf16 v[72:75], v[226:229], v[184:187], v[72:75]
	v_mfma_f32_16x16x32_bf16 v[68:71], v[202:205], v[194:197], v[68:71]
	ds_read_b128 v[188:191], v137 offset:55296
	v_mfma_f32_16x16x32_bf16 v[64:67], v[226:229], v[194:197], v[64:67]
	s_barrier
	ds_read_b128 v[168:171], v137 offset:50176
	ds_read_b128 v[176:179], v137 offset:52224
	ds_read_b128 v[184:187], v137 offset:54272
	ds_read_b128 v[194:197], v137 offset:56320
	v_lshl_add_u64 v[230:231], v[230:231], 0, s[92:93]
	s_add_u32 m0, s24, 0x8000
	s_nop 0
	global_load_lds_dwordx4 v[230:231], off
	v_lshl_add_u64 v[230:231], v[232:233], 0, s[92:93]
	s_add_u32 m0, s24, 0xa000
	s_nop 0
	global_load_lds_dwordx4 v[230:231], off
	s_waitcnt vmcnt(8)
	s_barrier
; #define WAIT_V(n) asm volatile("s_waitcnt vmcnt(" #n ")" ::: "memory")
; #define WAIT_L(n) asm volatile("s_waitcnt lgkmcnt(" #n ")" ::: "memory")
; #define BAR __builtin_amdgcn_s_barrier()
; #define SCHED __builtin_amdgcn_sched_barrier(0)
; #define STAGE(P, BASE, br, kt) do { const char* _g = (const char*)((BASE) + (size_t)(br) * GK + (kt) * BK); \
;     __builtin_amdgcn_global_load_lds((const unsigned*)(_g + voff0), (unsigned*)((char*)(P) + tx * 16), 16, 0, 0); \
;     __builtin_amdgcn_global_load_lds((const unsigned*)(_g + voff1), (unsigned*)((char*)(P) + tx * 16 + 8192), 16, 0, 0); } while (0)
; #define LDA(dst, b, h) _Pragma("unroll") for (int m = 0; m < 4; ++m) _Pragma("unroll") for (int k = 0; k < 2; ++k) \
;     dst[m][k] = *reinterpret_cast<const bf16x8*>((char*)shm + abase + (((b) * 2 + (h)) * 16384 + (m * 2 + k) * 1024))
; #define LDB(dst, b, h) _Pragma("unroll") for (int n = 0; n < 2; ++n) _Pragma("unroll") for (int k = 0; k < 2; ++k) \
;     dst[n][k] = *reinterpret_cast<const bf16x8*>((char*)shm + bbase + (((b) * 2 + (h)) * 16384 + (n * 2 + k) * 1024))
; template <bool SWAP>
; __device__ __forceinline__ void gemm_main(const u16* __restrict__ A, const u16* __restrict__ Bt, int brow, int bcol,
;                                           u16* shm, f32x4 (&acc)[2][2][4][2]) {
;     ...
;     BAR; WAIT_L(0); MMA(1, 0, At, B0); BAR; SCHED;
;     STAGE(SB(1, 1), Bt, bcol + HALF, t + 3);
;     WAIT_V(6); BAR; MMA(1, 1, At, B1); BAR;
;   }
;   { LDB(B0, 0, 0); LDA(At, 0, 0); STAGE(SA(1, 1), A, brow + HALF, nt - 1);
;     BAR; WAIT_L(0); MMA(0, 0, At, B0); BAR;
	s_waitcnt lgkmcnt(0)
	v_mfma_f32_16x16x32_bf16 v[60:63], v[148:151], v[164:167], v[60:63]
	v_mfma_f32_16x16x32_bf16 v[56:59], v[156:159], v[164:167], v[56:59]
	v_mfma_f32_16x16x32_bf16 v[52:55], v[148:151], v[172:175], v[52:55]
	v_mfma_f32_16x16x32_bf16 v[48:51], v[156:159], v[172:175], v[48:51]
	v_mfma_f32_16x16x32_bf16 v[44:47], v[148:151], v[180:183], v[44:47]
	v_mfma_f32_16x16x32_bf16 v[40:43], v[156:159], v[180:183], v[40:43]
	v_mfma_f32_16x16x32_bf16 v[36:39], v[148:151], v[188:191], v[36:39]
	v_mfma_f32_16x16x32_bf16 v[32:35], v[156:159], v[188:191], v[32:35]
	v_mfma_f32_16x16x32_bf16 v[60:63], v[152:155], v[168:171], v[60:63]
	v_mfma_f32_16x16x32_bf16 v[56:59], v[160:163], v[168:171], v[56:59]
	v_mfma_f32_16x16x32_bf16 v[52:55], v[152:155], v[176:179], v[52:55]
	v_mfma_f32_16x16x32_bf16 v[48:51], v[160:163], v[176:179], v[48:51]
	v_mfma_f32_16x16x32_bf16 v[44:47], v[152:155], v[184:187], v[44:47]
	v_mfma_f32_16x16x32_bf16 v[40:43], v[160:163], v[184:187], v[40:43]
	v_mfma_f32_16x16x32_bf16 v[36:39], v[152:155], v[194:197], v[36:39]
	v_mfma_f32_16x16x32_bf16 v[32:35], v[160:163], v[194:197], v[32:35]
	s_barrier
	ds_read_b128 v[148:151], v138
	ds_read_b128 v[152:155], v138 offset:1024
	ds_read_b128 v[156:159], v138 offset:2048
	ds_read_b128 v[160:163], v138 offset:3072
	v_lshl_add_u64 v[254:255], v[234:235], 0, s[72:73]
	s_add_u32 m0, s24, s31
	s_nop 0
	global_load_lds_dwordx4 v[254:255], off
	v_lshl_add_u64 v[254:255], v[236:237], 0, s[72:73]
	s_add_u32 m0, s24, s31
	s_add_u32 m0, m0, 0x2000
	s_nop 0
	global_load_lds_dwordx4 v[254:255], off
	s_waitcnt vmcnt(6)
	s_barrier
	v_mfma_f32_16x16x32_bf16 v[28:31], v[198:201], v[164:167], v[28:31]
	v_mfma_f32_16x16x32_bf16 v[24:27], v[206:209], v[164:167], v[24:27]
	v_mfma_f32_16x16x32_bf16 v[20:23], v[198:201], v[172:175], v[20:23]
	v_mfma_f32_16x16x32_bf16 v[16:19], v[206:209], v[172:175], v[16:19]
	v_mfma_f32_16x16x32_bf16 v[12:15], v[198:201], v[180:183], v[12:15]
	v_mfma_f32_16x16x32_bf16 v[8:11], v[206:209], v[180:183], v[8:11]
	v_mfma_f32_16x16x32_bf16 v[4:7], v[198:201], v[188:191], v[4:7]
	v_mfma_f32_16x16x32_bf16 v[0:3], v[206:209], v[188:191], v[0:3]
	v_mfma_f32_16x16x32_bf16 v[28:31], v[202:205], v[168:171], v[28:31]
	ds_read_b128 v[164:167], v137
	v_mfma_f32_16x16x32_bf16 v[24:27], v[226:229], v[168:171], v[24:27]
	v_mfma_f32_16x16x32_bf16 v[20:23], v[202:205], v[176:179], v[20:23]
	ds_read_b128 v[172:175], v137 offset:2048
	v_mfma_f32_16x16x32_bf16 v[16:19], v[226:229], v[176:179], v[16:19]
	v_mfma_f32_16x16x32_bf16 v[12:15], v[202:205], v[184:187], v[12:15]
	ds_read_b128 v[180:183], v137 offset:4096
	v_mfma_f32_16x16x32_bf16 v[8:11], v[226:229], v[184:187], v[8:11]
	v_mfma_f32_16x16x32_bf16 v[4:7], v[202:205], v[194:197], v[4:7]
	ds_read_b128 v[188:191], v137 offset:6144
	v_mfma_f32_16x16x32_bf16 v[0:3], v[226:229], v[194:197], v[0:3]
	s_add_i32 s3, s3, 2
	s_add_u32 vcc_lo, vcc_lo, 0x100
	s_addc_u32 vcc_hi, vcc_hi, 0
	s_cmp_lt_u32 s3, 28
	s_barrier
	s_cbranch_scc1 .LBB0_570
	v_lshlrev_b32_e32 v128, 3, v139
	v_lshlrev_b32_e32 v129, 5, v139
	v_and_b32_e32 v128, 0xffff0, v128
	v_and_b32_e32 v129, 32, v129
	v_add_u32_e32 v129, v129, v142
	v_add_lshl_u32 v128, v141, v128, 12
	v_lshl_add_u32 v192, v129, 1, v128
	v_lshlrev_b32_e32 v128, 3, v143
	v_lshlrev_b32_e32 v129, 5, v143
	v_and_b32_e32 v128, 0xffff0, v128
	v_and_b32_e32 v129, 32, v129
	v_add_u32_e32 v129, v129, v145
	v_add_lshl_u32 v128, v144, v128, 12
	v_lshl_add_u32 v144, v129, 1, v128
	v_mov_b32_e32 v145, v193
	v_lshl_add_u64 v[184:185], s[4:5], 0, v[192:193]
	s_mov_b64 s[14:15], 0xf80
	v_readfirstlane_b32 s3, v146
	v_lshl_add_u64 v[184:185], v[184:185], 0, s[14:15]
	s_mov_b32 m0, s3
	v_lshl_add_u64 v[144:145], s[4:5], 0, v[144:145]
	v_readfirstlane_b32 s3, v147
	ds_read_b128 v[128:131], v138
	ds_read_b128 v[132:135], v138 offset:1024
	ds_read_b128 v[140:143], v138 offset:2048
	ds_read_b128 v[148:151], v138 offset:3072
	ds_read_b128 v[152:155], v137
	ds_read_b128 v[156:159], v137 offset:1024
	ds_read_b128 v[160:163], v137 offset:2048
	ds_read_b128 v[164:167], v137 offset:3072
	ds_read_b128 v[168:171], v137 offset:4096
	ds_read_b128 v[172:175], v137 offset:5120
	ds_read_b128 v[176:179], v137 offset:6144
	ds_read_b128 v[180:183], v137 offset:7168
	global_load_lds_dwordx4 v[184:185], off
	v_lshl_add_u64 v[144:145], v[144:145], 0, s[14:15]
	s_mov_b32 m0, s3
	s_nop 0
	global_load_lds_dwordx4 v[144:145], off
	s_barrier
	s_waitcnt lgkmcnt(0)
	v_mfma_f32_16x16x32_bf16 v[116:119], v[128:131], v[160:163], v[116:119]
	v_mfma_f32_16x16x32_bf16 v[112:115], v[140:143], v[160:163], v[112:115]
	v_mfma_f32_16x16x32_bf16 v[100:103], v[128:131], v[176:179], v[100:103]
	v_mfma_f32_16x16x32_bf16 v[96:99], v[140:143], v[176:179], v[96:99]
	v_mfma_f32_16x16x32_bf16 v[124:127], v[128:131], v[152:155], v[124:127]
	v_mfma_f32_16x16x32_bf16 v[120:123], v[140:143], v[152:155], v[120:123]
	v_mfma_f32_16x16x32_bf16 v[116:119], v[132:135], v[164:167], v[116:119]
	v_mfma_f32_16x16x32_bf16 v[112:115], v[148:151], v[164:167], v[112:115]
	v_mfma_f32_16x16x32_bf16 v[108:111], v[128:131], v[168:171], v[108:111]
	v_mfma_f32_16x16x32_bf16 v[104:107], v[140:143], v[168:171], v[104:107]
	v_mfma_f32_16x16x32_bf16 v[100:103], v[132:135], v[180:183], v[100:103]
	v_mfma_f32_16x16x32_bf16 v[96:99], v[148:151], v[180:183], v[96:99]
	v_mfma_f32_16x16x32_bf16 v[124:127], v[132:135], v[156:159], v[124:127]
	v_mfma_f32_16x16x32_bf16 v[120:123], v[148:151], v[156:159], v[120:123]
	v_mfma_f32_16x16x32_bf16 v[108:111], v[132:135], v[172:175], v[108:111]
	v_mfma_f32_16x16x32_bf16 v[104:107], v[148:151], v[172:175], v[104:107]
	s_setprio 0
	s_barrier
; #define WAIT_V(n) asm volatile("s_waitcnt vmcnt(" #n ")" ::: "memory")
; #define WAIT_L(n) asm volatile("s_waitcnt lgkmcnt(" #n ")" ::: "memory")
; #define BAR __builtin_amdgcn_s_barrier()
; #define LDA(dst, b, h) _Pragma("unroll") for (int m = 0; m < 4; ++m) _Pragma("unroll") for (int k = 0; k < 2; ++k) \
;     dst[m][k] = *reinterpret_cast<const bf16x8*>((char*)shm + abase + (((b) * 2 + (h)) * 16384 + (m * 2 + k) * 1024))
; #define LDB(dst, b, h) _Pragma("unroll") for (int n = 0; n < 2; ++n) _Pragma("unroll") for (int k = 0; k < 2; ++k) \
;     dst[n][k] = *reinterpret_cast<const bf16x8*>((char*)shm + bbase + (((b) * 2 + (h)) * 16384 + (n * 2 + k) * 1024))
; template <bool SWAP>
; __device__ __forceinline__ void gemm_main(const u16* __restrict__ A, const u16* __restrict__ Bt, int brow, int bcol,
;                                           u16* shm, f32x4 (&acc)[2][2][4][2]) {
;     ...
;     BAR; WAIT_L(0); MMA(0, 0, At, B0); BAR;
;     LDB(B1, 0, 1); BAR; WAIT_L(0); MMA(0, 1, At, B1); BAR;
;     LDA(At, 0, 1); WAIT_V(4); BAR; WAIT_L(0); MMA(1, 0, At, B0); MMA(1, 1, At, B1); BAR; }
;   { LDB(B0, 1, 0); LDA(At, 1, 0); WAIT_V(2); BAR; WAIT_L(0); MMA(0, 0, At, B0); BAR;
	ds_read_b128 v[144:147], v138 offset:16384
	ds_read_b128 v[184:187], v138 offset:17408
	ds_read_b128 v[188:191], v138 offset:18432
	ds_read_b128 v[194:197], v138 offset:19456
	s_barrier
	s_waitcnt lgkmcnt(0)
	v_mfma_f32_16x16x32_bf16 v[92:95], v[144:147], v[152:155], v[92:95]
	v_mfma_f32_16x16x32_bf16 v[88:91], v[188:191], v[152:155], v[88:91]
	v_mfma_f32_16x16x32_bf16 v[84:87], v[144:147], v[160:163], v[84:87]
	v_mfma_f32_16x16x32_bf16 v[80:83], v[188:191], v[160:163], v[80:83]
	v_mfma_f32_16x16x32_bf16 v[76:79], v[144:147], v[168:171], v[76:79]
	v_mfma_f32_16x16x32_bf16 v[72:75], v[188:191], v[168:171], v[72:75]
	v_mfma_f32_16x16x32_bf16 v[68:71], v[144:147], v[176:179], v[68:71]
	v_mfma_f32_16x16x32_bf16 v[64:67], v[188:191], v[176:179], v[64:67]
	v_mfma_f32_16x16x32_bf16 v[92:95], v[184:187], v[156:159], v[92:95]
	v_mfma_f32_16x16x32_bf16 v[88:91], v[194:197], v[156:159], v[88:91]
	v_mfma_f32_16x16x32_bf16 v[84:87], v[184:187], v[164:167], v[84:87]
	v_mfma_f32_16x16x32_bf16 v[80:83], v[194:197], v[164:167], v[80:83]
	v_mfma_f32_16x16x32_bf16 v[76:79], v[184:187], v[172:175], v[76:79]
	v_mfma_f32_16x16x32_bf16 v[72:75], v[194:197], v[172:175], v[72:75]
	v_mfma_f32_16x16x32_bf16 v[68:71], v[184:187], v[180:183], v[68:71]
	v_mfma_f32_16x16x32_bf16 v[64:67], v[194:197], v[180:183], v[64:67]
	s_setprio 0
	s_barrier
	ds_read_b128 v[152:155], v137 offset:16384
	ds_read_b128 v[156:159], v137 offset:17408
	ds_read_b128 v[160:163], v137 offset:18432
	ds_read_b128 v[164:167], v137 offset:19456
	ds_read_b128 v[168:171], v137 offset:20480
	ds_read_b128 v[172:175], v137 offset:21504
	ds_read_b128 v[176:179], v137 offset:22528
	ds_read_b128 v[180:183], v137 offset:23552
	s_waitcnt vmcnt(4)
	s_barrier
	s_waitcnt lgkmcnt(0)
	v_mfma_f32_16x16x32_bf16 v[60:63], v[128:131], v[152:155], v[60:63]
	v_mfma_f32_16x16x32_bf16 v[56:59], v[140:143], v[152:155], v[56:59]
	v_mfma_f32_16x16x32_bf16 v[52:55], v[128:131], v[160:163], v[52:55]
	v_mfma_f32_16x16x32_bf16 v[48:51], v[140:143], v[160:163], v[48:51]
	v_mfma_f32_16x16x32_bf16 v[44:47], v[128:131], v[168:171], v[44:47]
	v_mfma_f32_16x16x32_bf16 v[40:43], v[140:143], v[168:171], v[40:43]
	v_mfma_f32_16x16x32_bf16 v[36:39], v[128:131], v[176:179], v[36:39]
	v_mfma_f32_16x16x32_bf16 v[32:35], v[140:143], v[176:179], v[32:35]
	v_mfma_f32_16x16x32_bf16 v[60:63], v[132:135], v[156:159], v[60:63]
	v_mfma_f32_16x16x32_bf16 v[56:59], v[148:151], v[156:159], v[56:59]
	v_mfma_f32_16x16x32_bf16 v[52:55], v[132:135], v[164:167], v[52:55]
	v_mfma_f32_16x16x32_bf16 v[48:51], v[148:151], v[164:167], v[48:51]
	v_mfma_f32_16x16x32_bf16 v[44:47], v[132:135], v[172:175], v[44:47]
	v_mfma_f32_16x16x32_bf16 v[40:43], v[148:151], v[172:175], v[40:43]
	v_mfma_f32_16x16x32_bf16 v[36:39], v[132:135], v[180:183], v[36:39]
	v_mfma_f32_16x16x32_bf16 v[32:35], v[148:151], v[180:183], v[32:35]
	s_setprio 0
	v_mfma_f32_16x16x32_bf16 v[28:31], v[144:147], v[152:155], v[28:31]
	v_mfma_f32_16x16x32_bf16 v[24:27], v[188:191], v[152:155], v[24:27]
	v_mfma_f32_16x16x32_bf16 v[20:23], v[144:147], v[160:163], v[20:23]
	v_mfma_f32_16x16x32_bf16 v[16:19], v[188:191], v[160:163], v[16:19]
	v_mfma_f32_16x16x32_bf16 v[12:15], v[144:147], v[168:171], v[12:15]
	v_mfma_f32_16x16x32_bf16 v[8:11], v[188:191], v[168:171], v[8:11]
	v_mfma_f32_16x16x32_bf16 v[4:7], v[144:147], v[176:179], v[4:7]
	v_mfma_f32_16x16x32_bf16 v[0:3], v[188:191], v[176:179], v[0:3]
	v_mfma_f32_16x16x32_bf16 v[28:31], v[184:187], v[156:159], v[28:31]
	v_mfma_f32_16x16x32_bf16 v[24:27], v[194:197], v[156:159], v[24:27]
	v_mfma_f32_16x16x32_bf16 v[20:23], v[184:187], v[164:167], v[20:23]
	v_mfma_f32_16x16x32_bf16 v[16:19], v[194:197], v[164:167], v[16:19]
	v_mfma_f32_16x16x32_bf16 v[12:15], v[184:187], v[172:175], v[12:15]
	v_mfma_f32_16x16x32_bf16 v[8:11], v[194:197], v[172:175], v[8:11]
	v_mfma_f32_16x16x32_bf16 v[4:7], v[184:187], v[180:183], v[4:7]
	v_mfma_f32_16x16x32_bf16 v[0:3], v[194:197], v[180:183], v[0:3]
	s_setprio 0
	s_barrier
	ds_read_b128 v[140:143], v138 offset:32768
	ds_read_b128 v[152:155], v138 offset:33792
	ds_read_b128 v[156:159], v138 offset:34816
	ds_read_b128 v[160:163], v138 offset:35840
	ds_read_b128 v[164:167], v137 offset:32768
	ds_read_b128 v[168:171], v137 offset:33792
	ds_read_b128 v[172:175], v137 offset:34816
	ds_read_b128 v[176:179], v137 offset:35840
	ds_read_b128 v[180:183], v137 offset:36864
	ds_read_b128 v[184:187], v137 offset:37888
	ds_read_b128 v[188:191], v137 offset:38912
	ds_read_b128 v[194:197], v137 offset:39936
	s_waitcnt vmcnt(2)
	s_barrier
; #define WAIT_V(n) asm volatile("s_waitcnt vmcnt(" #n ")" ::: "memory")
; #define WAIT_L(n) asm volatile("s_waitcnt lgkmcnt(" #n ")" ::: "memory")
; #define BAR __builtin_amdgcn_s_barrier()
; #define LDA(dst, b, h) _Pragma("unroll") for (int m = 0; m < 4; ++m) _Pragma("unroll") for (int k = 0; k < 2; ++k) \
;     dst[m][k] = *reinterpret_cast<const bf16x8*>((char*)shm + abase + (((b) * 2 + (h)) * 16384 + (m * 2 + k) * 1024))
; #define LDB(dst, b, h) _Pragma("unroll") for (int n = 0; n < 2; ++n) _Pragma("unroll") for (int k = 0; k < 2; ++k) \
;     dst[n][k] = *reinterpret_cast<const bf16x8*>((char*)shm + bbase + (((b) * 2 + (h)) * 16384 + (n * 2 + k) * 1024))
; template <bool SWAP>
; __device__ __forceinline__ void gemm_main(const u16* __restrict__ A, const u16* __restrict__ Bt, int brow, int bcol,
;                                           u16* shm, f32x4 (&acc)[2][2][4][2]) {
;     ...
;   { LDB(B0, 1, 0); LDA(At, 1, 0); WAIT_V(2); BAR; WAIT_L(0); MMA(0, 0, At, B0); BAR;
;     LDB(B1, 1, 1); WAIT_V(0); BAR; WAIT_L(0); MMA(0, 1, At, B1); BAR;
;     LDA(At, 1, 1); BAR; WAIT_L(0); MMA(1, 0, At, B0); MMA(1, 1, At, B1); BAR; }
;   if (wr == 0) BAR;
	s_waitcnt lgkmcnt(0)
	v_mfma_f32_16x16x32_bf16 v[124:127], v[140:143], v[164:167], v[124:127]
	v_mfma_f32_16x16x32_bf16 v[120:123], v[156:159], v[164:167], v[120:123]
	v_mfma_f32_16x16x32_bf16 v[116:119], v[140:143], v[172:175], v[116:119]
	v_mfma_f32_16x16x32_bf16 v[112:115], v[156:159], v[172:175], v[112:115]
	v_mfma_f32_16x16x32_bf16 v[108:111], v[140:143], v[180:183], v[108:111]
	v_mfma_f32_16x16x32_bf16 v[104:107], v[156:159], v[180:183], v[104:107]
	v_mfma_f32_16x16x32_bf16 v[100:103], v[140:143], v[188:191], v[100:103]
	v_mfma_f32_16x16x32_bf16 v[96:99], v[156:159], v[188:191], v[96:99]
	v_mfma_f32_16x16x32_bf16 v[148:151], v[152:155], v[168:171], v[124:127]
	v_mfma_f32_16x16x32_bf16 v[144:147], v[160:163], v[168:171], v[120:123]
	v_mfma_f32_16x16x32_bf16 v[132:135], v[152:155], v[176:179], v[116:119]
	v_mfma_f32_16x16x32_bf16 v[128:131], v[160:163], v[176:179], v[112:115]
	v_mfma_f32_16x16x32_bf16 v[116:119], v[152:155], v[184:187], v[108:111]
	v_mfma_f32_16x16x32_bf16 v[112:115], v[160:163], v[184:187], v[104:107]
	v_mfma_f32_16x16x32_bf16 v[100:103], v[152:155], v[194:197], v[100:103]
	v_mfma_f32_16x16x32_bf16 v[96:99], v[160:163], v[194:197], v[96:99]
	s_setprio 0
	s_barrier
	ds_read_b128 v[104:107], v138 offset:49152
	ds_read_b128 v[108:111], v138 offset:50176
	ds_read_b128 v[120:123], v138 offset:51200
	ds_read_b128 v[124:127], v138 offset:52224
	s_waitcnt vmcnt(0)
	s_barrier
	s_waitcnt lgkmcnt(0)
	v_mfma_f32_16x16x32_bf16 v[92:95], v[104:107], v[164:167], v[92:95]
	v_mfma_f32_16x16x32_bf16 v[88:91], v[120:123], v[164:167], v[88:91]
	v_mfma_f32_16x16x32_bf16 v[84:87], v[104:107], v[172:175], v[84:87]
	v_mfma_f32_16x16x32_bf16 v[80:83], v[120:123], v[172:175], v[80:83]
	v_mfma_f32_16x16x32_bf16 v[76:79], v[104:107], v[180:183], v[76:79]
	v_mfma_f32_16x16x32_bf16 v[72:75], v[120:123], v[180:183], v[72:75]
	v_mfma_f32_16x16x32_bf16 v[68:71], v[104:107], v[188:191], v[68:71]
	v_mfma_f32_16x16x32_bf16 v[64:67], v[120:123], v[188:191], v[64:67]
	v_mfma_f32_16x16x32_bf16 v[92:95], v[108:111], v[168:171], v[92:95]
	v_mfma_f32_16x16x32_bf16 v[88:91], v[124:127], v[168:171], v[88:91]
	v_mfma_f32_16x16x32_bf16 v[84:87], v[108:111], v[176:179], v[84:87]
	v_mfma_f32_16x16x32_bf16 v[80:83], v[124:127], v[176:179], v[80:83]
	v_mfma_f32_16x16x32_bf16 v[76:79], v[108:111], v[184:187], v[76:79]
	v_mfma_f32_16x16x32_bf16 v[72:75], v[124:127], v[184:187], v[72:75]
	v_mfma_f32_16x16x32_bf16 v[68:71], v[108:111], v[194:197], v[68:71]
	v_mfma_f32_16x16x32_bf16 v[64:67], v[124:127], v[194:197], v[64:67]
	s_setprio 0
	s_barrier
	ds_read_b128 v[164:167], v137 offset:49152
	ds_read_b128 v[168:171], v137 offset:50176
	ds_read_b128 v[172:175], v137 offset:51200
	ds_read_b128 v[176:179], v137 offset:52224
	ds_read_b128 v[180:183], v137 offset:53248
	ds_read_b128 v[184:187], v137 offset:54272
	ds_read_b128 v[188:191], v137 offset:55296
	ds_read_b128 v[194:197], v137 offset:56320
	s_barrier
	s_waitcnt lgkmcnt(0)
	v_mfma_f32_16x16x32_bf16 v[60:63], v[140:143], v[164:167], v[60:63]
	v_mfma_f32_16x16x32_bf16 v[56:59], v[156:159], v[164:167], v[56:59]
	v_mfma_f32_16x16x32_bf16 v[52:55], v[140:143], v[172:175], v[52:55]
	v_mfma_f32_16x16x32_bf16 v[48:51], v[156:159], v[172:175], v[48:51]
	v_mfma_f32_16x16x32_bf16 v[44:47], v[140:143], v[180:183], v[44:47]
	v_mfma_f32_16x16x32_bf16 v[40:43], v[156:159], v[180:183], v[40:43]
	v_mfma_f32_16x16x32_bf16 v[36:39], v[140:143], v[188:191], v[36:39]
	v_mfma_f32_16x16x32_bf16 v[32:35], v[156:159], v[188:191], v[32:35]
	v_mfma_f32_16x16x32_bf16 v[60:63], v[152:155], v[168:171], v[60:63]
	v_mfma_f32_16x16x32_bf16 v[56:59], v[160:163], v[168:171], v[56:59]
	v_mfma_f32_16x16x32_bf16 v[52:55], v[152:155], v[176:179], v[52:55]
	v_mfma_f32_16x16x32_bf16 v[48:51], v[160:163], v[176:179], v[48:51]
	v_mfma_f32_16x16x32_bf16 v[44:47], v[152:155], v[184:187], v[44:47]
	v_mfma_f32_16x16x32_bf16 v[40:43], v[160:163], v[184:187], v[40:43]
	v_mfma_f32_16x16x32_bf16 v[36:39], v[152:155], v[194:197], v[36:39]
	v_mfma_f32_16x16x32_bf16 v[32:35], v[160:163], v[194:197], v[32:35]
	s_setprio 0
	v_mfma_f32_16x16x32_bf16 v[28:31], v[104:107], v[164:167], v[28:31]
	v_mfma_f32_16x16x32_bf16 v[24:27], v[120:123], v[164:167], v[24:27]
	v_mfma_f32_16x16x32_bf16 v[20:23], v[104:107], v[172:175], v[20:23]
	v_mfma_f32_16x16x32_bf16 v[16:19], v[120:123], v[172:175], v[16:19]
	v_mfma_f32_16x16x32_bf16 v[12:15], v[104:107], v[180:183], v[12:15]
	v_mfma_f32_16x16x32_bf16 v[8:11], v[120:123], v[180:183], v[8:11]
	v_mfma_f32_16x16x32_bf16 v[4:7], v[104:107], v[188:191], v[4:7]
	v_mfma_f32_16x16x32_bf16 v[0:3], v[120:123], v[188:191], v[0:3]
	v_mfma_f32_16x16x32_bf16 v[28:31], v[108:111], v[168:171], v[28:31]
	v_mfma_f32_16x16x32_bf16 v[24:27], v[124:127], v[168:171], v[24:27]
	v_mfma_f32_16x16x32_bf16 v[20:23], v[108:111], v[176:179], v[20:23]
	v_mfma_f32_16x16x32_bf16 v[16:19], v[124:127], v[176:179], v[16:19]
	v_mfma_f32_16x16x32_bf16 v[12:15], v[108:111], v[184:187], v[12:15]
	v_mfma_f32_16x16x32_bf16 v[8:11], v[124:127], v[184:187], v[8:11]
	v_mfma_f32_16x16x32_bf16 v[4:7], v[108:111], v[194:197], v[4:7]
	v_mfma_f32_16x16x32_bf16 v[0:3], v[124:127], v[194:197], v[0:3]
	s_setprio 0
	s_movk_i32 s3, 0x100
	v_cmp_gt_u32_e32 vcc, s3, v136
	s_barrier
	s_and_saveexec_b64 s[4:5], vcc
	s_cbranch_execz .LBB0_573
	s_barrier

; #define WAIT_V(n) asm volatile("s_waitcnt vmcnt(" #n ")" ::: "memory")
; #define WAIT_L(n) asm volatile("s_waitcnt lgkmcnt(" #n ")" ::: "memory")
; #define BAR __builtin_amdgcn_s_barrier()
; #define SCHED __builtin_amdgcn_sched_barrier(0)
; #define STAGE(P, BASE, br, kt) do { const char* _g = (const char*)((BASE) + (size_t)(br) * GK + (kt) * BK); \
;     __builtin_amdgcn_global_load_lds((const unsigned*)(_g + voff0), (unsigned*)((char*)(P) + tx * 16), 16, 0, 0); \
;     __builtin_amdgcn_global_load_lds((const unsigned*)(_g + voff1), (unsigned*)((char*)(P) + tx * 16 + 8192), 16, 0, 0); } while (0)
; #define LDA(dst, b, h) _Pragma("unroll") for (int m = 0; m < 4; ++m) _Pragma("unroll") for (int k = 0; k < 2; ++k) \
;     dst[m][k] = *reinterpret_cast<const bf16x8*>((char*)shm + abase + (((b) * 2 + (h)) * 16384 + (m * 2 + k) * 1024))
; #define LDB(dst, b, h) _Pragma("unroll") for (int n = 0; n < 2; ++n) _Pragma("unroll") for (int k = 0; k < 2; ++k) \
;     dst[n][k] = *reinterpret_cast<const bf16x8*>((char*)shm + bbase + (((b) * 2 + (h)) * 16384 + (n * 2 + k) * 1024))
; template <bool SWAP>
; __device__ __forceinline__ void gemm_main(const u16* __restrict__ A, const u16* __restrict__ Bt, int brow, int bcol,
;                                           u16* shm, f32x4 (&acc)[2][2][4][2]) {
;     ...
;     LDB(B0, 0, 0); SCHED; LDA(At, 0, 0); STAGE(SA(1, 1), A, brow + HALF, t + 1);
;     WAIT_L(8); BAR; WAIT_L(0); MMA(0, 0, At, B0); BAR; SCHED;
;     LDB(B1, 0, 1); STAGE(SB(0, 0), Bt, bcol, t + 2);
;     BAR; WAIT_L(0); MMA(0, 1, At, B1); BAR;
;     LDA(At, 0, 1); STAGE(SA(0, 0), A, brow, t + 2);
;     BAR; WAIT_L(0); MMA(1, 0, At, B0); BAR; SCHED;
;     STAGE(SB(0, 1), Bt, bcol + HALF, t + 2);
;     WAIT_V(6); BAR; MMA(1, 1, At, B1); BAR;
.LBB0_576:
	ds_read_b128 v[168:171], v137 offset:1024
	ds_read_b128 v[176:179], v137 offset:3072
	ds_read_b128 v[184:187], v137 offset:5120
	ds_read_b128 v[194:197], v137 offset:7168
	v_add_u32_e32 v192, 0, v140
	v_add_u32_e32 v146, 0xc000, v192
	v_add_u32_e32 v147, 0xe000, v192
	s_add_u32 m0, s3, 0xc000
	v_lshl_add_u64 v[232:233], s[4:5], 0, v[134:135]
	s_add_u32 vcc_lo, s4, s10
	s_addc_u32 vcc_hi, s5, s11
	global_load_lds_dwordx4 v132, vcc
	s_add_u32 m0, s3, 0xe000
	s_nop 0
	global_load_lds_dwordx4 v134, vcc
	s_waitcnt lgkmcnt(8)
	s_barrier
	s_waitcnt lgkmcnt(0)
	v_mfma_f32_16x16x32_bf16 v[124:127], v[148:151], v[164:167], v[124:127]
	v_mfma_f32_16x16x32_bf16 v[120:123], v[156:159], v[164:167], v[120:123]
	v_mfma_f32_16x16x32_bf16 v[116:119], v[148:151], v[172:175], v[116:119]
	v_mfma_f32_16x16x32_bf16 v[112:115], v[156:159], v[172:175], v[112:115]
	v_mfma_f32_16x16x32_bf16 v[108:111], v[148:151], v[180:183], v[108:111]
	v_mfma_f32_16x16x32_bf16 v[104:107], v[156:159], v[180:183], v[104:107]
	v_mfma_f32_16x16x32_bf16 v[100:103], v[148:151], v[188:191], v[100:103]
	v_mfma_f32_16x16x32_bf16 v[96:99], v[156:159], v[188:191], v[96:99]
	v_mfma_f32_16x16x32_bf16 v[124:127], v[152:155], v[168:171], v[124:127]
	v_mfma_f32_16x16x32_bf16 v[120:123], v[160:163], v[168:171], v[120:123]
	v_mfma_f32_16x16x32_bf16 v[116:119], v[152:155], v[176:179], v[116:119]
	v_mfma_f32_16x16x32_bf16 v[112:115], v[160:163], v[176:179], v[112:115]
	v_mfma_f32_16x16x32_bf16 v[108:111], v[152:155], v[184:187], v[108:111]
	v_mfma_f32_16x16x32_bf16 v[104:107], v[160:163], v[184:187], v[104:107]
	v_mfma_f32_16x16x32_bf16 v[100:103], v[152:155], v[194:197], v[100:103]
	v_mfma_f32_16x16x32_bf16 v[96:99], v[160:163], v[194:197], v[96:99]
	s_barrier
	ds_read_b128 v[198:201], v138 offset:16384
	ds_read_b128 v[202:205], v138 offset:17408
	ds_read_b128 v[206:209], v138 offset:18432
	ds_read_b128 v[226:229], v138 offset:19456
	v_lshl_add_u64 v[234:235], s[4:5], 0, v[128:129]
	s_add_u32 m0, s3, s28
	s_nop 0
	s_add_u32 vcc_lo, s4, s12
	s_addc_u32 vcc_hi, s5, s13
	global_load_lds_dwordx4 v128, vcc
	v_lshl_add_u64 v[236:237], s[4:5], 0, v[130:131]
	s_add_u32 m0, s3, s28
	s_add_u32 m0, m0, 0x2000
	s_nop 0
	global_load_lds_dwordx4 v130, vcc
	s_barrier
	s_waitcnt lgkmcnt(0)
	v_mfma_f32_16x16x32_bf16 v[92:95], v[198:201], v[164:167], v[92:95]
	v_mfma_f32_16x16x32_bf16 v[88:91], v[206:209], v[164:167], v[88:91]
	v_mfma_f32_16x16x32_bf16 v[84:87], v[198:201], v[172:175], v[84:87]
	v_mfma_f32_16x16x32_bf16 v[80:83], v[206:209], v[172:175], v[80:83]
	v_mfma_f32_16x16x32_bf16 v[76:79], v[198:201], v[180:183], v[76:79]
	v_mfma_f32_16x16x32_bf16 v[72:75], v[206:209], v[180:183], v[72:75]
	v_mfma_f32_16x16x32_bf16 v[68:71], v[198:201], v[188:191], v[68:71]
	v_mfma_f32_16x16x32_bf16 v[64:67], v[206:209], v[188:191], v[64:67]
	v_mfma_f32_16x16x32_bf16 v[92:95], v[202:205], v[168:171], v[92:95]
	ds_read_b128 v[164:167], v137 offset:16384
	v_mfma_f32_16x16x32_bf16 v[88:91], v[226:229], v[168:171], v[88:91]
	v_mfma_f32_16x16x32_bf16 v[84:87], v[202:205], v[176:179], v[84:87]
	ds_read_b128 v[172:175], v137 offset:18432
	v_mfma_f32_16x16x32_bf16 v[80:83], v[226:229], v[176:179], v[80:83]
	v_mfma_f32_16x16x32_bf16 v[76:79], v[202:205], v[184:187], v[76:79]
	ds_read_b128 v[180:183], v137 offset:20480
	v_mfma_f32_16x16x32_bf16 v[72:75], v[226:229], v[184:187], v[72:75]
	v_mfma_f32_16x16x32_bf16 v[68:71], v[202:205], v[194:197], v[68:71]
	ds_read_b128 v[188:191], v137 offset:22528
	v_mfma_f32_16x16x32_bf16 v[64:67], v[226:229], v[194:197], v[64:67]
	s_barrier
	ds_read_b128 v[168:171], v137 offset:17408
	ds_read_b128 v[176:179], v137 offset:19456
	ds_read_b128 v[184:187], v137 offset:21504
	ds_read_b128 v[194:197], v137 offset:23552
	s_add_u32 m0, s3, 0x0
	s_nop 0
	s_add_u32 vcc_lo, s4, s14
	s_addc_u32 vcc_hi, s5, s15
	global_load_lds_dwordx4 v132, vcc
	s_add_u32 m0, s3, 0x2000
	s_nop 0
	global_load_lds_dwordx4 v134, vcc
	s_waitcnt vmcnt(8)
	s_barrier
	s_waitcnt lgkmcnt(0)
	v_mfma_f32_16x16x32_bf16 v[60:63], v[148:151], v[164:167], v[60:63]
	v_mfma_f32_16x16x32_bf16 v[56:59], v[156:159], v[164:167], v[56:59]
	v_mfma_f32_16x16x32_bf16 v[52:55], v[148:151], v[172:175], v[52:55]
	v_mfma_f32_16x16x32_bf16 v[48:51], v[156:159], v[172:175], v[48:51]
	v_mfma_f32_16x16x32_bf16 v[44:47], v[148:151], v[180:183], v[44:47]
	v_mfma_f32_16x16x32_bf16 v[40:43], v[156:159], v[180:183], v[40:43]
	v_mfma_f32_16x16x32_bf16 v[36:39], v[148:151], v[188:191], v[36:39]
	v_mfma_f32_16x16x32_bf16 v[32:35], v[156:159], v[188:191], v[32:35]
	v_mfma_f32_16x16x32_bf16 v[60:63], v[152:155], v[168:171], v[60:63]
	v_mfma_f32_16x16x32_bf16 v[56:59], v[160:163], v[168:171], v[56:59]
	v_mfma_f32_16x16x32_bf16 v[52:55], v[152:155], v[176:179], v[52:55]
	v_mfma_f32_16x16x32_bf16 v[48:51], v[160:163], v[176:179], v[48:51]
	v_mfma_f32_16x16x32_bf16 v[44:47], v[152:155], v[184:187], v[44:47]
	v_mfma_f32_16x16x32_bf16 v[40:43], v[160:163], v[184:187], v[40:43]
	v_mfma_f32_16x16x32_bf16 v[36:39], v[152:155], v[194:197], v[36:39]
	v_mfma_f32_16x16x32_bf16 v[32:35], v[160:163], v[194:197], v[32:35]
	s_barrier
	ds_read_b128 v[148:151], v138 offset:32768
	ds_read_b128 v[152:155], v138 offset:33792
	ds_read_b128 v[156:159], v138 offset:34816
	ds_read_b128 v[160:163], v138 offset:35840
	s_add_u32 m0, s3, s29
	s_nop 0
	s_add_u32 vcc_lo, s4, s80
	s_addc_u32 vcc_hi, s5, s81
	global_load_lds_dwordx4 v128, vcc
	s_add_u32 m0, s3, s29
	s_add_u32 m0, m0, 0x2000
	s_nop 0
	global_load_lds_dwordx4 v130, vcc
	s_waitcnt vmcnt(6)
	s_barrier
; #define WAIT_V(n) asm volatile("s_waitcnt vmcnt(" #n ")" ::: "memory")
; #define WAIT_L(n) asm volatile("s_waitcnt lgkmcnt(" #n ")" ::: "memory")
; #define BAR __builtin_amdgcn_s_barrier()
; #define SCHED __builtin_amdgcn_sched_barrier(0)
; #define STAGE(P, BASE, br, kt) do { const char* _g = (const char*)((BASE) + (size_t)(br) * GK + (kt) * BK); \
;     __builtin_amdgcn_global_load_lds((const unsigned*)(_g + voff0), (unsigned*)((char*)(P) + tx * 16), 16, 0, 0); \
;     __builtin_amdgcn_global_load_lds((const unsigned*)(_g + voff1), (unsigned*)((char*)(P) + tx * 16 + 8192), 16, 0, 0); } while (0)
; #define LDA(dst, b, h) _Pragma("unroll") for (int m = 0; m < 4; ++m) _Pragma("unroll") for (int k = 0; k < 2; ++k) \
;     dst[m][k] = *reinterpret_cast<const bf16x8*>((char*)shm + abase + (((b) * 2 + (h)) * 16384 + (m * 2 + k) * 1024))
; #define LDB(dst, b, h) _Pragma("unroll") for (int n = 0; n < 2; ++n) _Pragma("unroll") for (int k = 0; k < 2; ++k) \
;     dst[n][k] = *reinterpret_cast<const bf16x8*>((char*)shm + bbase + (((b) * 2 + (h)) * 16384 + (n * 2 + k) * 1024))
; template <bool SWAP>
; __device__ __forceinline__ void gemm_main(const u16* __restrict__ A, const u16* __restrict__ Bt, int brow, int bcol,
;                                           u16* shm, f32x4 (&acc)[2][2][4][2]) {
;     ...
;     WAIT_V(6); BAR; MMA(1, 1, At, B1); BAR;
;     LDB(B0, 1, 0); SCHED; LDA(At, 1, 0); STAGE(SA(0, 1), A, brow + HALF, t + 2);
;     WAIT_L(8); BAR; WAIT_L(0); MMA(0, 0, At, B0); BAR; SCHED;
;     LDB(B1, 1, 1); STAGE(SB(1, 0), Bt, bcol, t + 3);
;     BAR; WAIT_L(0); MMA(0, 1, At, B1); BAR;
;     LDA(At, 1, 1); STAGE(SA(1, 0), A, brow, t + 3);
	v_mfma_f32_16x16x32_bf16 v[28:31], v[198:201], v[164:167], v[28:31]
	v_mfma_f32_16x16x32_bf16 v[24:27], v[206:209], v[164:167], v[24:27]
	v_mfma_f32_16x16x32_bf16 v[20:23], v[198:201], v[172:175], v[20:23]
	v_mfma_f32_16x16x32_bf16 v[16:19], v[206:209], v[172:175], v[16:19]
	v_mfma_f32_16x16x32_bf16 v[12:15], v[198:201], v[180:183], v[12:15]
	v_mfma_f32_16x16x32_bf16 v[8:11], v[206:209], v[180:183], v[8:11]
	v_mfma_f32_16x16x32_bf16 v[4:7], v[198:201], v[188:191], v[4:7]
	v_mfma_f32_16x16x32_bf16 v[0:3], v[206:209], v[188:191], v[0:3]
	v_mfma_f32_16x16x32_bf16 v[28:31], v[202:205], v[168:171], v[28:31]
	ds_read_b128 v[164:167], v137 offset:32768
	v_mfma_f32_16x16x32_bf16 v[24:27], v[226:229], v[168:171], v[24:27]
	v_mfma_f32_16x16x32_bf16 v[20:23], v[202:205], v[176:179], v[20:23]
	ds_read_b128 v[172:175], v137 offset:34816
	v_mfma_f32_16x16x32_bf16 v[16:19], v[226:229], v[176:179], v[16:19]
	v_mfma_f32_16x16x32_bf16 v[12:15], v[202:205], v[184:187], v[12:15]
	ds_read_b128 v[180:183], v137 offset:36864
	v_mfma_f32_16x16x32_bf16 v[8:11], v[226:229], v[184:187], v[8:11]
	v_mfma_f32_16x16x32_bf16 v[4:7], v[202:205], v[194:197], v[4:7]
	ds_read_b128 v[188:191], v137 offset:38912
	v_mfma_f32_16x16x32_bf16 v[0:3], v[226:229], v[194:197], v[0:3]
	s_barrier
	ds_read_b128 v[168:171], v137 offset:33792
	ds_read_b128 v[176:179], v137 offset:35840
	ds_read_b128 v[184:187], v137 offset:37888
	ds_read_b128 v[194:197], v137 offset:39936
	s_add_u32 m0, s3, 0x4000
	s_nop 0
	s_add_u32 vcc_lo, s4, s66
	s_addc_u32 vcc_hi, s5, s67
	global_load_lds_dwordx4 v132, vcc
	s_add_u32 m0, s3, 0x6000
	s_nop 0
	global_load_lds_dwordx4 v134, vcc
	s_waitcnt lgkmcnt(8)
	s_barrier
	s_waitcnt lgkmcnt(0)
	v_mfma_f32_16x16x32_bf16 v[124:127], v[148:151], v[164:167], v[124:127]
	v_mfma_f32_16x16x32_bf16 v[120:123], v[156:159], v[164:167], v[120:123]
	v_mfma_f32_16x16x32_bf16 v[116:119], v[148:151], v[172:175], v[116:119]
	v_mfma_f32_16x16x32_bf16 v[112:115], v[156:159], v[172:175], v[112:115]
	v_mfma_f32_16x16x32_bf16 v[108:111], v[148:151], v[180:183], v[108:111]
	v_mfma_f32_16x16x32_bf16 v[104:107], v[156:159], v[180:183], v[104:107]
	v_mfma_f32_16x16x32_bf16 v[100:103], v[148:151], v[188:191], v[100:103]
	v_mfma_f32_16x16x32_bf16 v[96:99], v[156:159], v[188:191], v[96:99]
	v_mfma_f32_16x16x32_bf16 v[124:127], v[152:155], v[168:171], v[124:127]
	v_mfma_f32_16x16x32_bf16 v[120:123], v[160:163], v[168:171], v[120:123]
	v_mfma_f32_16x16x32_bf16 v[116:119], v[152:155], v[176:179], v[116:119]
	v_mfma_f32_16x16x32_bf16 v[112:115], v[160:163], v[176:179], v[112:115]
	v_mfma_f32_16x16x32_bf16 v[108:111], v[152:155], v[184:187], v[108:111]
	v_mfma_f32_16x16x32_bf16 v[104:107], v[160:163], v[184:187], v[104:107]
	v_mfma_f32_16x16x32_bf16 v[100:103], v[152:155], v[194:197], v[100:103]
	v_mfma_f32_16x16x32_bf16 v[96:99], v[160:163], v[194:197], v[96:99]
	s_barrier
	ds_read_b128 v[198:201], v138 offset:49152
	ds_read_b128 v[202:205], v138 offset:50176
	ds_read_b128 v[206:209], v138 offset:51200
	ds_read_b128 v[226:229], v138 offset:52224
	s_add_u32 m0, s3, s30
	s_nop 0
	s_add_u32 vcc_lo, s4, s86
	s_addc_u32 vcc_hi, s5, s87
	global_load_lds_dwordx4 v128, vcc
	v_lshl_add_u64 v[238:239], v[236:237], 0, s[86:87]
	s_add_u32 m0, s3, s30
	s_add_u32 m0, m0, 0x2000
	s_nop 0
	global_load_lds_dwordx4 v130, vcc
	s_barrier
	s_waitcnt lgkmcnt(0)
	v_mfma_f32_16x16x32_bf16 v[92:95], v[198:201], v[164:167], v[92:95]
	v_mfma_f32_16x16x32_bf16 v[88:91], v[206:209], v[164:167], v[88:91]
	v_mfma_f32_16x16x32_bf16 v[84:87], v[198:201], v[172:175], v[84:87]
	v_mfma_f32_16x16x32_bf16 v[80:83], v[206:209], v[172:175], v[80:83]
	v_mfma_f32_16x16x32_bf16 v[76:79], v[198:201], v[180:183], v[76:79]
	v_mfma_f32_16x16x32_bf16 v[72:75], v[206:209], v[180:183], v[72:75]
	v_mfma_f32_16x16x32_bf16 v[68:71], v[198:201], v[188:191], v[68:71]
	v_mfma_f32_16x16x32_bf16 v[64:67], v[206:209], v[188:191], v[64:67]
	v_mfma_f32_16x16x32_bf16 v[92:95], v[202:205], v[168:171], v[92:95]
	ds_read_b128 v[164:167], v137 offset:49152
	v_mfma_f32_16x16x32_bf16 v[88:91], v[226:229], v[168:171], v[88:91]
	v_mfma_f32_16x16x32_bf16 v[84:87], v[202:205], v[176:179], v[84:87]
	ds_read_b128 v[172:175], v137 offset:51200
	v_mfma_f32_16x16x32_bf16 v[80:83], v[226:229], v[176:179], v[80:83]
	v_mfma_f32_16x16x32_bf16 v[76:79], v[202:205], v[184:187], v[76:79]
	ds_read_b128 v[180:183], v137 offset:53248
	v_mfma_f32_16x16x32_bf16 v[72:75], v[226:229], v[184:187], v[72:75]
	v_mfma_f32_16x16x32_bf16 v[68:71], v[202:205], v[194:197], v[68:71]
	ds_read_b128 v[188:191], v137 offset:55296
	v_mfma_f32_16x16x32_bf16 v[64:67], v[226:229], v[194:197], v[64:67]
	s_barrier
	ds_read_b128 v[168:171], v137 offset:50176
	ds_read_b128 v[176:179], v137 offset:52224
	ds_read_b128 v[184:187], v137 offset:54272
	ds_read_b128 v[194:197], v137 offset:56320
	v_add_u32_e32 v225, 0x8000, v192
	s_add_u32 m0, s3, 0x8000
	s_nop 0
	s_add_u32 vcc_lo, s4, s26
	s_addc_u32 vcc_hi, s5, s27
	global_load_lds_dwordx4 v132, vcc
	v_lshl_add_u64 v[230:231], v[232:233], 0, s[26:27]
	s_add_u32 m0, s3, 0xa000
	s_nop 0
	global_load_lds_dwordx4 v134, vcc
	s_waitcnt vmcnt(8)
	s_barrier
; #define WAIT_V(n) asm volatile("s_waitcnt vmcnt(" #n ")" ::: "memory")
; #define WAIT_L(n) asm volatile("s_waitcnt lgkmcnt(" #n ")" ::: "memory")
; #define BAR __builtin_amdgcn_s_barrier()
; #define SCHED __builtin_amdgcn_sched_barrier(0)
; #define STAGE(P, BASE, br, kt) do { const char* _g = (const char*)((BASE) + (size_t)(br) * GK + (kt) * BK); \
;     __builtin_amdgcn_global_load_lds((const unsigned*)(_g + voff0), (unsigned*)((char*)(P) + tx * 16), 16, 0, 0); \
;     __builtin_amdgcn_global_load_lds((const unsigned*)(_g + voff1), (unsigned*)((char*)(P) + tx * 16 + 8192), 16, 0, 0); } while (0)
; #define LDA(dst, b, h) _Pragma("unroll") for (int m = 0; m < 4; ++m) _Pragma("unroll") for (int k = 0; k < 2; ++k) \
;     dst[m][k] = *reinterpret_cast<const bf16x8*>((char*)shm + abase + (((b) * 2 + (h)) * 16384 + (m * 2 + k) * 1024))
; #define LDB(dst, b, h) _Pragma("unroll") for (int n = 0; n < 2; ++n) _Pragma("unroll") for (int k = 0; k < 2; ++k) \
;     dst[n][k] = *reinterpret_cast<const bf16x8*>((char*)shm + bbase + (((b) * 2 + (h)) * 16384 + (n * 2 + k) * 1024))
; template <bool SWAP>
; __device__ __forceinline__ void gemm_main(const u16* __restrict__ A, const u16* __restrict__ Bt, int brow, int bcol,
;                                           u16* shm, f32x4 (&acc)[2][2][4][2]) {
;     ...
;     BAR; WAIT_L(0); MMA(1, 0, At, B0); BAR; SCHED;
;     STAGE(SB(1, 1), Bt, bcol + HALF, t + 3);
;     WAIT_V(6); BAR; MMA(1, 1, At, B1); BAR;
;   }
;   { LDB(B0, 0, 0); LDA(At, 0, 0); STAGE(SA(1, 1), A, brow + HALF, nt - 1);
;     BAR; WAIT_L(0); MMA(0, 0, At, B0); BAR;
	s_waitcnt lgkmcnt(0)
	v_mfma_f32_16x16x32_bf16 v[60:63], v[148:151], v[164:167], v[60:63]
	v_mfma_f32_16x16x32_bf16 v[56:59], v[156:159], v[164:167], v[56:59]
	v_mfma_f32_16x16x32_bf16 v[52:55], v[148:151], v[172:175], v[52:55]
	v_mfma_f32_16x16x32_bf16 v[48:51], v[156:159], v[172:175], v[48:51]
	v_mfma_f32_16x16x32_bf16 v[44:47], v[148:151], v[180:183], v[44:47]
	v_mfma_f32_16x16x32_bf16 v[40:43], v[156:159], v[180:183], v[40:43]
	v_mfma_f32_16x16x32_bf16 v[36:39], v[148:151], v[188:191], v[36:39]
	v_mfma_f32_16x16x32_bf16 v[32:35], v[156:159], v[188:191], v[32:35]
	v_mfma_f32_16x16x32_bf16 v[60:63], v[152:155], v[168:171], v[60:63]
	v_mfma_f32_16x16x32_bf16 v[56:59], v[160:163], v[168:171], v[56:59]
	v_mfma_f32_16x16x32_bf16 v[52:55], v[152:155], v[176:179], v[52:55]
	v_mfma_f32_16x16x32_bf16 v[48:51], v[160:163], v[176:179], v[48:51]
	v_mfma_f32_16x16x32_bf16 v[44:47], v[152:155], v[184:187], v[44:47]
	v_mfma_f32_16x16x32_bf16 v[40:43], v[160:163], v[184:187], v[40:43]
	v_mfma_f32_16x16x32_bf16 v[36:39], v[152:155], v[194:197], v[36:39]
	v_mfma_f32_16x16x32_bf16 v[32:35], v[160:163], v[194:197], v[32:35]
	s_barrier
	ds_read_b128 v[148:151], v138
	ds_read_b128 v[152:155], v138 offset:1024
	ds_read_b128 v[156:159], v138 offset:2048
	ds_read_b128 v[160:163], v138 offset:3072
	s_add_u32 m0, s3, s31
	s_nop 0
	s_add_u32 vcc_lo, s4, s56
	s_addc_u32 vcc_hi, s5, s57
	global_load_lds_dwordx4 v128, vcc
	v_lshl_add_u64 v[254:255], v[236:237], 0, s[56:57]
	s_add_u32 m0, s3, s31
	s_add_u32 m0, m0, 0x2000
	s_nop 0
	global_load_lds_dwordx4 v130, vcc
	s_waitcnt vmcnt(6)
	s_barrier
	v_mfma_f32_16x16x32_bf16 v[28:31], v[198:201], v[164:167], v[28:31]
	v_mfma_f32_16x16x32_bf16 v[24:27], v[206:209], v[164:167], v[24:27]
	v_mfma_f32_16x16x32_bf16 v[20:23], v[198:201], v[172:175], v[20:23]
	v_mfma_f32_16x16x32_bf16 v[16:19], v[206:209], v[172:175], v[16:19]
	v_mfma_f32_16x16x32_bf16 v[12:15], v[198:201], v[180:183], v[12:15]
	v_mfma_f32_16x16x32_bf16 v[8:11], v[206:209], v[180:183], v[8:11]
	v_mfma_f32_16x16x32_bf16 v[4:7], v[198:201], v[188:191], v[4:7]
	v_mfma_f32_16x16x32_bf16 v[0:3], v[206:209], v[188:191], v[0:3]
	v_mfma_f32_16x16x32_bf16 v[28:31], v[202:205], v[168:171], v[28:31]
	ds_read_b128 v[164:167], v137
	v_mfma_f32_16x16x32_bf16 v[24:27], v[226:229], v[168:171], v[24:27]
	v_mfma_f32_16x16x32_bf16 v[20:23], v[202:205], v[176:179], v[20:23]
	ds_read_b128 v[172:175], v137 offset:2048
	v_mfma_f32_16x16x32_bf16 v[16:19], v[226:229], v[176:179], v[16:19]
	v_mfma_f32_16x16x32_bf16 v[12:15], v[202:205], v[184:187], v[12:15]
	ds_read_b128 v[180:183], v137 offset:4096
	v_mfma_f32_16x16x32_bf16 v[8:11], v[226:229], v[184:187], v[8:11]
	v_mfma_f32_16x16x32_bf16 v[4:7], v[202:205], v[194:197], v[4:7]
	ds_read_b128 v[188:191], v137 offset:6144
	v_mfma_f32_16x16x32_bf16 v[0:3], v[226:229], v[194:197], v[0:3]
	s_add_i32 s2, s2, 2
	s_add_u32 s4, s4, 0x100
	s_addc_u32 s5, s5, 0
	s_cmp_lt_u32 s2, 28
	s_barrier
	s_cbranch_scc1 .LBB0_576
	v_lshlrev_b32_e32 v128, 3, v139
	v_lshlrev_b32_e32 v129, 5, v139
	v_and_b32_e32 v128, 0xffff0, v128
	v_and_b32_e32 v129, 32, v129
	v_add_u32_e32 v129, v129, v142
	v_add_lshl_u32 v128, v141, v128, 12
	v_lshl_add_u32 v192, v129, 1, v128
	v_lshlrev_b32_e32 v128, 3, v143
	v_lshlrev_b32_e32 v129, 5, v143
	v_and_b32_e32 v128, 0xffff0, v128
	v_and_b32_e32 v129, 32, v129
	v_add_u32_e32 v129, v129, v145
	v_add_lshl_u32 v128, v144, v128, 12
	v_lshl_add_u32 v144, v129, 1, v128
	v_mov_b32_e32 v145, v193
	v_lshl_add_u64 v[184:185], s[0:1], 0, v[192:193]
	s_mov_b64 s[4:5], 0xf80
	v_readfirstlane_b32 s2, v146
	v_lshl_add_u64 v[184:185], v[184:185], 0, s[4:5]
	s_mov_b32 m0, s2
	v_lshl_add_u64 v[144:145], s[0:1], 0, v[144:145]
	v_readfirstlane_b32 s0, v147
	ds_read_b128 v[128:131], v138
	ds_read_b128 v[132:135], v138 offset:1024
	ds_read_b128 v[140:143], v138 offset:2048
	ds_read_b128 v[148:151], v138 offset:3072
	ds_read_b128 v[152:155], v137
	ds_read_b128 v[156:159], v137 offset:1024
	ds_read_b128 v[160:163], v137 offset:2048
	ds_read_b128 v[164:167], v137 offset:3072
	ds_read_b128 v[168:171], v137 offset:4096
	ds_read_b128 v[172:175], v137 offset:5120
	ds_read_b128 v[176:179], v137 offset:6144
	ds_read_b128 v[180:183], v137 offset:7168
	global_load_lds_dwordx4 v[184:185], off
	v_lshl_add_u64 v[144:145], v[144:145], 0, s[4:5]
	s_mov_b32 m0, s0
	s_nop 0
	global_load_lds_dwordx4 v[144:145], off
	s_barrier
	s_waitcnt lgkmcnt(0)
	v_mfma_f32_16x16x32_bf16 v[124:127], v[128:131], v[152:155], v[124:127]
	v_mfma_f32_16x16x32_bf16 v[120:123], v[140:143], v[152:155], v[120:123]
	v_mfma_f32_16x16x32_bf16 v[116:119], v[128:131], v[160:163], v[116:119]
	v_mfma_f32_16x16x32_bf16 v[112:115], v[140:143], v[160:163], v[112:115]
	v_mfma_f32_16x16x32_bf16 v[108:111], v[128:131], v[168:171], v[108:111]
	v_mfma_f32_16x16x32_bf16 v[104:107], v[140:143], v[168:171], v[104:107]
	v_mfma_f32_16x16x32_bf16 v[100:103], v[128:131], v[176:179], v[100:103]
	v_mfma_f32_16x16x32_bf16 v[96:99], v[140:143], v[176:179], v[96:99]
	v_mfma_f32_16x16x32_bf16 v[124:127], v[132:135], v[156:159], v[124:127]
	v_mfma_f32_16x16x32_bf16 v[120:123], v[148:151], v[156:159], v[120:123]
	v_mfma_f32_16x16x32_bf16 v[116:119], v[132:135], v[164:167], v[116:119]
	v_mfma_f32_16x16x32_bf16 v[112:115], v[148:151], v[164:167], v[112:115]
	v_mfma_f32_16x16x32_bf16 v[108:111], v[132:135], v[172:175], v[108:111]
	v_mfma_f32_16x16x32_bf16 v[104:107], v[148:151], v[172:175], v[104:107]
	v_mfma_f32_16x16x32_bf16 v[100:103], v[132:135], v[180:183], v[100:103]
	v_mfma_f32_16x16x32_bf16 v[96:99], v[148:151], v[180:183], v[96:99]
	s_setprio 0
	s_barrier
; #define WAIT_V(n) asm volatile("s_waitcnt vmcnt(" #n ")" ::: "memory")
; #define WAIT_L(n) asm volatile("s_waitcnt lgkmcnt(" #n ")" ::: "memory")
; #define BAR __builtin_amdgcn_s_barrier()
; #define LDA(dst, b, h) _Pragma("unroll") for (int m = 0; m < 4; ++m) _Pragma("unroll") for (int k = 0; k < 2; ++k) \
;     dst[m][k] = *reinterpret_cast<const bf16x8*>((char*)shm + abase + (((b) * 2 + (h)) * 16384 + (m * 2 + k) * 1024))
; #define LDB(dst, b, h) _Pragma("unroll") for (int n = 0; n < 2; ++n) _Pragma("unroll") for (int k = 0; k < 2; ++k) \
;     dst[n][k] = *reinterpret_cast<const bf16x8*>((char*)shm + bbase + (((b) * 2 + (h)) * 16384 + (n * 2 + k) * 1024))
; template <bool SWAP>
; __device__ __forceinline__ void gemm_main(const u16* __restrict__ A, const u16* __restrict__ Bt, int brow, int bcol,
;                                           u16* shm, f32x4 (&acc)[2][2][4][2]) {
;     ...
;     BAR; WAIT_L(0); MMA(0, 0, At, B0); BAR;
;     LDB(B1, 0, 1); BAR; WAIT_L(0); MMA(0, 1, At, B1); BAR;
;     LDA(At, 0, 1); WAIT_V(4); BAR; WAIT_L(0); MMA(1, 0, At, B0); MMA(1, 1, At, B1); BAR; }
;   { LDB(B0, 1, 0); LDA(At, 1, 0); WAIT_V(2); BAR; WAIT_L(0); MMA(0, 0, At, B0); BAR;
	ds_read_b128 v[144:147], v138 offset:16384
	ds_read_b128 v[184:187], v138 offset:17408
	ds_read_b128 v[188:191], v138 offset:18432
	ds_read_b128 v[194:197], v138 offset:19456
	s_barrier
	s_waitcnt lgkmcnt(0)
	v_mfma_f32_16x16x32_bf16 v[92:95], v[144:147], v[152:155], v[92:95]
	v_mfma_f32_16x16x32_bf16 v[88:91], v[188:191], v[152:155], v[88:91]
	v_mfma_f32_16x16x32_bf16 v[84:87], v[144:147], v[160:163], v[84:87]
	v_mfma_f32_16x16x32_bf16 v[80:83], v[188:191], v[160:163], v[80:83]
	v_mfma_f32_16x16x32_bf16 v[76:79], v[144:147], v[168:171], v[76:79]
	v_mfma_f32_16x16x32_bf16 v[72:75], v[188:191], v[168:171], v[72:75]
	v_mfma_f32_16x16x32_bf16 v[68:71], v[144:147], v[176:179], v[68:71]
	v_mfma_f32_16x16x32_bf16 v[64:67], v[188:191], v[176:179], v[64:67]
	v_mfma_f32_16x16x32_bf16 v[92:95], v[184:187], v[156:159], v[92:95]
	v_mfma_f32_16x16x32_bf16 v[88:91], v[194:197], v[156:159], v[88:91]
	v_mfma_f32_16x16x32_bf16 v[84:87], v[184:187], v[164:167], v[84:87]
	v_mfma_f32_16x16x32_bf16 v[80:83], v[194:197], v[164:167], v[80:83]
	v_mfma_f32_16x16x32_bf16 v[76:79], v[184:187], v[172:175], v[76:79]
	v_mfma_f32_16x16x32_bf16 v[72:75], v[194:197], v[172:175], v[72:75]
	v_mfma_f32_16x16x32_bf16 v[68:71], v[184:187], v[180:183], v[68:71]
	v_mfma_f32_16x16x32_bf16 v[64:67], v[194:197], v[180:183], v[64:67]
	s_setprio 0
	s_barrier
	ds_read_b128 v[152:155], v137 offset:16384
	ds_read_b128 v[156:159], v137 offset:17408
	ds_read_b128 v[160:163], v137 offset:18432
	ds_read_b128 v[164:167], v137 offset:19456
	ds_read_b128 v[168:171], v137 offset:20480
	ds_read_b128 v[172:175], v137 offset:21504
	ds_read_b128 v[176:179], v137 offset:22528
	ds_read_b128 v[180:183], v137 offset:23552
	s_waitcnt vmcnt(4)
	s_barrier
	s_waitcnt lgkmcnt(0)
	v_mfma_f32_16x16x32_bf16 v[60:63], v[128:131], v[152:155], v[60:63]
	v_mfma_f32_16x16x32_bf16 v[56:59], v[140:143], v[152:155], v[56:59]
	v_mfma_f32_16x16x32_bf16 v[52:55], v[128:131], v[160:163], v[52:55]
	v_mfma_f32_16x16x32_bf16 v[48:51], v[140:143], v[160:163], v[48:51]
	v_mfma_f32_16x16x32_bf16 v[44:47], v[128:131], v[168:171], v[44:47]
	v_mfma_f32_16x16x32_bf16 v[40:43], v[140:143], v[168:171], v[40:43]
	v_mfma_f32_16x16x32_bf16 v[36:39], v[128:131], v[176:179], v[36:39]
	v_mfma_f32_16x16x32_bf16 v[32:35], v[140:143], v[176:179], v[32:35]
	v_mfma_f32_16x16x32_bf16 v[60:63], v[132:135], v[156:159], v[60:63]
	v_mfma_f32_16x16x32_bf16 v[56:59], v[148:151], v[156:159], v[56:59]
	v_mfma_f32_16x16x32_bf16 v[52:55], v[132:135], v[164:167], v[52:55]
	v_mfma_f32_16x16x32_bf16 v[48:51], v[148:151], v[164:167], v[48:51]
	v_mfma_f32_16x16x32_bf16 v[44:47], v[132:135], v[172:175], v[44:47]
	v_mfma_f32_16x16x32_bf16 v[40:43], v[148:151], v[172:175], v[40:43]
	v_mfma_f32_16x16x32_bf16 v[36:39], v[132:135], v[180:183], v[36:39]
	v_mfma_f32_16x16x32_bf16 v[32:35], v[148:151], v[180:183], v[32:35]
	s_setprio 0
	v_mfma_f32_16x16x32_bf16 v[28:31], v[144:147], v[152:155], v[28:31]
	v_mfma_f32_16x16x32_bf16 v[24:27], v[188:191], v[152:155], v[24:27]
	v_mfma_f32_16x16x32_bf16 v[20:23], v[144:147], v[160:163], v[20:23]
	v_mfma_f32_16x16x32_bf16 v[16:19], v[188:191], v[160:163], v[16:19]
	v_mfma_f32_16x16x32_bf16 v[12:15], v[144:147], v[168:171], v[12:15]
	v_mfma_f32_16x16x32_bf16 v[8:11], v[188:191], v[168:171], v[8:11]
	v_mfma_f32_16x16x32_bf16 v[4:7], v[144:147], v[176:179], v[4:7]
	v_mfma_f32_16x16x32_bf16 v[0:3], v[188:191], v[176:179], v[0:3]
	v_mfma_f32_16x16x32_bf16 v[28:31], v[184:187], v[156:159], v[28:31]
	v_mfma_f32_16x16x32_bf16 v[24:27], v[194:197], v[156:159], v[24:27]
	v_mfma_f32_16x16x32_bf16 v[20:23], v[184:187], v[164:167], v[20:23]
	v_mfma_f32_16x16x32_bf16 v[16:19], v[194:197], v[164:167], v[16:19]
	v_mfma_f32_16x16x32_bf16 v[12:15], v[184:187], v[172:175], v[12:15]
	v_mfma_f32_16x16x32_bf16 v[8:11], v[194:197], v[172:175], v[8:11]
	v_mfma_f32_16x16x32_bf16 v[4:7], v[184:187], v[180:183], v[4:7]
	v_mfma_f32_16x16x32_bf16 v[0:3], v[194:197], v[180:183], v[0:3]
	s_setprio 0
	s_barrier
	ds_read_b128 v[128:131], v138 offset:32768
	ds_read_b128 v[132:135], v138 offset:33792
	ds_read_b128 v[140:143], v138 offset:34816
	ds_read_b128 v[144:147], v138 offset:35840
	ds_read_b128 v[148:151], v137 offset:32768
	ds_read_b128 v[152:155], v137 offset:33792
	ds_read_b128 v[156:159], v137 offset:34816
	ds_read_b128 v[160:163], v137 offset:35840
	ds_read_b128 v[164:167], v137 offset:36864
	ds_read_b128 v[168:171], v137 offset:37888
	ds_read_b128 v[172:175], v137 offset:38912
	ds_read_b128 v[176:179], v137 offset:39936
	s_waitcnt vmcnt(2)
	s_barrier
; #define WAIT_V(n) asm volatile("s_waitcnt vmcnt(" #n ")" ::: "memory")
; #define WAIT_L(n) asm volatile("s_waitcnt lgkmcnt(" #n ")" ::: "memory")
; #define BAR __builtin_amdgcn_s_barrier()
; #define LDA(dst, b, h) _Pragma("unroll") for (int m = 0; m < 4; ++m) _Pragma("unroll") for (int k = 0; k < 2; ++k) \
;     dst[m][k] = *reinterpret_cast<const bf16x8*>((char*)shm + abase + (((b) * 2 + (h)) * 16384 + (m * 2 + k) * 1024))
; #define LDB(dst, b, h) _Pragma("unroll") for (int n = 0; n < 2; ++n) _Pragma("unroll") for (int k = 0; k < 2; ++k) \
;     dst[n][k] = *reinterpret_cast<const bf16x8*>((char*)shm + bbase + (((b) * 2 + (h)) * 16384 + (n * 2 + k) * 1024))
; template <bool SWAP>
; __device__ __forceinline__ void gemm_main(const u16* __restrict__ A, const u16* __restrict__ Bt, int brow, int bcol,
;                                           u16* shm, f32x4 (&acc)[2][2][4][2]) {
;     ...
;   { LDB(B0, 1, 0); LDA(At, 1, 0); WAIT_V(2); BAR; WAIT_L(0); MMA(0, 0, At, B0); BAR;
;     LDB(B1, 1, 1); WAIT_V(0); BAR; WAIT_L(0); MMA(0, 1, At, B1); BAR;
;     LDA(At, 1, 1); BAR; WAIT_L(0); MMA(1, 0, At, B0); MMA(1, 1, At, B1); BAR; }
;   if (wr == 0) BAR;
	s_waitcnt lgkmcnt(0)
	v_mfma_f32_16x16x32_bf16 v[124:127], v[128:131], v[148:151], v[124:127]
	v_mfma_f32_16x16x32_bf16 v[120:123], v[140:143], v[148:151], v[120:123]
	v_mfma_f32_16x16x32_bf16 v[116:119], v[128:131], v[156:159], v[116:119]
	v_mfma_f32_16x16x32_bf16 v[112:115], v[140:143], v[156:159], v[112:115]
	v_mfma_f32_16x16x32_bf16 v[108:111], v[128:131], v[164:167], v[108:111]
	v_mfma_f32_16x16x32_bf16 v[104:107], v[140:143], v[164:167], v[104:107]
	v_mfma_f32_16x16x32_bf16 v[100:103], v[128:131], v[172:175], v[100:103]
	v_mfma_f32_16x16x32_bf16 v[96:99], v[140:143], v[172:175], v[96:99]
	v_mfma_f32_16x16x32_bf16 v[124:127], v[132:135], v[152:155], v[124:127]
	v_mfma_f32_16x16x32_bf16 v[120:123], v[144:147], v[152:155], v[120:123]
	v_mfma_f32_16x16x32_bf16 v[116:119], v[132:135], v[160:163], v[116:119]
	v_mfma_f32_16x16x32_bf16 v[112:115], v[144:147], v[160:163], v[112:115]
	v_mfma_f32_16x16x32_bf16 v[108:111], v[132:135], v[168:171], v[108:111]
	v_mfma_f32_16x16x32_bf16 v[104:107], v[144:147], v[168:171], v[104:107]
	v_mfma_f32_16x16x32_bf16 v[100:103], v[132:135], v[176:179], v[100:103]
	v_mfma_f32_16x16x32_bf16 v[96:99], v[144:147], v[176:179], v[96:99]
	s_setprio 0
	s_barrier
	ds_read_b128 v[180:183], v138 offset:49152
	ds_read_b128 v[184:187], v138 offset:50176
	ds_read_b128 v[188:191], v138 offset:51200
	ds_read_b128 v[194:197], v138 offset:52224
	s_waitcnt vmcnt(0)
	s_barrier
	s_waitcnt lgkmcnt(0)
	v_mfma_f32_16x16x32_bf16 v[92:95], v[180:183], v[148:151], v[92:95]
	v_mfma_f32_16x16x32_bf16 v[88:91], v[188:191], v[148:151], v[88:91]
	v_mfma_f32_16x16x32_bf16 v[84:87], v[180:183], v[156:159], v[84:87]
	v_mfma_f32_16x16x32_bf16 v[80:83], v[188:191], v[156:159], v[80:83]
	v_mfma_f32_16x16x32_bf16 v[76:79], v[180:183], v[164:167], v[76:79]
	v_mfma_f32_16x16x32_bf16 v[72:75], v[188:191], v[164:167], v[72:75]
	v_mfma_f32_16x16x32_bf16 v[68:71], v[180:183], v[172:175], v[68:71]
	v_mfma_f32_16x16x32_bf16 v[64:67], v[188:191], v[172:175], v[64:67]
	v_mfma_f32_16x16x32_bf16 v[92:95], v[184:187], v[152:155], v[92:95]
	v_mfma_f32_16x16x32_bf16 v[88:91], v[194:197], v[152:155], v[88:91]
	v_mfma_f32_16x16x32_bf16 v[84:87], v[184:187], v[160:163], v[84:87]
	v_mfma_f32_16x16x32_bf16 v[80:83], v[194:197], v[160:163], v[80:83]
	v_mfma_f32_16x16x32_bf16 v[76:79], v[184:187], v[168:171], v[76:79]
	v_mfma_f32_16x16x32_bf16 v[72:75], v[194:197], v[168:171], v[72:75]
	v_mfma_f32_16x16x32_bf16 v[68:71], v[184:187], v[176:179], v[68:71]
	v_mfma_f32_16x16x32_bf16 v[64:67], v[194:197], v[176:179], v[64:67]
	s_setprio 0
	s_barrier
	ds_read_b128 v[148:151], v137 offset:49152
	ds_read_b128 v[152:155], v137 offset:50176
	ds_read_b128 v[156:159], v137 offset:51200
	ds_read_b128 v[160:163], v137 offset:52224
	ds_read_b128 v[164:167], v137 offset:53248
	ds_read_b128 v[168:171], v137 offset:54272
	ds_read_b128 v[172:175], v137 offset:55296
	ds_read_b128 v[176:179], v137 offset:56320
	s_barrier
	s_waitcnt lgkmcnt(0)
	v_mfma_f32_16x16x32_bf16 v[60:63], v[128:131], v[148:151], v[60:63]
	v_mfma_f32_16x16x32_bf16 v[56:59], v[140:143], v[148:151], v[56:59]
	v_mfma_f32_16x16x32_bf16 v[52:55], v[128:131], v[156:159], v[52:55]
	v_mfma_f32_16x16x32_bf16 v[48:51], v[140:143], v[156:159], v[48:51]
	v_mfma_f32_16x16x32_bf16 v[44:47], v[128:131], v[164:167], v[44:47]
	v_mfma_f32_16x16x32_bf16 v[40:43], v[140:143], v[164:167], v[40:43]
	v_mfma_f32_16x16x32_bf16 v[36:39], v[128:131], v[172:175], v[36:39]
	v_mfma_f32_16x16x32_bf16 v[32:35], v[140:143], v[172:175], v[32:35]
	v_mfma_f32_16x16x32_bf16 v[60:63], v[132:135], v[152:155], v[60:63]
	v_mfma_f32_16x16x32_bf16 v[56:59], v[144:147], v[152:155], v[56:59]
	v_mfma_f32_16x16x32_bf16 v[52:55], v[132:135], v[160:163], v[52:55]
	v_mfma_f32_16x16x32_bf16 v[48:51], v[144:147], v[160:163], v[48:51]
	v_mfma_f32_16x16x32_bf16 v[44:47], v[132:135], v[168:171], v[44:47]
	v_mfma_f32_16x16x32_bf16 v[40:43], v[144:147], v[168:171], v[40:43]
	v_mfma_f32_16x16x32_bf16 v[36:39], v[132:135], v[176:179], v[36:39]
	v_mfma_f32_16x16x32_bf16 v[32:35], v[144:147], v[176:179], v[32:35]
	s_setprio 0
	v_mfma_f32_16x16x32_bf16 v[28:31], v[180:183], v[148:151], v[28:31]
	v_mfma_f32_16x16x32_bf16 v[24:27], v[188:191], v[148:151], v[24:27]
	v_mfma_f32_16x16x32_bf16 v[20:23], v[180:183], v[156:159], v[20:23]
	v_mfma_f32_16x16x32_bf16 v[16:19], v[188:191], v[156:159], v[16:19]
	v_mfma_f32_16x16x32_bf16 v[12:15], v[180:183], v[164:167], v[12:15]
	v_mfma_f32_16x16x32_bf16 v[8:11], v[188:191], v[164:167], v[8:11]
	v_mfma_f32_16x16x32_bf16 v[4:7], v[180:183], v[172:175], v[4:7]
	v_mfma_f32_16x16x32_bf16 v[0:3], v[188:191], v[172:175], v[0:3]
	v_mfma_f32_16x16x32_bf16 v[28:31], v[184:187], v[152:155], v[28:31]
	v_mfma_f32_16x16x32_bf16 v[24:27], v[194:197], v[152:155], v[24:27]
	v_mfma_f32_16x16x32_bf16 v[20:23], v[184:187], v[160:163], v[20:23]
	v_mfma_f32_16x16x32_bf16 v[16:19], v[194:197], v[160:163], v[16:19]
	v_mfma_f32_16x16x32_bf16 v[12:15], v[184:187], v[168:171], v[12:15]
	v_mfma_f32_16x16x32_bf16 v[8:11], v[194:197], v[168:171], v[8:11]
	v_mfma_f32_16x16x32_bf16 v[4:7], v[184:187], v[176:179], v[4:7]
	v_mfma_f32_16x16x32_bf16 v[0:3], v[194:197], v[176:179], v[0:3]
	s_setprio 0
	s_movk_i32 s0, 0x100
	v_cmp_gt_u32_e32 vcc, s0, v136
	s_barrier
	s_and_saveexec_b64 s[0:1], vcc
	s_cbranch_execz .LBB0_579
	s_barrier

; #define WAIT_V(n) asm volatile("s_waitcnt vmcnt(" #n ")" ::: "memory")
; #define WAIT_L(n) asm volatile("s_waitcnt lgkmcnt(" #n ")" ::: "memory")
; #define BAR __builtin_amdgcn_s_barrier()
; #define SCHED __builtin_amdgcn_sched_barrier(0)
; #define STAGE(P, BASE, br, kt) do { const char* _g = (const char*)((BASE) + (size_t)(br) * GK + (kt) * BK); \
;     __builtin_amdgcn_global_load_lds((const unsigned*)(_g + voff0), (unsigned*)((char*)(P) + tx * 16), 16, 0, 0); \
;     __builtin_amdgcn_global_load_lds((const unsigned*)(_g + voff1), (unsigned*)((char*)(P) + tx * 16 + 8192), 16, 0, 0); } while (0)
; #define LDA(dst, b, h) _Pragma("unroll") for (int m = 0; m < 4; ++m) _Pragma("unroll") for (int k = 0; k < 2; ++k) \
;     dst[m][k] = *reinterpret_cast<const bf16x8*>((char*)shm + abase + (((b) * 2 + (h)) * 16384 + (m * 2 + k) * 1024))
; #define LDB(dst, b, h) _Pragma("unroll") for (int n = 0; n < 2; ++n) _Pragma("unroll") for (int k = 0; k < 2; ++k) \
;     dst[n][k] = *reinterpret_cast<const bf16x8*>((char*)shm + bbase + (((b) * 2 + (h)) * 16384 + (n * 2 + k) * 1024))
; template <bool SWAP>
; __device__ __forceinline__ void gemm_main(const u16* __restrict__ A, const u16* __restrict__ Bt, int brow, int bcol,
;                                           u16* shm, f32x4 (&acc)[2][2][4][2]) {
;     ...
;     LDB(B0, 0, 0); SCHED; LDA(At, 0, 0); STAGE(SA(1, 1), A, brow + HALF, t + 1);
;     WAIT_L(8); BAR; WAIT_L(0); MMA(0, 0, At, B0); BAR; SCHED;
;     LDB(B1, 0, 1); STAGE(SB(0, 0), Bt, bcol, t + 2);
;     BAR; WAIT_L(0); MMA(0, 1, At, B1); BAR;
;     LDA(At, 0, 1); STAGE(SA(0, 0), A, brow, t + 2);
;     BAR; WAIT_L(0); MMA(1, 0, At, B0); BAR; SCHED;
;     STAGE(SB(0, 1), Bt, bcol + HALF, t + 2);
;     WAIT_V(6); BAR; MMA(1, 1, At, B1); BAR;
.LBB0_627:
	ds_read_b128 v[170:173], v139 offset:1024
	ds_read_b128 v[178:181], v139 offset:3072
	ds_read_b128 v[186:189], v139 offset:5120
	ds_read_b128 v[198:201], v139 offset:7168
	v_add_u32_e32 v192, 0, v142
	v_add_u32_e32 v148, 0xc000, v192
	v_add_u32_e32 v149, 0xe000, v192
	s_add_u32 m0, s9, 0xc000
	v_lshl_add_u64 v[232:233], s[4:5], 0, v[134:135]
	s_add_u32 vcc_lo, s4, s68
	s_addc_u32 vcc_hi, s5, s69
	global_load_lds_dwordx4 v132, vcc
	s_add_u32 m0, s9, 0xe000
	s_nop 0
	global_load_lds_dwordx4 v134, vcc
	s_waitcnt lgkmcnt(8)
	s_barrier
	s_waitcnt lgkmcnt(0)
	v_mfma_f32_16x16x32_bf16 v[124:127], v[150:153], v[166:169], v[124:127]
	v_mfma_f32_16x16x32_bf16 v[120:123], v[158:161], v[166:169], v[120:123]
	v_mfma_f32_16x16x32_bf16 v[116:119], v[150:153], v[174:177], v[116:119]
	v_mfma_f32_16x16x32_bf16 v[112:115], v[158:161], v[174:177], v[112:115]
	v_mfma_f32_16x16x32_bf16 v[108:111], v[150:153], v[182:185], v[108:111]
	v_mfma_f32_16x16x32_bf16 v[104:107], v[158:161], v[182:185], v[104:107]
	v_mfma_f32_16x16x32_bf16 v[100:103], v[150:153], v[194:197], v[100:103]
	v_mfma_f32_16x16x32_bf16 v[96:99], v[158:161], v[194:197], v[96:99]
	v_mfma_f32_16x16x32_bf16 v[124:127], v[154:157], v[170:173], v[124:127]
	v_mfma_f32_16x16x32_bf16 v[120:123], v[162:165], v[170:173], v[120:123]
	v_mfma_f32_16x16x32_bf16 v[116:119], v[154:157], v[178:181], v[116:119]
	v_mfma_f32_16x16x32_bf16 v[112:115], v[162:165], v[178:181], v[112:115]
	v_mfma_f32_16x16x32_bf16 v[108:111], v[154:157], v[186:189], v[108:111]
	v_mfma_f32_16x16x32_bf16 v[104:107], v[162:165], v[186:189], v[104:107]
	v_mfma_f32_16x16x32_bf16 v[100:103], v[154:157], v[198:201], v[100:103]
	v_mfma_f32_16x16x32_bf16 v[96:99], v[162:165], v[198:201], v[96:99]
	s_barrier
	ds_read_b128 v[202:205], v140 offset:16384
	ds_read_b128 v[206:209], v140 offset:17408
	ds_read_b128 v[224:227], v140 offset:18432
	ds_read_b128 v[228:231], v140 offset:19456
	v_lshl_add_u64 v[234:235], s[4:5], 0, v[128:129]
	s_add_u32 m0, s9, s28
	s_nop 0
	s_add_u32 vcc_lo, s4, s94
	s_addc_u32 vcc_hi, s5, s95
	global_load_lds_dwordx4 v128, vcc
	v_lshl_add_u64 v[236:237], s[4:5], 0, v[130:131]
	s_add_u32 m0, s9, s28
	s_add_u32 m0, m0, 0x2000
	s_nop 0
	global_load_lds_dwordx4 v130, vcc
	s_barrier
	s_waitcnt lgkmcnt(0)
	v_mfma_f32_16x16x32_bf16 v[92:95], v[202:205], v[166:169], v[92:95]
	v_mfma_f32_16x16x32_bf16 v[88:91], v[224:227], v[166:169], v[88:91]
	v_mfma_f32_16x16x32_bf16 v[84:87], v[202:205], v[174:177], v[84:87]
	v_mfma_f32_16x16x32_bf16 v[80:83], v[224:227], v[174:177], v[80:83]
	v_mfma_f32_16x16x32_bf16 v[76:79], v[202:205], v[182:185], v[76:79]
	v_mfma_f32_16x16x32_bf16 v[72:75], v[224:227], v[182:185], v[72:75]
	v_mfma_f32_16x16x32_bf16 v[68:71], v[202:205], v[194:197], v[68:71]
	v_mfma_f32_16x16x32_bf16 v[64:67], v[224:227], v[194:197], v[64:67]
	v_mfma_f32_16x16x32_bf16 v[92:95], v[206:209], v[170:173], v[92:95]
	ds_read_b128 v[166:169], v139 offset:16384
	v_mfma_f32_16x16x32_bf16 v[88:91], v[228:231], v[170:173], v[88:91]
	v_mfma_f32_16x16x32_bf16 v[84:87], v[206:209], v[178:181], v[84:87]
	ds_read_b128 v[174:177], v139 offset:18432
	v_mfma_f32_16x16x32_bf16 v[80:83], v[228:231], v[178:181], v[80:83]
	v_mfma_f32_16x16x32_bf16 v[76:79], v[206:209], v[186:189], v[76:79]
	ds_read_b128 v[182:185], v139 offset:20480
	v_mfma_f32_16x16x32_bf16 v[72:75], v[228:231], v[186:189], v[72:75]
	v_mfma_f32_16x16x32_bf16 v[68:71], v[206:209], v[198:201], v[68:71]
	ds_read_b128 v[194:197], v139 offset:22528
	v_mfma_f32_16x16x32_bf16 v[64:67], v[228:231], v[198:201], v[64:67]
	s_barrier
	ds_read_b128 v[170:173], v139 offset:17408
	ds_read_b128 v[178:181], v139 offset:19456
	ds_read_b128 v[186:189], v139 offset:21504
	ds_read_b128 v[198:201], v139 offset:23552
	s_add_u32 m0, s9, 0x0
	s_nop 0
	s_add_u32 vcc_lo, s4, s62
	s_addc_u32 vcc_hi, s5, s63
	global_load_lds_dwordx4 v132, vcc
	s_add_u32 m0, s9, 0x2000
	s_nop 0
	global_load_lds_dwordx4 v134, vcc
	s_waitcnt vmcnt(8)
	s_barrier
	s_waitcnt lgkmcnt(0)
	v_mfma_f32_16x16x32_bf16 v[60:63], v[150:153], v[166:169], v[60:63]
	v_mfma_f32_16x16x32_bf16 v[56:59], v[158:161], v[166:169], v[56:59]
	v_mfma_f32_16x16x32_bf16 v[52:55], v[150:153], v[174:177], v[52:55]
	v_mfma_f32_16x16x32_bf16 v[48:51], v[158:161], v[174:177], v[48:51]
	v_mfma_f32_16x16x32_bf16 v[44:47], v[150:153], v[182:185], v[44:47]
	v_mfma_f32_16x16x32_bf16 v[40:43], v[158:161], v[182:185], v[40:43]
	v_mfma_f32_16x16x32_bf16 v[36:39], v[150:153], v[194:197], v[36:39]
	v_mfma_f32_16x16x32_bf16 v[32:35], v[158:161], v[194:197], v[32:35]
	v_mfma_f32_16x16x32_bf16 v[60:63], v[154:157], v[170:173], v[60:63]
	v_mfma_f32_16x16x32_bf16 v[56:59], v[162:165], v[170:173], v[56:59]
	v_mfma_f32_16x16x32_bf16 v[52:55], v[154:157], v[178:181], v[52:55]
	v_mfma_f32_16x16x32_bf16 v[48:51], v[162:165], v[178:181], v[48:51]
	v_mfma_f32_16x16x32_bf16 v[44:47], v[154:157], v[186:189], v[44:47]
	v_mfma_f32_16x16x32_bf16 v[40:43], v[162:165], v[186:189], v[40:43]
	v_mfma_f32_16x16x32_bf16 v[36:39], v[154:157], v[198:201], v[36:39]
	v_mfma_f32_16x16x32_bf16 v[32:35], v[162:165], v[198:201], v[32:35]
	s_barrier
	ds_read_b128 v[150:153], v140 offset:32768
	ds_read_b128 v[154:157], v140 offset:33792
	ds_read_b128 v[158:161], v140 offset:34816
	ds_read_b128 v[162:165], v140 offset:35840
	s_add_u32 m0, s9, s29
	s_nop 0
	s_add_u32 vcc_lo, s4, s78
	s_addc_u32 vcc_hi, s5, s79
	global_load_lds_dwordx4 v128, vcc
	s_add_u32 m0, s9, s29
	s_add_u32 m0, m0, 0x2000
	s_nop 0
	global_load_lds_dwordx4 v130, vcc
	s_waitcnt vmcnt(6)
	s_barrier
; #define WAIT_V(n) asm volatile("s_waitcnt vmcnt(" #n ")" ::: "memory")
; #define WAIT_L(n) asm volatile("s_waitcnt lgkmcnt(" #n ")" ::: "memory")
; #define BAR __builtin_amdgcn_s_barrier()
; #define SCHED __builtin_amdgcn_sched_barrier(0)
; #define STAGE(P, BASE, br, kt) do { const char* _g = (const char*)((BASE) + (size_t)(br) * GK + (kt) * BK); \
;     __builtin_amdgcn_global_load_lds((const unsigned*)(_g + voff0), (unsigned*)((char*)(P) + tx * 16), 16, 0, 0); \
;     __builtin_amdgcn_global_load_lds((const unsigned*)(_g + voff1), (unsigned*)((char*)(P) + tx * 16 + 8192), 16, 0, 0); } while (0)
; #define LDA(dst, b, h) _Pragma("unroll") for (int m = 0; m < 4; ++m) _Pragma("unroll") for (int k = 0; k < 2; ++k) \
;     dst[m][k] = *reinterpret_cast<const bf16x8*>((char*)shm + abase + (((b) * 2 + (h)) * 16384 + (m * 2 + k) * 1024))
; #define LDB(dst, b, h) _Pragma("unroll") for (int n = 0; n < 2; ++n) _Pragma("unroll") for (int k = 0; k < 2; ++k) \
;     dst[n][k] = *reinterpret_cast<const bf16x8*>((char*)shm + bbase + (((b) * 2 + (h)) * 16384 + (n * 2 + k) * 1024))
; template <bool SWAP>
; __device__ __forceinline__ void gemm_main(const u16* __restrict__ A, const u16* __restrict__ Bt, int brow, int bcol,
;                                           u16* shm, f32x4 (&acc)[2][2][4][2]) {
;     ...
;     WAIT_V(6); BAR; MMA(1, 1, At, B1); BAR;
;     LDB(B0, 1, 0); SCHED; LDA(At, 1, 0); STAGE(SA(0, 1), A, brow + HALF, t + 2);
;     WAIT_L(8); BAR; WAIT_L(0); MMA(0, 0, At, B0); BAR; SCHED;
;     LDB(B1, 1, 1); STAGE(SB(1, 0), Bt, bcol, t + 3);
;     BAR; WAIT_L(0); MMA(0, 1, At, B1); BAR;
;     LDA(At, 1, 1); STAGE(SA(1, 0), A, brow, t + 3);
	v_mfma_f32_16x16x32_bf16 v[28:31], v[202:205], v[166:169], v[28:31]
	v_mfma_f32_16x16x32_bf16 v[24:27], v[224:227], v[166:169], v[24:27]
	v_mfma_f32_16x16x32_bf16 v[20:23], v[202:205], v[174:177], v[20:23]
	v_mfma_f32_16x16x32_bf16 v[16:19], v[224:227], v[174:177], v[16:19]
	v_mfma_f32_16x16x32_bf16 v[12:15], v[202:205], v[182:185], v[12:15]
	v_mfma_f32_16x16x32_bf16 v[8:11], v[224:227], v[182:185], v[8:11]
	v_mfma_f32_16x16x32_bf16 v[4:7], v[202:205], v[194:197], v[4:7]
	v_mfma_f32_16x16x32_bf16 v[0:3], v[224:227], v[194:197], v[0:3]
	v_mfma_f32_16x16x32_bf16 v[28:31], v[206:209], v[170:173], v[28:31]
	ds_read_b128 v[166:169], v139 offset:32768
	v_mfma_f32_16x16x32_bf16 v[24:27], v[228:231], v[170:173], v[24:27]
	v_mfma_f32_16x16x32_bf16 v[20:23], v[206:209], v[178:181], v[20:23]
	ds_read_b128 v[174:177], v139 offset:34816
	v_mfma_f32_16x16x32_bf16 v[16:19], v[228:231], v[178:181], v[16:19]
	v_mfma_f32_16x16x32_bf16 v[12:15], v[206:209], v[186:189], v[12:15]
	ds_read_b128 v[182:185], v139 offset:36864
	v_mfma_f32_16x16x32_bf16 v[8:11], v[228:231], v[186:189], v[8:11]
	v_mfma_f32_16x16x32_bf16 v[4:7], v[206:209], v[198:201], v[4:7]
	ds_read_b128 v[194:197], v139 offset:38912
	v_mfma_f32_16x16x32_bf16 v[0:3], v[228:231], v[198:201], v[0:3]
	s_barrier
	ds_read_b128 v[170:173], v139 offset:33792
	ds_read_b128 v[178:181], v139 offset:35840
	ds_read_b128 v[186:189], v139 offset:37888
	ds_read_b128 v[198:201], v139 offset:39936
	s_add_u32 m0, s9, 0x4000
	s_nop 0
	s_add_u32 vcc_lo, s4, s88
	s_addc_u32 vcc_hi, s5, s89
	global_load_lds_dwordx4 v132, vcc
	s_add_u32 m0, s9, 0x6000
	s_nop 0
	global_load_lds_dwordx4 v134, vcc
	s_waitcnt lgkmcnt(8)
	s_barrier
	s_waitcnt lgkmcnt(0)
	v_mfma_f32_16x16x32_bf16 v[124:127], v[150:153], v[166:169], v[124:127]
	v_mfma_f32_16x16x32_bf16 v[120:123], v[158:161], v[166:169], v[120:123]
	v_mfma_f32_16x16x32_bf16 v[116:119], v[150:153], v[174:177], v[116:119]
	v_mfma_f32_16x16x32_bf16 v[112:115], v[158:161], v[174:177], v[112:115]
	v_mfma_f32_16x16x32_bf16 v[108:111], v[150:153], v[182:185], v[108:111]
	v_mfma_f32_16x16x32_bf16 v[104:107], v[158:161], v[182:185], v[104:107]
	v_mfma_f32_16x16x32_bf16 v[100:103], v[150:153], v[194:197], v[100:103]
	v_mfma_f32_16x16x32_bf16 v[96:99], v[158:161], v[194:197], v[96:99]
	v_mfma_f32_16x16x32_bf16 v[124:127], v[154:157], v[170:173], v[124:127]
	v_mfma_f32_16x16x32_bf16 v[120:123], v[162:165], v[170:173], v[120:123]
	v_mfma_f32_16x16x32_bf16 v[116:119], v[154:157], v[178:181], v[116:119]
	v_mfma_f32_16x16x32_bf16 v[112:115], v[162:165], v[178:181], v[112:115]
	v_mfma_f32_16x16x32_bf16 v[108:111], v[154:157], v[186:189], v[108:111]
	v_mfma_f32_16x16x32_bf16 v[104:107], v[162:165], v[186:189], v[104:107]
	v_mfma_f32_16x16x32_bf16 v[100:103], v[154:157], v[198:201], v[100:103]
	v_mfma_f32_16x16x32_bf16 v[96:99], v[162:165], v[198:201], v[96:99]
	s_barrier
	ds_read_b128 v[202:205], v140 offset:49152
	ds_read_b128 v[206:209], v140 offset:50176
	ds_read_b128 v[224:227], v140 offset:51200
	ds_read_b128 v[228:231], v140 offset:52224
	s_add_u32 m0, s9, s30
	s_nop 0
	s_add_u32 vcc_lo, s4, s52
	s_addc_u32 vcc_hi, s5, s53
	global_load_lds_dwordx4 v128, vcc
	v_lshl_add_u64 v[238:239], v[236:237], 0, s[52:53]
	s_add_u32 m0, s9, s30
	s_add_u32 m0, m0, 0x2000
	s_nop 0
	global_load_lds_dwordx4 v130, vcc
	s_barrier
	s_waitcnt lgkmcnt(0)
	v_mfma_f32_16x16x32_bf16 v[92:95], v[202:205], v[166:169], v[92:95]
	v_mfma_f32_16x16x32_bf16 v[88:91], v[224:227], v[166:169], v[88:91]
	v_mfma_f32_16x16x32_bf16 v[84:87], v[202:205], v[174:177], v[84:87]
	v_mfma_f32_16x16x32_bf16 v[80:83], v[224:227], v[174:177], v[80:83]
	v_mfma_f32_16x16x32_bf16 v[76:79], v[202:205], v[182:185], v[76:79]
	v_mfma_f32_16x16x32_bf16 v[72:75], v[224:227], v[182:185], v[72:75]
	v_mfma_f32_16x16x32_bf16 v[68:71], v[202:205], v[194:197], v[68:71]
	v_mfma_f32_16x16x32_bf16 v[64:67], v[224:227], v[194:197], v[64:67]
	v_mfma_f32_16x16x32_bf16 v[92:95], v[206:209], v[170:173], v[92:95]
	ds_read_b128 v[166:169], v139 offset:49152
	v_mfma_f32_16x16x32_bf16 v[88:91], v[228:231], v[170:173], v[88:91]
	v_mfma_f32_16x16x32_bf16 v[84:87], v[206:209], v[178:181], v[84:87]
	ds_read_b128 v[174:177], v139 offset:51200
	v_mfma_f32_16x16x32_bf16 v[80:83], v[228:231], v[178:181], v[80:83]
	v_mfma_f32_16x16x32_bf16 v[76:79], v[206:209], v[186:189], v[76:79]
	ds_read_b128 v[182:185], v139 offset:53248
	v_mfma_f32_16x16x32_bf16 v[72:75], v[228:231], v[186:189], v[72:75]
	v_mfma_f32_16x16x32_bf16 v[68:71], v[206:209], v[198:201], v[68:71]
	ds_read_b128 v[194:197], v139 offset:55296
	v_mfma_f32_16x16x32_bf16 v[64:67], v[228:231], v[198:201], v[64:67]
	s_barrier
	ds_read_b128 v[170:173], v139 offset:50176
	ds_read_b128 v[178:181], v139 offset:52224
	ds_read_b128 v[186:189], v139 offset:54272
	ds_read_b128 v[198:201], v139 offset:56320
	v_add_u32_e32 v223, 0x8000, v192
	s_add_u32 m0, s9, 0x8000
	s_nop 0
	s_add_u32 vcc_lo, s4, s44
	s_addc_u32 vcc_hi, s5, s45
	global_load_lds_dwordx4 v132, vcc
	v_lshl_add_u64 v[190:191], v[232:233], 0, s[44:45]
	s_add_u32 m0, s9, 0xa000
	s_nop 0
	global_load_lds_dwordx4 v134, vcc
	s_waitcnt vmcnt(8)
	s_barrier
; #define WAIT_V(n) asm volatile("s_waitcnt vmcnt(" #n ")" ::: "memory")
; #define WAIT_L(n) asm volatile("s_waitcnt lgkmcnt(" #n ")" ::: "memory")
; #define BAR __builtin_amdgcn_s_barrier()
; #define SCHED __builtin_amdgcn_sched_barrier(0)
; #define STAGE(P, BASE, br, kt) do { const char* _g = (const char*)((BASE) + (size_t)(br) * GK + (kt) * BK); \
;     __builtin_amdgcn_global_load_lds((const unsigned*)(_g + voff0), (unsigned*)((char*)(P) + tx * 16), 16, 0, 0); \
;     __builtin_amdgcn_global_load_lds((const unsigned*)(_g + voff1), (unsigned*)((char*)(P) + tx * 16 + 8192), 16, 0, 0); } while (0)
; #define LDA(dst, b, h) _Pragma("unroll") for (int m = 0; m < 4; ++m) _Pragma("unroll") for (int k = 0; k < 2; ++k) \
;     dst[m][k] = *reinterpret_cast<const bf16x8*>((char*)shm + abase + (((b) * 2 + (h)) * 16384 + (m * 2 + k) * 1024))
; #define LDB(dst, b, h) _Pragma("unroll") for (int n = 0; n < 2; ++n) _Pragma("unroll") for (int k = 0; k < 2; ++k) \
;     dst[n][k] = *reinterpret_cast<const bf16x8*>((char*)shm + bbase + (((b) * 2 + (h)) * 16384 + (n * 2 + k) * 1024))
; template <bool SWAP>
; __device__ __forceinline__ void gemm_main(const u16* __restrict__ A, const u16* __restrict__ Bt, int brow, int bcol,
;                                           u16* shm, f32x4 (&acc)[2][2][4][2]) {
;     ...
;     BAR; WAIT_L(0); MMA(1, 0, At, B0); BAR; SCHED;
;     STAGE(SB(1, 1), Bt, bcol + HALF, t + 3);
;     WAIT_V(6); BAR; MMA(1, 1, At, B1); BAR;
;   }
;   { LDB(B0, 0, 0); LDA(At, 0, 0); STAGE(SA(1, 1), A, brow + HALF, nt - 1);
;     BAR; WAIT_L(0); MMA(0, 0, At, B0); BAR;
	s_waitcnt lgkmcnt(0)
	v_mfma_f32_16x16x32_bf16 v[60:63], v[150:153], v[166:169], v[60:63]
	v_mfma_f32_16x16x32_bf16 v[56:59], v[158:161], v[166:169], v[56:59]
	v_mfma_f32_16x16x32_bf16 v[52:55], v[150:153], v[174:177], v[52:55]
	v_mfma_f32_16x16x32_bf16 v[48:51], v[158:161], v[174:177], v[48:51]
	v_mfma_f32_16x16x32_bf16 v[44:47], v[150:153], v[182:185], v[44:47]
	v_mfma_f32_16x16x32_bf16 v[40:43], v[158:161], v[182:185], v[40:43]
	v_mfma_f32_16x16x32_bf16 v[36:39], v[150:153], v[194:197], v[36:39]
	v_mfma_f32_16x16x32_bf16 v[32:35], v[158:161], v[194:197], v[32:35]
	v_mfma_f32_16x16x32_bf16 v[60:63], v[154:157], v[170:173], v[60:63]
	v_mfma_f32_16x16x32_bf16 v[56:59], v[162:165], v[170:173], v[56:59]
	v_mfma_f32_16x16x32_bf16 v[52:55], v[154:157], v[178:181], v[52:55]
	v_mfma_f32_16x16x32_bf16 v[48:51], v[162:165], v[178:181], v[48:51]
	v_mfma_f32_16x16x32_bf16 v[44:47], v[154:157], v[186:189], v[44:47]
	v_mfma_f32_16x16x32_bf16 v[40:43], v[162:165], v[186:189], v[40:43]
	v_mfma_f32_16x16x32_bf16 v[36:39], v[154:157], v[198:201], v[36:39]
	v_mfma_f32_16x16x32_bf16 v[32:35], v[162:165], v[198:201], v[32:35]
	s_barrier
	ds_read_b128 v[150:153], v140
	ds_read_b128 v[154:157], v140 offset:1024
	ds_read_b128 v[158:161], v140 offset:2048
	ds_read_b128 v[162:165], v140 offset:3072
	s_add_u32 m0, s9, s31
	s_nop 0
	s_add_u32 vcc_lo, s4, s38
	s_addc_u32 vcc_hi, s5, s39
	global_load_lds_dwordx4 v128, vcc
	v_lshl_add_u64 v[254:255], v[236:237], 0, s[38:39]
	s_add_u32 m0, s9, s31
	s_add_u32 m0, m0, 0x2000
	s_nop 0
	global_load_lds_dwordx4 v130, vcc
	s_waitcnt vmcnt(6)
	s_barrier
	v_mfma_f32_16x16x32_bf16 v[28:31], v[202:205], v[166:169], v[28:31]
	v_mfma_f32_16x16x32_bf16 v[24:27], v[224:227], v[166:169], v[24:27]
	v_mfma_f32_16x16x32_bf16 v[20:23], v[202:205], v[174:177], v[20:23]
	v_mfma_f32_16x16x32_bf16 v[16:19], v[224:227], v[174:177], v[16:19]
	v_mfma_f32_16x16x32_bf16 v[12:15], v[202:205], v[182:185], v[12:15]
	v_mfma_f32_16x16x32_bf16 v[8:11], v[224:227], v[182:185], v[8:11]
	v_mfma_f32_16x16x32_bf16 v[4:7], v[202:205], v[194:197], v[4:7]
	v_mfma_f32_16x16x32_bf16 v[0:3], v[224:227], v[194:197], v[0:3]
	v_mfma_f32_16x16x32_bf16 v[28:31], v[206:209], v[170:173], v[28:31]
	ds_read_b128 v[166:169], v139
	v_mfma_f32_16x16x32_bf16 v[24:27], v[228:231], v[170:173], v[24:27]
	v_mfma_f32_16x16x32_bf16 v[20:23], v[206:209], v[178:181], v[20:23]
	ds_read_b128 v[174:177], v139 offset:2048
	v_mfma_f32_16x16x32_bf16 v[16:19], v[228:231], v[178:181], v[16:19]
	v_mfma_f32_16x16x32_bf16 v[12:15], v[206:209], v[186:189], v[12:15]
	ds_read_b128 v[182:185], v139 offset:4096
	v_mfma_f32_16x16x32_bf16 v[8:11], v[228:231], v[186:189], v[8:11]
	v_mfma_f32_16x16x32_bf16 v[4:7], v[206:209], v[198:201], v[4:7]
	ds_read_b128 v[194:197], v139 offset:6144
	v_mfma_f32_16x16x32_bf16 v[0:3], v[228:231], v[198:201], v[0:3]
	s_add_i32 s8, s8, 2
	s_add_u32 s4, s4, 0x100
	s_addc_u32 s5, s5, 0
	s_cmp_lt_u32 s8, 28
	s_barrier
	s_cbranch_scc1 .LBB0_627
	s_and_b32 s4, s7, 0xffffe0
	s_and_b32 s5, s6, 31
	s_or_b32 s4, s4, s5
	s_lshl_b32 s10, s4, 8
	v_lshlrev_b32_e32 v128, 3, v141
	v_lshlrev_b32_e32 v129, 5, v141
	v_and_b32_e32 v128, 0xffff0, v128
	v_and_b32_e32 v129, 32, v129
	s_or_b32 s4, s10, 0x80
	v_add_u32_e32 v129, v129, v144
	v_add_lshl_u32 v128, v143, v128, 12
	s_ashr_i32 s5, s4, 31
	v_lshl_add_u32 v192, v129, 1, v128
	v_lshlrev_b32_e32 v128, 3, v145
	v_lshlrev_b32_e32 v129, 5, v145
	s_lshl_b64 s[4:5], s[4:5], 12
	v_and_b32_e32 v128, 0xffff0, v128
	v_and_b32_e32 v129, 32, v129
	s_add_u32 s4, s84, s4
	v_add_u32_e32 v129, v129, v147
	v_add_lshl_u32 v128, v146, v128, 12
	s_addc_u32 s5, s85, s5
	v_lshl_add_u32 v146, v129, 1, v128
	v_mov_b32_e32 v147, v193
	v_lshl_add_u64 v[186:187], s[4:5], 0, v[192:193]
	s_mov_b64 s[8:9], 0xf80
	v_readfirstlane_b32 s7, v148
	v_lshl_add_u64 v[186:187], v[186:187], 0, s[8:9]
	s_mov_b32 m0, s7
	v_lshl_add_u64 v[146:147], s[4:5], 0, v[146:147]
	v_readfirstlane_b32 s4, v149
	ds_read_b128 v[128:131], v140
	ds_read_b128 v[132:135], v140 offset:1024
	ds_read_b128 v[142:145], v140 offset:2048
	ds_read_b128 v[150:153], v140 offset:3072
	ds_read_b128 v[154:157], v139
	ds_read_b128 v[158:161], v139 offset:1024
	ds_read_b128 v[162:165], v139 offset:2048
	ds_read_b128 v[166:169], v139 offset:3072
	ds_read_b128 v[170:173], v139 offset:4096
	ds_read_b128 v[174:177], v139 offset:5120
	ds_read_b128 v[178:181], v139 offset:6144
	ds_read_b128 v[182:185], v139 offset:7168
	global_load_lds_dwordx4 v[186:187], off
	v_lshl_add_u64 v[146:147], v[146:147], 0, s[8:9]
	s_mov_b32 m0, s4
	s_nop 0
	global_load_lds_dwordx4 v[146:147], off
	s_barrier
	s_waitcnt lgkmcnt(0)
	v_mfma_f32_16x16x32_bf16 v[124:127], v[128:131], v[154:157], v[124:127]
	v_mfma_f32_16x16x32_bf16 v[116:119], v[128:131], v[162:165], v[116:119]
	v_mfma_f32_16x16x32_bf16 v[108:111], v[128:131], v[170:173], v[108:111]
	v_mfma_f32_16x16x32_bf16 v[100:103], v[128:131], v[178:181], v[100:103]
	v_mfma_f32_16x16x32_bf16 v[124:127], v[132:135], v[158:161], v[124:127]
	v_mfma_f32_16x16x32_bf16 v[120:123], v[142:145], v[154:157], v[120:123]
	v_mfma_f32_16x16x32_bf16 v[116:119], v[132:135], v[166:169], v[116:119]
	v_mfma_f32_16x16x32_bf16 v[112:115], v[142:145], v[162:165], v[112:115]
	v_mfma_f32_16x16x32_bf16 v[108:111], v[132:135], v[174:177], v[108:111]
	v_mfma_f32_16x16x32_bf16 v[104:107], v[142:145], v[170:173], v[104:107]
	v_mfma_f32_16x16x32_bf16 v[100:103], v[132:135], v[182:185], v[100:103]
	v_mfma_f32_16x16x32_bf16 v[96:99], v[142:145], v[178:181], v[96:99]
	v_mfma_f32_16x16x32_bf16 v[146:149], v[150:153], v[158:161], v[120:123]
	v_mfma_f32_16x16x32_bf16 v[186:189], v[150:153], v[166:169], v[112:115]
	v_mfma_f32_16x16x32_bf16 v[194:197], v[150:153], v[174:177], v[104:107]
	v_mfma_f32_16x16x32_bf16 v[198:201], v[150:153], v[182:185], v[96:99]
	s_setprio 0
	s_barrier
; #define WAIT_V(n) asm volatile("s_waitcnt vmcnt(" #n ")" ::: "memory")
; #define WAIT_L(n) asm volatile("s_waitcnt lgkmcnt(" #n ")" ::: "memory")
; #define BAR __builtin_amdgcn_s_barrier()
; #define LDA(dst, b, h) _Pragma("unroll") for (int m = 0; m < 4; ++m) _Pragma("unroll") for (int k = 0; k < 2; ++k) \
;     dst[m][k] = *reinterpret_cast<const bf16x8*>((char*)shm + abase + (((b) * 2 + (h)) * 16384 + (m * 2 + k) * 1024))
; #define LDB(dst, b, h) _Pragma("unroll") for (int n = 0; n < 2; ++n) _Pragma("unroll") for (int k = 0; k < 2; ++k) \
;     dst[n][k] = *reinterpret_cast<const bf16x8*>((char*)shm + bbase + (((b) * 2 + (h)) * 16384 + (n * 2 + k) * 1024))
; template <bool SWAP>
; __device__ __forceinline__ void gemm_main(const u16* __restrict__ A, const u16* __restrict__ Bt, int brow, int bcol,
;                                           u16* shm, f32x4 (&acc)[2][2][4][2]) {
;     ...
;     BAR; WAIT_L(0); MMA(0, 0, At, B0); BAR;
;     LDB(B1, 0, 1); BAR; WAIT_L(0); MMA(0, 1, At, B1); BAR;
;     LDA(At, 0, 1); WAIT_V(4); BAR; WAIT_L(0); MMA(1, 0, At, B0); MMA(1, 1, At, B1); BAR; }
;   { LDB(B0, 1, 0); LDA(At, 1, 0); WAIT_V(2); BAR; WAIT_L(0); MMA(0, 0, At, B0); BAR;
	s_nop 1
	ds_read_b128 v[96:99], v140 offset:16384
	ds_read_b128 v[104:107], v140 offset:17408
	ds_read_b128 v[112:115], v140 offset:18432
	ds_read_b128 v[120:123], v140 offset:19456
	s_barrier
	s_waitcnt lgkmcnt(0)
	v_mfma_f32_16x16x32_bf16 v[92:95], v[96:99], v[154:157], v[92:95]
	v_mfma_f32_16x16x32_bf16 v[84:87], v[96:99], v[162:165], v[84:87]
	v_mfma_f32_16x16x32_bf16 v[76:79], v[96:99], v[170:173], v[76:79]
	v_mfma_f32_16x16x32_bf16 v[68:71], v[96:99], v[178:181], v[68:71]
	v_mfma_f32_16x16x32_bf16 v[92:95], v[104:107], v[158:161], v[92:95]
	v_mfma_f32_16x16x32_bf16 v[88:91], v[112:115], v[154:157], v[88:91]
	v_mfma_f32_16x16x32_bf16 v[84:87], v[104:107], v[166:169], v[84:87]
	v_mfma_f32_16x16x32_bf16 v[80:83], v[112:115], v[162:165], v[80:83]
	v_mfma_f32_16x16x32_bf16 v[76:79], v[104:107], v[174:177], v[76:79]
	v_mfma_f32_16x16x32_bf16 v[72:75], v[112:115], v[170:173], v[72:75]
	v_mfma_f32_16x16x32_bf16 v[68:71], v[104:107], v[182:185], v[68:71]
	v_mfma_f32_16x16x32_bf16 v[64:67], v[112:115], v[178:181], v[64:67]
	v_mfma_f32_16x16x32_bf16 v[154:157], v[120:123], v[158:161], v[88:91]
	v_mfma_f32_16x16x32_bf16 v[158:161], v[120:123], v[166:169], v[80:83]
	v_mfma_f32_16x16x32_bf16 v[162:165], v[120:123], v[174:177], v[72:75]
	v_mfma_f32_16x16x32_bf16 v[166:169], v[120:123], v[182:185], v[64:67]
	s_setprio 0
	s_barrier
	s_nop 1
	ds_read_b128 v[64:67], v139 offset:16384
	ds_read_b128 v[72:75], v139 offset:17408
	ds_read_b128 v[80:83], v139 offset:18432
	ds_read_b128 v[88:91], v139 offset:19456
	ds_read_b128 v[170:173], v139 offset:20480
	ds_read_b128 v[174:177], v139 offset:21504
	ds_read_b128 v[178:181], v139 offset:22528
	ds_read_b128 v[182:185], v139 offset:23552
	s_waitcnt vmcnt(4)
	s_barrier
	s_waitcnt lgkmcnt(0)
	v_mfma_f32_16x16x32_bf16 v[60:63], v[128:131], v[64:67], v[60:63]
	v_mfma_f32_16x16x32_bf16 v[52:55], v[128:131], v[80:83], v[52:55]
	v_mfma_f32_16x16x32_bf16 v[44:47], v[128:131], v[170:173], v[44:47]
	v_mfma_f32_16x16x32_bf16 v[36:39], v[128:131], v[178:181], v[36:39]
	v_mfma_f32_16x16x32_bf16 v[60:63], v[132:135], v[72:75], v[60:63]
	v_mfma_f32_16x16x32_bf16 v[56:59], v[142:145], v[64:67], v[56:59]
	v_mfma_f32_16x16x32_bf16 v[52:55], v[132:135], v[88:91], v[52:55]
	v_mfma_f32_16x16x32_bf16 v[48:51], v[142:145], v[80:83], v[48:51]
	v_mfma_f32_16x16x32_bf16 v[44:47], v[132:135], v[174:177], v[44:47]
	v_mfma_f32_16x16x32_bf16 v[40:43], v[142:145], v[170:173], v[40:43]
	v_mfma_f32_16x16x32_bf16 v[36:39], v[132:135], v[182:185], v[36:39]
	v_mfma_f32_16x16x32_bf16 v[32:35], v[142:145], v[178:181], v[32:35]
	v_mfma_f32_16x16x32_bf16 v[202:205], v[150:153], v[72:75], v[56:59]
	v_mfma_f32_16x16x32_bf16 v[206:209], v[150:153], v[88:91], v[48:51]
	v_mfma_f32_16x16x32_bf16 v[224:227], v[150:153], v[174:177], v[40:43]
	v_mfma_f32_16x16x32_bf16 v[128:131], v[150:153], v[182:185], v[32:35]
	s_setprio 0
	v_mfma_f32_16x16x32_bf16 v[28:31], v[96:99], v[64:67], v[28:31]
	v_mfma_f32_16x16x32_bf16 v[20:23], v[96:99], v[80:83], v[20:23]
	v_mfma_f32_16x16x32_bf16 v[12:15], v[96:99], v[170:173], v[12:15]
	v_mfma_f32_16x16x32_bf16 v[4:7], v[96:99], v[178:181], v[4:7]
	v_mfma_f32_16x16x32_bf16 v[28:31], v[104:107], v[72:75], v[28:31]
	v_mfma_f32_16x16x32_bf16 v[24:27], v[112:115], v[64:67], v[24:27]
	v_mfma_f32_16x16x32_bf16 v[20:23], v[104:107], v[88:91], v[20:23]
	v_mfma_f32_16x16x32_bf16 v[16:19], v[112:115], v[80:83], v[16:19]
	v_mfma_f32_16x16x32_bf16 v[12:15], v[104:107], v[174:177], v[12:15]
	v_mfma_f32_16x16x32_bf16 v[8:11], v[112:115], v[170:173], v[8:11]
	v_mfma_f32_16x16x32_bf16 v[4:7], v[104:107], v[182:185], v[4:7]
	v_mfma_f32_16x16x32_bf16 v[0:3], v[112:115], v[178:181], v[0:3]
	v_mfma_f32_16x16x32_bf16 v[132:135], v[120:123], v[72:75], v[24:27]
	v_mfma_f32_16x16x32_bf16 v[142:145], v[120:123], v[88:91], v[16:19]
	v_mfma_f32_16x16x32_bf16 v[150:153], v[120:123], v[174:177], v[8:11]
	v_mfma_f32_16x16x32_bf16 v[170:173], v[120:123], v[182:185], v[0:3]
	s_setprio 0
	s_barrier
	s_nop 1
	ds_read_b128 v[0:3], v140 offset:32768
	ds_read_b128 v[8:11], v140 offset:33792
	ds_read_b128 v[16:19], v140 offset:34816
	ds_read_b128 v[24:27], v140 offset:35840
	ds_read_b128 v[32:35], v139 offset:32768
	ds_read_b128 v[40:43], v139 offset:33792
	ds_read_b128 v[48:51], v139 offset:34816
	ds_read_b128 v[56:59], v139 offset:35840
	ds_read_b128 v[64:67], v139 offset:36864
	ds_read_b128 v[174:177], v139 offset:37888
	ds_read_b128 v[178:181], v139 offset:38912
	ds_read_b128 v[182:185], v139 offset:39936
	s_waitcnt vmcnt(2)
	s_barrier
; #define WAIT_V(n) asm volatile("s_waitcnt vmcnt(" #n ")" ::: "memory")
; #define WAIT_L(n) asm volatile("s_waitcnt lgkmcnt(" #n ")" ::: "memory")
; #define BAR __builtin_amdgcn_s_barrier()
; #define LDA(dst, b, h) _Pragma("unroll") for (int m = 0; m < 4; ++m) _Pragma("unroll") for (int k = 0; k < 2; ++k) \
;     dst[m][k] = *reinterpret_cast<const bf16x8*>((char*)shm + abase + (((b) * 2 + (h)) * 16384 + (m * 2 + k) * 1024))
; #define LDB(dst, b, h) _Pragma("unroll") for (int n = 0; n < 2; ++n) _Pragma("unroll") for (int k = 0; k < 2; ++k) \
;     dst[n][k] = *reinterpret_cast<const bf16x8*>((char*)shm + bbase + (((b) * 2 + (h)) * 16384 + (n * 2 + k) * 1024))
; template <bool SWAP>
; __device__ __forceinline__ void gemm_main(const u16* __restrict__ A, const u16* __restrict__ Bt, int brow, int bcol,
;                                           u16* shm, f32x4 (&acc)[2][2][4][2]) {
;     ...
;   { LDB(B0, 1, 0); LDA(At, 1, 0); WAIT_V(2); BAR; WAIT_L(0); MMA(0, 0, At, B0); BAR;
;     LDB(B1, 1, 1); WAIT_V(0); BAR; WAIT_L(0); MMA(0, 1, At, B1); BAR;
;     LDA(At, 1, 1); BAR; WAIT_L(0); MMA(1, 0, At, B0); MMA(1, 1, At, B1); BAR; }
;   if (wr == 0) BAR;
	s_waitcnt lgkmcnt(0)
	v_mfma_f32_16x16x32_bf16 v[72:75], v[0:3], v[32:35], v[124:127]
	v_mfma_f32_16x16x32_bf16 v[120:123], v[8:11], v[40:43], v[72:75]
	v_mfma_f32_16x16x32_bf16 v[72:75], v[16:19], v[32:35], v[146:149]
	v_mfma_f32_16x16x32_bf16 v[124:127], v[24:27], v[40:43], v[72:75]
	v_mfma_f32_16x16x32_bf16 v[72:75], v[0:3], v[48:51], v[116:119]
	v_mfma_f32_16x16x32_bf16 v[112:115], v[8:11], v[56:59], v[72:75]
	v_mfma_f32_16x16x32_bf16 v[72:75], v[16:19], v[48:51], v[186:189]
	v_mfma_f32_16x16x32_bf16 v[116:119], v[24:27], v[56:59], v[72:75]
	v_mfma_f32_16x16x32_bf16 v[72:75], v[0:3], v[64:67], v[108:111]
	v_mfma_f32_16x16x32_bf16 v[104:107], v[8:11], v[174:177], v[72:75]
	v_mfma_f32_16x16x32_bf16 v[72:75], v[16:19], v[64:67], v[194:197]
	v_mfma_f32_16x16x32_bf16 v[108:111], v[24:27], v[174:177], v[72:75]
	v_mfma_f32_16x16x32_bf16 v[72:75], v[0:3], v[178:181], v[100:103]
	v_mfma_f32_16x16x32_bf16 v[96:99], v[8:11], v[182:185], v[72:75]
	v_mfma_f32_16x16x32_bf16 v[72:75], v[16:19], v[178:181], v[198:201]
	v_mfma_f32_16x16x32_bf16 v[100:103], v[24:27], v[182:185], v[72:75]
	s_setprio 0
	s_barrier
	ds_read_b128 v[146:149], v140 offset:49152
	ds_read_b128 v[186:189], v140 offset:50176
	ds_read_b128 v[194:197], v140 offset:51200
	ds_read_b128 v[198:201], v140 offset:52224
	s_waitcnt vmcnt(0)
	s_barrier
	s_waitcnt lgkmcnt(0)
	v_mfma_f32_16x16x32_bf16 v[72:75], v[146:149], v[32:35], v[92:95]
	v_mfma_f32_16x16x32_bf16 v[32:35], v[194:197], v[32:35], v[154:157]
	v_mfma_f32_16x16x32_bf16 v[92:95], v[198:201], v[40:43], v[32:35]
	v_mfma_f32_16x16x32_bf16 v[32:35], v[146:149], v[48:51], v[84:87]
	v_mfma_f32_16x16x32_bf16 v[80:83], v[186:189], v[56:59], v[32:35]
	v_mfma_f32_16x16x32_bf16 v[32:35], v[194:197], v[48:51], v[158:161]
	v_mfma_f32_16x16x32_bf16 v[84:87], v[198:201], v[56:59], v[32:35]
	v_mfma_f32_16x16x32_bf16 v[32:35], v[146:149], v[64:67], v[76:79]
	v_mfma_f32_16x16x32_bf16 v[88:91], v[186:189], v[40:43], v[72:75]
	v_mfma_f32_16x16x32_bf16 v[72:75], v[186:189], v[174:177], v[32:35]
	v_mfma_f32_16x16x32_bf16 v[32:35], v[194:197], v[64:67], v[162:165]
	v_mfma_f32_16x16x32_bf16 v[76:79], v[198:201], v[174:177], v[32:35]
	v_mfma_f32_16x16x32_bf16 v[32:35], v[146:149], v[178:181], v[68:71]
	v_mfma_f32_16x16x32_bf16 v[64:67], v[186:189], v[182:185], v[32:35]
	v_mfma_f32_16x16x32_bf16 v[32:35], v[194:197], v[178:181], v[166:169]
	v_mfma_f32_16x16x32_bf16 v[68:71], v[198:201], v[182:185], v[32:35]
	s_setprio 0
	s_barrier
	ds_read_b128 v[154:157], v139 offset:49152
	ds_read_b128 v[158:161], v139 offset:50176
	ds_read_b128 v[162:165], v139 offset:51200
	ds_read_b128 v[166:169], v139 offset:52224
	ds_read_b128 v[174:177], v139 offset:53248
	ds_read_b128 v[178:181], v139 offset:54272
	ds_read_b128 v[182:185], v139 offset:55296
	ds_read_b128 v[228:231], v139 offset:56320
	s_barrier
	s_waitcnt lgkmcnt(0)
	v_mfma_f32_16x16x32_bf16 v[32:35], v[0:3], v[154:157], v[60:63]
	v_mfma_f32_16x16x32_bf16 v[56:59], v[8:11], v[158:161], v[32:35]
	v_mfma_f32_16x16x32_bf16 v[32:35], v[16:19], v[154:157], v[202:205]
	v_mfma_f32_16x16x32_bf16 v[60:63], v[24:27], v[158:161], v[32:35]
	v_mfma_f32_16x16x32_bf16 v[32:35], v[0:3], v[162:165], v[52:55]
	v_mfma_f32_16x16x32_bf16 v[48:51], v[8:11], v[166:169], v[32:35]
	v_mfma_f32_16x16x32_bf16 v[32:35], v[16:19], v[162:165], v[206:209]
	v_mfma_f32_16x16x32_bf16 v[52:55], v[24:27], v[166:169], v[32:35]
	v_mfma_f32_16x16x32_bf16 v[32:35], v[0:3], v[174:177], v[44:47]
	v_mfma_f32_16x16x32_bf16 v[40:43], v[8:11], v[178:181], v[32:35]
	v_mfma_f32_16x16x32_bf16 v[32:35], v[16:19], v[174:177], v[224:227]
	v_mfma_f32_16x16x32_bf16 v[0:3], v[0:3], v[182:185], v[36:39]
	v_mfma_f32_16x16x32_bf16 v[44:47], v[24:27], v[178:181], v[32:35]
	v_mfma_f32_16x16x32_bf16 v[32:35], v[8:11], v[228:231], v[0:3]
	v_mfma_f32_16x16x32_bf16 v[0:3], v[16:19], v[182:185], v[128:131]
	v_mfma_f32_16x16x32_bf16 v[36:39], v[24:27], v[228:231], v[0:3]
	s_setprio 0
	v_mfma_f32_16x16x32_bf16 v[0:3], v[146:149], v[154:157], v[28:31]
	v_mfma_f32_16x16x32_bf16 v[24:27], v[186:189], v[158:161], v[0:3]
	v_mfma_f32_16x16x32_bf16 v[0:3], v[194:197], v[154:157], v[132:135]
	v_mfma_f32_16x16x32_bf16 v[28:31], v[198:201], v[158:161], v[0:3]
	v_mfma_f32_16x16x32_bf16 v[0:3], v[146:149], v[162:165], v[20:23]
	v_mfma_f32_16x16x32_bf16 v[16:19], v[186:189], v[166:169], v[0:3]
	v_mfma_f32_16x16x32_bf16 v[0:3], v[194:197], v[162:165], v[142:145]
	v_mfma_f32_16x16x32_bf16 v[20:23], v[198:201], v[166:169], v[0:3]
	v_mfma_f32_16x16x32_bf16 v[0:3], v[146:149], v[174:177], v[12:15]
	v_mfma_f32_16x16x32_bf16 v[8:11], v[186:189], v[178:181], v[0:3]
	v_mfma_f32_16x16x32_bf16 v[0:3], v[194:197], v[174:177], v[150:153]
	v_mfma_f32_16x16x32_bf16 v[12:15], v[198:201], v[178:181], v[0:3]
	v_mfma_f32_16x16x32_bf16 v[0:3], v[146:149], v[182:185], v[4:7]
	v_mfma_f32_16x16x32_bf16 v[4:7], v[194:197], v[182:185], v[170:173]
	v_mfma_f32_16x16x32_bf16 v[0:3], v[186:189], v[228:231], v[0:3]
	v_mfma_f32_16x16x32_bf16 v[4:7], v[198:201], v[228:231], v[4:7]
	s_setprio 0
	s_movk_i32 s4, 0x100
	v_cmp_gt_u32_e32 vcc, s4, v138
	s_barrier
	s_and_saveexec_b64 s[4:5], vcc
	s_cbranch_execz .LBB0_630
	s_barrier
